# inter-chunk scan unrolled over the 64 chunks with the next 16 chunks of loads always in flight
# speedup vs baseline: 1.0153x; 1.0003x over previous
; __device__ __forceinline__ float bf2f(bf16 v) { return __uint_as_float(((unsigned)v) << 16); }
; __device__ __forceinline__ unsigned f2bfu(float f) { return (unsigned)__builtin_bit_cast(unsigned short, (__bf16)f); }
; __global__ void __launch_bounds__(NTHR, 2) k_main(Args a) {
;     ...
;         for (int idx = gtid; idx < 2 * 8 * 8192; idx += gthreads) {
;             const int pn = idx & 8191, h = (idx >> 13) & 7, b = idx >> 16;
;             float run = 0.f;
; #pragma unroll 1
;             for (int c0 = 0; c0 < 64; c0 += 8) {
;                 float st[8], dc[8];
; #pragma unroll
;                 for (int j = 0; j < 8; ++j) { const int bch = (b * 64 + c0 + j) * 8 + h; st[j] = bf2f(__builtin_nontemporal_load(&STATES[(size_t)bch * 8192 + pn])); dc[j] = CDEC[bch]; }
; #pragma unroll
;                 for (int j = 0; j < 8; ++j) { const int bch = (b * 64 + c0 + j) * 8 + h; __builtin_amdgcn_raw_buffer_store_b16((short)f2bfu(run), rsPV, (int)(((unsigned)bch * 8192u + (unsigned)pn) * 2u), 0, 16); run = dc[j] * run + st[j]; }
;             }
;         }
.LBB0_377:
	v_and_b32_e32 v2, 0x1fff, v8
	v_ashrrev_i32_e32 v10, 10, v8
	v_lshlrev_b32_e32 v2, 1, v2
	v_lshl_add_u64 v[4:5], s[58:59], 0, v[2:3]
	v_lshrrev_b32_e32 v2, 6, v10
	v_bfe_u32 v6, v8, 13, 3
	v_and_b32_e32 v7, 0x1fffe, v9
	v_lshlrev_b32_e32 v10, 9, v2
	v_lshlrev_b32_e32 v2, 23, v2
	v_or3_b32 v6, v10, v6, 56
	v_or3_b32 v2, v2, v7, s10
	s_mov_b32 s12, -8
	v_mov_b32_e32 v10, 0
	v_subrev_u32_e32 v46, 56, v6
	v_and_b32_e32 v47, 0x1fff, v8
	v_lshlrev_b32_e32 v47, 1, v47
	v_lshl_add_u32 v47, v46, 14, v47
	v_lshlrev_b32_e32 v50, 2, v46
	v_add_u32_e32 v51, 0xfff20000, v2
	global_load_ushort v128, v47, s[58:59] nt
	v_add_u32_e32 v53, 0x20000, v47
	global_load_ushort v129, v53, s[58:59] nt
	v_add_u32_e32 v53, 0x40000, v47
	global_load_ushort v130, v53, s[58:59] nt
	v_add_u32_e32 v53, 0x60000, v47
	global_load_ushort v131, v53, s[58:59] nt
	v_add_u32_e32 v53, 0x80000, v47
	global_load_ushort v132, v53, s[58:59] nt
	v_add_u32_e32 v53, 0xa0000, v47
	global_load_ushort v133, v53, s[58:59] nt
	v_add_u32_e32 v53, 0xc0000, v47
	global_load_ushort v134, v53, s[58:59] nt
	v_add_u32_e32 v53, 0xe0000, v47
	global_load_ushort v135, v53, s[58:59] nt
	v_add_u32_e32 v53, 0x100000, v47
	global_load_ushort v136, v53, s[58:59] nt
	v_add_u32_e32 v53, 0x120000, v47
	global_load_ushort v137, v53, s[58:59] nt
	v_add_u32_e32 v53, 0x140000, v47
	global_load_ushort v138, v53, s[58:59] nt
	v_add_u32_e32 v53, 0x160000, v47
	global_load_ushort v139, v53, s[58:59] nt
	v_add_u32_e32 v53, 0x180000, v47
	global_load_ushort v140, v53, s[58:59] nt
	v_add_u32_e32 v53, 0x1a0000, v47
	global_load_ushort v141, v53, s[58:59] nt
	v_add_u32_e32 v53, 0x1c0000, v47
	global_load_ushort v142, v53, s[58:59] nt
	v_add_u32_e32 v53, 0x1e0000, v47
	global_load_ushort v143, v53, s[58:59] nt
	global_load_dword v160, v50, s[82:83]
	global_load_dword v161, v50, s[82:83] offset:32
	global_load_dword v162, v50, s[82:83] offset:64
	global_load_dword v163, v50, s[82:83] offset:96
	global_load_dword v164, v50, s[82:83] offset:128
	global_load_dword v165, v50, s[82:83] offset:160
	global_load_dword v166, v50, s[82:83] offset:192
	global_load_dword v167, v50, s[82:83] offset:224
	global_load_dword v168, v50, s[82:83] offset:256
	global_load_dword v169, v50, s[82:83] offset:288
	global_load_dword v170, v50, s[82:83] offset:320
	global_load_dword v171, v50, s[82:83] offset:352
	global_load_dword v172, v50, s[82:83] offset:384
	global_load_dword v173, v50, s[82:83] offset:416
	global_load_dword v174, v50, s[82:83] offset:448
	global_load_dword v175, v50, s[82:83] offset:480
	v_add_u32_e32 v53, 0x200000, v47
	global_load_ushort v144, v53, s[58:59] nt
	v_add_u32_e32 v53, 0x220000, v47
	global_load_ushort v145, v53, s[58:59] nt
	v_add_u32_e32 v53, 0x240000, v47
	global_load_ushort v146, v53, s[58:59] nt
	v_add_u32_e32 v53, 0x260000, v47
	global_load_ushort v147, v53, s[58:59] nt
	v_add_u32_e32 v53, 0x280000, v47
	global_load_ushort v148, v53, s[58:59] nt
	v_add_u32_e32 v53, 0x2a0000, v47
	global_load_ushort v149, v53, s[58:59] nt
	v_add_u32_e32 v53, 0x2c0000, v47
	global_load_ushort v150, v53, s[58:59] nt
	v_add_u32_e32 v53, 0x2e0000, v47
	global_load_ushort v151, v53, s[58:59] nt
	v_add_u32_e32 v53, 0x300000, v47
	global_load_ushort v152, v53, s[58:59] nt
	v_add_u32_e32 v53, 0x320000, v47
	global_load_ushort v153, v53, s[58:59] nt
	v_add_u32_e32 v53, 0x340000, v47
	global_load_ushort v154, v53, s[58:59] nt
	v_add_u32_e32 v53, 0x360000, v47
	global_load_ushort v155, v53, s[58:59] nt
	v_add_u32_e32 v53, 0x380000, v47
	global_load_ushort v156, v53, s[58:59] nt
	v_add_u32_e32 v53, 0x3a0000, v47
	global_load_ushort v157, v53, s[58:59] nt
	v_add_u32_e32 v53, 0x3c0000, v47
	global_load_ushort v158, v53, s[58:59] nt
	v_add_u32_e32 v53, 0x3e0000, v47
	global_load_ushort v159, v53, s[58:59] nt
	global_load_dword v176, v50, s[82:83] offset:512
	global_load_dword v177, v50, s[82:83] offset:544
	global_load_dword v178, v50, s[82:83] offset:576
	global_load_dword v179, v50, s[82:83] offset:608
	global_load_dword v180, v50, s[82:83] offset:640
	global_load_dword v181, v50, s[82:83] offset:672
	global_load_dword v182, v50, s[82:83] offset:704
	global_load_dword v183, v50, s[82:83] offset:736
	global_load_dword v184, v50, s[82:83] offset:768
	global_load_dword v185, v50, s[82:83] offset:800
	global_load_dword v186, v50, s[82:83] offset:832
	global_load_dword v187, v50, s[82:83] offset:864
	global_load_dword v188, v50, s[82:83] offset:896
	global_load_dword v189, v50, s[82:83] offset:928
	global_load_dword v190, v50, s[82:83] offset:960
	global_load_dword v191, v50, s[82:83] offset:992
	v_cvt_pk_bf16_f32 v52, v10, v10
	buffer_store_short v52, v51, s[4:7], 0 offen sc1
	s_waitcnt vmcnt(48)
	v_lshlrev_b32_e32 v128, 16, v128
	v_fmac_f32_e32 v128, v10, v160
	v_mov_b32_e32 v10, v128
	v_cvt_pk_bf16_f32 v52, v10, v10
	s_mov_b32 s13, 0x20000
	buffer_store_short v52, v51, s[4:7], s13 offen sc1
	s_waitcnt vmcnt(48)
	v_lshlrev_b32_e32 v129, 16, v129
	v_fmac_f32_e32 v129, v10, v161
	v_mov_b32_e32 v10, v129
	v_cvt_pk_bf16_f32 v52, v10, v10
	s_mov_b32 s13, 0x40000
	buffer_store_short v52, v51, s[4:7], s13 offen sc1
	s_waitcnt vmcnt(48)
	v_lshlrev_b32_e32 v130, 16, v130
	v_fmac_f32_e32 v130, v10, v162
	v_mov_b32_e32 v10, v130
	v_cvt_pk_bf16_f32 v52, v10, v10
	s_mov_b32 s13, 0x60000
	buffer_store_short v52, v51, s[4:7], s13 offen sc1
	s_waitcnt vmcnt(48)
	v_lshlrev_b32_e32 v131, 16, v131
	v_fmac_f32_e32 v131, v10, v163
	v_mov_b32_e32 v10, v131
	v_cvt_pk_bf16_f32 v52, v10, v10
	s_mov_b32 s13, 0x80000
	buffer_store_short v52, v51, s[4:7], s13 offen sc1
	s_waitcnt vmcnt(48)
; __device__ __forceinline__ float bf2f(bf16 v) { return __uint_as_float(((unsigned)v) << 16); }
; __device__ __forceinline__ unsigned f2bfu(float f) { return (unsigned)__builtin_bit_cast(unsigned short, (__bf16)f); }
; __global__ void __launch_bounds__(NTHR, 2) k_main(Args a) {
;     ...
;         for (int idx = gtid; idx < 2 * 8 * 8192; idx += gthreads) {
;             const int pn = idx & 8191, h = (idx >> 13) & 7, b = idx >> 16;
;             float run = 0.f;
; #pragma unroll 1
;             for (int c0 = 0; c0 < 64; c0 += 8) {
;                 float st[8], dc[8];
; #pragma unroll
;                 for (int j = 0; j < 8; ++j) { const int bch = (b * 64 + c0 + j) * 8 + h; st[j] = bf2f(__builtin_nontemporal_load(&STATES[(size_t)bch * 8192 + pn])); dc[j] = CDEC[bch]; }
; #pragma unroll
;                 for (int j = 0; j < 8; ++j) { const int bch = (b * 64 + c0 + j) * 8 + h; __builtin_amdgcn_raw_buffer_store_b16((short)f2bfu(run), rsPV, (int)(((unsigned)bch * 8192u + (unsigned)pn) * 2u), 0, 16); run = dc[j] * run + st[j]; }
;             }
;         }
	v_lshlrev_b32_e32 v132, 16, v132
	v_fmac_f32_e32 v132, v10, v164
	v_mov_b32_e32 v10, v132
	v_cvt_pk_bf16_f32 v52, v10, v10
	s_mov_b32 s13, 0xa0000
	buffer_store_short v52, v51, s[4:7], s13 offen sc1
	s_waitcnt vmcnt(48)
	v_lshlrev_b32_e32 v133, 16, v133
	v_fmac_f32_e32 v133, v10, v165
	v_mov_b32_e32 v10, v133
	v_cvt_pk_bf16_f32 v52, v10, v10
	s_mov_b32 s13, 0xc0000
	buffer_store_short v52, v51, s[4:7], s13 offen sc1
	s_waitcnt vmcnt(48)
	v_lshlrev_b32_e32 v134, 16, v134
	v_fmac_f32_e32 v134, v10, v166
	v_mov_b32_e32 v10, v134
	v_cvt_pk_bf16_f32 v52, v10, v10
	s_mov_b32 s13, 0xe0000
	buffer_store_short v52, v51, s[4:7], s13 offen sc1
	s_waitcnt vmcnt(48)
	v_lshlrev_b32_e32 v135, 16, v135
	v_fmac_f32_e32 v135, v10, v167
	v_mov_b32_e32 v10, v135
	v_cvt_pk_bf16_f32 v52, v10, v10
	s_mov_b32 s13, 0x100000
	buffer_store_short v52, v51, s[4:7], s13 offen sc1
	s_waitcnt vmcnt(48)
	v_lshlrev_b32_e32 v136, 16, v136
	v_fmac_f32_e32 v136, v10, v168
	v_mov_b32_e32 v10, v136
	v_cvt_pk_bf16_f32 v52, v10, v10
	s_mov_b32 s13, 0x120000
	buffer_store_short v52, v51, s[4:7], s13 offen sc1
	s_waitcnt vmcnt(48)
	v_lshlrev_b32_e32 v137, 16, v137
	v_fmac_f32_e32 v137, v10, v169
	v_mov_b32_e32 v10, v137
	v_cvt_pk_bf16_f32 v52, v10, v10
	s_mov_b32 s13, 0x140000
	buffer_store_short v52, v51, s[4:7], s13 offen sc1
	s_waitcnt vmcnt(48)
	v_lshlrev_b32_e32 v138, 16, v138
	v_fmac_f32_e32 v138, v10, v170
	v_mov_b32_e32 v10, v138
	v_cvt_pk_bf16_f32 v52, v10, v10
	s_mov_b32 s13, 0x160000
	buffer_store_short v52, v51, s[4:7], s13 offen sc1
	s_waitcnt vmcnt(48)
	v_lshlrev_b32_e32 v139, 16, v139
	v_fmac_f32_e32 v139, v10, v171
	v_mov_b32_e32 v10, v139
	v_cvt_pk_bf16_f32 v52, v10, v10
	s_mov_b32 s13, 0x180000
	buffer_store_short v52, v51, s[4:7], s13 offen sc1
	s_waitcnt vmcnt(48)
	v_lshlrev_b32_e32 v140, 16, v140
	v_fmac_f32_e32 v140, v10, v172
	v_mov_b32_e32 v10, v140
	v_cvt_pk_bf16_f32 v52, v10, v10
	s_mov_b32 s13, 0x1a0000
	buffer_store_short v52, v51, s[4:7], s13 offen sc1
	s_waitcnt vmcnt(48)
	v_lshlrev_b32_e32 v141, 16, v141
	v_fmac_f32_e32 v141, v10, v173
	v_mov_b32_e32 v10, v141
	v_cvt_pk_bf16_f32 v52, v10, v10
	s_mov_b32 s13, 0x1c0000
	buffer_store_short v52, v51, s[4:7], s13 offen sc1
	s_waitcnt vmcnt(48)
	v_lshlrev_b32_e32 v142, 16, v142
	v_fmac_f32_e32 v142, v10, v174
	v_mov_b32_e32 v10, v142
	v_cvt_pk_bf16_f32 v52, v10, v10
	s_mov_b32 s13, 0x1e0000
	buffer_store_short v52, v51, s[4:7], s13 offen sc1
	s_waitcnt vmcnt(48)
	v_lshlrev_b32_e32 v143, 16, v143
	v_fmac_f32_e32 v143, v10, v175
	v_mov_b32_e32 v10, v143
	v_add_u32_e32 v53, 0x400000, v47
	global_load_ushort v128, v53, s[58:59] nt
	v_add_u32_e32 v53, 0x420000, v47
	global_load_ushort v129, v53, s[58:59] nt
	v_add_u32_e32 v53, 0x440000, v47
	global_load_ushort v130, v53, s[58:59] nt
	v_add_u32_e32 v53, 0x460000, v47
	global_load_ushort v131, v53, s[58:59] nt
	v_add_u32_e32 v53, 0x480000, v47
	global_load_ushort v132, v53, s[58:59] nt
	v_add_u32_e32 v53, 0x4a0000, v47
	global_load_ushort v133, v53, s[58:59] nt
	v_add_u32_e32 v53, 0x4c0000, v47
	global_load_ushort v134, v53, s[58:59] nt
	v_add_u32_e32 v53, 0x4e0000, v47
	global_load_ushort v135, v53, s[58:59] nt
	v_add_u32_e32 v53, 0x500000, v47
	global_load_ushort v136, v53, s[58:59] nt
	v_add_u32_e32 v53, 0x520000, v47
	global_load_ushort v137, v53, s[58:59] nt
	v_add_u32_e32 v53, 0x540000, v47
	global_load_ushort v138, v53, s[58:59] nt
	v_add_u32_e32 v53, 0x560000, v47
	global_load_ushort v139, v53, s[58:59] nt
	v_add_u32_e32 v53, 0x580000, v47
	global_load_ushort v140, v53, s[58:59] nt
	v_add_u32_e32 v53, 0x5a0000, v47
	global_load_ushort v141, v53, s[58:59] nt
	v_add_u32_e32 v53, 0x5c0000, v47
	global_load_ushort v142, v53, s[58:59] nt
	v_add_u32_e32 v53, 0x5e0000, v47
	global_load_ushort v143, v53, s[58:59] nt
	global_load_dword v160, v50, s[82:83] offset:1024
	global_load_dword v161, v50, s[82:83] offset:1056
	global_load_dword v162, v50, s[82:83] offset:1088
	global_load_dword v163, v50, s[82:83] offset:1120
	global_load_dword v164, v50, s[82:83] offset:1152
	global_load_dword v165, v50, s[82:83] offset:1184
	global_load_dword v166, v50, s[82:83] offset:1216
	global_load_dword v167, v50, s[82:83] offset:1248
	global_load_dword v168, v50, s[82:83] offset:1280
	global_load_dword v169, v50, s[82:83] offset:1312
	global_load_dword v170, v50, s[82:83] offset:1344
	global_load_dword v171, v50, s[82:83] offset:1376
	global_load_dword v172, v50, s[82:83] offset:1408
	global_load_dword v173, v50, s[82:83] offset:1440
	global_load_dword v174, v50, s[82:83] offset:1472
	global_load_dword v175, v50, s[82:83] offset:1504
	v_cvt_pk_bf16_f32 v52, v10, v10
	s_mov_b32 s13, 0x200000
	buffer_store_short v52, v51, s[4:7], s13 offen sc1
	s_waitcnt vmcnt(63)
	v_lshlrev_b32_e32 v144, 16, v144
	v_fmac_f32_e32 v144, v10, v176
	v_mov_b32_e32 v10, v144
	v_cvt_pk_bf16_f32 v52, v10, v10
	s_mov_b32 s13, 0x220000
	buffer_store_short v52, v51, s[4:7], s13 offen sc1
	s_waitcnt vmcnt(63)
	v_lshlrev_b32_e32 v145, 16, v145
	v_fmac_f32_e32 v145, v10, v177
	v_mov_b32_e32 v10, v145
	v_cvt_pk_bf16_f32 v52, v10, v10
	s_mov_b32 s13, 0x240000
	buffer_store_short v52, v51, s[4:7], s13 offen sc1
	s_waitcnt vmcnt(63)
	v_lshlrev_b32_e32 v146, 16, v146
	v_fmac_f32_e32 v146, v10, v178
	v_mov_b32_e32 v10, v146
	v_cvt_pk_bf16_f32 v52, v10, v10
	s_mov_b32 s13, 0x260000
	buffer_store_short v52, v51, s[4:7], s13 offen sc1
	s_waitcnt vmcnt(63)
	v_lshlrev_b32_e32 v147, 16, v147
	v_fmac_f32_e32 v147, v10, v179
	v_mov_b32_e32 v10, v147
	v_cvt_pk_bf16_f32 v52, v10, v10
	s_mov_b32 s13, 0x280000
	buffer_store_short v52, v51, s[4:7], s13 offen sc1
	s_waitcnt vmcnt(63)
; __device__ __forceinline__ float bf2f(bf16 v) { return __uint_as_float(((unsigned)v) << 16); }
; __device__ __forceinline__ unsigned f2bfu(float f) { return (unsigned)__builtin_bit_cast(unsigned short, (__bf16)f); }
; __global__ void __launch_bounds__(NTHR, 2) k_main(Args a) {
;     ...
;         for (int idx = gtid; idx < 2 * 8 * 8192; idx += gthreads) {
;             const int pn = idx & 8191, h = (idx >> 13) & 7, b = idx >> 16;
;             float run = 0.f;
; #pragma unroll 1
;             for (int c0 = 0; c0 < 64; c0 += 8) {
;                 float st[8], dc[8];
; #pragma unroll
;                 for (int j = 0; j < 8; ++j) { const int bch = (b * 64 + c0 + j) * 8 + h; st[j] = bf2f(__builtin_nontemporal_load(&STATES[(size_t)bch * 8192 + pn])); dc[j] = CDEC[bch]; }
; #pragma unroll
;                 for (int j = 0; j < 8; ++j) { const int bch = (b * 64 + c0 + j) * 8 + h; __builtin_amdgcn_raw_buffer_store_b16((short)f2bfu(run), rsPV, (int)(((unsigned)bch * 8192u + (unsigned)pn) * 2u), 0, 16); run = dc[j] * run + st[j]; }
;             }
;         }
	v_lshlrev_b32_e32 v148, 16, v148
	v_fmac_f32_e32 v148, v10, v180
	v_mov_b32_e32 v10, v148
	v_cvt_pk_bf16_f32 v52, v10, v10
	s_mov_b32 s13, 0x2a0000
	buffer_store_short v52, v51, s[4:7], s13 offen sc1
	s_waitcnt vmcnt(63)
	v_lshlrev_b32_e32 v149, 16, v149
	v_fmac_f32_e32 v149, v10, v181
	v_mov_b32_e32 v10, v149
	v_cvt_pk_bf16_f32 v52, v10, v10
	s_mov_b32 s13, 0x2c0000
	buffer_store_short v52, v51, s[4:7], s13 offen sc1
	s_waitcnt vmcnt(63)
	v_lshlrev_b32_e32 v150, 16, v150
	v_fmac_f32_e32 v150, v10, v182
	v_mov_b32_e32 v10, v150
	v_cvt_pk_bf16_f32 v52, v10, v10
	s_mov_b32 s13, 0x2e0000
	buffer_store_short v52, v51, s[4:7], s13 offen sc1
	s_waitcnt vmcnt(63)
	v_lshlrev_b32_e32 v151, 16, v151
	v_fmac_f32_e32 v151, v10, v183
	v_mov_b32_e32 v10, v151
	v_cvt_pk_bf16_f32 v52, v10, v10
	s_mov_b32 s13, 0x300000
	buffer_store_short v52, v51, s[4:7], s13 offen sc1
	s_waitcnt vmcnt(63)
	v_lshlrev_b32_e32 v152, 16, v152
	v_fmac_f32_e32 v152, v10, v184
	v_mov_b32_e32 v10, v152
	v_cvt_pk_bf16_f32 v52, v10, v10
	s_mov_b32 s13, 0x320000
	buffer_store_short v52, v51, s[4:7], s13 offen sc1
	s_waitcnt vmcnt(63)
	v_lshlrev_b32_e32 v153, 16, v153
	v_fmac_f32_e32 v153, v10, v185
	v_mov_b32_e32 v10, v153
	v_cvt_pk_bf16_f32 v52, v10, v10
	s_mov_b32 s13, 0x340000
	buffer_store_short v52, v51, s[4:7], s13 offen sc1
	s_waitcnt vmcnt(63)
	v_lshlrev_b32_e32 v154, 16, v154
	v_fmac_f32_e32 v154, v10, v186
	v_mov_b32_e32 v10, v154
	v_cvt_pk_bf16_f32 v52, v10, v10
	s_mov_b32 s13, 0x360000
	buffer_store_short v52, v51, s[4:7], s13 offen sc1
	s_waitcnt vmcnt(63)
	v_lshlrev_b32_e32 v155, 16, v155
	v_fmac_f32_e32 v155, v10, v187
	v_mov_b32_e32 v10, v155
	v_cvt_pk_bf16_f32 v52, v10, v10
	s_mov_b32 s13, 0x380000
	buffer_store_short v52, v51, s[4:7], s13 offen sc1
	s_waitcnt vmcnt(63)
	v_lshlrev_b32_e32 v156, 16, v156
	v_fmac_f32_e32 v156, v10, v188
	v_mov_b32_e32 v10, v156
	v_cvt_pk_bf16_f32 v52, v10, v10
	s_mov_b32 s13, 0x3a0000
	buffer_store_short v52, v51, s[4:7], s13 offen sc1
	s_waitcnt vmcnt(63)
	v_lshlrev_b32_e32 v157, 16, v157
	v_fmac_f32_e32 v157, v10, v189
	v_mov_b32_e32 v10, v157
	v_cvt_pk_bf16_f32 v52, v10, v10
	s_mov_b32 s13, 0x3c0000
	buffer_store_short v52, v51, s[4:7], s13 offen sc1
	s_waitcnt vmcnt(63)
	v_lshlrev_b32_e32 v158, 16, v158
	v_fmac_f32_e32 v158, v10, v190
	v_mov_b32_e32 v10, v158
	v_cvt_pk_bf16_f32 v52, v10, v10
	s_mov_b32 s13, 0x3e0000
	buffer_store_short v52, v51, s[4:7], s13 offen sc1
	s_waitcnt vmcnt(63)
	v_lshlrev_b32_e32 v159, 16, v159
	v_fmac_f32_e32 v159, v10, v191
	v_mov_b32_e32 v10, v159
	v_add_u32_e32 v53, 0x600000, v47
	global_load_ushort v144, v53, s[58:59] nt
	v_add_u32_e32 v53, 0x620000, v47
	global_load_ushort v145, v53, s[58:59] nt
	v_add_u32_e32 v53, 0x640000, v47
	global_load_ushort v146, v53, s[58:59] nt
	v_add_u32_e32 v53, 0x660000, v47
	global_load_ushort v147, v53, s[58:59] nt
	v_add_u32_e32 v53, 0x680000, v47
	global_load_ushort v148, v53, s[58:59] nt
	v_add_u32_e32 v53, 0x6a0000, v47
	global_load_ushort v149, v53, s[58:59] nt
	v_add_u32_e32 v53, 0x6c0000, v47
	global_load_ushort v150, v53, s[58:59] nt
	v_add_u32_e32 v53, 0x6e0000, v47
	global_load_ushort v151, v53, s[58:59] nt
	v_add_u32_e32 v53, 0x700000, v47
	global_load_ushort v152, v53, s[58:59] nt
	v_add_u32_e32 v53, 0x720000, v47
	global_load_ushort v153, v53, s[58:59] nt
	v_add_u32_e32 v53, 0x740000, v47
	global_load_ushort v154, v53, s[58:59] nt
	v_add_u32_e32 v53, 0x760000, v47
	global_load_ushort v155, v53, s[58:59] nt
	v_add_u32_e32 v53, 0x780000, v47
	global_load_ushort v156, v53, s[58:59] nt
	v_add_u32_e32 v53, 0x7a0000, v47
	global_load_ushort v157, v53, s[58:59] nt
	v_add_u32_e32 v53, 0x7c0000, v47
	global_load_ushort v158, v53, s[58:59] nt
	v_add_u32_e32 v53, 0x7e0000, v47
	global_load_ushort v159, v53, s[58:59] nt
	global_load_dword v176, v50, s[82:83] offset:1536
	global_load_dword v177, v50, s[82:83] offset:1568
	global_load_dword v178, v50, s[82:83] offset:1600
	global_load_dword v179, v50, s[82:83] offset:1632
	global_load_dword v180, v50, s[82:83] offset:1664
	global_load_dword v181, v50, s[82:83] offset:1696
	global_load_dword v182, v50, s[82:83] offset:1728
	global_load_dword v183, v50, s[82:83] offset:1760
	global_load_dword v184, v50, s[82:83] offset:1792
	global_load_dword v185, v50, s[82:83] offset:1824
	global_load_dword v186, v50, s[82:83] offset:1856
	global_load_dword v187, v50, s[82:83] offset:1888
	global_load_dword v188, v50, s[82:83] offset:1920
	global_load_dword v189, v50, s[82:83] offset:1952
	global_load_dword v190, v50, s[82:83] offset:1984
	global_load_dword v191, v50, s[82:83] offset:2016
	v_cvt_pk_bf16_f32 v52, v10, v10
	s_mov_b32 s13, 0x400000
	buffer_store_short v52, v51, s[4:7], s13 offen sc1
	s_waitcnt vmcnt(63)
	v_lshlrev_b32_e32 v128, 16, v128
	v_fmac_f32_e32 v128, v10, v160
	v_mov_b32_e32 v10, v128
	v_cvt_pk_bf16_f32 v52, v10, v10
	s_mov_b32 s13, 0x420000
	buffer_store_short v52, v51, s[4:7], s13 offen sc1
	s_waitcnt vmcnt(63)
	v_lshlrev_b32_e32 v129, 16, v129
	v_fmac_f32_e32 v129, v10, v161
	v_mov_b32_e32 v10, v129
	v_cvt_pk_bf16_f32 v52, v10, v10
	s_mov_b32 s13, 0x440000
	buffer_store_short v52, v51, s[4:7], s13 offen sc1
	s_waitcnt vmcnt(63)
	v_lshlrev_b32_e32 v130, 16, v130
	v_fmac_f32_e32 v130, v10, v162
	v_mov_b32_e32 v10, v130
	v_cvt_pk_bf16_f32 v52, v10, v10
	s_mov_b32 s13, 0x460000
	buffer_store_short v52, v51, s[4:7], s13 offen sc1
	s_waitcnt vmcnt(63)
	v_lshlrev_b32_e32 v131, 16, v131
	v_fmac_f32_e32 v131, v10, v163
	v_mov_b32_e32 v10, v131
	v_cvt_pk_bf16_f32 v52, v10, v10
	s_mov_b32 s13, 0x480000
	buffer_store_short v52, v51, s[4:7], s13 offen sc1
	s_waitcnt vmcnt(63)
; __device__ __forceinline__ float bf2f(bf16 v) { return __uint_as_float(((unsigned)v) << 16); }
; __device__ __forceinline__ unsigned f2bfu(float f) { return (unsigned)__builtin_bit_cast(unsigned short, (__bf16)f); }
; __global__ void __launch_bounds__(NTHR, 2) k_main(Args a) {
;     ...
;         for (int idx = gtid; idx < 2 * 8 * 8192; idx += gthreads) {
;             const int pn = idx & 8191, h = (idx >> 13) & 7, b = idx >> 16;
;             float run = 0.f;
; #pragma unroll 1
;             for (int c0 = 0; c0 < 64; c0 += 8) {
;                 float st[8], dc[8];
; #pragma unroll
;                 for (int j = 0; j < 8; ++j) { const int bch = (b * 64 + c0 + j) * 8 + h; st[j] = bf2f(__builtin_nontemporal_load(&STATES[(size_t)bch * 8192 + pn])); dc[j] = CDEC[bch]; }
; #pragma unroll
;                 for (int j = 0; j < 8; ++j) { const int bch = (b * 64 + c0 + j) * 8 + h; __builtin_amdgcn_raw_buffer_store_b16((short)f2bfu(run), rsPV, (int)(((unsigned)bch * 8192u + (unsigned)pn) * 2u), 0, 16); run = dc[j] * run + st[j]; }
;             }
;         }
	v_lshlrev_b32_e32 v132, 16, v132
	v_fmac_f32_e32 v132, v10, v164
	v_mov_b32_e32 v10, v132
	v_cvt_pk_bf16_f32 v52, v10, v10
	s_mov_b32 s13, 0x4a0000
	buffer_store_short v52, v51, s[4:7], s13 offen sc1
	s_waitcnt vmcnt(63)
	v_lshlrev_b32_e32 v133, 16, v133
	v_fmac_f32_e32 v133, v10, v165
	v_mov_b32_e32 v10, v133
	v_cvt_pk_bf16_f32 v52, v10, v10
	s_mov_b32 s13, 0x4c0000
	buffer_store_short v52, v51, s[4:7], s13 offen sc1
	s_waitcnt vmcnt(63)
	v_lshlrev_b32_e32 v134, 16, v134
	v_fmac_f32_e32 v134, v10, v166
	v_mov_b32_e32 v10, v134
	v_cvt_pk_bf16_f32 v52, v10, v10
	s_mov_b32 s13, 0x4e0000
	buffer_store_short v52, v51, s[4:7], s13 offen sc1
	s_waitcnt vmcnt(63)
	v_lshlrev_b32_e32 v135, 16, v135
	v_fmac_f32_e32 v135, v10, v167
	v_mov_b32_e32 v10, v135
	v_cvt_pk_bf16_f32 v52, v10, v10
	s_mov_b32 s13, 0x500000
	buffer_store_short v52, v51, s[4:7], s13 offen sc1
	s_waitcnt vmcnt(63)
	v_lshlrev_b32_e32 v136, 16, v136
	v_fmac_f32_e32 v136, v10, v168
	v_mov_b32_e32 v10, v136
	v_cvt_pk_bf16_f32 v52, v10, v10
	s_mov_b32 s13, 0x520000
	buffer_store_short v52, v51, s[4:7], s13 offen sc1
	s_waitcnt vmcnt(63)
	v_lshlrev_b32_e32 v137, 16, v137
	v_fmac_f32_e32 v137, v10, v169
	v_mov_b32_e32 v10, v137
	v_cvt_pk_bf16_f32 v52, v10, v10
	s_mov_b32 s13, 0x540000
	buffer_store_short v52, v51, s[4:7], s13 offen sc1
	s_waitcnt vmcnt(63)
	v_lshlrev_b32_e32 v138, 16, v138
	v_fmac_f32_e32 v138, v10, v170
	v_mov_b32_e32 v10, v138
	v_cvt_pk_bf16_f32 v52, v10, v10
	s_mov_b32 s13, 0x560000
	buffer_store_short v52, v51, s[4:7], s13 offen sc1
	s_waitcnt vmcnt(63)
	v_lshlrev_b32_e32 v139, 16, v139
	v_fmac_f32_e32 v139, v10, v171
	v_mov_b32_e32 v10, v139
	v_cvt_pk_bf16_f32 v52, v10, v10
	s_mov_b32 s13, 0x580000
	buffer_store_short v52, v51, s[4:7], s13 offen sc1
	s_waitcnt vmcnt(63)
	v_lshlrev_b32_e32 v140, 16, v140
	v_fmac_f32_e32 v140, v10, v172
	v_mov_b32_e32 v10, v140
	v_cvt_pk_bf16_f32 v52, v10, v10
	s_mov_b32 s13, 0x5a0000
	buffer_store_short v52, v51, s[4:7], s13 offen sc1
	s_waitcnt vmcnt(63)
	v_lshlrev_b32_e32 v141, 16, v141
	v_fmac_f32_e32 v141, v10, v173
	v_mov_b32_e32 v10, v141
	v_cvt_pk_bf16_f32 v52, v10, v10
	s_mov_b32 s13, 0x5c0000
	buffer_store_short v52, v51, s[4:7], s13 offen sc1
	s_waitcnt vmcnt(63)
	v_lshlrev_b32_e32 v142, 16, v142
	v_fmac_f32_e32 v142, v10, v174
	v_mov_b32_e32 v10, v142
	v_cvt_pk_bf16_f32 v52, v10, v10
	s_mov_b32 s13, 0x5e0000
	buffer_store_short v52, v51, s[4:7], s13 offen sc1
	s_waitcnt vmcnt(63)
	v_lshlrev_b32_e32 v143, 16, v143
	v_fmac_f32_e32 v143, v10, v175
	v_mov_b32_e32 v10, v143
	v_cvt_pk_bf16_f32 v52, v10, v10
	s_mov_b32 s13, 0x600000
	buffer_store_short v52, v51, s[4:7], s13 offen sc1
	s_waitcnt vmcnt(32)
	v_lshlrev_b32_e32 v144, 16, v144
	v_fmac_f32_e32 v144, v10, v176
	v_mov_b32_e32 v10, v144
	v_cvt_pk_bf16_f32 v52, v10, v10
	s_mov_b32 s13, 0x620000
	buffer_store_short v52, v51, s[4:7], s13 offen sc1
	s_waitcnt vmcnt(32)
	v_lshlrev_b32_e32 v145, 16, v145
	v_fmac_f32_e32 v145, v10, v177
	v_mov_b32_e32 v10, v145
	v_cvt_pk_bf16_f32 v52, v10, v10
	s_mov_b32 s13, 0x640000
	buffer_store_short v52, v51, s[4:7], s13 offen sc1
	s_waitcnt vmcnt(32)
	v_lshlrev_b32_e32 v146, 16, v146
	v_fmac_f32_e32 v146, v10, v178
	v_mov_b32_e32 v10, v146
	v_cvt_pk_bf16_f32 v52, v10, v10
	s_mov_b32 s13, 0x660000
	buffer_store_short v52, v51, s[4:7], s13 offen sc1
	s_waitcnt vmcnt(32)
	v_lshlrev_b32_e32 v147, 16, v147
	v_fmac_f32_e32 v147, v10, v179
	v_mov_b32_e32 v10, v147
	v_cvt_pk_bf16_f32 v52, v10, v10
	s_mov_b32 s13, 0x680000
	buffer_store_short v52, v51, s[4:7], s13 offen sc1
	s_waitcnt vmcnt(32)
	v_lshlrev_b32_e32 v148, 16, v148
	v_fmac_f32_e32 v148, v10, v180
	v_mov_b32_e32 v10, v148
	v_cvt_pk_bf16_f32 v52, v10, v10
	s_mov_b32 s13, 0x6a0000
	buffer_store_short v52, v51, s[4:7], s13 offen sc1
	s_waitcnt vmcnt(32)
	v_lshlrev_b32_e32 v149, 16, v149
	v_fmac_f32_e32 v149, v10, v181
	v_mov_b32_e32 v10, v149
	v_cvt_pk_bf16_f32 v52, v10, v10
	s_mov_b32 s13, 0x6c0000
	buffer_store_short v52, v51, s[4:7], s13 offen sc1
	s_waitcnt vmcnt(32)
	v_lshlrev_b32_e32 v150, 16, v150
	v_fmac_f32_e32 v150, v10, v182
	v_mov_b32_e32 v10, v150
	v_cvt_pk_bf16_f32 v52, v10, v10
	s_mov_b32 s13, 0x6e0000
	buffer_store_short v52, v51, s[4:7], s13 offen sc1
	s_waitcnt vmcnt(32)
	v_lshlrev_b32_e32 v151, 16, v151
	v_fmac_f32_e32 v151, v10, v183
	v_mov_b32_e32 v10, v151
	v_cvt_pk_bf16_f32 v52, v10, v10
	s_mov_b32 s13, 0x700000
	buffer_store_short v52, v51, s[4:7], s13 offen sc1
	s_waitcnt vmcnt(32)
	v_lshlrev_b32_e32 v152, 16, v152
	v_fmac_f32_e32 v152, v10, v184
	v_mov_b32_e32 v10, v152
	v_cvt_pk_bf16_f32 v52, v10, v10
	s_mov_b32 s13, 0x720000
	buffer_store_short v52, v51, s[4:7], s13 offen sc1
	s_waitcnt vmcnt(32)
	v_lshlrev_b32_e32 v153, 16, v153
	v_fmac_f32_e32 v153, v10, v185
	v_mov_b32_e32 v10, v153
	v_cvt_pk_bf16_f32 v52, v10, v10
	s_mov_b32 s13, 0x740000
	buffer_store_short v52, v51, s[4:7], s13 offen sc1
	s_waitcnt vmcnt(32)
	v_lshlrev_b32_e32 v154, 16, v154
	v_fmac_f32_e32 v154, v10, v186
	v_mov_b32_e32 v10, v154
	v_cvt_pk_bf16_f32 v52, v10, v10
	s_mov_b32 s13, 0x760000
	buffer_store_short v52, v51, s[4:7], s13 offen sc1
	s_waitcnt vmcnt(32)
	v_lshlrev_b32_e32 v155, 16, v155
	v_fmac_f32_e32 v155, v10, v187
	v_mov_b32_e32 v10, v155
	v_cvt_pk_bf16_f32 v52, v10, v10
	s_mov_b32 s13, 0x780000
	buffer_store_short v52, v51, s[4:7], s13 offen sc1
	s_waitcnt vmcnt(32)
	v_lshlrev_b32_e32 v156, 16, v156
	v_fmac_f32_e32 v156, v10, v188
	v_mov_b32_e32 v10, v156
	v_cvt_pk_bf16_f32 v52, v10, v10
	s_mov_b32 s13, 0x7a0000
	buffer_store_short v52, v51, s[4:7], s13 offen sc1
	s_waitcnt vmcnt(32)
	v_lshlrev_b32_e32 v157, 16, v157
	v_fmac_f32_e32 v157, v10, v189
	v_mov_b32_e32 v10, v157
	v_cvt_pk_bf16_f32 v52, v10, v10
	s_mov_b32 s13, 0x7c0000
	buffer_store_short v52, v51, s[4:7], s13 offen sc1
	s_waitcnt vmcnt(32)
	v_lshlrev_b32_e32 v158, 16, v158
	v_fmac_f32_e32 v158, v10, v190
	v_mov_b32_e32 v10, v158
	v_cvt_pk_bf16_f32 v52, v10, v10
	s_mov_b32 s13, 0x7e0000
	buffer_store_short v52, v51, s[4:7], s13 offen sc1
	s_waitcnt vmcnt(32)
	v_lshlrev_b32_e32 v159, 16, v159
	v_fmac_f32_e32 v159, v10, v191
	v_mov_b32_e32 v10, v159
	v_add_u32_e32 v8, s56, v8
	v_cmp_lt_i32_e32 vcc, s11, v8
	s_or_b64 s[8:9], vcc, s[8:9]
	v_add_u32_e32 v9, s3, v9
	s_andn2_b64 exec, exec, s[8:9]
	s_cbranch_execnz .LBB0_377

; #define LAS __attribute__((address_space(3)))
; #define MFMA32(a, b, c) __builtin_amdgcn_mfma_f32_32x32x16_bf16((a), (b), (c), 0, 0, 0)
; __device__ __forceinline__ void sort16_desc(int (&v)[16]) {
;     ...
;     CE_(0,13); CE_(1,12); CE_(2,15); CE_(3,14); CE_(4,8); CE_(5,6); CE_(7,11); CE_(9,10);
;     CE_(0,5); CE_(1,7); CE_(2,9); CE_(3,4); CE_(6,13); CE_(8,14); CE_(10,15); CE_(11,12);
;     CE_(0,1); CE_(2,3); CE_(4,5); CE_(6,8); CE_(7,9); CE_(10,11); CE_(12,13); CE_(14,15);
;     CE_(0,2); CE_(1,3); CE_(4,10); CE_(5,11); CE_(6,7); CE_(8,9); CE_(12,14); CE_(13,15);
;     CE_(1,2); CE_(3,12); CE_(4,6); CE_(5,7); CE_(8,10); CE_(9,11); CE_(13,14);
;     CE_(1,4); CE_(2,6); CE_(5,8); CE_(7,10); CE_(9,13); CE_(11,14);
;     CE_(2,4); CE_(3,6); CE_(9,12); CE_(11,13);
;     CE_(3,5); CE_(6,8); CE_(7,9); CE_(10,12);
;     CE_(3,4); CE_(5,6); CE_(7,8); CE_(9,10); CE_(11,12);
;     CE_(6,7); CE_(8,9);
;     ...
; }
; __device__ __forceinline__ void route_task(int task, int tl0, const bf16* QP  , const LAS bf16* KHL, LAS unsigned short* EL, LAS float* GL, int lane) {
;     const int r = lane & 31, hi = lane >> 5, t = 4 * task + (r >> 3), head = r & 7;
;     int top[2][16]; bf16x8 qa[2][4];
;     { unsigned qo = (unsigned)t * (unsigned)D + (unsigned)(head * 128 + 8 * hi); asm volatile("" : "+v"(qo)); const bf16* qp = QP + qo;
; #pragma unroll
;       for (int hf = 0; hf < 2; ++hf)
; #pragma unroll
;         for (int ks = 0; ks < 4; ++ks) qa[hf][ks] = ldg8(qp + 64 * hf + 16 * ks); }
; #pragma unroll
;     for (int half = 0; half < 2; ++half) {
;         int cur[16];
; #pragma unroll
;         for (int kt = 0; kt < 4; ++kt) {
;             f32x16 X;
; #pragma unroll
;             for (int i = 0; i < 16; ++i) X[i] = 8.f;
;             const LAS bf16* khp = KHL + (half * 128 + 32 * kt + r) * 72 + 8 * hi;
; #pragma unroll
;             for (int ks = 0; ks < 4; ++ks) {
;                 const bf16x8 kh = lds8(khp + 16 * ks);
;                 X = MFMA32(kh, qa[half][ks], X);
;             }
;             int grp[16];
; #pragma unroll
;             for (int i = 0; i < 16; ++i) grp[i] = (int)((__float_as_uint(X[i]) | 127u) - (unsigned)(32 * kt + (i & 3) + 8 * (i >> 2)));
;             sort16_desc(grp);
;             if (kt == 0) {
; #pragma unroll
;                 for (int i = 0; i < 16; ++i) cur[i] = grp[i];
;             } else merge16_desc(cur, grp);
.LBB0_666:
	s_or_b64 exec, exec, s[10:11]
	s_lshl_b32 s10, s2, 4
	s_add_i32 s10, s10, s95
	s_lshl_b32 s10, s10, 12
	v_or_b32_e32 v82, s10, v88
	s_waitcnt lgkmcnt(0)
	s_barrier
	s_add_i32 s11, 0, 0x12000
	v_lshl_add_u64 v[70:71], v[82:83], 1, s[80:81]
	global_load_dwordx4 v[62:65], v[70:71], off
	global_load_dwordx4 v[54:57], v[70:71], off offset:32
	global_load_dwordx4 v[58:61], v[70:71], off offset:64
	global_load_dwordx4 v[50:53], v[70:71], off offset:96
	ds_read_b128 v[34:37], v94
	ds_read_b128 v[38:41], v94 offset:32
	s_add_i32 s10, s10, 0x8000
	s_mov_b32 s41, 0
	s_waitcnt vmcnt(3) lgkmcnt(1)
	v_mfma_f32_32x32x16_bf16 v[18:33], v[34:37], v[62:65], v[2:17]
	ds_read_b128 v[34:37], v94 offset:64
	ds_read_b128 v[66:69], v94 offset:96
	s_waitcnt vmcnt(2) lgkmcnt(2)
	v_mfma_f32_32x32x16_bf16 v[18:33], v[38:41], v[54:57], v[18:33]
	v_and_b32_e32 v38, 64, v112
	v_add_u32_e32 v122, 64, v38
	v_cmp_lt_i32_e32 vcc, v113, v122
	s_waitcnt vmcnt(1) lgkmcnt(1)
	v_mfma_f32_32x32x16_bf16 v[18:33], v[34:37], v[58:61], v[18:33]
	v_cndmask_b32_e32 v34, v112, v113, vcc
	v_lshlrev_b32_e32 v123, 2, v34
	global_load_dwordx4 v[46:49], v[70:71], off offset:128
	global_load_dwordx4 v[42:45], v[70:71], off offset:160
	global_load_dwordx4 v[38:41], v[70:71], off offset:192
	global_load_dwordx4 v[34:37], v[70:71], off offset:224
	s_waitcnt vmcnt(4) lgkmcnt(0)
	v_mfma_f32_32x32x16_bf16 v[18:33], v[66:69], v[50:53], v[18:33]
	s_nop 11
	v_or_b32_e32 v21, 0x7f, v21
	v_or_b32_e32 v32, 0x7f, v32
	v_or_b32_e32 v22, 0x7f, v22
	v_or_b32_e32 v26, 0x7f, v26
	v_or_b32_e32 v31, 0x7f, v31
	v_or_b32_e32 v23, 0x7f, v23
	v_or_b32_e32 v24, 0x7f, v24
	v_or_b32_e32 v27, 0x7f, v27
	v_or_b32_e32 v28, 0x7f, v28
	v_or_b32_e32 v20, 0x7f, v20
	v_or_b32_e32 v33, 0x7f, v33
	v_or_b32_e32 v25, 0x7f, v25
	v_or_b32_e32 v29, 0x7f, v29
	v_or_b32_e32 v19, 0x7f, v19
	v_or_b32_e32 v30, 0x7f, v30
	v_or_b32_e32 v18, 0x7f, v18
	v_add_u32_e32 v21, -3, v21
	v_subrev_u32_e32 v32, 26, v32
	v_add_u32_e32 v22, -8, v22
	v_add_u32_e32 v26, -16, v26
	v_subrev_u32_e32 v31, 25, v31
	v_add_u32_e32 v23, -9, v23
	v_add_u32_e32 v24, -10, v24
	v_subrev_u32_e32 v27, 17, v27
	v_subrev_u32_e32 v28, 18, v28
	v_add_u32_e32 v20, -2, v20
	v_subrev_u32_e32 v33, 27, v33
	v_add_u32_e32 v25, -11, v25
	v_subrev_u32_e32 v29, 19, v29
	v_add_u32_e32 v19, -1, v19
	v_subrev_u32_e32 v30, 24, v30
	v_max_i32_e32 v66, v21, v32
	v_max_i32_e32 v67, v22, v26
	v_max_i32_e32 v68, v18, v31
	v_max_i32_e32 v69, v23, v24
	v_min_i32_e32 v70, v27, v28
	v_min_i32_e32 v71, v20, v33
	v_min_i32_e32 v72, v25, v29
	v_min_i32_e32 v73, v19, v30
	v_min_i32_e32 v23, v23, v24
	v_min_i32_e32 v18, v18, v31
	v_min_i32_e32 v22, v22, v26
	v_min_i32_e32 v21, v21, v32
	v_max_i32_e32 v19, v19, v30
	v_max_i32_e32 v24, v25, v29
	v_max_i32_e32 v20, v20, v33
	v_max_i32_e32 v25, v27, v28
	v_min_i32_e32 v26, v66, v67
	v_min_i32_e32 v27, v68, v69
	v_max_i32_e32 v28, v70, v71
	v_max_i32_e32 v29, v72, v73
	v_max_i32_e32 v30, v23, v18
	v_max_i32_e32 v31, v22, v21
	v_min_i32_e32 v32, v19, v24
	v_min_i32_e32 v33, v20, v25
	v_min_i32_e32 v18, v23, v18
	v_min_i32_e32 v21, v22, v21
	v_min_i32_e32 v22, v70, v71
	v_max_i32_e32 v23, v68, v69
	v_max_i32_e32 v19, v19, v24
	v_max_i32_e32 v20, v20, v25
	v_max_i32_e32 v24, v66, v67
	v_min_i32_e32 v25, v26, v27
	v_max_i32_e32 v67, v30, v31
	v_min_i32_e32 v30, v30, v31
	v_min_i32_e32 v31, v32, v33
	v_max_i32_e32 v26, v26, v27
	v_max_i32_e32 v27, v28, v29
	v_min_i32_e32 v66, v28, v29
	v_max_i32_e32 v68, v32, v33
	v_min_i32_e32 v75, v21, v22
	v_max_i32_e32 v21, v21, v22
	v_min_i32_e32 v22, v23, v19
	v_min_i32_e32 v28, v20, v24
	v_max_i32_e32 v33, v30, v31
	v_min_i32_e32 v69, v26, v27
	v_max_i32_e32 v29, v25, v66
	v_min_i32_e32 v32, v67, v68
	v_min_i32_e32 v77, v25, v66
	v_min_i32_e32 v25, v22, v28
	v_max_i32_e32 v80, v22, v28
	v_min_i32_e32 v22, v33, v69
	v_max_i32_e32 v125, v20, v24
	v_max_i32_e32 v129, v67, v68
	v_max_i32_e32 v24, v33, v69
	ds_read_b128 v[66:69], v95
	v_min_i32_e32 v72, v72, v73
	v_min_i32_e32 v74, v72, v18
	v_max_i32_e32 v18, v72, v18
	v_max_i32_e32 v124, v23, v19
	v_min_i32_e32 v76, v30, v31
	v_max_i32_e32 v78, v74, v75
	v_min_i32_e32 v79, v18, v21
	v_min_i32_e32 v126, v124, v125
	v_max_i32_e32 v128, v26, v27
	v_max_i32_e32 v18, v18, v21
	v_max_i32_e32 v81, v76, v77
	v_max_i32_e32 v82, v78, v79
	v_min_i32_e32 v127, v80, v126
	v_min_i32_e32 v130, v128, v129
	v_min_i32_e32 v21, v29, v32
	v_min_i32_e32 v28, v25, v18
	v_max_i32_e32 v18, v25, v18
	v_max_i32_e32 v30, v81, v82
	v_min_i32_e32 v19, v127, v130
	v_max_i32_e32 v23, v29, v32
	v_max_i32_e32 v25, v21, v22
	v_max_i32_e32 v31, v30, v28
	v_min_i32_e32 v20, v18, v19
	v_min_i32_e32 v26, v23, v24
	v_max_i32_e32 v70, v25, v31
	v_min_i32_e32 v27, v20, v26
	v_min_i32_e32 v131, v70, v27
	v_max_i32_e32 v143, v70, v27
	ds_read_b128 v[70:73], v95 offset:32
	v_min_i32_e32 v132, v25, v31
	v_min_i32_e32 v133, v21, v22
	v_min_i32_e32 v134, v30, v28
	v_max_i32_e32 v138, v18, v19
	v_max_i32_e32 v139, v23, v24
	v_max_i32_e32 v141, v20, v26
	s_waitcnt lgkmcnt(1)
	v_mfma_f32_32x32x16_bf16 v[18:33], v[66:69], v[62:65], v[2:17]
	ds_read_b128 v[66:69], v95 offset:64
	v_max_i32_e32 v135, v133, v134
	v_max_i32_e32 v136, v132, v135
	v_min_i32_e32 v76, v76, v77
	v_min_i32_e32 v77, v78, v79
	v_min_i32_e32 v132, v132, v135
	v_max_i32_e32 v127, v127, v130
	s_waitcnt lgkmcnt(1)
	v_mfma_f32_32x32x16_bf16 v[18:33], v[70:73], v[54:57], v[18:33]
	ds_read_b128 v[70:73], v95 offset:96
	v_max_i32_e32 v80, v80, v126
	v_min_i32_e32 v74, v74, v75
	v_min_i32_e32 v140, v138, v139
	v_max_i32_e32 v78, v76, v77
	v_min_i32_e32 v79, v81, v82
	v_min_i32_e32 v82, v133, v134
	s_waitcnt lgkmcnt(1)
; #define LAS __attribute__((address_space(3)))
; #define MFMA32(a, b, c) __builtin_amdgcn_mfma_f32_32x32x16_bf16((a), (b), (c), 0, 0, 0)
; #define CE_(a, b) ce_desc(v[a], v[b])
; __device__ __forceinline__ void sort16_desc(int (&v)[16]) {
;     ...
;     CE_(0,13); CE_(1,12); CE_(2,15); CE_(3,14); CE_(4,8); CE_(5,6); CE_(7,11); CE_(9,10);
;     CE_(0,5); CE_(1,7); CE_(2,9); CE_(3,4); CE_(6,13); CE_(8,14); CE_(10,15); CE_(11,12);
;     CE_(0,1); CE_(2,3); CE_(4,5); CE_(6,8); CE_(7,9); CE_(10,11); CE_(12,13); CE_(14,15);
;     CE_(0,2); CE_(1,3); CE_(4,10); CE_(5,11); CE_(6,7); CE_(8,9); CE_(12,14); CE_(13,15);
;     CE_(1,2); CE_(3,12); CE_(4,6); CE_(5,7); CE_(8,10); CE_(9,11); CE_(13,14);
;     CE_(1,4); CE_(2,6); CE_(5,8); CE_(7,10); CE_(9,13); CE_(11,14);
;     CE_(2,4); CE_(3,6); CE_(9,12); CE_(11,13);
;     CE_(3,5); CE_(6,8); CE_(7,9); CE_(10,12);
;     CE_(3,4); CE_(5,6); CE_(7,8); CE_(9,10); CE_(11,12);
;     CE_(6,7); CE_(8,9);
;     ...
; }
; __device__ __forceinline__ void merge16_desc(int (&a)[16], const int (&b)[16]) {
; #pragma unroll
;     for (int i = 0; i < 16; ++i) a[i] = a[i] > b[15 - i] ? a[i] : b[15 - i];
; #pragma unroll
;     for (int j = 8; j > 0; j >>= 1)
; #pragma unroll
;         for (int i = 0; i < 16; ++i) { const int l = i ^ j; if (l > i) ce_desc(a[i], a[l]); }
; __device__ __forceinline__ void route_task(int task, int tl0, const bf16* QP  , const LAS bf16* KHL, LAS unsigned short* EL, LAS float* GL, int lane) {
;     ...
;         for (int kt = 0; kt < 4; ++kt) {
;             f32x16 X;
; #pragma unroll
;             for (int i = 0; i < 16; ++i) X[i] = 8.f;
;             const LAS bf16* khp = KHL + (half * 128 + 32 * kt + r) * 72 + 8 * hi;
; #pragma unroll
;             for (int ks = 0; ks < 4; ++ks) {
;                 const bf16x8 kh = lds8(khp + 16 * ks);
;                 X = MFMA32(kh, qa[half][ks], X);
;             }
;             int grp[16];
; #pragma unroll
;             for (int i = 0; i < 16; ++i) grp[i] = (int)((__float_as_uint(X[i]) | 127u) - (unsigned)(32 * kt + (i & 3) + 8 * (i >> 2)));
;             sort16_desc(grp);
;             if (kt == 0) {
; #pragma unroll
;                 for (int i = 0; i < 16; ++i) cur[i] = grp[i];
;             } else merge16_desc(cur, grp);
	v_mfma_f32_32x32x16_bf16 v[18:33], v[66:69], v[58:61], v[18:33]
	v_max_i32_e32 v66, v128, v129
	v_max_i32_e32 v134, v138, v139
	v_min_i32_e32 v76, v76, v77
	v_max_i32_e32 v81, v78, v79
	v_min_i32_e32 v78, v78, v79
	v_min_i32_e32 v67, v80, v66
	v_min_i32_e32 v142, v140, v141
	s_waitcnt lgkmcnt(0)
	v_mfma_f32_32x32x16_bf16 v[18:33], v[70:73], v[50:53], v[18:33]
	v_min_i32_e32 v68, v127, v67
	v_min_i32_e32 v137, v131, v136
	v_min_i32_e32 v144, v142, v143
	v_min_i32_e32 v133, v81, v82
	v_min_i32_e32 v69, v134, v68
	s_nop 6
	v_or_b32_e32 v21, 0x7f, v21
	v_or_b32_e32 v32, 0x7f, v32
	v_or_b32_e32 v22, 0x7f, v22
	v_or_b32_e32 v26, 0x7f, v26
	v_or_b32_e32 v18, 0x7f, v18
	v_or_b32_e32 v31, 0x7f, v31
	v_or_b32_e32 v23, 0x7f, v23
	v_or_b32_e32 v24, 0x7f, v24
	v_or_b32_e32 v27, 0x7f, v27
	v_or_b32_e32 v28, 0x7f, v28
	v_or_b32_e32 v20, 0x7f, v20
	v_or_b32_e32 v33, 0x7f, v33
	v_or_b32_e32 v25, 0x7f, v25
	v_or_b32_e32 v29, 0x7f, v29
	v_or_b32_e32 v19, 0x7f, v19
	v_or_b32_e32 v30, 0x7f, v30
	v_subrev_u32_e32 v21, 35, v21
	v_subrev_u32_e32 v32, 58, v32
	v_subrev_u32_e32 v22, 40, v22
	v_subrev_u32_e32 v26, 48, v26
	v_subrev_u32_e32 v18, 32, v18
	v_subrev_u32_e32 v31, 57, v31
	v_subrev_u32_e32 v23, 41, v23
	v_subrev_u32_e32 v24, 42, v24
	v_subrev_u32_e32 v27, 49, v27
	v_subrev_u32_e32 v28, 50, v28
	v_subrev_u32_e32 v20, 34, v20
	v_subrev_u32_e32 v33, 59, v33
	v_subrev_u32_e32 v25, 43, v25
	v_subrev_u32_e32 v29, 51, v29
	v_subrev_u32_e32 v19, 33, v19
	v_subrev_u32_e32 v30, 56, v30
	v_max_i32_e32 v70, v21, v32
	v_max_i32_e32 v71, v22, v26
	v_max_i32_e32 v73, v18, v31
	v_max_i32_e32 v75, v23, v24
	v_min_i32_e32 v126, v27, v28
	v_min_i32_e32 v128, v20, v33
	v_min_i32_e32 v130, v25, v29
	v_min_i32_e32 v135, v19, v30
	v_min_i32_e32 v23, v23, v24
	v_min_i32_e32 v18, v18, v31
	v_min_i32_e32 v22, v22, v26
	v_min_i32_e32 v21, v21, v32
	v_max_i32_e32 v19, v19, v30
	v_max_i32_e32 v25, v25, v29
	v_max_i32_e32 v20, v20, v33
	v_max_i32_e32 v27, v27, v28
	v_min_i32_e32 v72, v70, v71
	v_min_i32_e32 v77, v73, v75
	v_max_i32_e32 v129, v126, v128
	v_max_i32_e32 v138, v130, v135
	v_max_i32_e32 v24, v23, v18
	v_max_i32_e32 v26, v22, v21
	v_min_i32_e32 v29, v19, v25
	v_min_i32_e32 v28, v20, v27
	v_min_i32_e32 v130, v130, v135
	v_min_i32_e32 v18, v23, v18
	v_min_i32_e32 v21, v22, v21
	v_min_i32_e32 v22, v126, v128
	v_max_i32_e32 v73, v73, v75
	v_max_i32_e32 v19, v19, v25
	v_max_i32_e32 v20, v20, v27
	v_max_i32_e32 v27, v70, v71
	v_min_i32_e32 v79, v72, v77
	v_min_i32_e32 v139, v129, v138
	v_max_i32_e32 v31, v24, v26
	v_max_i32_e32 v30, v29, v28
	v_min_i32_e32 v24, v24, v26
	v_min_i32_e32 v26, v29, v28
	v_max_i32_e32 v29, v72, v77
	v_max_i32_e32 v72, v129, v138
	v_min_i32_e32 v23, v130, v18
	v_min_i32_e32 v126, v21, v22
	v_max_i32_e32 v18, v130, v18
	v_max_i32_e32 v21, v21, v22
	v_min_i32_e32 v25, v73, v19
	v_min_i32_e32 v70, v20, v27
	v_max_i32_e32 v19, v73, v19
	v_max_i32_e32 v20, v20, v27
	v_min_i32_e32 v32, v31, v30
	v_max_i32_e32 v28, v24, v26
	v_min_i32_e32 v77, v29, v72
	v_min_i32_e32 v24, v24, v26
	v_min_i32_e32 v26, v79, v139
	v_max_i32_e32 v128, v23, v126
	v_min_i32_e32 v22, v18, v21
	v_min_i32_e32 v71, v25, v70
	v_max_i32_e32 v25, v25, v70
	v_min_i32_e32 v27, v19, v20
	v_max_i32_e32 v29, v29, v72
	v_max_i32_e32 v30, v31, v30
	v_max_i32_e32 v145, v79, v139
	v_max_i32_e32 v79, v24, v26
	v_max_i32_e32 v130, v128, v22
	v_max_i32_e32 v18, v18, v21
	v_min_i32_e32 v70, v25, v27
	v_min_i32_e32 v31, v29, v30
	v_min_i32_e32 v33, v145, v32
	v_min_i32_e32 v129, v28, v77
	v_max_i32_e32 v135, v79, v130
	v_min_i32_e32 v21, v71, v18
	v_max_i32_e32 v18, v71, v18
	v_min_i32_e32 v71, v70, v31
	v_max_i32_e32 v32, v145, v32
	v_max_i32_e32 v28, v28, v77
	v_max_i32_e32 v138, v33, v129
	v_max_i32_e32 v75, v135, v21
	v_min_i32_e32 v72, v18, v71
	v_min_i32_e32 v73, v32, v28
	v_min_i32_e32 v33, v33, v129
	v_min_i32_e32 v21, v135, v21
	v_max_i32_e32 v18, v18, v71
	v_max_i32_e32 v28, v32, v28
	v_min_i32_e32 v24, v24, v26
	v_min_i32_e32 v22, v128, v22
	v_max_i32_e32 v25, v25, v27
	v_max_i32_e32 v27, v29, v30
	v_max_i32_e32 v139, v138, v75
	v_min_i32_e32 v77, v72, v73
	v_min_i32_e32 v75, v138, v75
	v_max_i32_e32 v129, v33, v21
	v_min_i32_e32 v32, v18, v28
	v_max_i32_e32 v71, v72, v73
	v_max_i32_e32 v26, v24, v22
	v_min_i32_e32 v79, v79, v130
	v_max_i32_e32 v18, v18, v28
	v_max_i32_e32 v28, v70, v31
	v_min_i32_e32 v29, v25, v27
	v_min_i32_e32 v145, v139, v77
	v_max_i32_e32 v135, v75, v129
	v_min_i32_e32 v72, v32, v71
	v_max_i32_e32 v73, v139, v77
	v_max_i32_e32 v128, v26, v79
	v_min_i32_e32 v21, v33, v21
	v_min_i32_e32 v30, v28, v29
	v_min_i32_e32 v138, v145, v135
	v_min_i32_e32 v77, v72, v73
	v_min_i32_e32 v33, v128, v21
	v_min_i32_e32 v75, v75, v129
	v_min_i32_e32 v31, v18, v30
	v_min_i32_e32 v26, v26, v79
	v_min_i32_e32 v22, v24, v22
	v_min_i32_e32 v23, v23, v126
	v_max3_i32 v23, v124, v125, v23
	v_max3_i32 v22, v80, v66, v22
	v_max3_i32 v24, v127, v67, v26
	v_max3_i32 v26, v134, v68, v33
	v_max3_i32 v21, v69, v128, v21
	v_max3_i32 v33, v140, v141, v75
	v_max3_i32 v66, v142, v143, v138
	v_max3_i32 v67, v144, v145, v135
	v_max3_i32 v68, v131, v136, v77
	v_max3_i32 v69, v137, v72, v73
	v_max3_i32 v32, v132, v32, v71
	v_max3_i32 v31, v81, v82, v31
	v_max3_i32 v18, v133, v18, v30
	v_max3_i32 v28, v78, v28, v29
	v_max3_i32 v25, v76, v25, v27
	v_max3_i32 v19, v74, v19, v20
	v_max_i32_e32 v20, v23, v68
	v_min_i32_e32 v23, v23, v68
	v_max_i32_e32 v27, v22, v69
	v_min_i32_e32 v22, v22, v69
	v_max_i32_e32 v29, v24, v32
	v_min_i32_e32 v24, v24, v32
	v_max_i32_e32 v30, v26, v31
	v_min_i32_e32 v26, v26, v31
	v_max_i32_e32 v31, v21, v18
	v_min_i32_e32 v18, v21, v18
	v_max_i32_e32 v21, v33, v28
	v_min_i32_e32 v28, v33, v28
	v_max_i32_e32 v32, v66, v25
	v_min_i32_e32 v25, v66, v25
	v_max_i32_e32 v33, v67, v19
	v_min_i32_e32 v19, v67, v19
	ds_read_b128 v[66:69], v94 offset:9216
	v_max_i32_e32 v70, v20, v31
	v_min_i32_e32 v74, v20, v31
	v_max_i32_e32 v20, v27, v21
	v_min_i32_e32 v75, v27, v21
	v_max_i32_e32 v21, v29, v32
	v_max_i32_e32 v27, v30, v33
	v_max_i32_e32 v127, v70, v21
	v_min_i32_e32 v128, v70, v21
	ds_read_b128 v[70:73], v94 offset:9248
	v_min_i32_e32 v76, v29, v32
	v_min_i32_e32 v77, v30, v33
	v_max_i32_e32 v78, v23, v18
	v_min_i32_e32 v79, v23, v18
	v_max_i32_e32 v80, v22, v28
	v_min_i32_e32 v81, v22, v28
	v_max_i32_e32 v82, v24, v25
	v_min_i32_e32 v124, v24, v25
	v_max_i32_e32 v125, v26, v19
	v_min_i32_e32 v126, v26, v19
	v_max_i32_e32 v129, v20, v27
	v_min_i32_e32 v130, v20, v27
	s_waitcnt lgkmcnt(1)
; #define LAS __attribute__((address_space(3)))
; #define MFMA32(a, b, c) __builtin_amdgcn_mfma_f32_32x32x16_bf16((a), (b), (c), 0, 0, 0)
; #define CE_(a, b) ce_desc(v[a], v[b])
; __device__ __forceinline__ void sort16_desc(int (&v)[16]) {
;     ...
;     CE_(0,13); CE_(1,12); CE_(2,15); CE_(3,14); CE_(4,8); CE_(5,6); CE_(7,11); CE_(9,10);
;     CE_(0,5); CE_(1,7); CE_(2,9); CE_(3,4); CE_(6,13); CE_(8,14); CE_(10,15); CE_(11,12);
;     CE_(0,1); CE_(2,3); CE_(4,5); CE_(6,8); CE_(7,9); CE_(10,11); CE_(12,13); CE_(14,15);
;     CE_(0,2); CE_(1,3); CE_(4,10); CE_(5,11); CE_(6,7); CE_(8,9); CE_(12,14); CE_(13,15);
;     CE_(1,2); CE_(3,12); CE_(4,6); CE_(5,7); CE_(8,10); CE_(9,11); CE_(13,14);
;     CE_(1,4); CE_(2,6); CE_(5,8); CE_(7,10); CE_(9,13); CE_(11,14);
;     CE_(2,4); CE_(3,6); CE_(9,12); CE_(11,13);
;     CE_(3,5); CE_(6,8); CE_(7,9); CE_(10,12);
;     CE_(3,4); CE_(5,6); CE_(7,8); CE_(9,10); CE_(11,12);
;     CE_(6,7); CE_(8,9);
;     ...
; }
; __device__ __forceinline__ void route_task(int task, int tl0, const bf16* QP  , const LAS bf16* KHL, LAS unsigned short* EL, LAS float* GL, int lane) {
;     ...
;         for (int kt = 0; kt < 4; ++kt) {
;             f32x16 X;
; #pragma unroll
;             for (int i = 0; i < 16; ++i) X[i] = 8.f;
;             const LAS bf16* khp = KHL + (half * 128 + 32 * kt + r) * 72 + 8 * hi;
; #pragma unroll
;             for (int ks = 0; ks < 4; ++ks) {
;                 const bf16x8 kh = lds8(khp + 16 * ks);
;                 X = MFMA32(kh, qa[half][ks], X);
;             }
;             int grp[16];
; #pragma unroll
;             for (int i = 0; i < 16; ++i) grp[i] = (int)((__float_as_uint(X[i]) | 127u) - (unsigned)(32 * kt + (i & 3) + 8 * (i >> 2)));
;             sort16_desc(grp);
;             if (kt == 0) {
; #pragma unroll
;                 for (int i = 0; i < 16; ++i) cur[i] = grp[i];
;             } else merge16_desc(cur, grp);
	v_mfma_f32_32x32x16_bf16 v[18:33], v[66:69], v[62:65], v[2:17]
	ds_read_b128 v[66:69], v94 offset:9280
	v_max_i32_e32 v131, v74, v76
	v_min_i32_e32 v74, v74, v76
	v_max_i32_e32 v76, v75, v77
	v_min_i32_e32 v75, v75, v77
	v_max_i32_e32 v77, v78, v82
	v_min_i32_e32 v78, v78, v82
	s_waitcnt lgkmcnt(1)
	v_mfma_f32_32x32x16_bf16 v[18:33], v[70:73], v[54:57], v[18:33]
	ds_read_b128 v[70:73], v94 offset:9312
	v_max_i32_e32 v82, v80, v125
	v_min_i32_e32 v80, v80, v125
	v_max_i32_e32 v125, v79, v124
	v_min_i32_e32 v79, v79, v124
	v_max_i32_e32 v124, v81, v126
	v_min_i32_e32 v81, v81, v126
	s_waitcnt lgkmcnt(1)
	v_mfma_f32_32x32x16_bf16 v[18:33], v[66:69], v[58:61], v[18:33]
	v_min_i32_e32 v126, v127, v129
	v_min_i32_e32 v66, v128, v130
	v_min_i32_e32 v67, v131, v76
	v_min_i32_e32 v69, v77, v82
	v_min_i32_e32 v132, v78, v80
	v_min_i32_e32 v133, v125, v124
	v_min_i32_e32 v68, v74, v75
	s_waitcnt lgkmcnt(0)
	v_mfma_f32_32x32x16_bf16 v[18:33], v[70:73], v[50:53], v[18:33]
	v_min_i32_e32 v134, v79, v81
	s_nop 10
	v_or_b32_e32 v21, 0x7f, v21
	v_or_b32_e32 v32, 0x7f, v32
	v_or_b32_e32 v22, 0x7f, v22
	v_or_b32_e32 v26, 0x7f, v26
	v_or_b32_e32 v18, 0x7f, v18
	v_or_b32_e32 v31, 0x7f, v31
	v_or_b32_e32 v23, 0x7f, v23
	v_or_b32_e32 v24, 0x7f, v24
	v_or_b32_e32 v27, 0x7f, v27
	v_or_b32_e32 v28, 0x7f, v28
	v_or_b32_e32 v20, 0x7f, v20
	v_or_b32_e32 v33, 0x7f, v33
	v_or_b32_e32 v25, 0x7f, v25
	v_or_b32_e32 v29, 0x7f, v29
	v_or_b32_e32 v19, 0x7f, v19
	v_or_b32_e32 v30, 0x7f, v30
	v_add_u32_e32 v21, 0xffffffbd, v21
	v_add_u32_e32 v32, 0xffffffa6, v32
	v_add_u32_e32 v22, 0xffffffb8, v22
	v_add_u32_e32 v26, 0xffffffb0, v26
	v_subrev_u32_e32 v18, 64, v18
	v_add_u32_e32 v31, 0xffffffa7, v31
	v_add_u32_e32 v23, 0xffffffb7, v23
	v_add_u32_e32 v24, 0xffffffb6, v24
	v_add_u32_e32 v27, 0xffffffaf, v27
	v_add_u32_e32 v28, 0xffffffae, v28
	v_add_u32_e32 v20, 0xffffffbe, v20
	v_add_u32_e32 v33, 0xffffffa5, v33
	v_add_u32_e32 v25, 0xffffffb5, v25
	v_add_u32_e32 v29, 0xffffffad, v29
	v_add_u32_e32 v19, 0xffffffbf, v19
	v_add_u32_e32 v30, 0xffffffa8, v30
	v_max_i32_e32 v70, v21, v32
	v_max_i32_e32 v71, v22, v26
	v_max_i32_e32 v73, v18, v31
	v_max_i32_e32 v135, v23, v24
	v_min_i32_e32 v138, v27, v28
	v_min_i32_e32 v139, v20, v33
	v_min_i32_e32 v141, v25, v29
	v_min_i32_e32 v142, v19, v30
	v_min_i32_e32 v23, v23, v24
	v_min_i32_e32 v18, v18, v31
	v_min_i32_e32 v22, v22, v26
	v_min_i32_e32 v21, v21, v32
	v_max_i32_e32 v19, v19, v30
	v_max_i32_e32 v25, v25, v29
	v_max_i32_e32 v20, v20, v33
	v_max_i32_e32 v27, v27, v28
	v_min_i32_e32 v72, v70, v71
	v_min_i32_e32 v136, v73, v135
	v_max_i32_e32 v140, v138, v139
	v_max_i32_e32 v143, v141, v142
	v_max_i32_e32 v24, v23, v18
	v_max_i32_e32 v26, v22, v21
	v_min_i32_e32 v29, v19, v25
	v_min_i32_e32 v28, v20, v27
	v_min_i32_e32 v141, v141, v142
	v_min_i32_e32 v18, v23, v18
	v_min_i32_e32 v21, v22, v21
	v_min_i32_e32 v22, v138, v139
	v_max_i32_e32 v73, v73, v135
	v_max_i32_e32 v19, v19, v25
	v_max_i32_e32 v20, v20, v27
	v_max_i32_e32 v27, v70, v71
	v_min_i32_e32 v137, v72, v136
	v_min_i32_e32 v144, v140, v143
	v_max_i32_e32 v31, v24, v26
	v_max_i32_e32 v30, v29, v28
	v_min_i32_e32 v24, v24, v26
	v_min_i32_e32 v26, v29, v28
	v_max_i32_e32 v29, v72, v136
	v_max_i32_e32 v72, v140, v143
	v_min_i32_e32 v23, v141, v18
	v_min_i32_e32 v138, v21, v22
	v_max_i32_e32 v18, v141, v18
	v_max_i32_e32 v21, v21, v22
	v_min_i32_e32 v25, v73, v19
	v_min_i32_e32 v70, v20, v27
	v_max_i32_e32 v19, v73, v19
	v_max_i32_e32 v20, v20, v27
	v_min_i32_e32 v32, v31, v30
	v_max_i32_e32 v28, v24, v26
	v_min_i32_e32 v136, v29, v72
	v_min_i32_e32 v24, v24, v26
	v_min_i32_e32 v26, v137, v144
	v_max_i32_e32 v139, v23, v138
	v_min_i32_e32 v22, v18, v21
	v_min_i32_e32 v71, v25, v70
	v_max_i32_e32 v25, v25, v70
	v_min_i32_e32 v27, v19, v20
	v_max_i32_e32 v29, v29, v72
	v_max_i32_e32 v30, v31, v30
	v_max_i32_e32 v145, v137, v144
	v_max_i32_e32 v137, v24, v26
	v_max_i32_e32 v141, v139, v22
	v_max_i32_e32 v18, v18, v21
	v_min_i32_e32 v70, v25, v27
	v_min_i32_e32 v31, v29, v30
	v_min_i32_e32 v33, v145, v32
	v_min_i32_e32 v140, v28, v136
	v_max_i32_e32 v142, v137, v141
	v_min_i32_e32 v21, v71, v18
	v_max_i32_e32 v18, v71, v18
	v_min_i32_e32 v71, v70, v31
	v_max_i32_e32 v32, v145, v32
	v_max_i32_e32 v28, v28, v136
	v_max_i32_e32 v143, v33, v140
	v_max_i32_e32 v135, v142, v21
	v_min_i32_e32 v72, v18, v71
	v_min_i32_e32 v73, v32, v28
	v_min_i32_e32 v33, v33, v140
	v_min_i32_e32 v21, v142, v21
	v_max_i32_e32 v18, v18, v71
	v_max_i32_e32 v28, v32, v28
	v_min_i32_e32 v24, v24, v26
	v_min_i32_e32 v22, v139, v22
	v_max_i32_e32 v25, v25, v27
	v_max_i32_e32 v27, v29, v30
	v_max_i32_e32 v144, v143, v135
	v_min_i32_e32 v136, v72, v73
	v_min_i32_e32 v135, v143, v135
	v_max_i32_e32 v140, v33, v21
	v_min_i32_e32 v32, v18, v28
	v_max_i32_e32 v71, v72, v73
	v_max_i32_e32 v26, v24, v22
	v_min_i32_e32 v137, v137, v141
	v_max_i32_e32 v18, v18, v28
	v_max_i32_e32 v28, v70, v31
	v_min_i32_e32 v29, v25, v27
	v_min_i32_e32 v145, v144, v136
	v_max_i32_e32 v142, v135, v140
	v_min_i32_e32 v72, v32, v71
	v_max_i32_e32 v73, v144, v136
	v_max_i32_e32 v139, v26, v137
	v_min_i32_e32 v21, v33, v21
	v_min_i32_e32 v30, v28, v29
	v_min_i32_e32 v143, v145, v142
	v_min_i32_e32 v136, v72, v73
	v_min_i32_e32 v33, v139, v21
	v_max_i32_e32 v21, v139, v21
	v_min_i32_e32 v135, v135, v140
	v_max_i32_e32 v32, v32, v71
	v_min_i32_e32 v31, v18, v30
	v_max_i32_e32 v18, v18, v30
	v_min_i32_e32 v26, v26, v137
	v_min_i32_e32 v22, v24, v22
	v_max_i32_e32 v24, v25, v27
	v_min_i32_e32 v23, v23, v138
	v_max3_i32 v23, v127, v129, v23
	v_max_i32_e32 v22, v126, v22
	v_max3_i32 v25, v128, v130, v26
	v_max_i32_e32 v26, v66, v33
; #define LAS __attribute__((address_space(3)))
; #define MFMA32(a, b, c) __builtin_amdgcn_mfma_f32_32x32x16_bf16((a), (b), (c), 0, 0, 0)
; #define CE_(a, b) ce_desc(v[a], v[b])
; __device__ __forceinline__ void sort16_desc(int (&v)[16]) {
;     ...
;     CE_(0,13); CE_(1,12); CE_(2,15); CE_(3,14); CE_(4,8); CE_(5,6); CE_(7,11); CE_(9,10);
;     CE_(0,5); CE_(1,7); CE_(2,9); CE_(3,4); CE_(6,13); CE_(8,14); CE_(10,15); CE_(11,12);
;     CE_(0,1); CE_(2,3); CE_(4,5); CE_(6,8); CE_(7,9); CE_(10,11); CE_(12,13); CE_(14,15);
;     CE_(0,2); CE_(1,3); CE_(4,10); CE_(5,11); CE_(6,7); CE_(8,9); CE_(12,14); CE_(13,15);
;     CE_(1,2); CE_(3,12); CE_(4,6); CE_(5,7); CE_(8,10); CE_(9,11); CE_(13,14);
;     CE_(1,4); CE_(2,6); CE_(5,8); CE_(7,10); CE_(9,13); CE_(11,14);
;     CE_(2,4); CE_(3,6); CE_(9,12); CE_(11,13);
;     CE_(3,5); CE_(6,8); CE_(7,9); CE_(10,12);
;     CE_(3,4); CE_(5,6); CE_(7,8); CE_(9,10); CE_(11,12);
;     CE_(6,7); CE_(8,9);
;     ...
; }
; __device__ __forceinline__ void merge16_desc(int (&a)[16], const int (&b)[16]) {
; #pragma unroll
;     for (int i = 0; i < 16; ++i) a[i] = a[i] > b[15 - i] ? a[i] : b[15 - i];
; #pragma unroll
;     for (int j = 8; j > 0; j >>= 1)
; #pragma unroll
;         for (int i = 0; i < 16; ++i) { const int l = i ^ j; if (l > i) ce_desc(a[i], a[l]); }
; __device__ __forceinline__ void route_task(int task, int tl0, const bf16* QP  , const LAS bf16* KHL, LAS unsigned short* EL, LAS float* GL, int lane) {
;     ...
;         for (int kt = 0; kt < 4; ++kt) {
;             f32x16 X;
; #pragma unroll
;             for (int i = 0; i < 16; ++i) X[i] = 8.f;
;             const LAS bf16* khp = KHL + (half * 128 + 32 * kt + r) * 72 + 8 * hi;
; #pragma unroll
;             for (int ks = 0; ks < 4; ++ks) {
;                 const bf16x8 kh = lds8(khp + 16 * ks);
;                 X = MFMA32(kh, qa[half][ks], X);
;             }
;             int grp[16];
; #pragma unroll
;             for (int i = 0; i < 16; ++i) grp[i] = (int)((__float_as_uint(X[i]) | 127u) - (unsigned)(32 * kt + (i & 3) + 8 * (i >> 2)));
;             sort16_desc(grp);
;             if (kt == 0) {
; #pragma unroll
;                 for (int i = 0; i < 16; ++i) cur[i] = grp[i];
;             } else merge16_desc(cur, grp);
	v_max3_i32 v21, v131, v76, v21
	v_max_i32_e32 v27, v67, v135
	v_max3_i32 v30, v74, v75, v143
	v_max3_i32 v66, v77, v82, v136
	v_max3_i32 v67, v69, v72, v73
	v_max3_i32 v32, v78, v80, v32
	v_max_i32_e32 v31, v132, v31
	v_max3_i32 v18, v125, v124, v18
	v_max3_i32 v28, v133, v28, v29
	v_max3_i32 v24, v79, v81, v24
	v_max3_i32 v33, v68, v145, v142
	v_max3_i32 v19, v134, v19, v20
	v_max_i32_e32 v20, v23, v66
	v_min_i32_e32 v23, v23, v66
	v_max_i32_e32 v29, v22, v67
	v_max_i32_e32 v66, v25, v32
	v_min_i32_e32 v25, v25, v32
	v_max_i32_e32 v32, v26, v31
	v_min_i32_e32 v26, v26, v31
	v_max_i32_e32 v31, v21, v18
	v_min_i32_e32 v18, v21, v18
	v_max_i32_e32 v21, v27, v28
	v_min_i32_e32 v27, v27, v28
	v_max_i32_e32 v28, v30, v24
	v_min_i32_e32 v22, v22, v67
	v_min_i32_e32 v24, v30, v24
	v_max_i32_e32 v30, v33, v19
	v_min_i32_e32 v19, v33, v19
	v_max_i32_e32 v33, v20, v31
	v_min_i32_e32 v74, v20, v31
	v_max_i32_e32 v20, v29, v21
	v_min_i32_e32 v75, v29, v21
	v_max_i32_e32 v21, v66, v28
	v_min_i32_e32 v76, v66, v28
	ds_read_b128 v[66:69], v96
	ds_read_b128 v[70:73], v96 offset:32
	v_max_i32_e32 v28, v32, v30
	v_min_i32_e32 v77, v32, v30
	v_max_i32_e32 v78, v23, v18
	v_min_i32_e32 v79, v23, v18
	v_max_i32_e32 v80, v22, v27
	v_min_i32_e32 v81, v22, v27
	v_max_i32_e32 v82, v25, v24
	v_min_i32_e32 v124, v25, v24
	v_max_i32_e32 v125, v26, v19
	v_min_i32_e32 v126, v26, v19
	v_max_i32_e32 v127, v33, v21
	v_min_i32_e32 v128, v33, v21
	v_max_i32_e32 v129, v20, v28
	v_min_i32_e32 v130, v20, v28
	s_waitcnt lgkmcnt(1)
	v_mfma_f32_32x32x16_bf16 v[18:33], v[66:69], v[62:65], v[2:17]
	ds_read_b128 v[62:65], v96 offset:64
	v_max_i32_e32 v67, v75, v77
	v_min_i32_e32 v68, v75, v77
	v_max_i32_e32 v75, v80, v125
	v_max_i32_e32 v131, v74, v76
	v_min_i32_e32 v66, v74, v76
	v_max_i32_e32 v69, v78, v82
	s_waitcnt lgkmcnt(1)
	v_mfma_f32_32x32x16_bf16 v[18:33], v[70:73], v[54:57], v[18:33]
	ds_read_b128 v[54:57], v96 offset:96
	v_min_i32_e32 v70, v80, v125
	v_max_i32_e32 v71, v79, v124
	v_min_i32_e32 v72, v79, v124
	v_min_i32_e32 v74, v78, v82
	v_max_i32_e32 v73, v81, v126
	v_min_i32_e32 v76, v81, v126
	s_waitcnt lgkmcnt(1)
	v_mfma_f32_32x32x16_bf16 v[18:33], v[62:65], v[58:61], v[18:33]
	v_min_i32_e32 v77, v127, v129
	v_min_i32_e32 v58, v128, v130
	v_min_i32_e32 v59, v131, v67
	v_min_i32_e32 v60, v66, v68
	v_min_i32_e32 v61, v69, v75
	v_min_i32_e32 v62, v74, v70
	v_min_i32_e32 v63, v71, v73
	s_waitcnt lgkmcnt(0)
	v_mfma_f32_32x32x16_bf16 v[18:33], v[54:57], v[50:53], v[18:33]
	v_min_i32_e32 v64, v72, v76
	s_nop 10
	v_or_b32_e32 v25, 0x7f, v25
	v_or_b32_e32 v29, 0x7f, v29
	v_or_b32_e32 v19, 0x7f, v19
	v_or_b32_e32 v30, 0x7f, v30
	v_or_b32_e32 v23, 0x7f, v23
	v_or_b32_e32 v24, 0x7f, v24
	v_or_b32_e32 v18, 0x7f, v18
	v_or_b32_e32 v31, 0x7f, v31
	v_or_b32_e32 v22, 0x7f, v22
	v_or_b32_e32 v26, 0x7f, v26
	v_or_b32_e32 v21, 0x7f, v21
	v_or_b32_e32 v32, 0x7f, v32
	v_or_b32_e32 v27, 0x7f, v27
	v_or_b32_e32 v28, 0x7f, v28
	v_or_b32_e32 v20, 0x7f, v20
	v_or_b32_e32 v33, 0x7f, v33
	v_add_u32_e32 v25, 0xffffff95, v25
	v_add_u32_e32 v29, 0xffffff8d, v29
	v_add_u32_e32 v19, 0xffffff9f, v19
	v_add_u32_e32 v30, 0xffffff88, v30
	v_add_u32_e32 v23, 0xffffff97, v23
	v_add_u32_e32 v24, 0xffffff96, v24
	v_add_u32_e32 v18, 0xffffffa0, v18
	v_add_u32_e32 v31, 0xffffff87, v31
	v_add_u32_e32 v22, 0xffffff98, v22
	v_add_u32_e32 v26, 0xffffff90, v26
	v_add_u32_e32 v21, 0xffffff9d, v21
	v_add_u32_e32 v32, 0xffffff86, v32
	v_add_u32_e32 v27, 0xffffff8f, v27
	v_add_u32_e32 v28, 0xffffff8e, v28
	v_add_u32_e32 v20, 0xffffff9e, v20
	v_add_u32_e32 v33, 0xffffff85, v33
	v_min_i32_e32 v50, v25, v29
	v_min_i32_e32 v51, v19, v30
	v_min_i32_e32 v53, v23, v24
	v_min_i32_e32 v54, v18, v31
	v_min_i32_e32 v57, v22, v26
	v_min_i32_e32 v65, v21, v32
	v_min_i32_e32 v79, v27, v28
	v_min_i32_e32 v80, v20, v33
	v_max_i32_e32 v18, v18, v31
	v_max_i32_e32 v23, v23, v24
	v_max_i32_e32 v19, v19, v30
	v_max_i32_e32 v25, v25, v29
	v_max_i32_e32 v20, v20, v33
	v_max_i32_e32 v27, v27, v28
	v_max_i32_e32 v21, v21, v32
	v_max_i32_e32 v22, v22, v26
	v_max_i32_e32 v24, v18, v23
	v_max_i32_e32 v29, v19, v25
	v_max_i32_e32 v28, v20, v27
	v_max_i32_e32 v26, v21, v22
	v_min_i32_e32 v30, v24, v29
	v_min_i32_e32 v31, v28, v26
	v_min_i32_e32 v55, v53, v54
	v_min_i32_e32 v32, v30, v31
	v_max_i32_e32 v30, v30, v31
	v_min_i32_e32 v21, v21, v22
	v_min_i32_e32 v18, v18, v23
	v_max_i32_e32 v23, v79, v80
	v_max_i32_e32 v31, v50, v51
	v_max_i32_e32 v53, v53, v54
	v_max_i32_e32 v54, v57, v65
	v_min_i32_e32 v19, v19, v25
	v_min_i32_e32 v20, v20, v27
	v_min_i32_e32 v52, v50, v51
	v_min_i32_e32 v78, v57, v65
	v_min_i32_e32 v81, v79, v80
	v_max_i32_e32 v22, v21, v18
	v_max_i32_e32 v57, v53, v54
	v_max_i32_e32 v25, v19, v20
	v_min_i32_e32 v18, v21, v18
	v_min_i32_e32 v21, v23, v31
	v_min_i32_e32 v56, v52, v55
	v_min_i32_e32 v82, v78, v81
	v_max_i32_e32 v33, v52, v55
	v_max_i32_e32 v52, v78, v81
	v_max_i32_e32 v24, v24, v29
	v_max_i32_e32 v26, v28, v26
	v_max_i32_e32 v50, v23, v31
	v_max_i32_e32 v27, v57, v25
	v_max_i32_e32 v23, v18, v21
	v_min_i32_e32 v25, v57, v25
	v_min_i32_e32 v53, v53, v54
	v_min_i32_e32 v19, v19, v20
	v_max_i32_e32 v55, v33, v52
	v_min_i32_e32 v28, v24, v26
	v_max_i32_e32 v51, v22, v50
	v_max_i32_e32 v31, v23, v25
	v_max_i32_e32 v20, v53, v19
	v_min_i32_e32 v23, v23, v25
	v_min_i32_e32 v19, v53, v19
	v_min_i32_e32 v18, v18, v21
	v_max_i32_e32 v25, v56, v82
	v_min_i32_e32 v33, v33, v52
	v_min_i32_e32 v29, v30, v28
	v_min_i32_e32 v65, v51, v27
	v_min_i32_e32 v22, v22, v50
	v_max_i32_e32 v21, v19, v18
	v_max_i32_e32 v52, v25, v33
	v_max_i32_e32 v78, v32, v55
	v_min_i32_e32 v79, v29, v65
	v_max_i32_e32 v50, v20, v22
	v_min_i32_e32 v20, v20, v22
; __device__ __forceinline__ void merge16_desc(int (&a)[16], const int (&b)[16]) {
; #pragma unroll
;     for (int i = 0; i < 16; ++i) a[i] = a[i] > b[15 - i] ? a[i] : b[15 - i];
; #pragma unroll
;     for (int j = 8; j > 0; j >>= 1)
; #pragma unroll
;         for (int i = 0; i < 16; ++i) { const int l = i ^ j; if (l > i) ce_desc(a[i], a[l]); }
; }
; __device__ __forceinline__ void route_task(int task, int tl0, const bf16* QP  , const LAS bf16* KHL, LAS unsigned short* EL, LAS float* GL, int lane) {
;     ...
;             } else merge16_desc(cur, grp);
;         }
;         { const unsigned h4 = 4u * (unsigned)hi;
; #pragma unroll
;           for (int i = 0; i < 16; ++i) cur[i] -= (int)h4; }
;         int oth[16];
; #pragma unroll
;         for (int i = 0; i < 16; ++i) oth[i] = __shfl_xor(cur[i], 32);
;         merge16_desc(cur, oth);
	v_max_i32_e32 v53, v21, v52
	v_min_i32_e32 v32, v32, v55
	v_max_i32_e32 v80, v78, v79
	v_max_i32_e32 v54, v31, v50
	v_min_i32_e32 v78, v78, v79
	v_min_i32_e32 v31, v31, v50
	v_max_i32_e32 v22, v23, v20
	v_max_i32_e32 v55, v53, v32
	v_min_i32_e32 v18, v19, v18
	v_min_i32_e32 v19, v25, v33
	v_min_i32_e32 v20, v23, v20
	v_min_i32_e32 v23, v53, v32
	v_max_i32_e32 v28, v30, v28
	v_max_i32_e32 v27, v51, v27
	v_min_i32_e32 v124, v56, v82
	v_min_i32_e32 v57, v80, v54
	v_max_i32_e32 v50, v78, v31
	v_max_i32_e32 v56, v22, v55
	v_min_i32_e32 v31, v78, v31
	v_max_i32_e32 v25, v18, v19
	v_min_i32_e32 v21, v21, v52
	v_min_i32_e32 v32, v20, v23
	v_max_i32_e32 v29, v29, v65
	v_min_i32_e32 v30, v28, v27
	v_min_i32_e32 v22, v22, v55
	v_max_i32_e32 v20, v20, v23
	v_min_i32_e32 v79, v57, v50
	v_max_i32_e32 v78, v56, v31
	v_max_i32_e32 v33, v25, v21
	v_max_i32_e32 v53, v80, v54
	v_min_i32_e32 v51, v29, v30
	v_min_i32_e32 v31, v56, v31
	v_max_i32_e32 v23, v22, v20
	v_min_i32_e32 v81, v79, v78
	v_max_i32_e32 v52, v33, v32
	v_max_i32_e32 v54, v53, v51
	v_min_i32_e32 v21, v25, v21
	v_max_i32_e32 v25, v57, v50
	v_min_i32_e32 v55, v31, v23
	v_max_i32_e32 v27, v28, v27
	v_min_i32_e32 v18, v18, v19
	v_min_i32_e32 v20, v22, v20
	v_min_i32_e32 v32, v33, v32
	v_min_i32_e32 v33, v53, v51
	v_max3_i32 v124, v127, v129, v124
	v_max3_i32 v69, v69, v75, v81
	v_max3_i32 v52, v131, v67, v52
	v_max3_i32 v54, v71, v73, v54
	v_max3_i32 v21, v128, v130, v21
	v_max3_i32 v25, v74, v70, v25
	v_max3_i32 v55, v66, v68, v55
	v_max3_i32 v27, v72, v76, v27
	v_max_i32_e32 v18, v77, v18
	v_max3_i32 v19, v61, v79, v78
	v_max_i32_e32 v20, v59, v20
	v_max3_i32 v22, v63, v29, v30
	v_max_i32_e32 v32, v58, v32
	v_max_i32_e32 v33, v62, v33
	v_max3_i32 v23, v60, v31, v23
	v_max3_i32 v24, v64, v24, v26
	v_min_i32_e32 v65, v52, v54
	v_min_i32_e32 v50, v21, v25
	v_min_i32_e32 v61, v18, v19
	v_min_i32_e32 v29, v20, v22
	v_min_i32_e32 v26, v23, v24
	v_max_i32_e32 v59, v124, v69
	v_max_i32_e32 v52, v52, v54
	v_max_i32_e32 v21, v21, v25
	v_max_i32_e32 v25, v55, v27
	v_max_i32_e32 v18, v18, v19
	v_max_i32_e32 v19, v20, v22
	v_max_i32_e32 v22, v32, v33
	v_max_i32_e32 v23, v23, v24
	v_min_i32_e32 v28, v55, v27
	v_max_i32_e32 v54, v59, v52
	v_max_i32_e32 v27, v21, v25
	v_max_i32_e32 v20, v18, v19
	v_max_i32_e32 v24, v22, v23
	v_min_i32_e32 v51, v32, v33
	v_max_i32_e32 v55, v54, v27
	v_max_i32_e32 v32, v20, v24
	v_min_i32_e32 v27, v54, v27
	v_min_i32_e32 v20, v20, v24
	v_max_i32_e32 v24, v27, v20
	v_min_i32_e32 v20, v27, v20
	v_min_i32_e32 v27, v59, v52
	v_min_i32_e32 v21, v21, v25
	v_min_i32_e32 v18, v18, v19
	v_min_i32_e32 v19, v22, v23
	v_min_i32_e32 v75, v124, v69
	v_max_i32_e32 v25, v27, v21
	v_max_i32_e32 v22, v18, v19
	v_min_i32_e32 v21, v27, v21
	v_min_i32_e32 v18, v18, v19
	v_min_i32_e32 v56, v50, v28
	v_min_i32_e32 v31, v51, v26
	v_max_i32_e32 v23, v25, v22
	v_min_i32_e32 v22, v25, v22
	v_max_i32_e32 v19, v21, v18
	v_min_i32_e32 v18, v21, v18
	v_max_i32_e32 v21, v75, v65
	v_max_i32_e32 v25, v50, v28
	v_max_i32_e32 v28, v61, v29
	v_max_i32_e32 v26, v51, v26
	v_min_i32_e32 v67, v75, v65
	v_min_i32_e32 v30, v61, v29
	v_max_i32_e32 v27, v21, v25
	v_min_i32_e32 v21, v21, v25
	v_min_i32_e32 v25, v28, v26
	v_min_i32_e32 v57, v67, v56
	v_min_i32_e32 v53, v30, v31
	v_max_i32_e32 v29, v28, v26
	v_max_i32_e32 v26, v21, v25
	v_min_i32_e32 v21, v21, v25
	v_max_i32_e32 v25, v67, v56
	v_max_i32_e32 v28, v30, v31
	v_min_i32_e32 v58, v57, v53
	v_max_i32_e32 v33, v55, v32
	v_min_i32_e32 v32, v55, v32
	v_max_i32_e32 v50, v27, v29
	v_min_i32_e32 v27, v27, v29
	v_max_i32_e32 v29, v25, v28
	v_min_i32_e32 v25, v25, v28
	v_max_i32_e32 v28, v57, v53
	v_sub_u32_e32 v30, v33, v87
	v_sub_u32_e32 v31, v32, v87
	v_sub_u32_e32 v24, v24, v87
	v_sub_u32_e32 v20, v20, v87
	v_sub_u32_e32 v23, v23, v87
	v_sub_u32_e32 v22, v22, v87
	v_sub_u32_e32 v19, v19, v87
	v_sub_u32_e32 v18, v18, v87
	v_sub_u32_e32 v32, v50, v87
	v_sub_u32_e32 v27, v27, v87
	v_sub_u32_e32 v26, v26, v87
	v_sub_u32_e32 v21, v21, v87
	v_sub_u32_e32 v29, v29, v87
	v_sub_u32_e32 v25, v25, v87
	v_sub_u32_e32 v28, v28, v87
	v_sub_u32_e32 v33, v58, v87
	ds_bpermute_b32 v50, v123, v30
	ds_bpermute_b32 v51, v123, v31
	ds_bpermute_b32 v52, v123, v24
	ds_bpermute_b32 v53, v123, v20
	ds_bpermute_b32 v54, v123, v23
	ds_bpermute_b32 v55, v123, v22
	ds_bpermute_b32 v56, v123, v19
	ds_bpermute_b32 v57, v123, v18
	ds_bpermute_b32 v58, v123, v32
	ds_bpermute_b32 v59, v123, v27
	ds_bpermute_b32 v60, v123, v26
	ds_bpermute_b32 v61, v123, v33
	ds_bpermute_b32 v62, v123, v28
	ds_bpermute_b32 v63, v123, v25
	ds_bpermute_b32 v64, v123, v29
	ds_bpermute_b32 v65, v123, v21
	s_waitcnt lgkmcnt(4)
	v_max_i32_e32 v30, v30, v61
	s_waitcnt lgkmcnt(3)
	v_max_i32_e32 v31, v31, v62
	s_waitcnt lgkmcnt(2)
	v_max_i32_e32 v24, v24, v63
	s_waitcnt lgkmcnt(1)
	v_max_i32_e32 v20, v20, v64
	s_waitcnt lgkmcnt(0)
; __device__ __forceinline__ void merge16_desc(int (&a)[16], const int (&b)[16]) {
; #pragma unroll
;     for (int i = 0; i < 16; ++i) a[i] = a[i] > b[15 - i] ? a[i] : b[15 - i];
; #pragma unroll
;     for (int j = 8; j > 0; j >>= 1)
; #pragma unroll
;         for (int i = 0; i < 16; ++i) { const int l = i ^ j; if (l > i) ce_desc(a[i], a[l]); }
; }
; __device__ __forceinline__ void route_task(int task, int tl0, const bf16* QP  , const LAS bf16* KHL, LAS unsigned short* EL, LAS float* GL, int lane) {
;     ...
;             } else merge16_desc(cur, grp);
;         }
;         { const unsigned h4 = 4u * (unsigned)hi;
; #pragma unroll
;           for (int i = 0; i < 16; ++i) cur[i] -= (int)h4; }
;         int oth[16];
; #pragma unroll
;         for (int i = 0; i < 16; ++i) oth[i] = __shfl_xor(cur[i], 32);
;         merge16_desc(cur, oth);
; #pragma unroll
;         for (int i = 0; i < 16; ++i) top[half][i] = cur[i];
;     }
	v_max_i32_e32 v23, v23, v65
	v_max_i32_e32 v22, v22, v60
	v_max_i32_e32 v19, v19, v59
	v_max_i32_e32 v18, v18, v58
	v_max_i32_e32 v32, v32, v57
	v_max_i32_e32 v27, v27, v56
	v_max_i32_e32 v26, v26, v55
	v_max_i32_e32 v21, v21, v54
	v_max_i32_e32 v29, v29, v53
	v_max_i32_e32 v25, v25, v52
	v_max_i32_e32 v28, v28, v51
	v_max_i32_e32 v33, v33, v50
	v_max_i32_e32 v50, v30, v32
	v_min_i32_e32 v30, v30, v32
	v_max_i32_e32 v32, v31, v27
	v_min_i32_e32 v27, v31, v27
	v_max_i32_e32 v31, v24, v26
	v_min_i32_e32 v24, v24, v26
	v_max_i32_e32 v26, v20, v21
	v_min_i32_e32 v20, v20, v21
	v_max_i32_e32 v21, v23, v29
	v_min_i32_e32 v23, v23, v29
	v_max_i32_e32 v29, v22, v25
	v_min_i32_e32 v22, v22, v25
	v_max_i32_e32 v25, v19, v28
	v_min_i32_e32 v19, v19, v28
	v_max_i32_e32 v28, v18, v33
	v_min_i32_e32 v18, v18, v33
	v_max_i32_e32 v33, v50, v21
	v_min_i32_e32 v21, v50, v21
	v_max_i32_e32 v50, v32, v29
	v_min_i32_e32 v29, v32, v29
	v_max_i32_e32 v32, v31, v25
	v_min_i32_e32 v25, v31, v25
	v_max_i32_e32 v31, v26, v28
	v_max_i32_e32 v64, v50, v31
	v_min_i32_e32 v67, v50, v31
	ds_read_b128 v[50:53], v94 offset:18432
	ds_read_b128 v[54:57], v94 offset:18464
	v_min_i32_e32 v26, v26, v28
	v_max_i32_e32 v28, v30, v23
	v_min_i32_e32 v58, v30, v23
	v_max_i32_e32 v23, v27, v22
	v_min_i32_e32 v59, v27, v22
	v_max_i32_e32 v22, v24, v19
	v_min_i32_e32 v60, v24, v19
	v_max_i32_e32 v19, v20, v18
	v_min_i32_e32 v61, v20, v18
	v_max_i32_e32 v62, v33, v32
	v_min_i32_e32 v66, v33, v32
	v_max_i32_e32 v68, v21, v25
	v_min_i32_e32 v69, v21, v25
	v_max_i32_e32 v70, v29, v26
	v_min_i32_e32 v71, v29, v26
	v_max_i32_e32 v72, v28, v22
	v_min_i32_e32 v73, v28, v22
	v_max_i32_e32 v74, v23, v19
	v_min_i32_e32 v75, v23, v19
	s_waitcnt vmcnt(3) lgkmcnt(1)
	v_mfma_f32_32x32x16_bf16 v[18:33], v[50:53], v[46:49], v[2:17]
	ds_read_b128 v[50:53], v94 offset:18496
	v_max_i32_e32 v76, v58, v60
	v_min_i32_e32 v77, v58, v60
	v_max_i32_e32 v78, v59, v61
	v_min_i32_e32 v79, v59, v61
	v_max_i32_e32 v63, v62, v64
	v_min_i32_e32 v65, v62, v64
	s_waitcnt vmcnt(2) lgkmcnt(1)
	v_mfma_f32_32x32x16_bf16 v[18:33], v[54:57], v[42:45], v[18:33]
	v_max_i32_e32 v64, v66, v67
	v_min_i32_e32 v62, v66, v67
	v_max_i32_e32 v61, v68, v70
	v_min_i32_e32 v60, v68, v70
	v_max_i32_e32 v59, v69, v71
	v_min_i32_e32 v57, v69, v71
	ds_read_b128 v[66:69], v94 offset:18528
	s_waitcnt vmcnt(1) lgkmcnt(1)
	v_mfma_f32_32x32x16_bf16 v[18:33], v[50:53], v[38:41], v[18:33]
	v_max_i32_e32 v55, v72, v74
	v_min_i32_e32 v58, v72, v74
	v_max_i32_e32 v56, v73, v75
	v_min_i32_e32 v54, v73, v75
	v_max_i32_e32 v53, v76, v78
	v_min_i32_e32 v52, v76, v78
	v_max_i32_e32 v51, v77, v79
	s_waitcnt vmcnt(0) lgkmcnt(0)
	v_mfma_f32_32x32x16_bf16 v[18:33], v[66:69], v[34:37], v[18:33]
	v_min_i32_e32 v50, v77, v79
	s_nop 10
	v_or_b32_e32 v21, 0x7f, v21
	v_or_b32_e32 v32, 0x7f, v32
	v_or_b32_e32 v22, 0x7f, v22
	v_or_b32_e32 v26, 0x7f, v26
	v_or_b32_e32 v31, 0x7f, v31
	v_or_b32_e32 v23, 0x7f, v23
	v_or_b32_e32 v24, 0x7f, v24
	v_or_b32_e32 v27, 0x7f, v27
	v_or_b32_e32 v28, 0x7f, v28
	v_or_b32_e32 v20, 0x7f, v20
	v_or_b32_e32 v33, 0x7f, v33
	v_or_b32_e32 v25, 0x7f, v25
	v_or_b32_e32 v29, 0x7f, v29
	v_or_b32_e32 v19, 0x7f, v19
	v_or_b32_e32 v30, 0x7f, v30
	v_add_u32_e32 v21, -3, v21
	v_subrev_u32_e32 v32, 26, v32
	v_add_u32_e32 v22, -8, v22
	v_add_u32_e32 v26, -16, v26
	v_or_b32_e32 v18, 0x7f, v18
	v_subrev_u32_e32 v31, 25, v31
	v_add_u32_e32 v23, -9, v23
	v_add_u32_e32 v24, -10, v24
	v_subrev_u32_e32 v27, 17, v27
	v_subrev_u32_e32 v28, 18, v28
	v_add_u32_e32 v20, -2, v20
	v_subrev_u32_e32 v33, 27, v33
	v_add_u32_e32 v25, -11, v25
	v_subrev_u32_e32 v29, 19, v29
	v_add_u32_e32 v19, -1, v19
	v_subrev_u32_e32 v30, 24, v30
	v_max_i32_e32 v66, v21, v32
	v_max_i32_e32 v67, v22, v26
	v_max_i32_e32 v69, v18, v31
	v_max_i32_e32 v70, v23, v24
	v_min_i32_e32 v73, v27, v28
	v_min_i32_e32 v74, v20, v33
	v_min_i32_e32 v76, v25, v29
	v_min_i32_e32 v77, v19, v30
	v_min_i32_e32 v23, v23, v24
	v_min_i32_e32 v18, v18, v31
	v_min_i32_e32 v22, v22, v26
	v_min_i32_e32 v21, v21, v32
	v_max_i32_e32 v19, v19, v30
	v_max_i32_e32 v25, v25, v29
	v_max_i32_e32 v20, v20, v33
	v_max_i32_e32 v27, v27, v28
	v_max_i32_e32 v24, v23, v18
	v_max_i32_e32 v26, v22, v21
	v_min_i32_e32 v29, v19, v25
	v_min_i32_e32 v28, v20, v27
	v_max_i32_e32 v31, v24, v26
	v_min_i32_e32 v24, v24, v26
	v_min_i32_e32 v26, v29, v28
	v_min_i32_e32 v68, v66, v67
	v_min_i32_e32 v71, v69, v70
	v_max_i32_e32 v75, v73, v74
	v_max_i32_e32 v78, v76, v77
	v_max_i32_e32 v30, v29, v28
	v_max_i32_e32 v28, v24, v26
	v_min_i32_e32 v81, v24, v26
	v_min_i32_e32 v24, v76, v77
	v_min_i32_e32 v18, v23, v18
	v_min_i32_e32 v21, v22, v21
	v_min_i32_e32 v22, v73, v74
	v_min_i32_e32 v72, v68, v71
	v_min_i32_e32 v79, v75, v78
	v_min_i32_e32 v76, v24, v18
	v_min_i32_e32 v74, v21, v22
	v_max_i32_e32 v18, v24, v18
	v_max_i32_e32 v21, v21, v22
	v_max_i32_e32 v23, v69, v70
	v_max_i32_e32 v19, v19, v25
	v_max_i32_e32 v20, v20, v27
	v_max_i32_e32 v25, v66, v67
	v_max_i32_e32 v80, v72, v79
	v_max_i32_e32 v29, v68, v71
	v_max_i32_e32 v68, v75, v78
	v_min_i32_e32 v79, v72, v79
	v_max_i32_e32 v77, v76, v74
	v_min_i32_e32 v124, v18, v21
	v_min_i32_e32 v24, v23, v19
	v_min_i32_e32 v26, v20, v25
	v_min_i32_e32 v32, v31, v30
	v_min_i32_e32 v71, v29, v68
	v_max_i32_e32 v82, v81, v79
	v_max_i32_e32 v125, v77, v124
	v_min_i32_e32 v27, v24, v26
	v_max_i32_e32 v18, v18, v21
	v_min_i32_e32 v33, v80, v32
	v_min_i32_e32 v75, v28, v71
	v_max_i32_e32 v22, v82, v125
	v_min_i32_e32 v21, v27, v18
	v_max_i32_e32 v78, v33, v75
	v_max_i32_e32 v66, v22, v21
	v_max_i32_e32 v70, v78, v66
	v_max_i32_e32 v131, v29, v68
	v_min_i32_e32 v78, v78, v66
	ds_read_b128 v[66:69], v97
	v_max_i32_e32 v127, v23, v19
	v_max_i32_e32 v128, v20, v25
	v_max_i32_e32 v126, v24, v26
	v_min_i32_e32 v129, v127, v128
	v_max_i32_e32 v132, v31, v30
	v_min_i32_e32 v130, v126, v129
	v_min_i32_e32 v133, v131, v132
	v_max_i32_e32 v18, v27, v18
	v_min_i32_e32 v19, v130, v133
	v_max_i32_e32 v23, v80, v32
	v_max_i32_e32 v24, v28, v71
	v_min_i32_e32 v20, v18, v19
	v_min_i32_e32 v25, v23, v24
	v_min_i32_e32 v26, v20, v25
	v_min_i32_e32 v80, v70, v26
	v_max_i32_e32 v143, v70, v26
	ds_read_b128 v[70:73], v97 offset:32
	v_min_i32_e32 v75, v33, v75
	v_min_i32_e32 v134, v22, v21
	v_max_i32_e32 v138, v18, v19
	v_max_i32_e32 v139, v23, v24
	v_max_i32_e32 v141, v20, v25
	s_waitcnt lgkmcnt(1)
; #define LAS __attribute__((address_space(3)))
; #define MFMA32(a, b, c) __builtin_amdgcn_mfma_f32_32x32x16_bf16((a), (b), (c), 0, 0, 0)
; #define CE_(a, b) ce_desc(v[a], v[b])
; __device__ __forceinline__ void sort16_desc(int (&v)[16]) {
;     ...
;     CE_(0,13); CE_(1,12); CE_(2,15); CE_(3,14); CE_(4,8); CE_(5,6); CE_(7,11); CE_(9,10);
;     CE_(0,5); CE_(1,7); CE_(2,9); CE_(3,4); CE_(6,13); CE_(8,14); CE_(10,15); CE_(11,12);
;     CE_(0,1); CE_(2,3); CE_(4,5); CE_(6,8); CE_(7,9); CE_(10,11); CE_(12,13); CE_(14,15);
;     CE_(0,2); CE_(1,3); CE_(4,10); CE_(5,11); CE_(6,7); CE_(8,9); CE_(12,14); CE_(13,15);
;     CE_(1,2); CE_(3,12); CE_(4,6); CE_(5,7); CE_(8,10); CE_(9,11); CE_(13,14);
;     CE_(1,4); CE_(2,6); CE_(5,8); CE_(7,10); CE_(9,13); CE_(11,14);
;     CE_(2,4); CE_(3,6); CE_(9,12); CE_(11,13);
;     CE_(3,5); CE_(6,8); CE_(7,9); CE_(10,12);
;     CE_(3,4); CE_(5,6); CE_(7,8); CE_(9,10); CE_(11,12);
;     CE_(6,7); CE_(8,9);
;     ...
; }
; __device__ __forceinline__ void route_task(int task, int tl0, const bf16* QP  , const LAS bf16* KHL, LAS unsigned short* EL, LAS float* GL, int lane) {
;     ...
;         for (int kt = 0; kt < 4; ++kt) {
;             f32x16 X;
; #pragma unroll
;             for (int i = 0; i < 16; ++i) X[i] = 8.f;
;             const LAS bf16* khp = KHL + (half * 128 + 32 * kt + r) * 72 + 8 * hi;
; #pragma unroll
;             for (int ks = 0; ks < 4; ++ks) {
;                 const bf16x8 kh = lds8(khp + 16 * ks);
;                 X = MFMA32(kh, qa[half][ks], X);
;             }
;             int grp[16];
; #pragma unroll
;             for (int i = 0; i < 16; ++i) grp[i] = (int)((__float_as_uint(X[i]) | 127u) - (unsigned)(32 * kt + (i & 3) + 8 * (i >> 2)));
;             sort16_desc(grp);
;             if (kt == 0) {
; #pragma unroll
;                 for (int i = 0; i < 16; ++i) cur[i] = grp[i];
;             } else merge16_desc(cur, grp);
	v_mfma_f32_32x32x16_bf16 v[18:33], v[66:69], v[46:49], v[2:17]
	ds_read_b128 v[66:69], v97 offset:64
	v_max_i32_e32 v135, v75, v134
	v_max_i32_e32 v136, v78, v135
	v_min_i32_e32 v79, v81, v79
	v_min_i32_e32 v77, v77, v124
	v_min_i32_e32 v78, v78, v135
	v_max_i32_e32 v130, v130, v133
	s_waitcnt lgkmcnt(1)
	v_mfma_f32_32x32x16_bf16 v[18:33], v[70:73], v[42:45], v[18:33]
	ds_read_b128 v[70:73], v97 offset:96
	v_max_i32_e32 v126, v126, v129
	v_min_i32_e32 v74, v76, v74
	v_min_i32_e32 v140, v138, v139
	v_max_i32_e32 v81, v79, v77
	v_min_i32_e32 v82, v82, v125
	v_min_i32_e32 v75, v75, v134
	s_waitcnt lgkmcnt(1)
	v_mfma_f32_32x32x16_bf16 v[18:33], v[66:69], v[38:41], v[18:33]
	v_max_i32_e32 v66, v131, v132
	v_max_i32_e32 v134, v138, v139
	v_min_i32_e32 v77, v79, v77
	v_max_i32_e32 v124, v81, v82
	v_min_i32_e32 v81, v81, v82
	v_min_i32_e32 v67, v126, v66
	v_min_i32_e32 v142, v140, v141
	s_waitcnt lgkmcnt(0)
	v_mfma_f32_32x32x16_bf16 v[18:33], v[70:73], v[34:37], v[18:33]
	v_min_i32_e32 v68, v130, v67
	v_min_i32_e32 v137, v80, v136
	v_min_i32_e32 v144, v142, v143
	v_min_i32_e32 v125, v124, v75
	v_min_i32_e32 v69, v134, v68
	s_nop 6
	v_or_b32_e32 v21, 0x7f, v21
	v_or_b32_e32 v32, 0x7f, v32
	v_or_b32_e32 v22, 0x7f, v22
	v_or_b32_e32 v26, 0x7f, v26
	v_or_b32_e32 v18, 0x7f, v18
	v_or_b32_e32 v31, 0x7f, v31
	v_or_b32_e32 v23, 0x7f, v23
	v_or_b32_e32 v24, 0x7f, v24
	v_or_b32_e32 v27, 0x7f, v27
	v_or_b32_e32 v28, 0x7f, v28
	v_or_b32_e32 v20, 0x7f, v20
	v_or_b32_e32 v33, 0x7f, v33
	v_or_b32_e32 v25, 0x7f, v25
	v_or_b32_e32 v29, 0x7f, v29
	v_or_b32_e32 v19, 0x7f, v19
	v_or_b32_e32 v30, 0x7f, v30
	v_subrev_u32_e32 v21, 35, v21
	v_subrev_u32_e32 v32, 58, v32
	v_subrev_u32_e32 v22, 40, v22
	v_subrev_u32_e32 v26, 48, v26
	v_subrev_u32_e32 v18, 32, v18
	v_subrev_u32_e32 v31, 57, v31
	v_subrev_u32_e32 v23, 41, v23
	v_subrev_u32_e32 v24, 42, v24
	v_subrev_u32_e32 v27, 49, v27
	v_subrev_u32_e32 v28, 50, v28
	v_subrev_u32_e32 v20, 34, v20
	v_subrev_u32_e32 v33, 59, v33
	v_subrev_u32_e32 v25, 43, v25
	v_subrev_u32_e32 v29, 51, v29
	v_subrev_u32_e32 v19, 33, v19
	v_subrev_u32_e32 v30, 56, v30
	v_max_i32_e32 v70, v21, v32
	v_max_i32_e32 v71, v22, v26
	v_max_i32_e32 v73, v18, v31
	v_max_i32_e32 v76, v23, v24
	v_min_i32_e32 v129, v27, v28
	v_min_i32_e32 v131, v20, v33
	v_min_i32_e32 v133, v25, v29
	v_min_i32_e32 v135, v19, v30
	v_min_i32_e32 v23, v23, v24
	v_min_i32_e32 v18, v18, v31
	v_min_i32_e32 v22, v22, v26
	v_min_i32_e32 v21, v21, v32
	v_max_i32_e32 v19, v19, v30
	v_max_i32_e32 v25, v25, v29
	v_max_i32_e32 v20, v20, v33
	v_max_i32_e32 v27, v27, v28
	v_min_i32_e32 v72, v70, v71
	v_min_i32_e32 v79, v73, v76
	v_max_i32_e32 v132, v129, v131
	v_max_i32_e32 v138, v133, v135
	v_max_i32_e32 v24, v23, v18
	v_max_i32_e32 v26, v22, v21
	v_min_i32_e32 v29, v19, v25
	v_min_i32_e32 v28, v20, v27
	v_min_i32_e32 v133, v133, v135
	v_min_i32_e32 v18, v23, v18
	v_min_i32_e32 v21, v22, v21
	v_min_i32_e32 v22, v129, v131
	v_max_i32_e32 v73, v73, v76
	v_max_i32_e32 v19, v19, v25
	v_max_i32_e32 v20, v20, v27
	v_max_i32_e32 v27, v70, v71
	v_min_i32_e32 v82, v72, v79
	v_min_i32_e32 v139, v132, v138
	v_max_i32_e32 v31, v24, v26
	v_max_i32_e32 v30, v29, v28
	v_min_i32_e32 v24, v24, v26
	v_min_i32_e32 v26, v29, v28
	v_max_i32_e32 v29, v72, v79
	v_max_i32_e32 v72, v132, v138
	v_min_i32_e32 v23, v133, v18
	v_min_i32_e32 v129, v21, v22
	v_max_i32_e32 v18, v133, v18
	v_max_i32_e32 v21, v21, v22
	v_min_i32_e32 v25, v73, v19
	v_min_i32_e32 v70, v20, v27
	v_max_i32_e32 v19, v73, v19
	v_max_i32_e32 v20, v20, v27
	v_min_i32_e32 v32, v31, v30
	v_max_i32_e32 v28, v24, v26
	v_min_i32_e32 v79, v29, v72
	v_min_i32_e32 v24, v24, v26
	v_min_i32_e32 v26, v82, v139
	v_max_i32_e32 v131, v23, v129
	v_min_i32_e32 v22, v18, v21
	v_min_i32_e32 v71, v25, v70
	v_max_i32_e32 v25, v25, v70
	v_min_i32_e32 v27, v19, v20
	v_max_i32_e32 v29, v29, v72
	v_max_i32_e32 v30, v31, v30
	v_max_i32_e32 v145, v82, v139
	v_max_i32_e32 v82, v24, v26
	v_max_i32_e32 v133, v131, v22
	v_max_i32_e32 v18, v18, v21
	v_min_i32_e32 v70, v25, v27
	v_min_i32_e32 v31, v29, v30
	v_min_i32_e32 v33, v145, v32
	v_min_i32_e32 v132, v28, v79
	v_max_i32_e32 v135, v82, v133
	v_min_i32_e32 v21, v71, v18
	v_max_i32_e32 v18, v71, v18
	v_min_i32_e32 v71, v70, v31
	v_max_i32_e32 v32, v145, v32
	v_max_i32_e32 v28, v28, v79
	v_max_i32_e32 v138, v33, v132
	v_max_i32_e32 v76, v135, v21
	v_min_i32_e32 v72, v18, v71
	v_min_i32_e32 v73, v32, v28
	v_min_i32_e32 v33, v33, v132
	v_min_i32_e32 v21, v135, v21
	v_max_i32_e32 v18, v18, v71
	v_max_i32_e32 v28, v32, v28
	v_min_i32_e32 v24, v24, v26
	v_min_i32_e32 v22, v131, v22
	v_max_i32_e32 v25, v25, v27
	v_max_i32_e32 v27, v29, v30
	v_max_i32_e32 v139, v138, v76
	v_min_i32_e32 v79, v72, v73
	v_min_i32_e32 v76, v138, v76
	v_max_i32_e32 v132, v33, v21
	v_min_i32_e32 v32, v18, v28
	v_max_i32_e32 v71, v72, v73
	v_max_i32_e32 v26, v24, v22
	v_min_i32_e32 v82, v82, v133
	v_max_i32_e32 v18, v18, v28
	v_max_i32_e32 v28, v70, v31
	v_min_i32_e32 v29, v25, v27
	v_min_i32_e32 v145, v139, v79
	v_max_i32_e32 v135, v76, v132
	v_min_i32_e32 v72, v32, v71
	v_max_i32_e32 v73, v139, v79
	v_max_i32_e32 v131, v26, v82
	v_min_i32_e32 v21, v33, v21
	v_min_i32_e32 v30, v28, v29
	v_min_i32_e32 v138, v145, v135
	v_min_i32_e32 v79, v72, v73
	v_min_i32_e32 v33, v131, v21
	v_min_i32_e32 v76, v76, v132
	v_min_i32_e32 v31, v18, v30
	v_min_i32_e32 v26, v26, v82
	v_min_i32_e32 v22, v24, v22
	v_min_i32_e32 v23, v23, v129
	v_max3_i32 v23, v127, v128, v23
	v_max3_i32 v22, v126, v66, v22
	v_max3_i32 v24, v130, v67, v26
	v_max3_i32 v26, v134, v68, v33
	v_max3_i32 v21, v69, v131, v21
	v_max3_i32 v33, v140, v141, v76
	v_max3_i32 v66, v142, v143, v138
; #define LAS __attribute__((address_space(3)))
; #define MFMA32(a, b, c) __builtin_amdgcn_mfma_f32_32x32x16_bf16((a), (b), (c), 0, 0, 0)
; #define CE_(a, b) ce_desc(v[a], v[b])
; __device__ __forceinline__ void sort16_desc(int (&v)[16]) {
;     ...
;     CE_(0,13); CE_(1,12); CE_(2,15); CE_(3,14); CE_(4,8); CE_(5,6); CE_(7,11); CE_(9,10);
;     CE_(0,5); CE_(1,7); CE_(2,9); CE_(3,4); CE_(6,13); CE_(8,14); CE_(10,15); CE_(11,12);
;     CE_(0,1); CE_(2,3); CE_(4,5); CE_(6,8); CE_(7,9); CE_(10,11); CE_(12,13); CE_(14,15);
;     CE_(0,2); CE_(1,3); CE_(4,10); CE_(5,11); CE_(6,7); CE_(8,9); CE_(12,14); CE_(13,15);
;     CE_(1,2); CE_(3,12); CE_(4,6); CE_(5,7); CE_(8,10); CE_(9,11); CE_(13,14);
;     CE_(1,4); CE_(2,6); CE_(5,8); CE_(7,10); CE_(9,13); CE_(11,14);
;     CE_(2,4); CE_(3,6); CE_(9,12); CE_(11,13);
;     CE_(3,5); CE_(6,8); CE_(7,9); CE_(10,12);
;     CE_(3,4); CE_(5,6); CE_(7,8); CE_(9,10); CE_(11,12);
;     CE_(6,7); CE_(8,9);
;     ...
; }
; __device__ __forceinline__ void merge16_desc(int (&a)[16], const int (&b)[16]) {
; #pragma unroll
;     for (int i = 0; i < 16; ++i) a[i] = a[i] > b[15 - i] ? a[i] : b[15 - i];
; #pragma unroll
;     for (int j = 8; j > 0; j >>= 1)
; #pragma unroll
;         for (int i = 0; i < 16; ++i) { const int l = i ^ j; if (l > i) ce_desc(a[i], a[l]); }
; __device__ __forceinline__ void route_task(int task, int tl0, const bf16* QP  , const LAS bf16* KHL, LAS unsigned short* EL, LAS float* GL, int lane) {
;     ...
;         for (int kt = 0; kt < 4; ++kt) {
;             f32x16 X;
; #pragma unroll
;             for (int i = 0; i < 16; ++i) X[i] = 8.f;
;             const LAS bf16* khp = KHL + (half * 128 + 32 * kt + r) * 72 + 8 * hi;
; #pragma unroll
;             for (int ks = 0; ks < 4; ++ks) {
;                 const bf16x8 kh = lds8(khp + 16 * ks);
;                 X = MFMA32(kh, qa[half][ks], X);
;             }
;             int grp[16];
; #pragma unroll
;             for (int i = 0; i < 16; ++i) grp[i] = (int)((__float_as_uint(X[i]) | 127u) - (unsigned)(32 * kt + (i & 3) + 8 * (i >> 2)));
;             sort16_desc(grp);
;             if (kt == 0) {
; #pragma unroll
;                 for (int i = 0; i < 16; ++i) cur[i] = grp[i];
;             } else merge16_desc(cur, grp);
	v_max3_i32 v67, v144, v145, v135
	v_max3_i32 v68, v80, v136, v79
	v_max3_i32 v69, v137, v72, v73
	v_max3_i32 v32, v78, v32, v71
	v_max3_i32 v31, v124, v75, v31
	v_max3_i32 v18, v125, v18, v30
	v_max3_i32 v28, v81, v28, v29
	v_max3_i32 v25, v77, v25, v27
	v_max3_i32 v19, v74, v19, v20
	v_max_i32_e32 v20, v23, v68
	v_min_i32_e32 v23, v23, v68
	v_max_i32_e32 v27, v22, v69
	v_min_i32_e32 v22, v22, v69
	v_max_i32_e32 v29, v24, v32
	v_min_i32_e32 v24, v24, v32
	v_max_i32_e32 v30, v26, v31
	v_min_i32_e32 v26, v26, v31
	v_max_i32_e32 v31, v21, v18
	v_min_i32_e32 v18, v21, v18
	v_max_i32_e32 v21, v33, v28
	v_min_i32_e32 v28, v33, v28
	v_max_i32_e32 v32, v66, v25
	v_min_i32_e32 v25, v66, v25
	v_max_i32_e32 v33, v67, v19
	v_min_i32_e32 v19, v67, v19
	ds_read_b128 v[66:69], v94 offset:27648
	v_max_i32_e32 v70, v20, v31
	v_min_i32_e32 v74, v20, v31
	v_max_i32_e32 v20, v27, v21
	v_min_i32_e32 v75, v27, v21
	v_max_i32_e32 v21, v29, v32
	v_max_i32_e32 v27, v30, v33
	v_max_i32_e32 v127, v70, v21
	v_min_i32_e32 v128, v70, v21
	ds_read_b128 v[70:73], v94 offset:27680
	v_min_i32_e32 v76, v29, v32
	v_min_i32_e32 v77, v30, v33
	v_max_i32_e32 v78, v23, v18
	v_min_i32_e32 v79, v23, v18
	v_max_i32_e32 v80, v22, v28
	v_min_i32_e32 v81, v22, v28
	v_max_i32_e32 v82, v24, v25
	v_min_i32_e32 v124, v24, v25
	v_max_i32_e32 v125, v26, v19
	v_min_i32_e32 v126, v26, v19
	v_max_i32_e32 v129, v20, v27
	v_min_i32_e32 v130, v20, v27
	s_waitcnt lgkmcnt(1)
	v_mfma_f32_32x32x16_bf16 v[18:33], v[66:69], v[46:49], v[2:17]
	ds_read_b128 v[66:69], v94 offset:27712
	v_max_i32_e32 v131, v74, v76
	v_min_i32_e32 v74, v74, v76
	v_max_i32_e32 v76, v75, v77
	v_min_i32_e32 v75, v75, v77
	v_max_i32_e32 v77, v78, v82
	v_min_i32_e32 v78, v78, v82
	s_waitcnt lgkmcnt(1)
	v_mfma_f32_32x32x16_bf16 v[18:33], v[70:73], v[42:45], v[18:33]
	ds_read_b128 v[70:73], v94 offset:27744
	v_max_i32_e32 v82, v80, v125
	v_min_i32_e32 v80, v80, v125
	v_max_i32_e32 v125, v79, v124
	v_min_i32_e32 v79, v79, v124
	v_max_i32_e32 v124, v81, v126
	v_min_i32_e32 v81, v81, v126
	s_waitcnt lgkmcnt(1)
	v_mfma_f32_32x32x16_bf16 v[18:33], v[66:69], v[38:41], v[18:33]
	v_min_i32_e32 v126, v127, v129
	v_min_i32_e32 v66, v128, v130
	v_min_i32_e32 v67, v131, v76
	v_min_i32_e32 v69, v77, v82
	v_min_i32_e32 v132, v78, v80
	v_min_i32_e32 v133, v125, v124
	v_min_i32_e32 v68, v74, v75
	s_waitcnt lgkmcnt(0)
	v_mfma_f32_32x32x16_bf16 v[18:33], v[70:73], v[34:37], v[18:33]
	v_min_i32_e32 v134, v79, v81
	s_nop 10
	v_or_b32_e32 v21, 0x7f, v21
	v_or_b32_e32 v32, 0x7f, v32
	v_or_b32_e32 v22, 0x7f, v22
	v_or_b32_e32 v26, 0x7f, v26
	v_or_b32_e32 v18, 0x7f, v18
	v_or_b32_e32 v31, 0x7f, v31
	v_or_b32_e32 v23, 0x7f, v23
	v_or_b32_e32 v24, 0x7f, v24
	v_or_b32_e32 v27, 0x7f, v27
	v_or_b32_e32 v28, 0x7f, v28
	v_or_b32_e32 v20, 0x7f, v20
	v_or_b32_e32 v33, 0x7f, v33
	v_or_b32_e32 v25, 0x7f, v25
	v_or_b32_e32 v29, 0x7f, v29
	v_or_b32_e32 v19, 0x7f, v19
	v_or_b32_e32 v30, 0x7f, v30
	v_add_u32_e32 v21, 0xffffffbd, v21
	v_add_u32_e32 v32, 0xffffffa6, v32
	v_add_u32_e32 v22, 0xffffffb8, v22
	v_add_u32_e32 v26, 0xffffffb0, v26
	v_subrev_u32_e32 v18, 64, v18
	v_add_u32_e32 v31, 0xffffffa7, v31
	v_add_u32_e32 v23, 0xffffffb7, v23
	v_add_u32_e32 v24, 0xffffffb6, v24
	v_add_u32_e32 v27, 0xffffffaf, v27
	v_add_u32_e32 v28, 0xffffffae, v28
	v_add_u32_e32 v20, 0xffffffbe, v20
	v_add_u32_e32 v33, 0xffffffa5, v33
	v_add_u32_e32 v25, 0xffffffb5, v25
	v_add_u32_e32 v29, 0xffffffad, v29
	v_add_u32_e32 v19, 0xffffffbf, v19
	v_add_u32_e32 v30, 0xffffffa8, v30
	v_max_i32_e32 v70, v21, v32
	v_max_i32_e32 v71, v22, v26
	v_max_i32_e32 v73, v18, v31
	v_max_i32_e32 v135, v23, v24
	v_min_i32_e32 v138, v27, v28
	v_min_i32_e32 v139, v20, v33
	v_min_i32_e32 v141, v25, v29
	v_min_i32_e32 v142, v19, v30
	v_min_i32_e32 v23, v23, v24
	v_min_i32_e32 v18, v18, v31
	v_min_i32_e32 v22, v22, v26
	v_min_i32_e32 v21, v21, v32
	v_max_i32_e32 v19, v19, v30
	v_max_i32_e32 v25, v25, v29
	v_max_i32_e32 v20, v20, v33
	v_max_i32_e32 v27, v27, v28
	v_min_i32_e32 v72, v70, v71
	v_min_i32_e32 v136, v73, v135
	v_max_i32_e32 v140, v138, v139
	v_max_i32_e32 v143, v141, v142
	v_max_i32_e32 v24, v23, v18
	v_max_i32_e32 v26, v22, v21
	v_min_i32_e32 v29, v19, v25
	v_min_i32_e32 v28, v20, v27
	v_min_i32_e32 v141, v141, v142
	v_min_i32_e32 v18, v23, v18
	v_min_i32_e32 v21, v22, v21
	v_min_i32_e32 v22, v138, v139
	v_max_i32_e32 v73, v73, v135
	v_max_i32_e32 v19, v19, v25
	v_max_i32_e32 v20, v20, v27
	v_max_i32_e32 v27, v70, v71
	v_min_i32_e32 v137, v72, v136
	v_min_i32_e32 v144, v140, v143
	v_max_i32_e32 v31, v24, v26
	v_max_i32_e32 v30, v29, v28
	v_min_i32_e32 v24, v24, v26
	v_min_i32_e32 v26, v29, v28
	v_max_i32_e32 v29, v72, v136
	v_max_i32_e32 v72, v140, v143
	v_min_i32_e32 v23, v141, v18
	v_min_i32_e32 v138, v21, v22
	v_max_i32_e32 v18, v141, v18
	v_max_i32_e32 v21, v21, v22
	v_min_i32_e32 v25, v73, v19
	v_min_i32_e32 v70, v20, v27
	v_max_i32_e32 v19, v73, v19
	v_max_i32_e32 v20, v20, v27
	v_min_i32_e32 v32, v31, v30
	v_max_i32_e32 v28, v24, v26
	v_min_i32_e32 v136, v29, v72
	v_min_i32_e32 v24, v24, v26
	v_min_i32_e32 v26, v137, v144
	v_max_i32_e32 v139, v23, v138
	v_min_i32_e32 v22, v18, v21
	v_min_i32_e32 v71, v25, v70
	v_max_i32_e32 v25, v25, v70
	v_min_i32_e32 v27, v19, v20
	v_max_i32_e32 v29, v29, v72
	v_max_i32_e32 v30, v31, v30
	v_max_i32_e32 v145, v137, v144
	v_max_i32_e32 v137, v24, v26
	v_max_i32_e32 v141, v139, v22
	v_max_i32_e32 v18, v18, v21
	v_min_i32_e32 v70, v25, v27
	v_min_i32_e32 v31, v29, v30
	v_min_i32_e32 v33, v145, v32
	v_min_i32_e32 v140, v28, v136
	v_max_i32_e32 v142, v137, v141
	v_min_i32_e32 v21, v71, v18
	v_max_i32_e32 v18, v71, v18
	v_min_i32_e32 v71, v70, v31
; #define LAS __attribute__((address_space(3)))
; #define MFMA32(a, b, c) __builtin_amdgcn_mfma_f32_32x32x16_bf16((a), (b), (c), 0, 0, 0)
; #define CE_(a, b) ce_desc(v[a], v[b])
; __device__ __forceinline__ void sort16_desc(int (&v)[16]) {
;     ...
;     CE_(0,13); CE_(1,12); CE_(2,15); CE_(3,14); CE_(4,8); CE_(5,6); CE_(7,11); CE_(9,10);
;     CE_(0,5); CE_(1,7); CE_(2,9); CE_(3,4); CE_(6,13); CE_(8,14); CE_(10,15); CE_(11,12);
;     CE_(0,1); CE_(2,3); CE_(4,5); CE_(6,8); CE_(7,9); CE_(10,11); CE_(12,13); CE_(14,15);
;     CE_(0,2); CE_(1,3); CE_(4,10); CE_(5,11); CE_(6,7); CE_(8,9); CE_(12,14); CE_(13,15);
;     CE_(1,2); CE_(3,12); CE_(4,6); CE_(5,7); CE_(8,10); CE_(9,11); CE_(13,14);
;     CE_(1,4); CE_(2,6); CE_(5,8); CE_(7,10); CE_(9,13); CE_(11,14);
;     CE_(2,4); CE_(3,6); CE_(9,12); CE_(11,13);
;     CE_(3,5); CE_(6,8); CE_(7,9); CE_(10,12);
;     CE_(3,4); CE_(5,6); CE_(7,8); CE_(9,10); CE_(11,12);
;     CE_(6,7); CE_(8,9);
;     ...
; }
; __device__ __forceinline__ void merge16_desc(int (&a)[16], const int (&b)[16]) {
; #pragma unroll
;     for (int i = 0; i < 16; ++i) a[i] = a[i] > b[15 - i] ? a[i] : b[15 - i];
; #pragma unroll
;     for (int j = 8; j > 0; j >>= 1)
; #pragma unroll
;         for (int i = 0; i < 16; ++i) { const int l = i ^ j; if (l > i) ce_desc(a[i], a[l]); }
; }
; __device__ __forceinline__ void route_task(int task, int tl0, const bf16* QP  , const LAS bf16* KHL, LAS unsigned short* EL, LAS float* GL, int lane) {
;     ...
;         for (int kt = 0; kt < 4; ++kt) {
;             f32x16 X;
; #pragma unroll
;             for (int i = 0; i < 16; ++i) X[i] = 8.f;
;             const LAS bf16* khp = KHL + (half * 128 + 32 * kt + r) * 72 + 8 * hi;
; #pragma unroll
;             for (int ks = 0; ks < 4; ++ks) {
;                 const bf16x8 kh = lds8(khp + 16 * ks);
;                 X = MFMA32(kh, qa[half][ks], X);
;             }
;             int grp[16];
; #pragma unroll
;             for (int i = 0; i < 16; ++i) grp[i] = (int)((__float_as_uint(X[i]) | 127u) - (unsigned)(32 * kt + (i & 3) + 8 * (i >> 2)));
;             sort16_desc(grp);
;             if (kt == 0) {
; #pragma unroll
;                 for (int i = 0; i < 16; ++i) cur[i] = grp[i];
;             } else merge16_desc(cur, grp);
	v_max_i32_e32 v32, v145, v32
	v_max_i32_e32 v28, v28, v136
	v_max_i32_e32 v143, v33, v140
	v_max_i32_e32 v135, v142, v21
	v_min_i32_e32 v72, v18, v71
	v_min_i32_e32 v73, v32, v28
	v_min_i32_e32 v33, v33, v140
	v_min_i32_e32 v21, v142, v21
	v_max_i32_e32 v18, v18, v71
	v_max_i32_e32 v28, v32, v28
	v_min_i32_e32 v24, v24, v26
	v_min_i32_e32 v22, v139, v22
	v_max_i32_e32 v25, v25, v27
	v_max_i32_e32 v27, v29, v30
	v_max_i32_e32 v144, v143, v135
	v_min_i32_e32 v136, v72, v73
	v_min_i32_e32 v135, v143, v135
	v_max_i32_e32 v140, v33, v21
	v_min_i32_e32 v32, v18, v28
	v_max_i32_e32 v71, v72, v73
	v_max_i32_e32 v26, v24, v22
	v_min_i32_e32 v137, v137, v141
	v_max_i32_e32 v18, v18, v28
	v_max_i32_e32 v28, v70, v31
	v_min_i32_e32 v29, v25, v27
	v_min_i32_e32 v145, v144, v136
	v_max_i32_e32 v142, v135, v140
	v_min_i32_e32 v72, v32, v71
	v_max_i32_e32 v73, v144, v136
	v_max_i32_e32 v139, v26, v137
	v_min_i32_e32 v21, v33, v21
	v_min_i32_e32 v30, v28, v29
	v_min_i32_e32 v143, v145, v142
	v_min_i32_e32 v136, v72, v73
	v_min_i32_e32 v33, v139, v21
	v_max_i32_e32 v21, v139, v21
	v_min_i32_e32 v135, v135, v140
	v_max_i32_e32 v32, v32, v71
	v_min_i32_e32 v31, v18, v30
	v_max_i32_e32 v18, v18, v30
	v_min_i32_e32 v26, v26, v137
	v_min_i32_e32 v22, v24, v22
	v_max_i32_e32 v24, v25, v27
	v_min_i32_e32 v23, v23, v138
	v_max3_i32 v23, v127, v129, v23
	v_max_i32_e32 v22, v126, v22
	v_max3_i32 v25, v128, v130, v26
	v_max_i32_e32 v26, v66, v33
	v_max3_i32 v21, v131, v76, v21
	v_max_i32_e32 v27, v67, v135
	v_max3_i32 v30, v74, v75, v143
	v_max3_i32 v66, v77, v82, v136
	v_max3_i32 v67, v69, v72, v73
	v_max3_i32 v32, v78, v80, v32
	v_max_i32_e32 v31, v132, v31
	v_max3_i32 v18, v125, v124, v18
	v_max3_i32 v28, v133, v28, v29
	v_max3_i32 v24, v79, v81, v24
	v_max3_i32 v33, v68, v145, v142
	v_max3_i32 v19, v134, v19, v20
	v_max_i32_e32 v20, v23, v66
	v_min_i32_e32 v23, v23, v66
	v_max_i32_e32 v29, v22, v67
	v_max_i32_e32 v66, v25, v32
	v_min_i32_e32 v25, v25, v32
	v_max_i32_e32 v32, v26, v31
	v_min_i32_e32 v26, v26, v31
	v_max_i32_e32 v31, v21, v18
	v_min_i32_e32 v18, v21, v18
	v_max_i32_e32 v21, v27, v28
	v_min_i32_e32 v27, v27, v28
	v_max_i32_e32 v28, v30, v24
	v_min_i32_e32 v22, v22, v67
	v_min_i32_e32 v24, v30, v24
	v_max_i32_e32 v30, v33, v19
	v_min_i32_e32 v19, v33, v19
	v_max_i32_e32 v33, v20, v31
	v_min_i32_e32 v74, v20, v31
	v_max_i32_e32 v20, v29, v21
	v_min_i32_e32 v75, v29, v21
	v_max_i32_e32 v21, v66, v28
	v_min_i32_e32 v76, v66, v28
	ds_read_b128 v[66:69], v98
	ds_read_b128 v[70:73], v98 offset:32
	v_max_i32_e32 v28, v32, v30
	v_min_i32_e32 v77, v32, v30
	v_max_i32_e32 v78, v23, v18
	v_min_i32_e32 v79, v23, v18
	v_max_i32_e32 v80, v22, v27
	v_min_i32_e32 v81, v22, v27
	v_max_i32_e32 v82, v25, v24
	v_min_i32_e32 v124, v25, v24
	v_max_i32_e32 v125, v26, v19
	v_min_i32_e32 v126, v26, v19
	v_max_i32_e32 v127, v33, v21
	v_min_i32_e32 v128, v33, v21
	v_max_i32_e32 v129, v20, v28
	v_min_i32_e32 v130, v20, v28
	s_waitcnt lgkmcnt(1)
	v_mfma_f32_32x32x16_bf16 v[18:33], v[66:69], v[46:49], v[2:17]
	ds_read_b128 v[46:49], v98 offset:64
	v_max_i32_e32 v67, v75, v77
	v_min_i32_e32 v68, v75, v77
	v_max_i32_e32 v75, v80, v125
	v_max_i32_e32 v131, v74, v76
	v_min_i32_e32 v66, v74, v76
	v_max_i32_e32 v69, v78, v82
	s_waitcnt lgkmcnt(1)
	v_mfma_f32_32x32x16_bf16 v[18:33], v[70:73], v[42:45], v[18:33]
	ds_read_b128 v[42:45], v98 offset:96
	v_min_i32_e32 v70, v80, v125
	v_max_i32_e32 v71, v79, v124
	v_min_i32_e32 v72, v79, v124
	v_min_i32_e32 v74, v78, v82
	v_max_i32_e32 v73, v81, v126
	v_min_i32_e32 v76, v81, v126
	s_waitcnt lgkmcnt(1)
	v_mfma_f32_32x32x16_bf16 v[18:33], v[46:49], v[38:41], v[18:33]
	v_min_i32_e32 v77, v127, v129
	v_min_i32_e32 v38, v128, v130
	v_min_i32_e32 v39, v131, v67
	v_min_i32_e32 v40, v66, v68
	v_min_i32_e32 v41, v69, v75
	v_min_i32_e32 v46, v74, v70
	v_min_i32_e32 v47, v71, v73
	s_waitcnt lgkmcnt(0)
	v_mfma_f32_32x32x16_bf16 v[18:33], v[42:45], v[34:37], v[18:33]
	v_min_i32_e32 v48, v72, v76
	s_nop 10
	v_or_b32_e32 v25, 0x7f, v25
	v_or_b32_e32 v29, 0x7f, v29
	v_or_b32_e32 v19, 0x7f, v19
	v_or_b32_e32 v30, 0x7f, v30
	v_or_b32_e32 v23, 0x7f, v23
	v_or_b32_e32 v24, 0x7f, v24
	v_or_b32_e32 v18, 0x7f, v18
	v_or_b32_e32 v31, 0x7f, v31
	v_or_b32_e32 v22, 0x7f, v22
	v_or_b32_e32 v26, 0x7f, v26
	v_or_b32_e32 v21, 0x7f, v21
	v_or_b32_e32 v32, 0x7f, v32
	v_or_b32_e32 v27, 0x7f, v27
	v_or_b32_e32 v28, 0x7f, v28
	v_or_b32_e32 v20, 0x7f, v20
	v_or_b32_e32 v33, 0x7f, v33
	v_add_u32_e32 v25, 0xffffff95, v25
	v_add_u32_e32 v29, 0xffffff8d, v29
	v_add_u32_e32 v19, 0xffffff9f, v19
	v_add_u32_e32 v30, 0xffffff88, v30
	v_add_u32_e32 v23, 0xffffff97, v23
	v_add_u32_e32 v24, 0xffffff96, v24
	v_add_u32_e32 v18, 0xffffffa0, v18
	v_add_u32_e32 v31, 0xffffff87, v31
	v_add_u32_e32 v22, 0xffffff98, v22
	v_add_u32_e32 v26, 0xffffff90, v26
	v_add_u32_e32 v21, 0xffffff9d, v21
	v_add_u32_e32 v32, 0xffffff86, v32
	v_add_u32_e32 v27, 0xffffff8f, v27
	v_add_u32_e32 v28, 0xffffff8e, v28
	v_add_u32_e32 v20, 0xffffff9e, v20
	v_add_u32_e32 v33, 0xffffff85, v33
	v_min_i32_e32 v34, v25, v29
	v_min_i32_e32 v35, v19, v30
	v_min_i32_e32 v37, v23, v24
	v_min_i32_e32 v42, v18, v31
	v_min_i32_e32 v45, v22, v26
	v_min_i32_e32 v49, v21, v32
	v_min_i32_e32 v79, v27, v28
	v_min_i32_e32 v80, v20, v33
	v_max_i32_e32 v18, v18, v31
	v_max_i32_e32 v23, v23, v24
	v_max_i32_e32 v19, v19, v30
	v_max_i32_e32 v25, v25, v29
	v_max_i32_e32 v20, v20, v33
	v_max_i32_e32 v27, v27, v28
	v_max_i32_e32 v21, v21, v32
	v_max_i32_e32 v22, v22, v26
	v_max_i32_e32 v24, v18, v23
	v_max_i32_e32 v29, v19, v25
	v_max_i32_e32 v28, v20, v27
	v_max_i32_e32 v26, v21, v22
	v_min_i32_e32 v30, v24, v29
	v_min_i32_e32 v31, v28, v26
; #define CE_(a, b) ce_desc(v[a], v[b])
; __device__ __forceinline__ void sort16_desc(int (&v)[16]) {
;     ...
;     CE_(0,13); CE_(1,12); CE_(2,15); CE_(3,14); CE_(4,8); CE_(5,6); CE_(7,11); CE_(9,10);
;     CE_(0,5); CE_(1,7); CE_(2,9); CE_(3,4); CE_(6,13); CE_(8,14); CE_(10,15); CE_(11,12);
;     CE_(0,1); CE_(2,3); CE_(4,5); CE_(6,8); CE_(7,9); CE_(10,11); CE_(12,13); CE_(14,15);
;     CE_(0,2); CE_(1,3); CE_(4,10); CE_(5,11); CE_(6,7); CE_(8,9); CE_(12,14); CE_(13,15);
;     CE_(1,2); CE_(3,12); CE_(4,6); CE_(5,7); CE_(8,10); CE_(9,11); CE_(13,14);
;     CE_(1,4); CE_(2,6); CE_(5,8); CE_(7,10); CE_(9,13); CE_(11,14);
;     CE_(2,4); CE_(3,6); CE_(9,12); CE_(11,13);
;     CE_(3,5); CE_(6,8); CE_(7,9); CE_(10,12);
;     CE_(3,4); CE_(5,6); CE_(7,8); CE_(9,10); CE_(11,12);
;     CE_(6,7); CE_(8,9);
;     ...
; }
; __device__ __forceinline__ void merge16_desc(int (&a)[16], const int (&b)[16]) {
; #pragma unroll
;     for (int i = 0; i < 16; ++i) a[i] = a[i] > b[15 - i] ? a[i] : b[15 - i];
; #pragma unroll
;     for (int j = 8; j > 0; j >>= 1)
; #pragma unroll
;         for (int i = 0; i < 16; ++i) { const int l = i ^ j; if (l > i) ce_desc(a[i], a[l]); }
; }
; __device__ __forceinline__ void route_task(int task, int tl0, const bf16* QP  , const LAS bf16* KHL, LAS unsigned short* EL, LAS float* GL, int lane) {
;     ...
;         { const unsigned h4 = 4u * (unsigned)hi;
; #pragma unroll
;           for (int i = 0; i < 16; ++i) cur[i] -= (int)h4; }
;         int oth[16];
; #pragma unroll
;         for (int i = 0; i < 16; ++i) oth[i] = __shfl_xor(cur[i], 32);
;         merge16_desc(cur, oth);
	v_min_i32_e32 v43, v37, v42
	v_min_i32_e32 v32, v30, v31
	v_max_i32_e32 v30, v30, v31
	v_min_i32_e32 v21, v21, v22
	v_min_i32_e32 v18, v18, v23
	v_max_i32_e32 v23, v79, v80
	v_max_i32_e32 v31, v34, v35
	v_max_i32_e32 v37, v37, v42
	v_max_i32_e32 v42, v45, v49
	v_min_i32_e32 v19, v19, v25
	v_min_i32_e32 v20, v20, v27
	v_min_i32_e32 v36, v34, v35
	v_min_i32_e32 v78, v45, v49
	v_min_i32_e32 v81, v79, v80
	v_max_i32_e32 v22, v21, v18
	v_max_i32_e32 v45, v37, v42
	v_max_i32_e32 v25, v19, v20
	v_min_i32_e32 v18, v21, v18
	v_min_i32_e32 v21, v23, v31
	v_min_i32_e32 v44, v36, v43
	v_min_i32_e32 v82, v78, v81
	v_max_i32_e32 v33, v36, v43
	v_max_i32_e32 v36, v78, v81
	v_max_i32_e32 v24, v24, v29
	v_max_i32_e32 v26, v28, v26
	v_max_i32_e32 v34, v23, v31
	v_max_i32_e32 v27, v45, v25
	v_max_i32_e32 v23, v18, v21
	v_min_i32_e32 v25, v45, v25
	v_min_i32_e32 v37, v37, v42
	v_min_i32_e32 v19, v19, v20
	v_max_i32_e32 v43, v33, v36
	v_min_i32_e32 v28, v24, v26
	v_max_i32_e32 v35, v22, v34
	v_max_i32_e32 v31, v23, v25
	v_max_i32_e32 v20, v37, v19
	v_min_i32_e32 v23, v23, v25
	v_min_i32_e32 v19, v37, v19
	v_min_i32_e32 v18, v18, v21
	v_max_i32_e32 v25, v44, v82
	v_min_i32_e32 v33, v33, v36
	v_min_i32_e32 v29, v30, v28
	v_min_i32_e32 v49, v35, v27
	v_min_i32_e32 v22, v22, v34
	v_max_i32_e32 v21, v19, v18
	v_max_i32_e32 v36, v25, v33
	v_max_i32_e32 v78, v32, v43
	v_min_i32_e32 v79, v29, v49
	v_max_i32_e32 v34, v20, v22
	v_min_i32_e32 v20, v20, v22
	v_max_i32_e32 v37, v21, v36
	v_min_i32_e32 v32, v32, v43
	v_max_i32_e32 v80, v78, v79
	v_max_i32_e32 v42, v31, v34
	v_min_i32_e32 v78, v78, v79
	v_min_i32_e32 v31, v31, v34
	v_max_i32_e32 v22, v23, v20
	v_max_i32_e32 v43, v37, v32
	v_min_i32_e32 v18, v19, v18
	v_min_i32_e32 v19, v25, v33
	v_min_i32_e32 v20, v23, v20
	v_min_i32_e32 v23, v37, v32
	v_max_i32_e32 v28, v30, v28
	v_max_i32_e32 v27, v35, v27
	v_min_i32_e32 v124, v44, v82
	v_min_i32_e32 v45, v80, v42
	v_max_i32_e32 v34, v78, v31
	v_max_i32_e32 v44, v22, v43
	v_min_i32_e32 v31, v78, v31
	v_max_i32_e32 v25, v18, v19
	v_min_i32_e32 v21, v21, v36
	v_min_i32_e32 v32, v20, v23
	v_max_i32_e32 v29, v29, v49
	v_min_i32_e32 v30, v28, v27
	v_min_i32_e32 v22, v22, v43
	v_max_i32_e32 v20, v20, v23
	v_min_i32_e32 v79, v45, v34
	v_max_i32_e32 v78, v44, v31
	v_max_i32_e32 v33, v25, v21
	v_max_i32_e32 v37, v80, v42
	v_min_i32_e32 v35, v29, v30
	v_min_i32_e32 v31, v44, v31
	v_max_i32_e32 v23, v22, v20
	v_min_i32_e32 v81, v79, v78
	v_max_i32_e32 v36, v33, v32
	v_max_i32_e32 v42, v37, v35
	v_min_i32_e32 v21, v25, v21
	v_max_i32_e32 v25, v45, v34
	v_min_i32_e32 v43, v31, v23
	v_max_i32_e32 v27, v28, v27
	v_min_i32_e32 v18, v18, v19
	v_min_i32_e32 v20, v22, v20
	v_min_i32_e32 v32, v33, v32
	v_min_i32_e32 v33, v37, v35
	v_max3_i32 v124, v127, v129, v124
	v_max3_i32 v69, v69, v75, v81
	v_max3_i32 v36, v131, v67, v36
	v_max3_i32 v42, v71, v73, v42
	v_max3_i32 v21, v128, v130, v21
	v_max3_i32 v25, v74, v70, v25
	v_max3_i32 v43, v66, v68, v43
	v_max3_i32 v27, v72, v76, v27
	v_max_i32_e32 v18, v77, v18
	v_max3_i32 v19, v41, v79, v78
	v_max_i32_e32 v20, v39, v20
	v_max3_i32 v22, v47, v29, v30
	v_max_i32_e32 v32, v38, v32
	v_max_i32_e32 v33, v46, v33
	v_max3_i32 v23, v40, v31, v23
	v_max3_i32 v24, v48, v24, v26
	v_min_i32_e32 v49, v36, v42
	v_min_i32_e32 v34, v21, v25
	v_min_i32_e32 v41, v18, v19
	v_min_i32_e32 v29, v20, v22
	v_min_i32_e32 v26, v23, v24
	v_max_i32_e32 v39, v124, v69
	v_max_i32_e32 v36, v36, v42
	v_max_i32_e32 v21, v21, v25
	v_max_i32_e32 v25, v43, v27
	v_max_i32_e32 v18, v18, v19
	v_max_i32_e32 v19, v20, v22
	v_max_i32_e32 v22, v32, v33
	v_max_i32_e32 v23, v23, v24
	v_min_i32_e32 v28, v43, v27
	v_max_i32_e32 v40, v39, v36
	v_max_i32_e32 v27, v21, v25
	v_max_i32_e32 v20, v18, v19
	v_max_i32_e32 v24, v22, v23
	v_min_i32_e32 v35, v32, v33
	v_max_i32_e32 v42, v40, v27
	v_max_i32_e32 v32, v20, v24
	v_min_i32_e32 v27, v40, v27
	v_min_i32_e32 v20, v20, v24
	v_max_i32_e32 v24, v27, v20
	v_min_i32_e32 v20, v27, v20
	v_min_i32_e32 v27, v39, v36
	v_min_i32_e32 v21, v21, v25
	v_min_i32_e32 v18, v18, v19
	v_min_i32_e32 v19, v22, v23
	v_min_i32_e32 v75, v124, v69
	v_max_i32_e32 v25, v27, v21
	v_max_i32_e32 v22, v18, v19
	v_min_i32_e32 v21, v27, v21
	v_min_i32_e32 v18, v18, v19
	v_min_i32_e32 v44, v34, v28
	v_min_i32_e32 v31, v35, v26
	v_max_i32_e32 v23, v25, v22
	v_min_i32_e32 v22, v25, v22
	v_max_i32_e32 v19, v21, v18
	v_min_i32_e32 v18, v21, v18
	v_max_i32_e32 v21, v75, v49
	v_max_i32_e32 v25, v34, v28
	v_max_i32_e32 v28, v41, v29
	v_max_i32_e32 v26, v35, v26
	v_min_i32_e32 v67, v75, v49
	v_min_i32_e32 v30, v41, v29
	v_max_i32_e32 v27, v21, v25
	v_min_i32_e32 v21, v21, v25
	v_min_i32_e32 v25, v28, v26
	v_min_i32_e32 v45, v67, v44
	v_min_i32_e32 v37, v30, v31
	v_max_i32_e32 v29, v28, v26
	v_max_i32_e32 v26, v21, v25
	v_min_i32_e32 v21, v21, v25
	v_max_i32_e32 v25, v67, v44
	v_max_i32_e32 v28, v30, v31
	v_min_i32_e32 v38, v45, v37
	v_max_i32_e32 v33, v42, v32
	v_min_i32_e32 v32, v42, v32
	v_max_i32_e32 v34, v27, v29
	v_min_i32_e32 v27, v27, v29
	v_max_i32_e32 v29, v25, v28
	v_min_i32_e32 v25, v25, v28
	v_max_i32_e32 v28, v45, v37
	v_sub_u32_e32 v30, v33, v87
	v_sub_u32_e32 v31, v32, v87
	v_sub_u32_e32 v24, v24, v87
	v_sub_u32_e32 v20, v20, v87
	v_sub_u32_e32 v23, v23, v87
	v_sub_u32_e32 v22, v22, v87
	v_sub_u32_e32 v19, v19, v87
	v_sub_u32_e32 v18, v18, v87
	v_sub_u32_e32 v32, v34, v87
	v_sub_u32_e32 v27, v27, v87
	v_sub_u32_e32 v26, v26, v87
	v_sub_u32_e32 v21, v21, v87
	v_sub_u32_e32 v29, v29, v87
	v_sub_u32_e32 v25, v25, v87
	v_sub_u32_e32 v28, v28, v87
	v_sub_u32_e32 v33, v38, v87
	ds_bpermute_b32 v34, v123, v30
	ds_bpermute_b32 v35, v123, v31
	ds_bpermute_b32 v36, v123, v24
	ds_bpermute_b32 v37, v123, v20
	ds_bpermute_b32 v38, v123, v23
	ds_bpermute_b32 v39, v123, v22
	ds_bpermute_b32 v40, v123, v19
	ds_bpermute_b32 v41, v123, v18
	ds_bpermute_b32 v42, v123, v32
	ds_bpermute_b32 v43, v123, v27
	ds_bpermute_b32 v44, v123, v26
	ds_bpermute_b32 v45, v123, v33
	ds_bpermute_b32 v46, v123, v28
	ds_bpermute_b32 v47, v123, v25
	ds_bpermute_b32 v48, v123, v29
	ds_bpermute_b32 v49, v123, v21
	s_waitcnt lgkmcnt(4)
; __device__ __forceinline__ void route_task(int task, int tl0, const bf16* QP  , const LAS bf16* KHL, LAS unsigned short* EL, LAS float* GL, int lane) {
;     ...
;         merge16_desc(cur, oth);
; #pragma unroll
;         for (int i = 0; i < 16; ++i) top[half][i] = cur[i];
;     }
;     unsigned P1[4], P2[4];
; #pragma unroll
;     for (int q = 0; q < 4; ++q) { P1[q] = 0u; P2[q] = 0u;
; #pragma unroll
;         for (int s = 0; s < 4; ++s) { P1[q] |= (127u - ((unsigned)top[0][4 * q + s] & 127u)) << (8 * s); P2[q] |= (127u - ((unsigned)top[1][4 * q + s] & 127u)) << (8 * s); } }
;     int bk[16];
;     {
;         int hi2 = hi; asm volatile("" : "+v"(hi2));
;         const bool h1 = hi2 != 0;
;         constexpr int A1[16] = {1, 1, 1, 1, 1, 1, 1, 1, 2, 2, 2, 2, 2, 3, 3, 3}, B1[16] = {0, 1, 2, 3, 4, 5, 6, 7, 0, 1, 2, 3, 4, 0, 1, 2};
; #pragma unroll
;         for (int i = 0; i < 16; ++i) { const float ta = __int_as_float(h1 ? top[0][A1[i]] : top[0][0]), tb = __int_as_float(h1 ? top[1][B1[i]] : top[1][i]); const unsigned code = h1 ? (unsigned)(A1[i] * 16 + B1[i]) : (unsigned)i;
;             bk[i] = (int)((__float_as_uint(ta + tb) | 255u) - code); }
	v_max_i32_e32 v30, v30, v45
	s_waitcnt lgkmcnt(3)
	v_max_i32_e32 v31, v31, v46
	s_waitcnt lgkmcnt(2)
	v_max_i32_e32 v24, v24, v47
	s_waitcnt lgkmcnt(1)
	v_max_i32_e32 v20, v20, v48
	s_waitcnt lgkmcnt(0)
	v_max_i32_e32 v23, v23, v49
	v_max_i32_e32 v22, v22, v44
	v_max_i32_e32 v19, v19, v43
	v_max_i32_e32 v18, v18, v42
	v_max_i32_e32 v32, v32, v41
	v_max_i32_e32 v27, v27, v40
	v_max_i32_e32 v26, v26, v39
	v_max_i32_e32 v21, v21, v38
	v_max_i32_e32 v29, v29, v37
	v_max_i32_e32 v25, v25, v36
	v_max_i32_e32 v28, v28, v35
	v_max_i32_e32 v33, v33, v34
	v_max_i32_e32 v34, v30, v32
	v_min_i32_e32 v30, v30, v32
	v_max_i32_e32 v32, v31, v27
	v_min_i32_e32 v27, v31, v27
	v_max_i32_e32 v31, v24, v26
	v_min_i32_e32 v24, v24, v26
	v_max_i32_e32 v26, v20, v21
	v_min_i32_e32 v20, v20, v21
	v_max_i32_e32 v21, v23, v29
	v_min_i32_e32 v23, v23, v29
	v_max_i32_e32 v29, v22, v25
	v_min_i32_e32 v22, v22, v25
	v_max_i32_e32 v25, v19, v28
	v_min_i32_e32 v19, v19, v28
	v_max_i32_e32 v28, v18, v33
	v_min_i32_e32 v18, v18, v33
	v_max_i32_e32 v33, v34, v21
	v_min_i32_e32 v21, v34, v21
	v_max_i32_e32 v34, v32, v29
	v_min_i32_e32 v29, v32, v29
	v_max_i32_e32 v32, v31, v25
	v_min_i32_e32 v25, v31, v25
	v_max_i32_e32 v31, v26, v28
	v_min_i32_e32 v26, v26, v28
	v_max_i32_e32 v28, v30, v23
	v_min_i32_e32 v23, v30, v23
	v_max_i32_e32 v30, v27, v22
	v_min_i32_e32 v22, v27, v22
	v_max_i32_e32 v27, v24, v19
	v_min_i32_e32 v19, v24, v19
	v_max_i32_e32 v24, v20, v18
	v_min_i32_e32 v18, v20, v18
	v_max_i32_e32 v20, v33, v32
	v_min_i32_e32 v32, v33, v32
	v_max_i32_e32 v33, v34, v31
	v_min_i32_e32 v31, v34, v31
	v_max_i32_e32 v34, v21, v25
	v_min_i32_e32 v21, v21, v25
	v_max_i32_e32 v25, v29, v26
	v_min_i32_e32 v29, v29, v26
	v_max_i32_e32 v35, v28, v27
	v_min_i32_e32 v27, v28, v27
	v_max_i32_e32 v28, v30, v24
	v_min_i32_e32 v24, v30, v24
	v_max_i32_e32 v30, v23, v19
	v_min_i32_e32 v19, v23, v19
	v_max_i32_e32 v23, v22, v18
	v_min_i32_e32 v18, v22, v18
	v_max_i32_e32 v26, v20, v33
	v_min_i32_e32 v33, v20, v33
	v_lshlrev_b32_e32 v20, 8, v65
	v_lshlrev_b32_e32 v22, 16, v64
	v_max_i32_e32 v36, v32, v31
	v_max_i32_e32 v40, v19, v18
	v_min_i32_e32 v41, v19, v18
	v_and_b32_e32 v18, 0x7f, v63
	v_and_b32_e32 v20, 0x7f00, v20
	v_and_b32_e32 v22, 0x7f0000, v22
	v_max_i32_e32 v37, v21, v29
	v_min_i32_e32 v29, v21, v29
	v_lshlrev_b32_e32 v21, 8, v33
	v_or3_b32 v18, v20, v18, v22
	v_lshlrev_b32_e32 v20, 16, v36
	v_and_b32_e32 v19, 0x7f, v26
	v_and_b32_e32 v21, 0x7f00, v21
	v_and_b32_e32 v20, 0x7f0000, v20
	v_or3_b32 v20, v21, v19, v20
	v_lshlrev_b32_e32 v19, 24, v62
	v_min_i32_e32 v31, v32, v31
	v_and_b32_e32 v19, 0x7f000000, v19
	v_bitop3_b32 v19, v18, s68, v19 bitop3:0x36
	v_lshlrev_b32_e32 v18, 24, v31
	v_max_i32_e32 v38, v35, v28
	v_min_i32_e32 v28, v35, v28
	v_max_i32_e32 v35, v27, v24
	v_min_i32_e32 v27, v27, v24
	v_and_b32_e32 v18, 0x7f000000, v18
	v_lshlrev_b32_e32 v22, 8, v60
	v_lshlrev_b32_e32 v24, 16, v59
	v_max_i32_e32 v32, v34, v25
	v_min_i32_e32 v34, v34, v25
	v_bitop3_b32 v18, v20, s68, v18 bitop3:0x36
	v_and_b32_e32 v20, 0x7f, v61
	v_and_b32_e32 v22, 0x7f00, v22
	v_and_b32_e32 v24, 0x7f0000, v24
	v_max_i32_e32 v39, v30, v23
	v_min_i32_e32 v30, v30, v23
	v_lshlrev_b32_e32 v23, 8, v34
	v_or3_b32 v20, v22, v20, v24
	v_lshlrev_b32_e32 v22, 16, v37
	v_and_b32_e32 v21, 0x7f, v32
	v_and_b32_e32 v23, 0x7f00, v23
	v_and_b32_e32 v22, 0x7f0000, v22
	v_or3_b32 v22, v23, v21, v22
	v_lshlrev_b32_e32 v21, 24, v57
	v_and_b32_e32 v21, 0x7f000000, v21
	v_bitop3_b32 v21, v20, s68, v21 bitop3:0x36
	v_lshlrev_b32_e32 v20, 24, v29
	v_and_b32_e32 v20, 0x7f000000, v20
	v_lshlrev_b32_e32 v24, 8, v58
	v_lshlrev_b32_e32 v42, 16, v56
	v_bitop3_b32 v20, v22, s68, v20 bitop3:0x36
	v_and_b32_e32 v22, 0x7f, v55
	v_and_b32_e32 v24, 0x7f00, v24
	v_and_b32_e32 v42, 0x7f0000, v42
	v_lshlrev_b32_e32 v25, 8, v28
	v_or3_b32 v22, v24, v22, v42
	v_lshlrev_b32_e32 v24, 16, v35
	v_and_b32_e32 v23, 0x7f, v38
	v_and_b32_e32 v25, 0x7f00, v25
	v_and_b32_e32 v24, 0x7f0000, v24
	v_or3_b32 v24, v25, v23, v24
	v_lshlrev_b32_e32 v23, 24, v54
	v_and_b32_e32 v23, 0x7f000000, v23
	v_bitop3_b32 v23, v22, s68, v23 bitop3:0x36
	v_lshlrev_b32_e32 v22, 24, v27
	v_and_b32_e32 v22, 0x7f000000, v22
	v_lshlrev_b32_e32 v42, 8, v52
	v_lshlrev_b32_e32 v44, 16, v51
	v_bitop3_b32 v22, v24, s68, v22 bitop3:0x36
	v_and_b32_e32 v24, 0x7f, v53
	v_and_b32_e32 v42, 0x7f00, v42
	v_and_b32_e32 v44, 0x7f0000, v44
	v_lshlrev_b32_e32 v43, 8, v30
	v_or3_b32 v24, v42, v24, v44
	v_lshlrev_b32_e32 v42, 16, v40
	v_and_b32_e32 v25, 0x7f, v39
	v_and_b32_e32 v43, 0x7f00, v43
	v_and_b32_e32 v42, 0x7f0000, v42
	v_or3_b32 v42, v43, v25, v42
	v_lshlrev_b32_e32 v25, 24, v50
	v_and_b32_e32 v25, 0x7f000000, v25
	v_bitop3_b32 v25, v24, s68, v25 bitop3:0x36
	v_lshlrev_b32_e32 v24, 24, v41
	v_and_b32_e32 v24, 0x7f000000, v24
	v_bitop3_b32 v24, v42, s68, v24 bitop3:0x36
	v_mov_b32_e32 v42, v86
	v_add_f32_e32 v55, v55, v26
	v_cmp_eq_u32_e32 vcc, 0, v42
	v_add_f32_e32 v56, v56, v26
	v_add_f32_e32 v54, v54, v26
	v_cndmask_b32_e32 v42, v65, v63, vcc
	v_add_f32_e32 v44, v42, v26
	v_cndmask_b32_e64 v43, -16, 0, vcc
	v_or_b32_e32 v44, 0xff, v44
	v_add_f32_e32 v45, v42, v33
	v_add_u32_e32 v43, v44, v43
	v_cndmask_b32_e64 v44, v99, -1, vcc
	v_or_b32_e32 v45, 0xff, v45
	v_add_f32_e32 v46, v42, v36
	v_add_u32_e32 v44, v45, v44
	v_cndmask_b32_e64 v45, v100, -2, vcc
	v_or_b32_e32 v46, 0xff, v46
	v_add_f32_e32 v47, v42, v31
	v_add_u32_e32 v45, v46, v45
	v_cndmask_b32_e64 v46, v101, -3, vcc
	v_or_b32_e32 v47, 0xff, v47
	v_add_f32_e32 v48, v42, v32
	v_add_u32_e32 v46, v47, v46
	v_cndmask_b32_e64 v47, v102, -4, vcc
	v_or_b32_e32 v48, 0xff, v48
	v_add_f32_e32 v34, v42, v34
	v_add_f32_e32 v37, v42, v37
; #define CE_(a, b) ce_desc(v[a], v[b])
; __device__ __forceinline__ void sort16_desc(int (&v)[16]) {
;     ...
;     CE_(0,13); CE_(1,12); CE_(2,15); CE_(3,14); CE_(4,8); CE_(5,6); CE_(7,11); CE_(9,10);
;     CE_(0,5); CE_(1,7); CE_(2,9); CE_(3,4); CE_(6,13); CE_(8,14); CE_(10,15); CE_(11,12);
;     CE_(0,1); CE_(2,3); CE_(4,5); CE_(6,8); CE_(7,9); CE_(10,11); CE_(12,13); CE_(14,15);
;     CE_(0,2); CE_(1,3); CE_(4,10); CE_(5,11); CE_(6,7); CE_(8,9); CE_(12,14); CE_(13,15);
;     CE_(1,2); CE_(3,12); CE_(4,6); CE_(5,7); CE_(8,10); CE_(9,11); CE_(13,14);
;     CE_(1,4); CE_(2,6); CE_(5,8); CE_(7,10); CE_(9,13); CE_(11,14);
;     CE_(2,4); CE_(3,6); CE_(9,12); CE_(11,13);
;     CE_(3,5); CE_(6,8); CE_(7,9); CE_(10,12);
;     CE_(3,4); CE_(5,6); CE_(7,8); CE_(9,10); CE_(11,12);
;     CE_(6,7); CE_(8,9);
;     ...
; }
; __device__ __forceinline__ void route_task(int task, int tl0, const bf16* QP  , const LAS bf16* KHL, LAS unsigned short* EL, LAS float* GL, int lane) {
;     ...
;         for (int i = 0; i < 16; ++i) { const float ta = __int_as_float(h1 ? top[0][A1[i]] : top[0][0]), tb = __int_as_float(h1 ? top[1][B1[i]] : top[1][i]); const unsigned code = h1 ? (unsigned)(A1[i] * 16 + B1[i]) : (unsigned)i;
;             bk[i] = (int)((__float_as_uint(ta + tb) | 255u) - code); }
;         sort16_desc(bk);
;         int oth[16];
; #pragma unroll
;         for (int i = 0; i < 16; ++i) oth[i] = __shfl_xor(bk[i], 32);
;         merge16_desc(bk, oth);
	v_add_f32_e32 v29, v42, v29
	v_cndmask_b32_e32 v42, v64, v63, vcc
	v_cndmask_b32_e32 v32, v32, v39, vcc
	v_add_u32_e32 v47, v48, v47
	v_cndmask_b32_e64 v48, v103, -5, vcc
	v_or_b32_e32 v34, 0xff, v34
	v_add_f32_e32 v32, v42, v32
	v_add_u32_e32 v34, v34, v48
	v_cndmask_b32_e64 v48, v104, -6, vcc
	v_or_b32_e32 v37, 0xff, v37
	v_cndmask_b32_e32 v38, v26, v38, vcc
	v_cndmask_b32_e64 v39, v116, -12, vcc
	v_or_b32_e32 v32, 0xff, v32
	v_add_u32_e32 v37, v37, v48
	v_cndmask_b32_e64 v48, v105, -7, vcc
	v_or_b32_e32 v29, 0xff, v29
	v_add_f32_e32 v38, v42, v38
	v_cndmask_b32_e32 v28, v33, v28, vcc
	v_add_u32_e32 v32, v32, v39
	v_cndmask_b32_e32 v39, v62, v63, vcc
	v_cndmask_b32_e32 v30, v26, v30, vcc
	v_add_u32_e32 v29, v29, v48
	v_cndmask_b32_e64 v48, v106, -8, vcc
	v_or_b32_e32 v38, 0xff, v38
	v_add_f32_e32 v28, v42, v28
	v_cndmask_b32_e32 v35, v36, v35, vcc
	v_cndmask_b32_e32 v27, v31, v27, vcc
	v_add_f32_e32 v30, v39, v30
	v_cndmask_b32_e32 v40, v33, v40, vcc
	v_add_u32_e32 v38, v38, v48
	v_cndmask_b32_e64 v48, v107, -9, vcc
	v_or_b32_e32 v28, 0xff, v28
	v_add_f32_e32 v35, v42, v35
	v_add_f32_e32 v27, v42, v27
	v_cndmask_b32_e64 v42, v117, -13, vcc
	v_or_b32_e32 v30, 0xff, v30
	v_add_f32_e32 v40, v39, v40
	v_cndmask_b32_e32 v41, v36, v41, vcc
	v_add_u32_e32 v28, v28, v48
	v_cndmask_b32_e64 v48, v114, -10, vcc
	v_or_b32_e32 v35, 0xff, v35
	v_add_u32_e32 v30, v30, v42
	v_cndmask_b32_e64 v42, v118, -14, vcc
	v_or_b32_e32 v40, 0xff, v40
	v_add_f32_e32 v39, v39, v41
	v_add_u32_e32 v35, v35, v48
	v_cndmask_b32_e64 v48, v115, -11, vcc
	v_or_b32_e32 v27, 0xff, v27
	v_add_u32_e32 v40, v40, v42
	v_cndmask_b32_e64 v42, v119, -15, vcc
	v_or_b32_e32 v39, 0xff, v39
	v_add_u32_e32 v27, v27, v48
	v_add_u32_e32 v39, v39, v42
	v_max_i32_e32 v41, v43, v30
	v_min_i32_e32 v30, v43, v30
	v_max_i32_e32 v42, v44, v32
	v_min_i32_e32 v32, v44, v32
	v_max_i32_e32 v43, v45, v39
	v_min_i32_e32 v39, v45, v39
	v_max_i32_e32 v44, v46, v40
	v_min_i32_e32 v40, v46, v40
	v_max_i32_e32 v45, v47, v38
	v_min_i32_e32 v38, v47, v38
	v_max_i32_e32 v46, v34, v37
	v_min_i32_e32 v34, v34, v37
	v_max_i32_e32 v37, v29, v27
	v_min_i32_e32 v27, v29, v27
	v_max_i32_e32 v29, v28, v35
	v_min_i32_e32 v28, v28, v35
	v_max_i32_e32 v35, v41, v46
	v_min_i32_e32 v41, v41, v46
	v_max_i32_e32 v46, v42, v37
	v_min_i32_e32 v37, v42, v37
	v_max_i32_e32 v42, v43, v29
	v_min_i32_e32 v29, v43, v29
	v_max_i32_e32 v43, v44, v45
	v_min_i32_e32 v44, v44, v45
	v_max_i32_e32 v45, v34, v30
	v_min_i32_e32 v30, v34, v30
	v_max_i32_e32 v34, v38, v40
	v_min_i32_e32 v38, v38, v40
	v_max_i32_e32 v40, v28, v39
	v_min_i32_e32 v28, v28, v39
	v_max_i32_e32 v39, v27, v32
	v_min_i32_e32 v27, v27, v32
	v_max_i32_e32 v32, v35, v46
	v_min_i32_e32 v35, v35, v46
	v_max_i32_e32 v46, v42, v43
	v_min_i32_e32 v42, v42, v43
	v_max_i32_e32 v43, v44, v41
	v_min_i32_e32 v41, v44, v41
	v_max_i32_e32 v44, v45, v34
	v_min_i32_e32 v34, v45, v34
	v_max_i32_e32 v45, v37, v29
	v_min_i32_e32 v29, v37, v29
	v_max_i32_e32 v37, v40, v39
	v_min_i32_e32 v39, v40, v39
	v_max_i32_e32 v40, v27, v30
	v_min_i32_e32 v27, v27, v30
	v_max_i32_e32 v30, v38, v28
	v_min_i32_e32 v28, v38, v28
	v_max_i32_e32 v38, v32, v46
	v_min_i32_e32 v32, v32, v46
	v_max_i32_e32 v46, v35, v42
	v_min_i32_e32 v35, v35, v42
	v_max_i32_e32 v42, v43, v37
	v_min_i32_e32 v37, v43, v37
	v_max_i32_e32 v43, v41, v39
	v_min_i32_e32 v39, v41, v39
	v_max_i32_e32 v41, v44, v45
	v_min_i32_e32 v44, v44, v45
	v_max_i32_e32 v45, v34, v29
	v_min_i32_e32 v29, v34, v29
	v_max_i32_e32 v34, v40, v30
	v_min_i32_e32 v30, v40, v30
	v_max_i32_e32 v40, v27, v28
	v_min_i32_e32 v27, v27, v28
	v_max_i32_e32 v28, v46, v32
	v_min_i32_e32 v32, v46, v32
	v_max_i32_e32 v46, v35, v34
	v_min_i32_e32 v34, v35, v34
	v_max_i32_e32 v35, v42, v41
	v_min_i32_e32 v41, v42, v41
	v_max_i32_e32 v42, v43, v44
	v_min_i32_e32 v43, v43, v44
	v_max_i32_e32 v44, v45, v37
	v_min_i32_e32 v37, v45, v37
	v_max_i32_e32 v45, v29, v39
	v_min_i32_e32 v29, v29, v39
	v_max_i32_e32 v39, v40, v30
	v_min_i32_e32 v30, v40, v30
	v_max_i32_e32 v40, v28, v35
	v_min_i32_e32 v28, v28, v35
	v_max_i32_e32 v35, v32, v41
	v_min_i32_e32 v32, v32, v41
	v_max_i32_e32 v41, v42, v44
	v_min_i32_e32 v42, v42, v44
	v_max_i32_e32 v44, v43, v37
	v_min_i32_e32 v37, v43, v37
	v_max_i32_e32 v43, v45, v39
	v_min_i32_e32 v39, v45, v39
	v_max_i32_e32 v45, v29, v30
	v_min_i32_e32 v29, v29, v30
	v_max_i32_e32 v30, v35, v28
	v_min_i32_e32 v28, v35, v28
	v_max_i32_e32 v35, v46, v32
	v_min_i32_e32 v32, v46, v32
	v_max_i32_e32 v46, v43, v34
	v_min_i32_e32 v34, v43, v34
	v_max_i32_e32 v43, v45, v39
	v_min_i32_e32 v39, v45, v39
	v_max_i32_e32 v45, v35, v41
	v_min_i32_e32 v35, v35, v41
	v_max_i32_e32 v41, v32, v42
	v_min_i32_e32 v32, v32, v42
	v_max_i32_e32 v42, v44, v46
	v_min_i32_e32 v44, v44, v46
	v_max_i32_e32 v46, v37, v34
	v_min_i32_e32 v34, v37, v34
	v_max_i32_e32 v37, v45, v28
	v_min_i32_e32 v28, v45, v28
	v_max_i32_e32 v45, v35, v41
	v_min_i32_e32 v35, v35, v41
	v_max_i32_e32 v41, v42, v32
	v_min_i32_e32 v32, v42, v32
	v_max_i32_e32 v42, v44, v46
	v_min_i32_e32 v44, v44, v46
	v_max_i32_e32 v46, v43, v34
	v_min_i32_e32 v34, v43, v34
	v_max_i32_e32 v43, v35, v41
	v_min_i32_e32 v35, v35, v41
	v_max_i32_e32 v41, v32, v42
	v_min_i32_e32 v32, v32, v42
	ds_bpermute_b32 v67, v123, v41
	ds_bpermute_b32 v68, v123, v32
	ds_bpermute_b32 v69, v123, v44
	ds_bpermute_b32 v64, v123, v45
	ds_bpermute_b32 v65, v123, v43
	ds_bpermute_b32 v66, v123, v35
	s_waitcnt lgkmcnt(4)
	v_max_i32_e32 v43, v43, v68
	s_waitcnt lgkmcnt(3)
; #define CAND(a, b) (int)((__float_as_uint(__int_as_float(top[0][a]) + __int_as_float(top[1][b])) | 255u) - (unsigned)((a) * 16 + (b)))
; __device__ __forceinline__ void route_task(int task, int tl0, const bf16* QP  , const LAS bf16* KHL, LAS unsigned short* EL, LAS float* GL, int lane) {
;     ...
; #pragma unroll
;         for (int i = 0; i < 16; ++i) oth[i] = __shfl_xor(bk[i], 32);
;         merge16_desc(bk, oth);
;     }
;     ...
;     {
;         int gk[16];
;         gk[0] = CAND(3, 3); gk[1] = CAND(4, 0); gk[2] = CAND(4, 1); gk[3] = CAND(4, 2); gk[4] = CAND(5, 0); gk[5] = CAND(5, 1); gk[6] = CAND(6, 0); gk[7] = CAND(6, 1);
;         gk[8] = CAND(7, 0); gk[9] = CAND(7, 1); gk[10] = CAND(8, 0); gk[11] = CAND(9, 0); gk[12] = CAND(10, 0); gk[13] = CAND(11, 0); gk[14] = CAND(12, 0); gk[15] = CAND(13, 0);
;         sort16_desc(gk);
	v_max_i32_e32 v45, v45, v69
	v_max_i32_e32 v35, v35, v67
	v_add_f32_e32 v31, v62, v31
	v_add_f32_e32 v62, v61, v26
	v_add_f32_e32 v67, v61, v33
	v_add_f32_e32 v36, v61, v36
	v_add_f32_e32 v61, v60, v26
	v_add_f32_e32 v60, v60, v33
	v_add_f32_e32 v68, v59, v26
	v_add_f32_e32 v59, v59, v33
	v_add_f32_e32 v69, v57, v26
	v_add_f32_e32 v33, v57, v33
	v_add_f32_e32 v57, v58, v26
	v_add_f32_e32 v53, v53, v26
	v_add_f32_e32 v52, v52, v26
	ds_bpermute_b32 v70, v123, v27
	v_or_b32_e32 v31, 0xff, v31
	v_or_b32_e32 v62, 0xff, v62
	v_or_b32_e32 v67, 0xff, v67
	v_or_b32_e32 v36, 0xff, v36
	v_or_b32_e32 v61, 0xff, v61
	v_or_b32_e32 v60, 0xff, v60
	v_or_b32_e32 v68, 0xff, v68
	v_or_b32_e32 v59, 0xff, v59
	v_or_b32_e32 v69, 0xff, v69
	v_or_b32_e32 v33, 0xff, v33
	v_or_b32_e32 v55, 0xff, v55
	v_or_b32_e32 v57, 0xff, v57
	v_or_b32_e32 v56, 0xff, v56
	v_or_b32_e32 v54, 0xff, v54
	v_or_b32_e32 v53, 0xff, v53
	v_or_b32_e32 v52, 0xff, v52
	v_subrev_u32_e32 v31, 51, v31
	v_subrev_u32_e32 v62, 64, v62
	v_add_u32_e32 v67, 0xffffffbf, v67
	v_add_u32_e32 v36, 0xffffffbe, v36
	v_add_u32_e32 v61, 0xffffffb0, v61
	v_add_u32_e32 v60, 0xffffffaf, v60
	v_add_u32_e32 v68, 0xffffffa0, v68
	v_add_u32_e32 v59, 0xffffff9f, v59
	v_add_u32_e32 v69, 0xffffff90, v69
	v_add_u32_e32 v33, 0xffffff8f, v33
	v_add_u32_e32 v55, 0xffffff80, v55
	v_add_u32_e32 v57, 0xffffff70, v57
	v_add_u32_e32 v56, 0xffffff60, v56
	v_add_u32_e32 v54, 0xffffff50, v54
	v_add_u32_e32 v53, 0xffffff40, v53
	v_add_u32_e32 v52, 0xffffff30, v52
	ds_bpermute_b32 v42, v123, v38
	ds_bpermute_b32 v47, v123, v40
	ds_bpermute_b32 v48, v123, v30
	ds_bpermute_b32 v49, v123, v37
	ds_bpermute_b32 v63, v123, v28
	ds_bpermute_b32 v71, v123, v29
	ds_bpermute_b32 v72, v123, v39
	ds_bpermute_b32 v73, v123, v34
	ds_bpermute_b32 v74, v123, v46
	v_max_i32_e32 v58, v31, v54
	v_min_i32_e32 v31, v31, v54
	v_max_i32_e32 v54, v62, v56
	v_min_i32_e32 v56, v62, v56
	v_max_i32_e32 v62, v67, v52
	v_min_i32_e32 v52, v67, v52
	v_max_i32_e32 v67, v36, v53
	v_min_i32_e32 v36, v36, v53
	v_max_i32_e32 v53, v61, v69
	v_min_i32_e32 v61, v61, v69
	v_max_i32_e32 v69, v60, v68
	v_min_i32_e32 v60, v60, v68
	v_max_i32_e32 v68, v59, v57
	v_min_i32_e32 v57, v59, v57
	v_max_i32_e32 v59, v33, v55
	v_min_i32_e32 v33, v33, v55
	v_max_i32_e32 v55, v58, v69
	v_min_i32_e32 v58, v58, v69
	v_max_i32_e32 v69, v54, v68
	v_min_i32_e32 v54, v54, v68
	v_max_i32_e32 v68, v62, v59
	v_min_i32_e32 v59, v62, v59
	v_max_i32_e32 v62, v67, v53
	v_min_i32_e32 v53, v67, v53
	v_max_i32_e32 v67, v60, v31
	v_min_i32_e32 v31, v60, v31
	v_max_i32_e32 v60, v61, v36
	v_min_i32_e32 v36, v61, v36
	v_max_i32_e32 v61, v33, v52
	v_min_i32_e32 v33, v33, v52
	v_max_i32_e32 v52, v57, v56
	v_min_i32_e32 v56, v57, v56
	v_max_i32_e32 v57, v55, v69
	v_min_i32_e32 v55, v55, v69
	v_max_i32_e32 v69, v68, v62
	v_min_i32_e32 v62, v68, v62
	v_max_i32_e32 v68, v53, v58
	v_min_i32_e32 v53, v53, v58
	v_max_i32_e32 v58, v67, v60
	v_min_i32_e32 v60, v67, v60
	v_max_i32_e32 v67, v54, v59
	v_min_i32_e32 v54, v54, v59
	v_max_i32_e32 v59, v61, v52
	v_min_i32_e32 v52, v61, v52
	v_max_i32_e32 v61, v56, v31
	v_min_i32_e32 v31, v56, v31
	v_max_i32_e32 v56, v36, v33
	v_min_i32_e32 v33, v36, v33
	s_waitcnt lgkmcnt(9)
	v_max_i32_e32 v38, v38, v70
	v_min_i32_e32 v36, v57, v69
	v_max_i32_e32 v70, v55, v62
	v_min_i32_e32 v55, v55, v62
	v_max_i32_e32 v62, v68, v59
	v_min_i32_e32 v59, v68, v59
	v_max_i32_e32 v68, v53, v52
	v_min_i32_e32 v52, v53, v52
	v_max_i32_e32 v53, v58, v67
	v_min_i32_e32 v58, v58, v67
	v_max_i32_e32 v67, v60, v54
	v_min_i32_e32 v54, v60, v54
	v_max_i32_e32 v60, v61, v56
	v_min_i32_e32 v56, v61, v56
	v_max_i32_e32 v61, v31, v33
	v_min_i32_e32 v31, v31, v33
	v_max_i32_e32 v33, v70, v36
	v_min_i32_e32 v36, v70, v36
	v_max_i32_e32 v70, v55, v60
	v_min_i32_e32 v55, v55, v60
	v_max_i32_e32 v60, v62, v53
	v_min_i32_e32 v53, v62, v53
	v_max_i32_e32 v62, v68, v58
	v_min_i32_e32 v58, v68, v58
	v_max_i32_e32 v68, v67, v59
	v_min_i32_e32 v59, v67, v59
	v_max_i32_e32 v67, v54, v52
	v_min_i32_e32 v52, v54, v52
	v_max_i32_e32 v54, v61, v56
	s_waitcnt lgkmcnt(3)
	v_max_i32_e32 v40, v40, v71
	s_waitcnt lgkmcnt(2)
	v_max_i32_e32 v30, v30, v72
	s_waitcnt lgkmcnt(1)
	v_max_i32_e32 v37, v37, v73
	s_waitcnt lgkmcnt(0)
	v_max_i32_e32 v28, v28, v74
	v_max_i32_e32 v41, v41, v66
	v_max_i32_e32 v32, v32, v65
	v_max_i32_e32 v44, v44, v64
	v_max_i32_e32 v46, v46, v63
	v_max_i32_e32 v34, v34, v49
	v_max_i32_e32 v39, v39, v48
	v_max_i32_e32 v29, v29, v47
	v_max_i32_e32 v27, v27, v42
	v_min_i32_e32 v56, v61, v56
	v_max_i32_e32 v61, v33, v60
	v_min_i32_e32 v33, v33, v60
	v_max_i32_e32 v60, v36, v53
	v_min_i32_e32 v36, v36, v53
	v_max_i32_e32 v53, v62, v68
	v_min_i32_e32 v62, v62, v68
	v_max_i32_e32 v68, v58, v59
	v_min_i32_e32 v58, v58, v59
	v_max_i32_e32 v59, v67, v54
	v_max_i32_e32 v42, v38, v41
	v_min_i32_e32 v38, v38, v41
	v_max_i32_e32 v41, v40, v32
	v_min_i32_e32 v32, v40, v32
	v_max_i32_e32 v40, v30, v44
	v_min_i32_e32 v30, v30, v44
	v_max_i32_e32 v44, v37, v46
	v_min_i32_e32 v37, v37, v46
	v_max_i32_e32 v46, v28, v34
	v_min_i32_e32 v28, v28, v34
	v_max_i32_e32 v34, v45, v39
	v_min_i32_e32 v39, v45, v39
	v_max_i32_e32 v45, v43, v29
	v_min_i32_e32 v29, v43, v29
	v_max_i32_e32 v43, v35, v27
	v_min_i32_e32 v27, v35, v27
	v_min_i32_e32 v54, v67, v54
	v_max_i32_e32 v67, v52, v56
	v_max_i32_e32 v71, v70, v36
	v_min_i32_e32 v36, v70, v36
	v_max_i32_e32 v70, v59, v55
	v_min_i32_e32 v55, v59, v55
	v_max_i32_e32 v35, v42, v46
	v_min_i32_e32 v42, v42, v46
	v_max_i32_e32 v46, v41, v34
	v_min_i32_e32 v34, v41, v34
	v_max_i32_e32 v41, v40, v45
	v_min_i32_e32 v40, v40, v45
	v_max_i32_e32 v45, v44, v43
	v_min_i32_e32 v43, v44, v43
; #define CAND(a, b) (int)((__float_as_uint(__int_as_float(top[0][a]) + __int_as_float(top[1][b])) | 255u) - (unsigned)((a) * 16 + (b)))
; __device__ __forceinline__ void route_task(int task, int tl0, const bf16* QP  , const LAS bf16* KHL, LAS unsigned short* EL, LAS float* GL, int lane) {
;     ...
;         sort16_desc(gk);
;         merge16_desc(bk, gk);
;     }
;     {
;         const int c14 = CAND(14, 0), c15 = CAND(15, 0);
;         const int n14 = max(bk[14], c14), n15 = max(min(bk[14], c14), max(bk[15], c15));
;         bk[14] = n14; bk[15] = n15;
;     }
;     ...
;     int my[8];
; #pragma unroll
;     for (int i = 0; i < 8; ++i) { int lo_ = bk[i], hi_ = bk[8 + i]; asm volatile("" : "+v"(lo_), "+v"(hi_)); my[i] = hi ? hi_ : lo_; }
;     int bv[8];
; #pragma unroll
;     for (int i = 0; i < 8; ++i) {
;         const unsigned cd = 255u - ((unsigned)my[i] & 255u), ca = cd >> 4, cb = cd & 15u;
;         const unsigned wa = (ca >> 2) == 0u ? P1[0] : (ca >> 2) == 1u ? P1[1] : (ca >> 2) == 2u ? P1[2] : P1[3];
;         const unsigned wb = (cb >> 2) == 0u ? P2[0] : (cb >> 2) == 1u ? P2[1] : (cb >> 2) == 2u ? P2[2] : P2[3];
;         bv[i] = (int)((((wa >> (8u * (ca & 3u))) & 255u) << 7) | ((wb >> (8u * (cb & 3u))) & 255u));
	v_max_i32_e32 v44, v38, v28
	v_min_i32_e32 v28, v38, v28
	v_max_i32_e32 v38, v32, v39
	v_min_i32_e32 v32, v32, v39
	v_max_i32_e32 v39, v30, v29
	v_min_i32_e32 v29, v30, v29
	v_max_i32_e32 v30, v37, v27
	v_min_i32_e32 v27, v37, v27
	v_min_i32_e32 v52, v52, v56
	v_min_i32_e32 v56, v60, v33
	v_max_i32_e32 v59, v67, v54
	v_min_i32_e32 v54, v67, v54
	v_max_i32_e32 v67, v71, v53
	v_min_i32_e32 v53, v71, v53
	v_max_i32_e32 v71, v36, v62
	v_min_i32_e32 v36, v36, v62
	v_max_i32_e32 v62, v68, v70
	v_min_i32_e32 v68, v68, v70
	v_max_i32_e32 v70, v58, v55
	v_max_i32_e32 v37, v35, v41
	v_min_i32_e32 v35, v35, v41
	v_max_i32_e32 v41, v46, v45
	v_min_i32_e32 v45, v46, v45
	v_max_i32_e32 v46, v42, v40
	v_min_i32_e32 v40, v42, v40
	v_max_i32_e32 v42, v34, v43
	v_min_i32_e32 v34, v34, v43
	v_max_i32_e32 v43, v44, v39
	v_min_i32_e32 v39, v44, v39
	v_max_i32_e32 v44, v38, v30
	v_min_i32_e32 v30, v38, v30
	v_max_i32_e32 v38, v28, v29
	v_min_i32_e32 v28, v28, v29
	v_max_i32_e32 v29, v32, v27
	v_min_i32_e32 v27, v32, v27
	v_min_i32_e32 v55, v58, v55
	v_max_i32_e32 v58, v67, v56
	v_min_i32_e32 v56, v67, v56
	v_max_i32_e32 v67, v53, v71
	v_min_i32_e32 v53, v53, v71
	v_max_i32_e32 v71, v62, v36
	v_min_i32_e32 v36, v62, v36
	v_max_i32_e32 v62, v68, v70
	v_min_i32_e32 v32, v37, v41
	v_min_i32_e32 v47, v35, v45
	v_min_i32_e32 v48, v46, v42
	v_min_i32_e32 v49, v40, v34
	v_min_i32_e32 v63, v43, v44
	v_min_i32_e32 v64, v39, v30
	v_min_i32_e32 v65, v38, v29
	v_min_i32_e32 v66, v28, v27
	v_min_i32_e32 v68, v68, v70
	v_max_i32_e32 v70, v59, v55
	v_min_i32_e32 v55, v59, v55
	v_min_i32_e32 v59, v53, v71
	v_min_i32_e32 v72, v36, v62
	v_max3_i32 v31, v37, v41, v31
	v_max_i32_e32 v32, v32, v52
	v_max3_i32 v35, v35, v45, v54
	v_max_i32_e32 v37, v47, v55
	v_max3_i32 v41, v46, v42, v70
	v_max_i32_e32 v42, v48, v68
	v_max3_i32 v34, v40, v34, v72
	v_max3_i32 v36, v49, v36, v62
	v_max3_i32 v40, v43, v44, v59
	v_max3_i32 v43, v63, v53, v71
	v_max3_i32 v30, v39, v30, v67
	v_max_i32_e32 v39, v64, v56
	v_max3_i32 v29, v38, v29, v58
	v_max3_i32 v33, v65, v60, v33
	v_max3_i32 v27, v28, v27, v61
	v_max3_i32 v28, v66, v57, v69
	v_max_i32_e32 v38, v31, v40
	v_min_i32_e32 v31, v31, v40
	v_max_i32_e32 v40, v32, v43
	v_min_i32_e32 v32, v32, v43
	v_max_i32_e32 v43, v35, v30
	v_min_i32_e32 v30, v35, v30
	v_max_i32_e32 v35, v37, v39
	v_min_i32_e32 v37, v37, v39
	v_max_i32_e32 v39, v41, v29
	v_min_i32_e32 v29, v41, v29
	v_max_i32_e32 v41, v42, v33
	v_min_i32_e32 v33, v42, v33
	v_max_i32_e32 v42, v34, v27
	v_min_i32_e32 v27, v34, v27
	v_max_i32_e32 v34, v36, v28
	v_min_i32_e32 v28, v36, v28
	v_max_i32_e32 v36, v38, v39
	v_min_i32_e32 v38, v38, v39
	v_max_i32_e32 v39, v40, v41
	v_min_i32_e32 v40, v40, v41
	v_max_i32_e32 v41, v43, v42
	v_min_i32_e32 v42, v43, v42
	v_max_i32_e32 v43, v35, v34
	v_min_i32_e32 v34, v35, v34
	v_max_i32_e32 v35, v31, v29
	v_min_i32_e32 v29, v31, v29
	v_max_i32_e32 v31, v32, v33
	v_min_i32_e32 v32, v32, v33
	v_max_i32_e32 v33, v30, v27
	v_min_i32_e32 v27, v30, v27
	v_max_i32_e32 v30, v37, v28
	v_min_i32_e32 v28, v37, v28
	v_max_i32_e32 v37, v36, v41
	v_min_i32_e32 v36, v36, v41
	v_max_i32_e32 v41, v39, v43
	v_min_i32_e32 v39, v39, v43
	v_max_i32_e32 v43, v38, v42
	v_min_i32_e32 v38, v38, v42
	v_max_i32_e32 v42, v40, v34
	v_min_i32_e32 v34, v40, v34
	v_max_i32_e32 v40, v35, v33
	v_min_i32_e32 v33, v35, v33
	v_max_i32_e32 v35, v31, v30
	v_min_i32_e32 v30, v31, v30
	v_max_i32_e32 v31, v29, v27
	v_min_i32_e32 v27, v29, v27
	v_max_i32_e32 v29, v32, v28
	v_min_i32_e32 v28, v32, v28
	v_max_i32_e32 v32, v37, v41
	v_min_i32_e32 v37, v37, v41
	v_max_i32_e32 v41, v36, v39
	v_min_i32_e32 v36, v36, v39
	v_max_i32_e32 v39, v43, v42
	v_min_i32_e32 v42, v43, v42
	v_max_i32_e32 v43, v38, v34
	v_min_i32_e32 v34, v38, v34
	v_max_i32_e32 v38, v40, v35
	v_min_i32_e32 v35, v40, v35
	v_max_i32_e32 v40, v33, v30
	v_min_i32_e32 v30, v33, v30
	v_max_i32_e32 v33, v31, v29
	v_min_i32_e32 v29, v31, v29
	v_max_i32_e32 v31, v27, v28
	v_min_i32_e32 v27, v27, v28
	v_add_f32_e32 v28, v51, v26
	v_or_b32_e32 v28, 0xff, v28
	v_add_f32_e32 v26, v50, v26
	v_add_u32_e32 v28, 0xffffff20, v28
	v_or_b32_e32 v26, 0xff, v26
	v_add_u32_e32 v26, 0xffffff10, v26
	v_max_i32_e32 v44, v31, v28
	v_min_i32_e32 v28, v31, v28
	v_max3_i32 v26, v28, v27, v26
	v_mov_b32_e32 v27, v32
	s_nop 0
	v_cndmask_b32_e64 v27, v38, v27, s[6:7]
	v_not_b32_e32 v28, v27
	v_bfe_u32 v45, v28, 6, 2
	v_cmp_eq_u32_e32 vcc, 2, v45
	v_cndmask_b32_e64 v34, v26, v34, s[6:7]
	v_bitop3_b32 v26, v27, s3, v27 bitop3:0xc
	v_cndmask_b32_e32 v46, v25, v23, vcc
	v_cmp_eq_u32_e32 vcc, 1, v45
	v_cndmask_b32_e64 v31, v35, v37, s[6:7]
	v_not_b32_e32 v35, v31
	v_cndmask_b32_e32 v45, v46, v21, vcc
	v_cmp_gt_u32_e32 vcc, 64, v26
	v_cndmask_b32_e64 v37, v40, v41, s[6:7]
	v_cndmask_b32_e64 v41, v44, v43, s[6:7]
	v_cndmask_b32_e32 v26, v45, v19, vcc
	v_bfe_u32 v45, v28, 2, 2
	v_cmp_eq_u32_e32 vcc, 2, v45
	v_bitop3_b32 v44, v27, 15, v27 bitop3:0xc
	v_bfe_u32 v47, v35, 6, 2
	v_cndmask_b32_e32 v46, v24, v22, vcc
	v_cmp_eq_u32_e32 vcc, 1, v45
	v_not_b32_e32 v38, v37
	v_bfe_u32 v49, v38, 6, 2
	v_cndmask_b32_e32 v45, v46, v20, vcc
	v_cmp_gt_u32_e32 vcc, 4, v44
	v_bitop3_b32 v46, v31, 15, v31 bitop3:0xc
	v_cndmask_b32_e64 v30, v30, v36, s[6:7]
	v_cndmask_b32_e32 v44, v45, v18, vcc
	v_cmp_eq_u32_e32 vcc, 2, v47
	v_bitop3_b32 v45, v31, s3, v31 bitop3:0xc
	v_not_b32_e32 v36, v30
	v_cndmask_b32_e32 v48, v25, v23, vcc
	v_cmp_eq_u32_e32 vcc, 1, v47
	v_bfe_u32 v51, v36, 6, 2
	v_cndmask_b32_e64 v33, v33, v39, s[6:7]
	v_cndmask_b32_e32 v47, v48, v21, vcc
	v_cmp_gt_u32_e32 vcc, 64, v45
	v_not_b32_e32 v39, v33
	v_bfe_u32 v53, v39, 6, 2
	v_cndmask_b32_e32 v45, v47, v19, vcc
; __device__ __forceinline__ void route_task(int task, int tl0, const bf16* QP  , const LAS bf16* KHL, LAS unsigned short* EL, LAS float* GL, int lane) {
;     ...
;     for (int i = 0; i < 8; ++i) {
;         const unsigned cd = 255u - ((unsigned)my[i] & 255u), ca = cd >> 4, cb = cd & 15u;
;         const unsigned wa = (ca >> 2) == 0u ? P1[0] : (ca >> 2) == 1u ? P1[1] : (ca >> 2) == 2u ? P1[2] : P1[3];
;         const unsigned wb = (cb >> 2) == 0u ? P2[0] : (cb >> 2) == 1u ? P2[1] : (cb >> 2) == 2u ? P2[2] : P2[3];
;         bv[i] = (int)((((wa >> (8u * (ca & 3u))) & 255u) << 7) | ((wb >> (8u * (cb & 3u))) & 255u));
;     }
;     float e[8], se = 0.f;
; #pragma unroll
;     for (int i = 0; i < 8; ++i) { e[i] = __expf(__int_as_float(my[i]) - __int_as_float(bk[0])); se += e[i]; }
;     se += __shfl_xor(se, 32);
	v_bfe_u32 v47, v35, 2, 2
	v_cmp_eq_u32_e32 vcc, 2, v47
	v_cndmask_b32_e64 v29, v29, v42, s[6:7]
	v_not_b32_e32 v40, v29
	v_cndmask_b32_e32 v48, v24, v22, vcc
	v_cmp_eq_u32_e32 vcc, 1, v47
	v_bfe_u32 v55, v40, 6, 2
	v_not_b32_e32 v42, v41
	v_cndmask_b32_e32 v47, v48, v20, vcc
	v_cmp_gt_u32_e32 vcc, 4, v46
	v_bitop3_b32 v48, v37, 15, v37 bitop3:0xc
	v_bfe_u32 v57, v42, 6, 2
	v_cndmask_b32_e32 v46, v47, v18, vcc
	v_cmp_eq_u32_e32 vcc, 2, v49
	v_bitop3_b32 v47, v37, s3, v37 bitop3:0xc
	v_not_b32_e32 v43, v34
	v_cndmask_b32_e32 v50, v25, v23, vcc
	v_cmp_eq_u32_e32 vcc, 1, v49
	v_bfe_u32 v59, v43, 6, 2
	v_or_b32_e32 v82, s10, v88
	v_cndmask_b32_e32 v49, v50, v21, vcc
	v_cmp_gt_u32_e32 vcc, 64, v47
	s_nop 1
	v_cndmask_b32_e32 v47, v49, v19, vcc
	v_bfe_u32 v49, v38, 2, 2
	v_cmp_eq_u32_e32 vcc, 2, v49
	s_nop 1
	v_cndmask_b32_e32 v50, v24, v22, vcc
	v_cmp_eq_u32_e32 vcc, 1, v49
	s_nop 1
	v_cndmask_b32_e32 v49, v50, v20, vcc
	v_cmp_gt_u32_e32 vcc, 4, v48
	v_bitop3_b32 v50, v30, 15, v30 bitop3:0xc
	s_nop 0
	v_cndmask_b32_e32 v48, v49, v18, vcc
	v_cmp_eq_u32_e32 vcc, 2, v51
	v_bitop3_b32 v49, v30, s3, v30 bitop3:0xc
	s_nop 0
	v_cndmask_b32_e32 v52, v25, v23, vcc
	v_cmp_eq_u32_e32 vcc, 1, v51
	s_nop 1
	v_cndmask_b32_e32 v51, v52, v21, vcc
	v_cmp_gt_u32_e32 vcc, 64, v49
	s_nop 1
	v_cndmask_b32_e32 v49, v51, v19, vcc
	v_bfe_u32 v51, v36, 2, 2
	v_cmp_eq_u32_e32 vcc, 2, v51
	s_nop 1
	v_cndmask_b32_e32 v52, v24, v22, vcc
	v_cmp_eq_u32_e32 vcc, 1, v51
	s_nop 1
	v_cndmask_b32_e32 v51, v52, v20, vcc
	v_cmp_gt_u32_e32 vcc, 4, v50
	v_bitop3_b32 v52, v33, 15, v33 bitop3:0xc
	s_nop 0
	v_cndmask_b32_e32 v50, v51, v18, vcc
	v_cmp_eq_u32_e32 vcc, 2, v53
	v_bitop3_b32 v51, v33, s3, v33 bitop3:0xc
	s_nop 0
	v_cndmask_b32_e32 v54, v25, v23, vcc
	v_cmp_eq_u32_e32 vcc, 1, v53
	s_nop 1
	v_cndmask_b32_e32 v53, v54, v21, vcc
	v_cmp_gt_u32_e32 vcc, 64, v51
	s_nop 1
	v_cndmask_b32_e32 v51, v53, v19, vcc
	v_bfe_u32 v53, v39, 2, 2
	v_cmp_eq_u32_e32 vcc, 2, v53
	s_nop 1
	v_cndmask_b32_e32 v54, v24, v22, vcc
	v_cmp_eq_u32_e32 vcc, 1, v53
	s_nop 1
	v_cndmask_b32_e32 v53, v54, v20, vcc
	v_cmp_gt_u32_e32 vcc, 4, v52
	v_bitop3_b32 v54, v29, 15, v29 bitop3:0xc
	s_nop 0
	v_cndmask_b32_e32 v52, v53, v18, vcc
	v_cmp_eq_u32_e32 vcc, 2, v55
	v_bitop3_b32 v53, v29, s3, v29 bitop3:0xc
	s_nop 0
	v_cndmask_b32_e32 v56, v25, v23, vcc
	v_cmp_eq_u32_e32 vcc, 1, v55
	s_nop 1
	v_cndmask_b32_e32 v55, v56, v21, vcc
	v_cmp_gt_u32_e32 vcc, 64, v53
	s_nop 1
	v_cndmask_b32_e32 v53, v55, v19, vcc
	v_bfe_u32 v55, v40, 2, 2
	v_cmp_eq_u32_e32 vcc, 2, v55
	s_nop 1
	v_cndmask_b32_e32 v56, v24, v22, vcc
	v_cmp_eq_u32_e32 vcc, 1, v55
	s_nop 1
	v_cndmask_b32_e32 v55, v56, v20, vcc
	v_cmp_gt_u32_e32 vcc, 4, v54
	v_bitop3_b32 v56, v41, 15, v41 bitop3:0xc
	s_nop 0
	v_cndmask_b32_e32 v54, v55, v18, vcc
	v_cmp_eq_u32_e32 vcc, 2, v57
	v_bitop3_b32 v55, v41, s3, v41 bitop3:0xc
	s_nop 0
	v_cndmask_b32_e32 v58, v25, v23, vcc
	v_cmp_eq_u32_e32 vcc, 1, v57
	s_nop 1
	v_cndmask_b32_e32 v57, v58, v21, vcc
	v_cmp_gt_u32_e32 vcc, 64, v55
	s_nop 1
	v_cndmask_b32_e32 v55, v57, v19, vcc
	v_bfe_u32 v57, v42, 2, 2
	v_cmp_eq_u32_e32 vcc, 2, v57
	s_nop 1
	v_cndmask_b32_e32 v58, v24, v22, vcc
	v_cmp_eq_u32_e32 vcc, 1, v57
	s_nop 1
	v_cndmask_b32_e32 v57, v58, v20, vcc
	v_cmp_gt_u32_e32 vcc, 4, v56
	v_bitop3_b32 v58, v34, 15, v34 bitop3:0xc
	s_nop 0
	v_cndmask_b32_e32 v56, v57, v18, vcc
	v_cmp_eq_u32_e32 vcc, 2, v59
	v_bitop3_b32 v57, v34, s3, v34 bitop3:0xc
	s_nop 0
	v_cndmask_b32_e32 v23, v25, v23, vcc
	v_cmp_eq_u32_e32 vcc, 1, v59
	v_sub_f32_e32 v25, v30, v32
	v_mul_f32_e32 v25, 0x3fb8aa3b, v25
	v_cndmask_b32_e32 v21, v23, v21, vcc
	v_cmp_gt_u32_e32 vcc, 64, v57
	v_lshrrev_b32_e32 v23, 1, v39
	v_and_b32_e32 v23, 24, v23
	v_cndmask_b32_e32 v19, v21, v19, vcc
	v_bfe_u32 v21, v43, 2, 2
	v_cmp_eq_u32_e32 vcc, 2, v21
	v_lshrrev_b32_e32 v23, v23, v51
	v_lshlrev_b32_e32 v23, 7, v23
	v_cndmask_b32_e32 v22, v24, v22, vcc
	v_cmp_eq_u32_e32 vcc, 1, v21
	v_lshrrev_b32_e32 v21, 1, v42
	v_and_b32_e32 v21, 24, v21
	v_cndmask_b32_e32 v20, v22, v20, vcc
	v_cmp_gt_u32_e32 vcc, 4, v58
	v_lshrrev_b32_e32 v21, v21, v55
	v_lshrrev_b32_e32 v22, 1, v40
	v_cndmask_b32_e32 v18, v20, v18, vcc
	v_lshlrev_b32_e32 v20, 3, v42
	v_lshlrev_b32_e32 v21, 7, v21
	v_and_b32_e32 v22, 24, v22
	v_lshrrev_b32_e32 v20, v20, v56
	v_and_b32_e32 v21, 0x7f80, v21
	v_lshrrev_b32_e32 v22, v22, v53
	v_and_or_b32 v21, v20, s3, v21
	v_lshlrev_b32_e32 v20, 3, v40
	v_lshlrev_b32_e32 v22, 7, v22
	v_lshrrev_b32_e32 v20, v20, v54
	v_and_b32_e32 v22, 0x7f80, v22
	v_and_or_b32 v20, v20, s3, v22
	v_lshlrev_b32_e32 v22, 3, v39
	v_lshrrev_b32_e32 v22, v22, v52
	v_and_b32_e32 v23, 0x7f80, v23
	v_and_or_b32 v39, v22, s3, v23
	v_lshrrev_b32_e32 v23, 1, v36
	v_and_b32_e32 v23, 24, v23
	v_lshrrev_b32_e32 v23, v23, v49
	v_lshlrev_b32_e32 v22, 3, v36
	v_lshlrev_b32_e32 v23, 7, v23
	v_lshrrev_b32_e32 v22, v22, v50
	v_and_b32_e32 v23, 0x7f80, v23
	v_and_or_b32 v36, v22, s3, v23
	v_lshrrev_b32_e32 v23, 1, v38
	v_and_b32_e32 v23, 24, v23
	v_lshrrev_b32_e32 v23, v23, v47
	v_lshlrev_b32_e32 v22, 3, v38
	v_lshlrev_b32_e32 v23, 7, v23
	v_lshrrev_b32_e32 v22, v22, v48
	v_and_b32_e32 v23, 0x7f80, v23
	v_and_or_b32 v38, v22, s3, v23
	v_lshrrev_b32_e32 v23, 1, v35
	v_and_b32_e32 v23, 24, v23
	v_lshrrev_b32_e32 v23, v23, v45
	v_lshlrev_b32_e32 v22, 3, v35
	v_lshlrev_b32_e32 v23, 7, v23
	v_lshrrev_b32_e32 v22, v22, v46
	v_and_b32_e32 v23, 0x7f80, v23
	v_and_or_b32 v35, v22, s3, v23
	v_lshrrev_b32_e32 v23, 1, v28
	v_and_b32_e32 v23, 24, v23
	v_lshrrev_b32_e32 v23, v23, v26
	v_lshlrev_b32_e32 v22, 3, v28
	v_lshlrev_b32_e32 v23, 7, v23
	v_lshrrev_b32_e32 v22, v22, v44
	v_and_b32_e32 v23, 0x7f80, v23
	v_and_or_b32 v40, v22, s3, v23
	v_sub_f32_e32 v22, v27, v32
	v_mul_f32_e32 v22, 0x3fb8aa3b, v22
	v_sub_f32_e32 v23, v31, v32
	v_exp_f32_e32 v22, v22
	v_mul_f32_e32 v23, 0x3fb8aa3b, v23
	v_sub_f32_e32 v24, v37, v32
	v_exp_f32_e32 v23, v23
	v_mul_f32_e32 v24, 0x3fb8aa3b, v24
	v_exp_f32_e32 v24, v24
	v_exp_f32_e32 v25, v25
	v_add_f32_e32 v26, 0, v22
	v_add_f32_e32 v26, v23, v26
	v_add_f32_e32 v26, v24, v26
	v_add_f32_e32 v30, v25, v26
	v_sub_f32_e32 v26, v33, v32
	v_mul_f32_e32 v26, 0x3fb8aa3b, v26
	v_sub_f32_e32 v27, v29, v32
	v_exp_f32_e32 v26, v26
	v_mul_f32_e32 v27, 0x3fb8aa3b, v27
	v_sub_f32_e32 v28, v41, v32
	v_exp_f32_e32 v27, v27
	v_mul_f32_e32 v28, 0x3fb8aa3b, v28
	v_sub_f32_e32 v29, v34, v32
	v_exp_f32_e32 v28, v28
	v_mul_f32_e32 v29, 0x3fb8aa3b, v29
	v_exp_f32_e32 v29, v29
	v_add_f32_e32 v30, v26, v30
	v_add_f32_e32 v30, v27, v30
	v_add_f32_e32 v30, v28, v30
	v_add_f32_e32 v30, v29, v30
	ds_bpermute_b32 v31, v123, v30
	v_lshrrev_b32_e32 v42, 1, v43
	v_and_b32_e32 v32, 24, v42
	v_lshrrev_b32_e32 v19, v32, v19
	v_lshlrev_b32_e32 v19, 7, v19
	s_waitcnt lgkmcnt(0)
; #define LAS __attribute__((address_space(3)))
; #define MFMA32(a, b, c) __builtin_amdgcn_mfma_f32_32x32x16_bf16((a), (b), (c), 0, 0, 0)
; __device__ __forceinline__ void route_task(int task, int tl0, const bf16* QP  , const LAS bf16* KHL, LAS unsigned short* EL, LAS float* GL, int lane) {
;     const int r = lane & 31, hi = lane >> 5, t = 4 * task + (r >> 3), head = r & 7;
;     int top[2][16]; bf16x8 qa[2][4];
;     { unsigned qo = (unsigned)t * (unsigned)D + (unsigned)(head * 128 + 8 * hi); asm volatile("" : "+v"(qo)); const bf16* qp = QP + qo;
; #pragma unroll
;       for (int hf = 0; hf < 2; ++hf)
; #pragma unroll
;         for (int ks = 0; ks < 4; ++ks) qa[hf][ks] = ldg8(qp + 64 * hf + 16 * ks); }
; #pragma unroll
;     for (int half = 0; half < 2; ++half) {
;         int cur[16];
; #pragma unroll
;         for (int kt = 0; kt < 4; ++kt) {
;             f32x16 X;
; #pragma unroll
;             for (int i = 0; i < 16; ++i) X[i] = 8.f;
;             const LAS bf16* khp = KHL + (half * 128 + 32 * kt + r) * 72 + 8 * hi;
; #pragma unroll
;             for (int ks = 0; ks < 4; ++ks) {
;                 const bf16x8 kh = lds8(khp + 16 * ks);
;                 X = MFMA32(kh, qa[half][ks], X);
;             }
;             int grp[16];
; #pragma unroll
;             for (int i = 0; i < 16; ++i) grp[i] = (int)((__float_as_uint(X[i]) | 127u) - (unsigned)(32 * kt + (i & 3) + 8 * (i >> 2)));
;             sort16_desc(grp);
;     ...
;     se += __shfl_xor(se, 32);
;     const float inv = 1.f / se;
;     {
;         int l2 = lane; asm volatile("" : "+v"(l2));
;         const int o2 = (tl0 + ((l2 & 31) >> 3)) * 128 + (l2 & 7) * 16 + 8 * (l2 >> 5);
;         LAS v4u* ip = (LAS v4u*)(EL + o2); typedef float f4v __attribute__((ext_vector_type(4))); LAS f4v* gp = (LAS f4v*)(GL + o2);
;         ip[0] = (v4u){(unsigned)bv[0] | ((unsigned)bv[1] << 16), (unsigned)bv[2] | ((unsigned)bv[3] << 16), (unsigned)bv[4] | ((unsigned)bv[5] << 16), (unsigned)bv[6] | ((unsigned)bv[7] << 16)};
;         gp[0] = (f4v){e[0] * inv, e[1] * inv, e[2] * inv, e[3] * inv}; gp[1] = (f4v){e[4] * inv, e[5] * inv, e[6] * inv, e[7] * inv};
;     }
	v_add_f32_e32 v30, v30, v31
	v_div_scale_f32 v31, s[12:13], v30, v30, 1.0
	v_rcp_f32_e32 v32, v31
	v_lshlrev_b32_e32 v33, 3, v43
	v_and_b32_e32 v19, 0x7f80, v19
	v_lshrrev_b32_e32 v18, v33, v18
	v_and_or_b32 v33, v18, s3, v19
	v_fma_f32 v18, -v31, v32, 1.0
	v_fmac_f32_e32 v32, v18, v32
	v_div_scale_f32 v18, vcc, 1.0, v30, 1.0
	v_mul_f32_e32 v19, v18, v32
	v_fma_f32 v34, -v31, v19, v18
	v_fmac_f32_e32 v19, v34, v32
	v_fma_f32 v18, -v31, v19, v18
	v_div_fmas_f32 v18, v18, v32, v19
	v_div_fixup_f32 v30, v18, v30, 1.0
	v_mov_b32_e32 v18, v1
	v_lshl_or_b32 v20, v20, 16, v39
	v_lshrrev_b32_e32 v19, 3, v18
	v_and_or_b32 v19, v19, 3, s55
	v_lshlrev_b32_e32 v31, 4, v18
	v_ashrrev_i32_e32 v18, 2, v18
	v_lshlrev_b32_e32 v19, 7, v19
	v_and_b32_e32 v31, 0x70, v31
	v_and_b32_e32 v18, -8, v18
	v_add3_u32 v18, v18, v31, v19
	v_lshl_add_u32 v31, v18, 1, s11
	v_lshl_add_u32 v32, v18, 2, s69
	v_lshl_or_b32 v18, v35, 16, v40
	v_lshl_or_b32 v19, v36, 16, v38
	v_lshl_or_b32 v21, v33, 16, v21
	ds_write_b128 v31, v[18:21]
	v_pk_mul_f32 v[20:21], v[24:25], v[30:31] op_sel_hi:[1,0]
	v_pk_mul_f32 v[18:19], v[22:23], v[30:31] op_sel_hi:[1,0]
	ds_write_b128 v32, v[18:21]
	v_pk_mul_f32 v[20:21], v[28:29], v[30:31] op_sel_hi:[1,0]
	v_pk_mul_f32 v[18:19], v[26:27], v[30:31] op_sel_hi:[1,0]
	ds_write_b128 v32, v[18:21] offset:16
	v_mov_b64_e32 v[32:33], s[30:31]
	v_lshl_add_u64 v[128:129], v[82:83], 1, s[80:81]
	global_load_dwordx4 v[78:81], v[128:129], off
	global_load_dwordx4 v[74:77], v[128:129], off offset:32
	global_load_dwordx4 v[70:73], v[128:129], off offset:64
	global_load_dwordx4 v[66:69], v[128:129], off offset:96
	ds_read_b128 v[50:53], v94
	ds_read_b128 v[54:57], v94 offset:32
	v_mov_b64_e32 v[30:31], s[28:29]
	v_mov_b64_e32 v[28:29], s[26:27]
	v_mov_b64_e32 v[26:27], s[24:25]
	v_mov_b64_e32 v[24:25], s[22:23]
	v_mov_b64_e32 v[22:23], s[20:21]
	v_mov_b64_e32 v[20:21], s[18:19]
	v_mov_b64_e32 v[18:19], s[16:17]
	s_waitcnt vmcnt(3) lgkmcnt(1)
	s_nop 0
	v_mfma_f32_32x32x16_bf16 v[34:49], v[50:53], v[78:81], v[18:33]
	ds_read_b128 v[50:53], v94 offset:64
	ds_read_b128 v[124:127], v94 offset:96
	s_waitcnt vmcnt(2) lgkmcnt(2)
	v_mfma_f32_32x32x16_bf16 v[34:49], v[54:57], v[74:77], v[34:49]
	s_waitcnt vmcnt(1) lgkmcnt(1)
	v_mfma_f32_32x32x16_bf16 v[34:49], v[50:53], v[70:73], v[34:49]
	global_load_dwordx4 v[62:65], v[128:129], off offset:128
	global_load_dwordx4 v[58:61], v[128:129], off offset:160
	global_load_dwordx4 v[54:57], v[128:129], off offset:192
	global_load_dwordx4 v[50:53], v[128:129], off offset:224
	s_waitcnt vmcnt(4) lgkmcnt(0)
	v_mfma_f32_32x32x16_bf16 v[34:49], v[124:127], v[66:69], v[34:49]
	s_nop 11
	v_or_b32_e32 v37, 0x7f, v37
	v_or_b32_e32 v48, 0x7f, v48
	v_or_b32_e32 v38, 0x7f, v38
	v_or_b32_e32 v42, 0x7f, v42
	v_or_b32_e32 v47, 0x7f, v47
	v_or_b32_e32 v39, 0x7f, v39
	v_or_b32_e32 v40, 0x7f, v40
	v_or_b32_e32 v43, 0x7f, v43
	v_or_b32_e32 v44, 0x7f, v44
	v_or_b32_e32 v36, 0x7f, v36
	v_or_b32_e32 v49, 0x7f, v49
	v_or_b32_e32 v41, 0x7f, v41
	v_or_b32_e32 v45, 0x7f, v45
	v_or_b32_e32 v35, 0x7f, v35
	v_or_b32_e32 v46, 0x7f, v46
	v_add_u32_e32 v37, -3, v37
	v_subrev_u32_e32 v48, 26, v48
	v_add_u32_e32 v38, -8, v38
	v_add_u32_e32 v42, -16, v42
	v_or_b32_e32 v34, 0x7f, v34
	v_subrev_u32_e32 v47, 25, v47
	v_add_u32_e32 v39, -9, v39
	v_add_u32_e32 v40, -10, v40
	v_subrev_u32_e32 v43, 17, v43
	v_subrev_u32_e32 v44, 18, v44
	v_add_u32_e32 v36, -2, v36
	v_subrev_u32_e32 v49, 27, v49
	v_add_u32_e32 v41, -11, v41
	v_subrev_u32_e32 v45, 19, v45
	v_add_u32_e32 v35, -1, v35
	v_subrev_u32_e32 v46, 24, v46
	v_max_i32_e32 v82, v37, v48
	v_max_i32_e32 v124, v38, v42
	v_max_i32_e32 v126, v34, v47
	v_max_i32_e32 v127, v39, v40
	v_min_i32_e32 v130, v43, v44
	v_min_i32_e32 v131, v36, v49
	v_min_i32_e32 v133, v41, v45
	v_min_i32_e32 v134, v35, v46
	v_min_i32_e32 v39, v39, v40
	v_min_i32_e32 v34, v34, v47
	v_min_i32_e32 v38, v38, v42
	v_min_i32_e32 v37, v37, v48
	v_max_i32_e32 v35, v35, v46
	v_max_i32_e32 v41, v41, v45
	v_max_i32_e32 v36, v36, v49
	v_max_i32_e32 v43, v43, v44
	v_min_i32_e32 v125, v82, v124
	v_min_i32_e32 v128, v126, v127
	v_max_i32_e32 v132, v130, v131
	v_max_i32_e32 v135, v133, v134
	v_max_i32_e32 v40, v39, v34
	v_max_i32_e32 v42, v38, v37
	v_min_i32_e32 v45, v35, v41
	v_min_i32_e32 v44, v36, v43
	v_min_i32_e32 v129, v125, v128
	v_max_i32_e32 v47, v40, v42
	v_max_i32_e32 v46, v45, v44
	v_min_i32_e32 v40, v40, v42
	v_min_i32_e32 v42, v45, v44
	v_max_i32_e32 v45, v125, v128
	v_max_i32_e32 v125, v132, v135
	v_min_i32_e32 v128, v45, v125
	v_min_i32_e32 v34, v39, v34
	v_max_i32_e32 v39, v126, v127
	v_max_i32_e32 v35, v35, v41
	v_max_i32_e32 v41, v82, v124
	v_max_i32_e32 v148, v45, v125
	ds_read_b128 v[124:127], v95
	v_max_i32_e32 v44, v40, v42
	v_min_i32_e32 v138, v40, v42
	v_min_i32_e32 v40, v133, v134
	v_min_i32_e32 v37, v38, v37
	v_min_i32_e32 v38, v130, v131
	v_max_i32_e32 v36, v36, v43
	v_min_i32_e32 v136, v132, v135
	v_min_i32_e32 v133, v40, v34
	v_min_i32_e32 v134, v37, v38
	v_max_i32_e32 v34, v40, v34
	v_max_i32_e32 v37, v37, v38
	v_min_i32_e32 v40, v39, v35
	v_min_i32_e32 v42, v36, v41
	v_max_i32_e32 v144, v39, v35
	v_max_i32_e32 v145, v36, v41
	v_max_i32_e32 v137, v129, v136
	v_min_i32_e32 v136, v129, v136
	v_max_i32_e32 v140, v133, v134
	v_min_i32_e32 v141, v34, v37
	v_max_i32_e32 v143, v40, v42
	v_min_i32_e32 v146, v144, v145
	v_max_i32_e32 v149, v47, v46
	v_min_i32_e32 v48, v47, v46
	v_max_i32_e32 v139, v138, v136
	v_max_i32_e32 v142, v140, v141
	v_min_i32_e32 v43, v40, v42
	v_max_i32_e32 v34, v34, v37
	v_min_i32_e32 v147, v143, v146
	v_min_i32_e32 v150, v148, v149
	v_min_i32_e32 v49, v137, v48
	v_min_i32_e32 v132, v44, v128
	v_max_i32_e32 v38, v139, v142
	v_min_i32_e32 v37, v43, v34
	v_max_i32_e32 v34, v43, v34
	v_min_i32_e32 v35, v147, v150
	v_max_i32_e32 v39, v137, v48
	v_max_i32_e32 v40, v44, v128
	v_max_i32_e32 v135, v49, v132
	v_max_i32_e32 v82, v38, v37
	v_min_i32_e32 v36, v34, v35
	v_min_i32_e32 v41, v39, v40
	v_max_i32_e32 v129, v135, v82
	v_min_i32_e32 v42, v36, v41
	v_min_i32_e32 v137, v129, v42
	v_max_i32_e32 v159, v129, v42
	ds_read_b128 v[128:131], v95 offset:32
	v_min_i32_e32 v82, v135, v82
	v_min_i32_e32 v132, v49, v132
	v_min_i32_e32 v135, v38, v37
	v_max_i32_e32 v154, v34, v35
	v_max_i32_e32 v155, v39, v40
	v_max_i32_e32 v157, v36, v41
	s_waitcnt lgkmcnt(1)
; #define LAS __attribute__((address_space(3)))
; #define MFMA32(a, b, c) __builtin_amdgcn_mfma_f32_32x32x16_bf16((a), (b), (c), 0, 0, 0)
; #define CE_(a, b) ce_desc(v[a], v[b])
; __device__ __forceinline__ void sort16_desc(int (&v)[16]) {
;     ...
;     CE_(0,13); CE_(1,12); CE_(2,15); CE_(3,14); CE_(4,8); CE_(5,6); CE_(7,11); CE_(9,10);
;     CE_(0,5); CE_(1,7); CE_(2,9); CE_(3,4); CE_(6,13); CE_(8,14); CE_(10,15); CE_(11,12);
;     CE_(0,1); CE_(2,3); CE_(4,5); CE_(6,8); CE_(7,9); CE_(10,11); CE_(12,13); CE_(14,15);
;     CE_(0,2); CE_(1,3); CE_(4,10); CE_(5,11); CE_(6,7); CE_(8,9); CE_(12,14); CE_(13,15);
;     CE_(1,2); CE_(3,12); CE_(4,6); CE_(5,7); CE_(8,10); CE_(9,11); CE_(13,14);
;     CE_(1,4); CE_(2,6); CE_(5,8); CE_(7,10); CE_(9,13); CE_(11,14);
;     CE_(2,4); CE_(3,6); CE_(9,12); CE_(11,13);
;     CE_(3,5); CE_(6,8); CE_(7,9); CE_(10,12);
;     CE_(3,4); CE_(5,6); CE_(7,8); CE_(9,10); CE_(11,12);
;     CE_(6,7); CE_(8,9);
;     ...
; }
; __device__ __forceinline__ void route_task(int task, int tl0, const bf16* QP  , const LAS bf16* KHL, LAS unsigned short* EL, LAS float* GL, int lane) {
;     ...
;         for (int kt = 0; kt < 4; ++kt) {
;             f32x16 X;
; #pragma unroll
;             for (int i = 0; i < 16; ++i) X[i] = 8.f;
;             const LAS bf16* khp = KHL + (half * 128 + 32 * kt + r) * 72 + 8 * hi;
; #pragma unroll
;             for (int ks = 0; ks < 4; ++ks) {
;                 const bf16x8 kh = lds8(khp + 16 * ks);
;                 X = MFMA32(kh, qa[half][ks], X);
;             }
;             int grp[16];
; #pragma unroll
;             for (int i = 0; i < 16; ++i) grp[i] = (int)((__float_as_uint(X[i]) | 127u) - (unsigned)(32 * kt + (i & 3) + 8 * (i >> 2)));
;             sort16_desc(grp);
;             if (kt == 0) {
; #pragma unroll
;                 for (int i = 0; i < 16; ++i) cur[i] = grp[i];
;             } else merge16_desc(cur, grp);
	v_mfma_f32_32x32x16_bf16 v[34:49], v[124:127], v[78:81], v[18:33]
	ds_read_b128 v[124:127], v95 offset:64
	v_max_i32_e32 v151, v132, v135
	v_max_i32_e32 v152, v82, v151
	v_min_i32_e32 v136, v138, v136
	v_min_i32_e32 v138, v140, v141
	v_min_i32_e32 v82, v82, v151
	v_max_i32_e32 v147, v147, v150
	s_waitcnt lgkmcnt(1)
	v_mfma_f32_32x32x16_bf16 v[34:49], v[128:131], v[74:77], v[34:49]
	ds_read_b128 v[128:131], v95 offset:96
	v_max_i32_e32 v143, v143, v146
	v_min_i32_e32 v133, v133, v134
	v_min_i32_e32 v156, v154, v155
	v_max_i32_e32 v140, v136, v138
	v_min_i32_e32 v139, v139, v142
	v_max_i32_e32 v142, v154, v155
	s_waitcnt lgkmcnt(1)
	v_mfma_f32_32x32x16_bf16 v[34:49], v[124:127], v[70:73], v[34:49]
	v_max_i32_e32 v124, v148, v149
	v_min_i32_e32 v136, v136, v138
	v_max_i32_e32 v141, v140, v139
	v_min_i32_e32 v139, v140, v139
	v_min_i32_e32 v125, v143, v124
	v_min_i32_e32 v158, v156, v157
	v_min_i32_e32 v132, v132, v135
	s_waitcnt lgkmcnt(0)
	v_mfma_f32_32x32x16_bf16 v[34:49], v[128:131], v[66:69], v[34:49]
	v_min_i32_e32 v126, v147, v125
	v_min_i32_e32 v153, v137, v152
	v_min_i32_e32 v160, v158, v159
	v_min_i32_e32 v135, v141, v132
	v_min_i32_e32 v127, v142, v126
	s_nop 6
	v_or_b32_e32 v37, 0x7f, v37
	v_or_b32_e32 v48, 0x7f, v48
	v_or_b32_e32 v38, 0x7f, v38
	v_or_b32_e32 v42, 0x7f, v42
	v_or_b32_e32 v34, 0x7f, v34
	v_or_b32_e32 v47, 0x7f, v47
	v_or_b32_e32 v39, 0x7f, v39
	v_or_b32_e32 v40, 0x7f, v40
	v_or_b32_e32 v43, 0x7f, v43
	v_or_b32_e32 v44, 0x7f, v44
	v_or_b32_e32 v36, 0x7f, v36
	v_or_b32_e32 v49, 0x7f, v49
	v_or_b32_e32 v41, 0x7f, v41
	v_or_b32_e32 v45, 0x7f, v45
	v_or_b32_e32 v35, 0x7f, v35
	v_or_b32_e32 v46, 0x7f, v46
	v_subrev_u32_e32 v37, 35, v37
	v_subrev_u32_e32 v48, 58, v48
	v_subrev_u32_e32 v38, 40, v38
	v_subrev_u32_e32 v42, 48, v42
	v_subrev_u32_e32 v34, 32, v34
	v_subrev_u32_e32 v47, 57, v47
	v_subrev_u32_e32 v39, 41, v39
	v_subrev_u32_e32 v40, 42, v40
	v_subrev_u32_e32 v43, 49, v43
	v_subrev_u32_e32 v44, 50, v44
	v_subrev_u32_e32 v36, 34, v36
	v_subrev_u32_e32 v49, 59, v49
	v_subrev_u32_e32 v41, 43, v41
	v_subrev_u32_e32 v45, 51, v45
	v_subrev_u32_e32 v35, 33, v35
	v_subrev_u32_e32 v46, 56, v46
	v_max_i32_e32 v128, v37, v48
	v_max_i32_e32 v129, v38, v42
	v_max_i32_e32 v131, v34, v47
	v_max_i32_e32 v134, v39, v40
	v_min_i32_e32 v146, v43, v44
	v_min_i32_e32 v148, v36, v49
	v_min_i32_e32 v150, v41, v45
	v_min_i32_e32 v151, v35, v46
	v_min_i32_e32 v39, v39, v40
	v_min_i32_e32 v34, v34, v47
	v_min_i32_e32 v38, v38, v42
	v_min_i32_e32 v37, v37, v48
	v_max_i32_e32 v35, v35, v46
	v_max_i32_e32 v41, v41, v45
	v_max_i32_e32 v36, v36, v49
	v_max_i32_e32 v43, v43, v44
	v_min_i32_e32 v130, v128, v129
	v_min_i32_e32 v138, v131, v134
	v_max_i32_e32 v149, v146, v148
	v_max_i32_e32 v154, v150, v151
	v_max_i32_e32 v40, v39, v34
	v_max_i32_e32 v42, v38, v37
	v_min_i32_e32 v45, v35, v41
	v_min_i32_e32 v44, v36, v43
	v_min_i32_e32 v150, v150, v151
	v_min_i32_e32 v34, v39, v34
	v_min_i32_e32 v37, v38, v37
	v_min_i32_e32 v38, v146, v148
	v_max_i32_e32 v131, v131, v134
	v_max_i32_e32 v35, v35, v41
	v_max_i32_e32 v36, v36, v43
	v_max_i32_e32 v43, v128, v129
	v_min_i32_e32 v140, v130, v138
	v_min_i32_e32 v155, v149, v154
	v_max_i32_e32 v47, v40, v42
	v_max_i32_e32 v46, v45, v44
	v_min_i32_e32 v40, v40, v42
	v_min_i32_e32 v42, v45, v44
	v_max_i32_e32 v45, v130, v138
	v_max_i32_e32 v130, v149, v154
	v_min_i32_e32 v39, v150, v34
	v_min_i32_e32 v146, v37, v38
	v_max_i32_e32 v34, v150, v34
	v_max_i32_e32 v37, v37, v38
	v_min_i32_e32 v41, v131, v35
	v_min_i32_e32 v128, v36, v43
	v_max_i32_e32 v35, v131, v35
	v_max_i32_e32 v36, v36, v43
	v_min_i32_e32 v48, v47, v46
	v_max_i32_e32 v44, v40, v42
	v_min_i32_e32 v138, v45, v130
	v_min_i32_e32 v40, v40, v42
	v_min_i32_e32 v42, v140, v155
	v_max_i32_e32 v148, v39, v146
	v_min_i32_e32 v38, v34, v37
	v_min_i32_e32 v129, v41, v128
	v_max_i32_e32 v41, v41, v128
	v_min_i32_e32 v43, v35, v36
	v_max_i32_e32 v45, v45, v130
	v_max_i32_e32 v46, v47, v46
	v_max_i32_e32 v161, v140, v155
	v_max_i32_e32 v140, v40, v42
	v_max_i32_e32 v150, v148, v38
	v_max_i32_e32 v34, v34, v37
	v_min_i32_e32 v128, v41, v43
	v_min_i32_e32 v47, v45, v46
	v_min_i32_e32 v49, v161, v48
	v_min_i32_e32 v149, v44, v138
	v_max_i32_e32 v151, v140, v150
	v_min_i32_e32 v37, v129, v34
	v_max_i32_e32 v34, v129, v34
	v_min_i32_e32 v129, v128, v47
	v_max_i32_e32 v48, v161, v48
	v_max_i32_e32 v44, v44, v138
	v_max_i32_e32 v154, v49, v149
	v_max_i32_e32 v134, v151, v37
	v_min_i32_e32 v130, v34, v129
	v_min_i32_e32 v131, v48, v44
	v_min_i32_e32 v49, v49, v149
	v_min_i32_e32 v37, v151, v37
	v_max_i32_e32 v34, v34, v129
	v_max_i32_e32 v44, v48, v44
	v_min_i32_e32 v40, v40, v42
	v_min_i32_e32 v38, v148, v38
	v_max_i32_e32 v41, v41, v43
	v_max_i32_e32 v43, v45, v46
	v_max_i32_e32 v155, v154, v134
	v_min_i32_e32 v138, v130, v131
	v_min_i32_e32 v134, v154, v134
	v_max_i32_e32 v149, v49, v37
	v_min_i32_e32 v48, v34, v44
	v_max_i32_e32 v129, v130, v131
	v_max_i32_e32 v42, v40, v38
	v_min_i32_e32 v140, v140, v150
	v_max_i32_e32 v34, v34, v44
	v_max_i32_e32 v44, v128, v47
	v_min_i32_e32 v45, v41, v43
	v_min_i32_e32 v161, v155, v138
	v_max_i32_e32 v151, v134, v149
	v_min_i32_e32 v130, v48, v129
	v_max_i32_e32 v131, v155, v138
	v_max_i32_e32 v148, v42, v140
	v_min_i32_e32 v37, v49, v37
	v_min_i32_e32 v46, v44, v45
	v_min_i32_e32 v154, v161, v151
	v_min_i32_e32 v138, v130, v131
	v_min_i32_e32 v49, v148, v37
	v_min_i32_e32 v134, v134, v149
	v_min_i32_e32 v47, v34, v46
	v_min_i32_e32 v42, v42, v140
	v_min_i32_e32 v38, v40, v38
	v_min_i32_e32 v39, v39, v146
	v_max3_i32 v39, v144, v145, v39
	v_max3_i32 v38, v143, v124, v38
	v_max3_i32 v40, v147, v125, v42
; #define LAS __attribute__((address_space(3)))
; #define MFMA32(a, b, c) __builtin_amdgcn_mfma_f32_32x32x16_bf16((a), (b), (c), 0, 0, 0)
; #define CE_(a, b) ce_desc(v[a], v[b])
; __device__ __forceinline__ void sort16_desc(int (&v)[16]) {
;     ...
;     CE_(0,13); CE_(1,12); CE_(2,15); CE_(3,14); CE_(4,8); CE_(5,6); CE_(7,11); CE_(9,10);
;     CE_(0,5); CE_(1,7); CE_(2,9); CE_(3,4); CE_(6,13); CE_(8,14); CE_(10,15); CE_(11,12);
;     CE_(0,1); CE_(2,3); CE_(4,5); CE_(6,8); CE_(7,9); CE_(10,11); CE_(12,13); CE_(14,15);
;     CE_(0,2); CE_(1,3); CE_(4,10); CE_(5,11); CE_(6,7); CE_(8,9); CE_(12,14); CE_(13,15);
;     CE_(1,2); CE_(3,12); CE_(4,6); CE_(5,7); CE_(8,10); CE_(9,11); CE_(13,14);
;     CE_(1,4); CE_(2,6); CE_(5,8); CE_(7,10); CE_(9,13); CE_(11,14);
;     CE_(2,4); CE_(3,6); CE_(9,12); CE_(11,13);
;     CE_(3,5); CE_(6,8); CE_(7,9); CE_(10,12);
;     CE_(3,4); CE_(5,6); CE_(7,8); CE_(9,10); CE_(11,12);
;     CE_(6,7); CE_(8,9);
;     ...
; }
; __device__ __forceinline__ void merge16_desc(int (&a)[16], const int (&b)[16]) {
; #pragma unroll
;     for (int i = 0; i < 16; ++i) a[i] = a[i] > b[15 - i] ? a[i] : b[15 - i];
; #pragma unroll
;     for (int j = 8; j > 0; j >>= 1)
; #pragma unroll
;         for (int i = 0; i < 16; ++i) { const int l = i ^ j; if (l > i) ce_desc(a[i], a[l]); }
; }
; __device__ __forceinline__ void route_task(int task, int tl0, const bf16* QP  , const LAS bf16* KHL, LAS unsigned short* EL, LAS float* GL, int lane) {
;     ...
;         for (int kt = 0; kt < 4; ++kt) {
;             f32x16 X;
; #pragma unroll
;             for (int i = 0; i < 16; ++i) X[i] = 8.f;
;             const LAS bf16* khp = KHL + (half * 128 + 32 * kt + r) * 72 + 8 * hi;
; #pragma unroll
;             for (int ks = 0; ks < 4; ++ks) {
;                 const bf16x8 kh = lds8(khp + 16 * ks);
;                 X = MFMA32(kh, qa[half][ks], X);
;             }
;             int grp[16];
; #pragma unroll
;             for (int i = 0; i < 16; ++i) grp[i] = (int)((__float_as_uint(X[i]) | 127u) - (unsigned)(32 * kt + (i & 3) + 8 * (i >> 2)));
;             sort16_desc(grp);
;             if (kt == 0) {
; #pragma unroll
;                 for (int i = 0; i < 16; ++i) cur[i] = grp[i];
;             } else merge16_desc(cur, grp);
	v_max3_i32 v42, v142, v126, v49
	v_max3_i32 v37, v127, v148, v37
	v_max3_i32 v49, v156, v157, v134
	v_max3_i32 v124, v158, v159, v154
	v_max3_i32 v125, v160, v161, v151
	v_max3_i32 v126, v137, v152, v138
	v_max3_i32 v127, v153, v130, v131
	v_max3_i32 v48, v82, v48, v129
	v_max3_i32 v47, v141, v132, v47
	v_max3_i32 v34, v135, v34, v46
	v_max3_i32 v44, v139, v44, v45
	v_max3_i32 v41, v136, v41, v43
	v_max3_i32 v35, v133, v35, v36
	v_max_i32_e32 v36, v39, v126
	v_min_i32_e32 v39, v39, v126
	v_max_i32_e32 v43, v38, v127
	v_min_i32_e32 v38, v38, v127
	v_max_i32_e32 v45, v40, v48
	v_min_i32_e32 v40, v40, v48
	v_max_i32_e32 v46, v42, v47
	v_min_i32_e32 v42, v42, v47
	v_max_i32_e32 v47, v37, v34
	v_min_i32_e32 v34, v37, v34
	v_max_i32_e32 v37, v49, v44
	v_min_i32_e32 v44, v49, v44
	v_max_i32_e32 v48, v124, v41
	v_min_i32_e32 v41, v124, v41
	v_max_i32_e32 v49, v125, v35
	v_min_i32_e32 v35, v125, v35
	ds_read_b128 v[124:127], v94 offset:9216
	ds_read_b128 v[128:131], v94 offset:9248
	v_max_i32_e32 v82, v36, v47
	v_min_i32_e32 v132, v36, v47
	v_max_i32_e32 v36, v43, v37
	v_min_i32_e32 v133, v43, v37
	v_max_i32_e32 v37, v45, v48
	v_max_i32_e32 v43, v46, v49
	v_min_i32_e32 v134, v45, v48
	v_min_i32_e32 v135, v46, v49
	v_max_i32_e32 v136, v39, v34
	v_min_i32_e32 v137, v39, v34
	v_max_i32_e32 v138, v38, v44
	v_min_i32_e32 v139, v38, v44
	v_max_i32_e32 v140, v40, v41
	v_min_i32_e32 v141, v40, v41
	v_max_i32_e32 v142, v42, v35
	v_min_i32_e32 v143, v42, v35
	v_max_i32_e32 v144, v82, v37
	v_min_i32_e32 v82, v82, v37
	v_max_i32_e32 v145, v36, v43
	v_min_i32_e32 v146, v36, v43
	s_waitcnt lgkmcnt(1)
	v_mfma_f32_32x32x16_bf16 v[34:49], v[124:127], v[78:81], v[18:33]
	ds_read_b128 v[124:127], v94 offset:9280
	v_max_i32_e32 v147, v132, v134
	v_min_i32_e32 v132, v132, v134
	v_max_i32_e32 v134, v133, v135
	v_min_i32_e32 v133, v133, v135
	v_max_i32_e32 v135, v136, v140
	v_min_i32_e32 v136, v136, v140
	s_waitcnt lgkmcnt(1)
	v_mfma_f32_32x32x16_bf16 v[34:49], v[128:131], v[74:77], v[34:49]
	ds_read_b128 v[128:131], v94 offset:9312
	v_max_i32_e32 v140, v138, v142
	v_min_i32_e32 v138, v138, v142
	v_max_i32_e32 v142, v137, v141
	v_min_i32_e32 v137, v137, v141
	v_max_i32_e32 v141, v139, v143
	v_min_i32_e32 v139, v139, v143
	s_waitcnt lgkmcnt(1)
	v_mfma_f32_32x32x16_bf16 v[34:49], v[124:127], v[70:73], v[34:49]
	v_min_i32_e32 v143, v144, v145
	v_min_i32_e32 v124, v82, v146
	v_min_i32_e32 v127, v135, v140
	v_min_i32_e32 v125, v147, v134
	v_min_i32_e32 v126, v132, v133
	v_min_i32_e32 v149, v142, v141
	v_min_i32_e32 v148, v136, v138
	s_waitcnt lgkmcnt(0)
	v_mfma_f32_32x32x16_bf16 v[34:49], v[128:131], v[66:69], v[34:49]
	v_min_i32_e32 v150, v137, v139
	s_nop 10
	v_or_b32_e32 v37, 0x7f, v37
	v_or_b32_e32 v48, 0x7f, v48
	v_or_b32_e32 v38, 0x7f, v38
	v_or_b32_e32 v42, 0x7f, v42
	v_or_b32_e32 v34, 0x7f, v34
	v_or_b32_e32 v47, 0x7f, v47
	v_or_b32_e32 v39, 0x7f, v39
	v_or_b32_e32 v40, 0x7f, v40
	v_or_b32_e32 v43, 0x7f, v43
	v_or_b32_e32 v44, 0x7f, v44
	v_or_b32_e32 v36, 0x7f, v36
	v_or_b32_e32 v49, 0x7f, v49
	v_or_b32_e32 v41, 0x7f, v41
	v_or_b32_e32 v45, 0x7f, v45
	v_or_b32_e32 v35, 0x7f, v35
	v_or_b32_e32 v46, 0x7f, v46
	v_add_u32_e32 v37, 0xffffffbd, v37
	v_add_u32_e32 v48, 0xffffffa6, v48
	v_add_u32_e32 v38, 0xffffffb8, v38
	v_add_u32_e32 v42, 0xffffffb0, v42
	v_subrev_u32_e32 v34, 64, v34
	v_add_u32_e32 v47, 0xffffffa7, v47
	v_add_u32_e32 v39, 0xffffffb7, v39
	v_add_u32_e32 v40, 0xffffffb6, v40
	v_add_u32_e32 v43, 0xffffffaf, v43
	v_add_u32_e32 v44, 0xffffffae, v44
	v_add_u32_e32 v36, 0xffffffbe, v36
	v_add_u32_e32 v49, 0xffffffa5, v49
	v_add_u32_e32 v41, 0xffffffb5, v41
	v_add_u32_e32 v45, 0xffffffad, v45
	v_add_u32_e32 v35, 0xffffffbf, v35
	v_add_u32_e32 v46, 0xffffffa8, v46
	v_max_i32_e32 v128, v37, v48
	v_max_i32_e32 v129, v38, v42
	v_max_i32_e32 v131, v34, v47
	v_max_i32_e32 v151, v39, v40
	v_min_i32_e32 v154, v43, v44
	v_min_i32_e32 v155, v36, v49
	v_min_i32_e32 v157, v41, v45
	v_min_i32_e32 v158, v35, v46
	v_min_i32_e32 v39, v39, v40
	v_min_i32_e32 v34, v34, v47
	v_min_i32_e32 v38, v38, v42
	v_min_i32_e32 v37, v37, v48
	v_max_i32_e32 v35, v35, v46
	v_max_i32_e32 v41, v41, v45
	v_max_i32_e32 v36, v36, v49
	v_max_i32_e32 v43, v43, v44
	v_min_i32_e32 v130, v128, v129
	v_min_i32_e32 v152, v131, v151
	v_max_i32_e32 v156, v154, v155
	v_max_i32_e32 v159, v157, v158
	v_max_i32_e32 v40, v39, v34
	v_max_i32_e32 v42, v38, v37
	v_min_i32_e32 v45, v35, v41
	v_min_i32_e32 v44, v36, v43
	v_min_i32_e32 v157, v157, v158
	v_min_i32_e32 v34, v39, v34
	v_min_i32_e32 v37, v38, v37
	v_min_i32_e32 v38, v154, v155
	v_max_i32_e32 v131, v131, v151
	v_max_i32_e32 v35, v35, v41
	v_max_i32_e32 v36, v36, v43
	v_max_i32_e32 v43, v128, v129
	v_min_i32_e32 v153, v130, v152
	v_min_i32_e32 v160, v156, v159
	v_max_i32_e32 v47, v40, v42
	v_max_i32_e32 v46, v45, v44
	v_min_i32_e32 v40, v40, v42
	v_min_i32_e32 v42, v45, v44
	v_max_i32_e32 v45, v130, v152
	v_max_i32_e32 v130, v156, v159
	v_min_i32_e32 v39, v157, v34
	v_min_i32_e32 v154, v37, v38
	v_max_i32_e32 v34, v157, v34
	v_max_i32_e32 v37, v37, v38
	v_min_i32_e32 v41, v131, v35
	v_min_i32_e32 v128, v36, v43
	v_max_i32_e32 v35, v131, v35
	v_max_i32_e32 v36, v36, v43
	v_min_i32_e32 v48, v47, v46
	v_max_i32_e32 v44, v40, v42
	v_min_i32_e32 v152, v45, v130
	v_min_i32_e32 v40, v40, v42
	v_min_i32_e32 v42, v153, v160
	v_max_i32_e32 v155, v39, v154
	v_min_i32_e32 v38, v34, v37
	v_min_i32_e32 v129, v41, v128
	v_max_i32_e32 v41, v41, v128
	v_min_i32_e32 v43, v35, v36
	v_max_i32_e32 v45, v45, v130
	v_max_i32_e32 v46, v47, v46
	v_max_i32_e32 v161, v153, v160
	v_max_i32_e32 v153, v40, v42
	v_max_i32_e32 v157, v155, v38
	v_max_i32_e32 v34, v34, v37
; #define LAS __attribute__((address_space(3)))
; #define MFMA32(a, b, c) __builtin_amdgcn_mfma_f32_32x32x16_bf16((a), (b), (c), 0, 0, 0)
; #define CE_(a, b) ce_desc(v[a], v[b])
; __device__ __forceinline__ void sort16_desc(int (&v)[16]) {
;     ...
;     CE_(0,13); CE_(1,12); CE_(2,15); CE_(3,14); CE_(4,8); CE_(5,6); CE_(7,11); CE_(9,10);
;     CE_(0,5); CE_(1,7); CE_(2,9); CE_(3,4); CE_(6,13); CE_(8,14); CE_(10,15); CE_(11,12);
;     CE_(0,1); CE_(2,3); CE_(4,5); CE_(6,8); CE_(7,9); CE_(10,11); CE_(12,13); CE_(14,15);
;     CE_(0,2); CE_(1,3); CE_(4,10); CE_(5,11); CE_(6,7); CE_(8,9); CE_(12,14); CE_(13,15);
;     CE_(1,2); CE_(3,12); CE_(4,6); CE_(5,7); CE_(8,10); CE_(9,11); CE_(13,14);
;     CE_(1,4); CE_(2,6); CE_(5,8); CE_(7,10); CE_(9,13); CE_(11,14);
;     CE_(2,4); CE_(3,6); CE_(9,12); CE_(11,13);
;     CE_(3,5); CE_(6,8); CE_(7,9); CE_(10,12);
;     CE_(3,4); CE_(5,6); CE_(7,8); CE_(9,10); CE_(11,12);
;     CE_(6,7); CE_(8,9);
;     ...
; }
; __device__ __forceinline__ void merge16_desc(int (&a)[16], const int (&b)[16]) {
; #pragma unroll
;     for (int i = 0; i < 16; ++i) a[i] = a[i] > b[15 - i] ? a[i] : b[15 - i];
; #pragma unroll
;     for (int j = 8; j > 0; j >>= 1)
; #pragma unroll
;         for (int i = 0; i < 16; ++i) { const int l = i ^ j; if (l > i) ce_desc(a[i], a[l]); }
; }
; __device__ __forceinline__ void route_task(int task, int tl0, const bf16* QP  , const LAS bf16* KHL, LAS unsigned short* EL, LAS float* GL, int lane) {
;     ...
;         for (int kt = 0; kt < 4; ++kt) {
;             f32x16 X;
; #pragma unroll
;             for (int i = 0; i < 16; ++i) X[i] = 8.f;
;             const LAS bf16* khp = KHL + (half * 128 + 32 * kt + r) * 72 + 8 * hi;
; #pragma unroll
;             for (int ks = 0; ks < 4; ++ks) {
;                 const bf16x8 kh = lds8(khp + 16 * ks);
;                 X = MFMA32(kh, qa[half][ks], X);
;             }
;             int grp[16];
; #pragma unroll
;             for (int i = 0; i < 16; ++i) grp[i] = (int)((__float_as_uint(X[i]) | 127u) - (unsigned)(32 * kt + (i & 3) + 8 * (i >> 2)));
;             sort16_desc(grp);
;             if (kt == 0) {
; #pragma unroll
;                 for (int i = 0; i < 16; ++i) cur[i] = grp[i];
;             } else merge16_desc(cur, grp);
	v_min_i32_e32 v128, v41, v43
	v_min_i32_e32 v47, v45, v46
	v_min_i32_e32 v49, v161, v48
	v_min_i32_e32 v156, v44, v152
	v_max_i32_e32 v158, v153, v157
	v_min_i32_e32 v37, v129, v34
	v_max_i32_e32 v34, v129, v34
	v_min_i32_e32 v129, v128, v47
	v_max_i32_e32 v48, v161, v48
	v_max_i32_e32 v44, v44, v152
	v_min_i32_e32 v40, v40, v42
	v_min_i32_e32 v38, v155, v38
	v_max_i32_e32 v159, v49, v156
	v_max_i32_e32 v151, v158, v37
	v_min_i32_e32 v130, v34, v129
	v_min_i32_e32 v131, v48, v44
	v_min_i32_e32 v49, v49, v156
	v_min_i32_e32 v37, v158, v37
	v_max_i32_e32 v34, v34, v129
	v_max_i32_e32 v44, v48, v44
	v_max_i32_e32 v42, v40, v38
	v_min_i32_e32 v153, v153, v157
	v_max_i32_e32 v160, v159, v151
	v_min_i32_e32 v152, v130, v131
	v_max_i32_e32 v156, v49, v37
	v_min_i32_e32 v48, v34, v44
	v_max_i32_e32 v129, v130, v131
	v_max_i32_e32 v155, v42, v153
	v_min_i32_e32 v37, v49, v37
	v_min_i32_e32 v151, v159, v151
	v_min_i32_e32 v130, v48, v129
	v_max_i32_e32 v131, v160, v152
	v_min_i32_e32 v49, v155, v37
	v_max_i32_e32 v41, v41, v43
	v_max_i32_e32 v43, v45, v46
	v_min_i32_e32 v42, v42, v153
	v_min_i32_e32 v38, v40, v38
	v_min_i32_e32 v161, v160, v152
	v_max_i32_e32 v158, v151, v156
	v_min_i32_e32 v151, v151, v156
	v_max_i32_e32 v34, v34, v44
	v_max_i32_e32 v44, v128, v47
	v_min_i32_e32 v45, v41, v43
	v_max_i32_e32 v40, v41, v43
	v_max_i32_e32 v38, v143, v38
	v_max3_i32 v41, v82, v146, v42
	v_max_i32_e32 v42, v124, v49
	v_max3_i32 v124, v127, v130, v131
	v_min_i32_e32 v46, v44, v45
	v_max_i32_e32 v43, v125, v151
	v_max3_i32 v49, v126, v161, v158
	v_max3_i32 v44, v149, v44, v45
	v_max_i32_e32 v45, v38, v124
	v_min_i32_e32 v38, v38, v124
	ds_read_b128 v[124:127], v96
	v_min_i32_e32 v159, v161, v158
	v_min_i32_e32 v152, v130, v131
	v_max_i32_e32 v37, v155, v37
	v_max_i32_e32 v48, v48, v129
	v_min_i32_e32 v47, v34, v46
	v_max_i32_e32 v34, v34, v46
	v_min_i32_e32 v39, v39, v154
	v_max3_i32 v39, v144, v145, v39
	v_max3_i32 v37, v147, v134, v37
	v_max3_i32 v46, v132, v133, v159
	v_max3_i32 v82, v135, v140, v152
	v_max3_i32 v48, v136, v138, v48
	v_max_i32_e32 v47, v148, v47
	v_max3_i32 v34, v142, v141, v34
	v_max3_i32 v40, v137, v139, v40
	v_max3_i32 v35, v150, v35, v36
	v_max_i32_e32 v36, v39, v82
	v_min_i32_e32 v39, v39, v82
	v_max_i32_e32 v82, v41, v48
	v_min_i32_e32 v41, v41, v48
	v_max_i32_e32 v48, v42, v47
	v_min_i32_e32 v42, v42, v47
	v_max_i32_e32 v47, v37, v34
	v_min_i32_e32 v34, v37, v34
	v_max_i32_e32 v37, v43, v44
	v_min_i32_e32 v43, v43, v44
	v_max_i32_e32 v44, v46, v40
	v_min_i32_e32 v40, v46, v40
	v_max_i32_e32 v46, v49, v35
	v_min_i32_e32 v35, v49, v35
	v_max_i32_e32 v49, v36, v47
	v_min_i32_e32 v132, v36, v47
	v_max_i32_e32 v36, v45, v37
	v_min_i32_e32 v133, v45, v37
	v_max_i32_e32 v37, v82, v44
	v_min_i32_e32 v82, v82, v44
	v_max_i32_e32 v44, v48, v46
	ds_read_b128 v[128:131], v96 offset:32
	v_min_i32_e32 v134, v48, v46
	v_max_i32_e32 v135, v39, v34
	v_min_i32_e32 v136, v39, v34
	v_max_i32_e32 v137, v38, v43
	v_min_i32_e32 v138, v38, v43
	v_max_i32_e32 v139, v41, v40
	v_min_i32_e32 v140, v41, v40
	v_max_i32_e32 v141, v42, v35
	v_min_i32_e32 v142, v42, v35
	v_max_i32_e32 v143, v49, v37
	v_min_i32_e32 v144, v49, v37
	v_max_i32_e32 v145, v36, v44
	v_min_i32_e32 v146, v36, v44
	s_waitcnt lgkmcnt(1)
	v_mfma_f32_32x32x16_bf16 v[34:49], v[124:127], v[78:81], v[18:33]
	ds_read_b128 v[78:81], v96 offset:64
	v_max_i32_e32 v147, v132, v82
	v_min_i32_e32 v82, v132, v82
	v_max_i32_e32 v132, v137, v141
	v_max_i32_e32 v124, v133, v134
	v_min_i32_e32 v125, v133, v134
	v_max_i32_e32 v126, v135, v139
	s_waitcnt lgkmcnt(1)
	v_mfma_f32_32x32x16_bf16 v[34:49], v[128:131], v[74:77], v[34:49]
	ds_read_b128 v[74:77], v96 offset:96
	v_min_i32_e32 v128, v137, v141
	v_max_i32_e32 v129, v136, v140
	v_min_i32_e32 v130, v136, v140
	v_min_i32_e32 v127, v135, v139
	v_max_i32_e32 v131, v138, v142
	v_min_i32_e32 v133, v138, v142
	s_waitcnt lgkmcnt(1)
	v_mfma_f32_32x32x16_bf16 v[34:49], v[78:81], v[70:73], v[34:49]
	v_min_i32_e32 v134, v143, v145
	v_min_i32_e32 v70, v144, v146
	v_min_i32_e32 v71, v147, v124
	v_min_i32_e32 v72, v82, v125
	v_min_i32_e32 v73, v126, v132
	v_min_i32_e32 v78, v127, v128
	v_min_i32_e32 v79, v129, v131
	s_waitcnt lgkmcnt(0)
	v_mfma_f32_32x32x16_bf16 v[34:49], v[74:77], v[66:69], v[34:49]
	v_min_i32_e32 v80, v130, v133
	s_nop 10
	v_or_b32_e32 v41, 0x7f, v41
	v_or_b32_e32 v45, 0x7f, v45
	v_or_b32_e32 v35, 0x7f, v35
	v_or_b32_e32 v46, 0x7f, v46
	v_or_b32_e32 v39, 0x7f, v39
	v_or_b32_e32 v40, 0x7f, v40
	v_or_b32_e32 v34, 0x7f, v34
	v_or_b32_e32 v47, 0x7f, v47
	v_or_b32_e32 v38, 0x7f, v38
	v_or_b32_e32 v42, 0x7f, v42
	v_or_b32_e32 v37, 0x7f, v37
	v_or_b32_e32 v48, 0x7f, v48
	v_or_b32_e32 v43, 0x7f, v43
	v_or_b32_e32 v44, 0x7f, v44
	v_or_b32_e32 v36, 0x7f, v36
	v_or_b32_e32 v49, 0x7f, v49
	v_add_u32_e32 v41, 0xffffff95, v41
	v_add_u32_e32 v45, 0xffffff8d, v45
	v_add_u32_e32 v35, 0xffffff9f, v35
	v_add_u32_e32 v46, 0xffffff88, v46
	v_add_u32_e32 v39, 0xffffff97, v39
	v_add_u32_e32 v40, 0xffffff96, v40
	v_add_u32_e32 v34, 0xffffffa0, v34
	v_add_u32_e32 v47, 0xffffff87, v47
	v_add_u32_e32 v38, 0xffffff98, v38
	v_add_u32_e32 v42, 0xffffff90, v42
	v_add_u32_e32 v37, 0xffffff9d, v37
	v_add_u32_e32 v48, 0xffffff86, v48
	v_add_u32_e32 v43, 0xffffff8f, v43
	v_add_u32_e32 v44, 0xffffff8e, v44
	v_add_u32_e32 v36, 0xffffff9e, v36
	v_add_u32_e32 v49, 0xffffff85, v49
	v_min_i32_e32 v66, v41, v45
	v_min_i32_e32 v67, v35, v46
	v_min_i32_e32 v69, v39, v40
	v_min_i32_e32 v74, v34, v47
	v_min_i32_e32 v77, v38, v42
	v_min_i32_e32 v81, v37, v48
	v_min_i32_e32 v136, v43, v44
	v_min_i32_e32 v137, v36, v49
	v_max_i32_e32 v34, v34, v47
	v_max_i32_e32 v39, v39, v40
	v_max_i32_e32 v35, v35, v46
; #define CE_(a, b) ce_desc(v[a], v[b])
; __device__ __forceinline__ void sort16_desc(int (&v)[16]) {
;     ...
;     CE_(0,13); CE_(1,12); CE_(2,15); CE_(3,14); CE_(4,8); CE_(5,6); CE_(7,11); CE_(9,10);
;     CE_(0,5); CE_(1,7); CE_(2,9); CE_(3,4); CE_(6,13); CE_(8,14); CE_(10,15); CE_(11,12);
;     CE_(0,1); CE_(2,3); CE_(4,5); CE_(6,8); CE_(7,9); CE_(10,11); CE_(12,13); CE_(14,15);
;     CE_(0,2); CE_(1,3); CE_(4,10); CE_(5,11); CE_(6,7); CE_(8,9); CE_(12,14); CE_(13,15);
;     CE_(1,2); CE_(3,12); CE_(4,6); CE_(5,7); CE_(8,10); CE_(9,11); CE_(13,14);
;     CE_(1,4); CE_(2,6); CE_(5,8); CE_(7,10); CE_(9,13); CE_(11,14);
;     CE_(2,4); CE_(3,6); CE_(9,12); CE_(11,13);
;     CE_(3,5); CE_(6,8); CE_(7,9); CE_(10,12);
;     CE_(3,4); CE_(5,6); CE_(7,8); CE_(9,10); CE_(11,12);
;     CE_(6,7); CE_(8,9);
;     ...
; }
; __device__ __forceinline__ void merge16_desc(int (&a)[16], const int (&b)[16]) {
; #pragma unroll
;     for (int i = 0; i < 16; ++i) a[i] = a[i] > b[15 - i] ? a[i] : b[15 - i];
; #pragma unroll
;     for (int j = 8; j > 0; j >>= 1)
; #pragma unroll
;         for (int i = 0; i < 16; ++i) { const int l = i ^ j; if (l > i) ce_desc(a[i], a[l]); }
; }
; __device__ __forceinline__ void route_task(int task, int tl0, const bf16* QP  , const LAS bf16* KHL, LAS unsigned short* EL, LAS float* GL, int lane) {
;     ...
;         { const unsigned h4 = 4u * (unsigned)hi;
; #pragma unroll
;           for (int i = 0; i < 16; ++i) cur[i] -= (int)h4; }
;         int oth[16];
; #pragma unroll
;         for (int i = 0; i < 16; ++i) oth[i] = __shfl_xor(cur[i], 32);
;         merge16_desc(cur, oth);
	v_max_i32_e32 v41, v41, v45
	v_max_i32_e32 v36, v36, v49
	v_max_i32_e32 v43, v43, v44
	v_max_i32_e32 v37, v37, v48
	v_max_i32_e32 v38, v38, v42
	v_max_i32_e32 v40, v34, v39
	v_max_i32_e32 v45, v35, v41
	v_max_i32_e32 v44, v36, v43
	v_max_i32_e32 v42, v37, v38
	v_min_i32_e32 v46, v40, v45
	v_min_i32_e32 v47, v44, v42
	v_min_i32_e32 v75, v69, v74
	v_min_i32_e32 v48, v46, v47
	v_max_i32_e32 v46, v46, v47
	v_min_i32_e32 v37, v37, v38
	v_min_i32_e32 v34, v34, v39
	v_max_i32_e32 v39, v136, v137
	v_max_i32_e32 v47, v66, v67
	v_max_i32_e32 v69, v69, v74
	v_max_i32_e32 v74, v77, v81
	v_min_i32_e32 v35, v35, v41
	v_min_i32_e32 v36, v36, v43
	v_min_i32_e32 v68, v66, v67
	v_min_i32_e32 v135, v77, v81
	v_min_i32_e32 v138, v136, v137
	v_max_i32_e32 v38, v37, v34
	v_max_i32_e32 v77, v69, v74
	v_max_i32_e32 v41, v35, v36
	v_min_i32_e32 v34, v37, v34
	v_min_i32_e32 v37, v39, v47
	v_min_i32_e32 v76, v68, v75
	v_min_i32_e32 v139, v135, v138
	v_max_i32_e32 v49, v68, v75
	v_max_i32_e32 v68, v135, v138
	v_max_i32_e32 v40, v40, v45
	v_max_i32_e32 v42, v44, v42
	v_max_i32_e32 v66, v39, v47
	v_max_i32_e32 v43, v77, v41
	v_max_i32_e32 v39, v34, v37
	v_min_i32_e32 v41, v77, v41
	v_min_i32_e32 v69, v69, v74
	v_min_i32_e32 v35, v35, v36
	v_max_i32_e32 v75, v49, v68
	v_min_i32_e32 v44, v40, v42
	v_max_i32_e32 v67, v38, v66
	v_max_i32_e32 v47, v39, v41
	v_max_i32_e32 v36, v69, v35
	v_min_i32_e32 v39, v39, v41
	v_min_i32_e32 v35, v69, v35
	v_min_i32_e32 v34, v34, v37
	v_max_i32_e32 v41, v76, v139
	v_min_i32_e32 v49, v49, v68
	v_min_i32_e32 v45, v46, v44
	v_min_i32_e32 v81, v67, v43
	v_min_i32_e32 v38, v38, v66
	v_max_i32_e32 v37, v35, v34
	v_max_i32_e32 v68, v41, v49
	v_max_i32_e32 v135, v48, v75
	v_min_i32_e32 v136, v45, v81
	v_max_i32_e32 v66, v36, v38
	v_min_i32_e32 v36, v36, v38
	v_max_i32_e32 v69, v37, v68
	v_min_i32_e32 v48, v48, v75
	v_max_i32_e32 v137, v135, v136
	v_max_i32_e32 v74, v47, v66
	v_min_i32_e32 v135, v135, v136
	v_min_i32_e32 v47, v47, v66
	v_max_i32_e32 v38, v39, v36
	v_max_i32_e32 v75, v69, v48
	v_min_i32_e32 v34, v35, v34
	v_min_i32_e32 v35, v41, v49
	v_min_i32_e32 v36, v39, v36
	v_min_i32_e32 v39, v69, v48
	v_max_i32_e32 v44, v46, v44
	v_max_i32_e32 v43, v67, v43
	v_min_i32_e32 v140, v76, v139
	v_min_i32_e32 v77, v137, v74
	v_max_i32_e32 v66, v135, v47
	v_max_i32_e32 v76, v38, v75
	v_min_i32_e32 v47, v135, v47
	v_max_i32_e32 v41, v34, v35
	v_min_i32_e32 v37, v37, v68
	v_min_i32_e32 v48, v36, v39
	v_max_i32_e32 v45, v45, v81
	v_min_i32_e32 v46, v44, v43
	v_min_i32_e32 v38, v38, v75
	v_max_i32_e32 v36, v36, v39
	v_min_i32_e32 v136, v77, v66
	v_max_i32_e32 v135, v76, v47
	v_max_i32_e32 v49, v41, v37
	v_max_i32_e32 v69, v137, v74
	v_min_i32_e32 v67, v45, v46
	v_min_i32_e32 v47, v76, v47
	v_max_i32_e32 v39, v38, v36
	v_min_i32_e32 v138, v136, v135
	v_max_i32_e32 v68, v49, v48
	v_max_i32_e32 v74, v69, v67
	v_min_i32_e32 v37, v41, v37
	v_max_i32_e32 v41, v77, v66
	v_min_i32_e32 v75, v47, v39
	v_max_i32_e32 v43, v44, v43
	v_min_i32_e32 v34, v34, v35
	v_min_i32_e32 v36, v38, v36
	v_min_i32_e32 v48, v49, v48
	v_min_i32_e32 v49, v69, v67
	v_max3_i32 v140, v143, v145, v140
	v_max3_i32 v126, v126, v132, v138
	v_max3_i32 v68, v147, v124, v68
	v_max3_i32 v74, v129, v131, v74
	v_max3_i32 v37, v144, v146, v37
	v_max3_i32 v41, v127, v128, v41
	v_max3_i32 v75, v82, v125, v75
	v_max3_i32 v43, v130, v133, v43
	v_max_i32_e32 v34, v134, v34
	v_max3_i32 v35, v73, v136, v135
	v_max_i32_e32 v36, v71, v36
	v_max3_i32 v38, v79, v45, v46
	v_max_i32_e32 v48, v70, v48
	v_max_i32_e32 v49, v78, v49
	v_max3_i32 v39, v72, v47, v39
	v_max3_i32 v40, v80, v40, v42
	v_min_i32_e32 v81, v68, v74
	v_min_i32_e32 v66, v37, v41
	v_min_i32_e32 v73, v34, v35
	v_min_i32_e32 v45, v36, v38
	v_min_i32_e32 v42, v39, v40
	v_max_i32_e32 v71, v140, v126
	v_max_i32_e32 v68, v68, v74
	v_max_i32_e32 v37, v37, v41
	v_max_i32_e32 v41, v75, v43
	v_max_i32_e32 v34, v34, v35
	v_max_i32_e32 v35, v36, v38
	v_max_i32_e32 v38, v48, v49
	v_max_i32_e32 v39, v39, v40
	v_min_i32_e32 v44, v75, v43
	v_max_i32_e32 v72, v71, v68
	v_max_i32_e32 v43, v37, v41
	v_max_i32_e32 v36, v34, v35
	v_max_i32_e32 v40, v38, v39
	v_min_i32_e32 v67, v48, v49
	v_max_i32_e32 v74, v72, v43
	v_max_i32_e32 v48, v36, v40
	v_min_i32_e32 v43, v72, v43
	v_min_i32_e32 v36, v36, v40
	v_max_i32_e32 v40, v43, v36
	v_min_i32_e32 v36, v43, v36
	v_min_i32_e32 v43, v71, v68
	v_min_i32_e32 v37, v37, v41
	v_min_i32_e32 v34, v34, v35
	v_min_i32_e32 v35, v38, v39
	v_min_i32_e32 v132, v140, v126
	v_max_i32_e32 v41, v43, v37
	v_max_i32_e32 v38, v34, v35
	v_min_i32_e32 v37, v43, v37
	v_min_i32_e32 v34, v34, v35
	v_min_i32_e32 v76, v66, v44
	v_min_i32_e32 v47, v67, v42
	v_max_i32_e32 v39, v41, v38
	v_min_i32_e32 v38, v41, v38
	v_max_i32_e32 v35, v37, v34
	v_min_i32_e32 v34, v37, v34
	v_max_i32_e32 v37, v132, v81
	v_max_i32_e32 v41, v66, v44
	v_max_i32_e32 v44, v73, v45
	v_max_i32_e32 v42, v67, v42
	v_min_i32_e32 v124, v132, v81
	v_min_i32_e32 v46, v73, v45
	v_max_i32_e32 v43, v37, v41
	v_min_i32_e32 v37, v37, v41
	v_min_i32_e32 v41, v44, v42
	v_min_i32_e32 v77, v124, v76
	v_min_i32_e32 v69, v46, v47
	v_max_i32_e32 v45, v44, v42
	v_max_i32_e32 v42, v37, v41
	v_min_i32_e32 v37, v37, v41
	v_max_i32_e32 v41, v124, v76
	v_max_i32_e32 v44, v46, v47
	v_min_i32_e32 v70, v77, v69
	v_max_i32_e32 v49, v74, v48
	v_min_i32_e32 v48, v74, v48
	v_max_i32_e32 v66, v43, v45
	v_min_i32_e32 v43, v43, v45
	v_max_i32_e32 v45, v41, v44
	v_min_i32_e32 v41, v41, v44
	v_max_i32_e32 v44, v77, v69
	v_sub_u32_e32 v46, v49, v87
	v_sub_u32_e32 v47, v48, v87
	v_sub_u32_e32 v40, v40, v87
	v_sub_u32_e32 v36, v36, v87
	v_sub_u32_e32 v39, v39, v87
	v_sub_u32_e32 v38, v38, v87
	v_sub_u32_e32 v35, v35, v87
	v_sub_u32_e32 v34, v34, v87
	v_sub_u32_e32 v48, v66, v87
	v_sub_u32_e32 v43, v43, v87
	v_sub_u32_e32 v42, v42, v87
	v_sub_u32_e32 v37, v37, v87
	v_sub_u32_e32 v45, v45, v87
	v_sub_u32_e32 v41, v41, v87
	v_sub_u32_e32 v44, v44, v87
	v_sub_u32_e32 v49, v70, v87
	ds_bpermute_b32 v66, v123, v46
	ds_bpermute_b32 v67, v123, v47
	ds_bpermute_b32 v68, v123, v40
	ds_bpermute_b32 v69, v123, v36
	ds_bpermute_b32 v70, v123, v39
	ds_bpermute_b32 v71, v123, v38
	ds_bpermute_b32 v72, v123, v35
	ds_bpermute_b32 v73, v123, v34
	ds_bpermute_b32 v74, v123, v48
	ds_bpermute_b32 v75, v123, v43
	ds_bpermute_b32 v76, v123, v42
	ds_bpermute_b32 v77, v123, v49
	ds_bpermute_b32 v78, v123, v44
	ds_bpermute_b32 v79, v123, v41
	ds_bpermute_b32 v80, v123, v45
	ds_bpermute_b32 v81, v123, v37
	s_waitcnt lgkmcnt(4)
; #define LAS __attribute__((address_space(3)))
; #define MFMA32(a, b, c) __builtin_amdgcn_mfma_f32_32x32x16_bf16((a), (b), (c), 0, 0, 0)
; __device__ __forceinline__ void route_task(int task, int tl0, const bf16* QP  , const LAS bf16* KHL, LAS unsigned short* EL, LAS float* GL, int lane) {
;     ...
;         for (int kt = 0; kt < 4; ++kt) {
;             f32x16 X;
; #pragma unroll
;             for (int i = 0; i < 16; ++i) X[i] = 8.f;
;             const LAS bf16* khp = KHL + (half * 128 + 32 * kt + r) * 72 + 8 * hi;
; #pragma unroll
;             for (int ks = 0; ks < 4; ++ks) {
;                 const bf16x8 kh = lds8(khp + 16 * ks);
;                 X = MFMA32(kh, qa[half][ks], X);
;             }
;             int grp[16];
; #pragma unroll
;             for (int i = 0; i < 16; ++i) grp[i] = (int)((__float_as_uint(X[i]) | 127u) - (unsigned)(32 * kt + (i & 3) + 8 * (i >> 2)));
;             sort16_desc(grp);
;     ...
;         for (int i = 0; i < 16; ++i) oth[i] = __shfl_xor(cur[i], 32);
;         merge16_desc(cur, oth);
; #pragma unroll
;         for (int i = 0; i < 16; ++i) top[half][i] = cur[i];
	v_max_i32_e32 v46, v46, v77
	s_waitcnt lgkmcnt(3)
	v_max_i32_e32 v47, v47, v78
	s_waitcnt lgkmcnt(2)
	v_max_i32_e32 v40, v40, v79
	s_waitcnt lgkmcnt(1)
	v_max_i32_e32 v36, v36, v80
	s_waitcnt lgkmcnt(0)
	v_max_i32_e32 v39, v39, v81
	v_max_i32_e32 v38, v38, v76
	v_max_i32_e32 v35, v35, v75
	v_max_i32_e32 v34, v34, v74
	v_max_i32_e32 v48, v48, v73
	v_max_i32_e32 v43, v43, v72
	v_max_i32_e32 v42, v42, v71
	v_max_i32_e32 v37, v37, v70
	v_max_i32_e32 v45, v45, v69
	v_max_i32_e32 v41, v41, v68
	v_max_i32_e32 v44, v44, v67
	v_max_i32_e32 v49, v49, v66
	v_max_i32_e32 v66, v46, v48
	v_min_i32_e32 v46, v46, v48
	v_max_i32_e32 v48, v47, v43
	v_min_i32_e32 v43, v47, v43
	v_max_i32_e32 v47, v40, v42
	v_min_i32_e32 v40, v40, v42
	v_max_i32_e32 v42, v36, v37
	v_min_i32_e32 v36, v36, v37
	v_max_i32_e32 v37, v39, v45
	v_min_i32_e32 v39, v39, v45
	v_max_i32_e32 v45, v38, v41
	v_min_i32_e32 v38, v38, v41
	v_max_i32_e32 v41, v35, v44
	v_min_i32_e32 v35, v35, v44
	v_max_i32_e32 v44, v34, v49
	v_min_i32_e32 v34, v34, v49
	v_max_i32_e32 v49, v66, v37
	v_min_i32_e32 v37, v66, v37
	v_max_i32_e32 v66, v48, v45
	v_min_i32_e32 v45, v48, v45
	v_max_i32_e32 v48, v47, v41
	v_min_i32_e32 v41, v47, v41
	v_max_i32_e32 v47, v42, v44
	v_max_i32_e32 v80, v66, v47
	v_min_i32_e32 v124, v66, v47
	ds_read_b128 v[66:69], v94 offset:18432
	ds_read_b128 v[70:73], v94 offset:18464
	v_min_i32_e32 v42, v42, v44
	v_max_i32_e32 v44, v46, v39
	v_min_i32_e32 v74, v46, v39
	v_max_i32_e32 v39, v43, v38
	v_min_i32_e32 v75, v43, v38
	v_max_i32_e32 v38, v40, v35
	v_min_i32_e32 v76, v40, v35
	v_max_i32_e32 v35, v36, v34
	v_min_i32_e32 v77, v36, v34
	v_max_i32_e32 v78, v49, v48
	v_min_i32_e32 v82, v49, v48
	v_max_i32_e32 v125, v37, v41
	v_min_i32_e32 v126, v37, v41
	v_max_i32_e32 v127, v45, v42
	v_min_i32_e32 v128, v45, v42
	v_max_i32_e32 v129, v44, v38
	v_min_i32_e32 v130, v44, v38
	v_max_i32_e32 v131, v39, v35
	v_min_i32_e32 v132, v39, v35
	s_waitcnt vmcnt(3) lgkmcnt(1)
	v_mfma_f32_32x32x16_bf16 v[34:49], v[66:69], v[62:65], v[18:33]
	ds_read_b128 v[66:69], v94 offset:18496
	v_max_i32_e32 v133, v74, v76
	v_min_i32_e32 v134, v74, v76
	v_max_i32_e32 v135, v75, v77
	v_min_i32_e32 v136, v75, v77
	v_max_i32_e32 v79, v78, v80
	v_min_i32_e32 v81, v78, v80
	s_waitcnt vmcnt(2) lgkmcnt(1)
	v_mfma_f32_32x32x16_bf16 v[34:49], v[70:73], v[58:61], v[34:49]
	v_max_i32_e32 v80, v82, v124
	v_min_i32_e32 v78, v82, v124
	v_max_i32_e32 v77, v125, v127
	v_min_i32_e32 v76, v125, v127
	v_max_i32_e32 v75, v126, v128
	v_min_i32_e32 v73, v126, v128
	ds_read_b128 v[124:127], v94 offset:18528
	s_waitcnt vmcnt(1) lgkmcnt(1)
	v_mfma_f32_32x32x16_bf16 v[34:49], v[66:69], v[54:57], v[34:49]
	v_max_i32_e32 v71, v129, v131
	v_min_i32_e32 v74, v129, v131
	v_max_i32_e32 v72, v130, v132
	v_min_i32_e32 v70, v130, v132
	v_max_i32_e32 v69, v133, v135
	v_min_i32_e32 v68, v133, v135
	v_max_i32_e32 v67, v134, v136
	s_waitcnt vmcnt(0) lgkmcnt(0)
	v_mfma_f32_32x32x16_bf16 v[34:49], v[124:127], v[50:53], v[34:49]
	v_min_i32_e32 v66, v134, v136
	s_nop 10
	v_or_b32_e32 v37, 0x7f, v37
	v_or_b32_e32 v48, 0x7f, v48
	v_or_b32_e32 v38, 0x7f, v38
	v_or_b32_e32 v42, 0x7f, v42
	v_or_b32_e32 v47, 0x7f, v47
	v_or_b32_e32 v39, 0x7f, v39
	v_or_b32_e32 v40, 0x7f, v40
	v_or_b32_e32 v43, 0x7f, v43
	v_or_b32_e32 v44, 0x7f, v44
	v_or_b32_e32 v36, 0x7f, v36
	v_or_b32_e32 v49, 0x7f, v49
	v_or_b32_e32 v41, 0x7f, v41
	v_or_b32_e32 v45, 0x7f, v45
	v_or_b32_e32 v35, 0x7f, v35
	v_or_b32_e32 v46, 0x7f, v46
	v_add_u32_e32 v37, -3, v37
	v_subrev_u32_e32 v48, 26, v48
	v_add_u32_e32 v38, -8, v38
	v_add_u32_e32 v42, -16, v42
	v_or_b32_e32 v34, 0x7f, v34
	v_subrev_u32_e32 v47, 25, v47
	v_add_u32_e32 v39, -9, v39
	v_add_u32_e32 v40, -10, v40
	v_subrev_u32_e32 v43, 17, v43
	v_subrev_u32_e32 v44, 18, v44
	v_add_u32_e32 v36, -2, v36
	v_subrev_u32_e32 v49, 27, v49
	v_add_u32_e32 v41, -11, v41
	v_subrev_u32_e32 v45, 19, v45
	v_add_u32_e32 v35, -1, v35
	v_subrev_u32_e32 v46, 24, v46
	v_max_i32_e32 v82, v37, v48
	v_max_i32_e32 v124, v38, v42
	v_max_i32_e32 v126, v34, v47
	v_max_i32_e32 v127, v39, v40
	v_min_i32_e32 v130, v43, v44
	v_min_i32_e32 v131, v36, v49
	v_min_i32_e32 v133, v41, v45
	v_min_i32_e32 v134, v35, v46
	v_min_i32_e32 v39, v39, v40
	v_min_i32_e32 v34, v34, v47
	v_min_i32_e32 v38, v38, v42
	v_min_i32_e32 v37, v37, v48
	v_max_i32_e32 v35, v35, v46
	v_max_i32_e32 v41, v41, v45
	v_max_i32_e32 v36, v36, v49
	v_max_i32_e32 v43, v43, v44
	v_min_i32_e32 v125, v82, v124
	v_min_i32_e32 v128, v126, v127
	v_max_i32_e32 v132, v130, v131
	v_max_i32_e32 v135, v133, v134
	v_max_i32_e32 v40, v39, v34
	v_max_i32_e32 v42, v38, v37
	v_min_i32_e32 v45, v35, v41
	v_min_i32_e32 v44, v36, v43
	v_min_i32_e32 v129, v125, v128
	v_max_i32_e32 v47, v40, v42
	v_max_i32_e32 v46, v45, v44
	v_min_i32_e32 v40, v40, v42
	v_min_i32_e32 v42, v45, v44
	v_max_i32_e32 v45, v125, v128
	v_max_i32_e32 v125, v132, v135
	v_min_i32_e32 v128, v45, v125
	v_min_i32_e32 v34, v39, v34
	v_max_i32_e32 v39, v126, v127
	v_max_i32_e32 v35, v35, v41
	v_max_i32_e32 v41, v82, v124
	v_max_i32_e32 v148, v45, v125
	ds_read_b128 v[124:127], v97
	v_max_i32_e32 v44, v40, v42
	v_min_i32_e32 v138, v40, v42
	v_min_i32_e32 v40, v133, v134
	v_min_i32_e32 v37, v38, v37
	v_min_i32_e32 v38, v130, v131
	v_max_i32_e32 v36, v36, v43
	v_min_i32_e32 v136, v132, v135
	v_min_i32_e32 v133, v40, v34
	v_min_i32_e32 v134, v37, v38
	v_max_i32_e32 v34, v40, v34
	v_max_i32_e32 v37, v37, v38
	v_min_i32_e32 v40, v39, v35
	v_min_i32_e32 v42, v36, v41
	v_max_i32_e32 v144, v39, v35
	v_max_i32_e32 v145, v36, v41
	v_max_i32_e32 v137, v129, v136
	v_min_i32_e32 v136, v129, v136
	v_max_i32_e32 v140, v133, v134
	v_min_i32_e32 v141, v34, v37
	v_max_i32_e32 v143, v40, v42
	v_min_i32_e32 v146, v144, v145
	v_max_i32_e32 v149, v47, v46
	v_min_i32_e32 v48, v47, v46
	v_max_i32_e32 v139, v138, v136
	v_max_i32_e32 v142, v140, v141
	v_min_i32_e32 v43, v40, v42
	v_max_i32_e32 v34, v34, v37
	v_min_i32_e32 v147, v143, v146
	v_min_i32_e32 v150, v148, v149
	v_min_i32_e32 v49, v137, v48
	v_min_i32_e32 v132, v44, v128
	v_max_i32_e32 v38, v139, v142
	v_min_i32_e32 v37, v43, v34
	v_max_i32_e32 v34, v43, v34
	v_min_i32_e32 v35, v147, v150
	v_max_i32_e32 v39, v137, v48
	v_max_i32_e32 v40, v44, v128
	v_max_i32_e32 v135, v49, v132
	v_max_i32_e32 v82, v38, v37
	v_min_i32_e32 v36, v34, v35
	v_min_i32_e32 v41, v39, v40
	v_max_i32_e32 v129, v135, v82
	v_min_i32_e32 v42, v36, v41
	v_min_i32_e32 v137, v129, v42
	v_max_i32_e32 v159, v129, v42
	ds_read_b128 v[128:131], v97 offset:32
	v_min_i32_e32 v82, v135, v82
	v_min_i32_e32 v132, v49, v132
	v_min_i32_e32 v135, v38, v37
	v_max_i32_e32 v154, v34, v35
	v_max_i32_e32 v155, v39, v40
	v_max_i32_e32 v157, v36, v41
	s_waitcnt lgkmcnt(1)
; #define LAS __attribute__((address_space(3)))
; #define MFMA32(a, b, c) __builtin_amdgcn_mfma_f32_32x32x16_bf16((a), (b), (c), 0, 0, 0)
; __device__ __forceinline__ void route_task(int task, int tl0, const bf16* QP  , const LAS bf16* KHL, LAS unsigned short* EL, LAS float* GL, int lane) {
;     ...
;         for (int kt = 0; kt < 4; ++kt) {
;             f32x16 X;
; #pragma unroll
;             for (int i = 0; i < 16; ++i) X[i] = 8.f;
;             const LAS bf16* khp = KHL + (half * 128 + 32 * kt + r) * 72 + 8 * hi;
; #pragma unroll
;             for (int ks = 0; ks < 4; ++ks) {
;                 const bf16x8 kh = lds8(khp + 16 * ks);
;                 X = MFMA32(kh, qa[half][ks], X);
;             }
;             int grp[16];
; #pragma unroll
;             for (int i = 0; i < 16; ++i) grp[i] = (int)((__float_as_uint(X[i]) | 127u) - (unsigned)(32 * kt + (i & 3) + 8 * (i >> 2)));
;             sort16_desc(grp);
;             if (kt == 0) {
; #pragma unroll
;                 for (int i = 0; i < 16; ++i) cur[i] = grp[i];
;             } else merge16_desc(cur, grp);
	v_mfma_f32_32x32x16_bf16 v[34:49], v[124:127], v[62:65], v[18:33]
	ds_read_b128 v[124:127], v97 offset:64
	v_max_i32_e32 v151, v132, v135
	v_max_i32_e32 v152, v82, v151
	v_min_i32_e32 v136, v138, v136
	v_min_i32_e32 v138, v140, v141
	v_min_i32_e32 v82, v82, v151
	v_max_i32_e32 v147, v147, v150
	s_waitcnt lgkmcnt(1)
	v_mfma_f32_32x32x16_bf16 v[34:49], v[128:131], v[58:61], v[34:49]
	ds_read_b128 v[128:131], v97 offset:96
	v_max_i32_e32 v143, v143, v146
	v_min_i32_e32 v133, v133, v134
	v_min_i32_e32 v156, v154, v155
	v_max_i32_e32 v140, v136, v138
	v_min_i32_e32 v139, v139, v142
	v_max_i32_e32 v142, v154, v155
	s_waitcnt lgkmcnt(1)
	v_mfma_f32_32x32x16_bf16 v[34:49], v[124:127], v[54:57], v[34:49]
	v_max_i32_e32 v124, v148, v149
	v_min_i32_e32 v136, v136, v138
	v_max_i32_e32 v141, v140, v139
	v_min_i32_e32 v139, v140, v139
	v_min_i32_e32 v125, v143, v124
	v_min_i32_e32 v158, v156, v157
	v_min_i32_e32 v132, v132, v135
	s_waitcnt lgkmcnt(0)
	v_mfma_f32_32x32x16_bf16 v[34:49], v[128:131], v[50:53], v[34:49]
	v_min_i32_e32 v126, v147, v125
	v_min_i32_e32 v153, v137, v152
	v_min_i32_e32 v160, v158, v159
	v_min_i32_e32 v135, v141, v132
	v_min_i32_e32 v127, v142, v126
	s_nop 6
	v_or_b32_e32 v37, 0x7f, v37
	v_or_b32_e32 v48, 0x7f, v48
	v_or_b32_e32 v38, 0x7f, v38
	v_or_b32_e32 v42, 0x7f, v42
	v_or_b32_e32 v34, 0x7f, v34
	v_or_b32_e32 v47, 0x7f, v47
	v_or_b32_e32 v39, 0x7f, v39
	v_or_b32_e32 v40, 0x7f, v40
	v_or_b32_e32 v43, 0x7f, v43
	v_or_b32_e32 v44, 0x7f, v44
	v_or_b32_e32 v36, 0x7f, v36
	v_or_b32_e32 v49, 0x7f, v49
	v_or_b32_e32 v41, 0x7f, v41
	v_or_b32_e32 v45, 0x7f, v45
	v_or_b32_e32 v35, 0x7f, v35
	v_or_b32_e32 v46, 0x7f, v46
	v_subrev_u32_e32 v37, 35, v37
	v_subrev_u32_e32 v48, 58, v48
	v_subrev_u32_e32 v38, 40, v38
	v_subrev_u32_e32 v42, 48, v42
	v_subrev_u32_e32 v34, 32, v34
	v_subrev_u32_e32 v47, 57, v47
	v_subrev_u32_e32 v39, 41, v39
	v_subrev_u32_e32 v40, 42, v40
	v_subrev_u32_e32 v43, 49, v43
	v_subrev_u32_e32 v44, 50, v44
	v_subrev_u32_e32 v36, 34, v36
	v_subrev_u32_e32 v49, 59, v49
	v_subrev_u32_e32 v41, 43, v41
	v_subrev_u32_e32 v45, 51, v45
	v_subrev_u32_e32 v35, 33, v35
	v_subrev_u32_e32 v46, 56, v46
	v_max_i32_e32 v128, v37, v48
	v_max_i32_e32 v129, v38, v42
	v_max_i32_e32 v131, v34, v47
	v_max_i32_e32 v134, v39, v40
	v_min_i32_e32 v146, v43, v44
	v_min_i32_e32 v148, v36, v49
	v_min_i32_e32 v150, v41, v45
	v_min_i32_e32 v151, v35, v46
	v_min_i32_e32 v39, v39, v40
	v_min_i32_e32 v34, v34, v47
	v_min_i32_e32 v38, v38, v42
	v_min_i32_e32 v37, v37, v48
	v_max_i32_e32 v35, v35, v46
	v_max_i32_e32 v41, v41, v45
	v_max_i32_e32 v36, v36, v49
	v_max_i32_e32 v43, v43, v44
	v_min_i32_e32 v130, v128, v129
	v_min_i32_e32 v138, v131, v134
	v_max_i32_e32 v149, v146, v148
	v_max_i32_e32 v154, v150, v151
	v_max_i32_e32 v40, v39, v34
	v_max_i32_e32 v42, v38, v37
	v_min_i32_e32 v45, v35, v41
	v_min_i32_e32 v44, v36, v43
	v_min_i32_e32 v150, v150, v151
	v_min_i32_e32 v34, v39, v34
	v_min_i32_e32 v37, v38, v37
	v_min_i32_e32 v38, v146, v148
	v_max_i32_e32 v131, v131, v134
	v_max_i32_e32 v35, v35, v41
	v_max_i32_e32 v36, v36, v43
	v_max_i32_e32 v43, v128, v129
	v_min_i32_e32 v140, v130, v138
	v_min_i32_e32 v155, v149, v154
	v_max_i32_e32 v47, v40, v42
	v_max_i32_e32 v46, v45, v44
	v_min_i32_e32 v40, v40, v42
	v_min_i32_e32 v42, v45, v44
	v_max_i32_e32 v45, v130, v138
	v_max_i32_e32 v130, v149, v154
	v_min_i32_e32 v39, v150, v34
	v_min_i32_e32 v146, v37, v38
	v_max_i32_e32 v34, v150, v34
	v_max_i32_e32 v37, v37, v38
	v_min_i32_e32 v41, v131, v35
	v_min_i32_e32 v128, v36, v43
	v_max_i32_e32 v35, v131, v35
	v_max_i32_e32 v36, v36, v43
	v_min_i32_e32 v48, v47, v46
	v_max_i32_e32 v44, v40, v42
	v_min_i32_e32 v138, v45, v130
	v_min_i32_e32 v40, v40, v42
	v_min_i32_e32 v42, v140, v155
	v_max_i32_e32 v148, v39, v146
	v_min_i32_e32 v38, v34, v37
	v_min_i32_e32 v129, v41, v128
	v_max_i32_e32 v41, v41, v128
	v_min_i32_e32 v43, v35, v36
	v_max_i32_e32 v45, v45, v130
	v_max_i32_e32 v46, v47, v46
	v_max_i32_e32 v161, v140, v155
	v_max_i32_e32 v140, v40, v42
	v_max_i32_e32 v150, v148, v38
	v_max_i32_e32 v34, v34, v37
	v_min_i32_e32 v128, v41, v43
	v_min_i32_e32 v47, v45, v46
	v_min_i32_e32 v49, v161, v48
	v_min_i32_e32 v149, v44, v138
	v_max_i32_e32 v151, v140, v150
	v_min_i32_e32 v37, v129, v34
	v_max_i32_e32 v34, v129, v34
	v_min_i32_e32 v129, v128, v47
	v_max_i32_e32 v48, v161, v48
	v_max_i32_e32 v44, v44, v138
	v_max_i32_e32 v154, v49, v149
	v_max_i32_e32 v134, v151, v37
	v_min_i32_e32 v130, v34, v129
	v_min_i32_e32 v131, v48, v44
	v_min_i32_e32 v49, v49, v149
	v_min_i32_e32 v37, v151, v37
	v_max_i32_e32 v34, v34, v129
	v_max_i32_e32 v44, v48, v44
	v_min_i32_e32 v40, v40, v42
	v_min_i32_e32 v38, v148, v38
	v_max_i32_e32 v41, v41, v43
	v_max_i32_e32 v43, v45, v46
	v_max_i32_e32 v155, v154, v134
	v_min_i32_e32 v138, v130, v131
	v_min_i32_e32 v134, v154, v134
	v_max_i32_e32 v149, v49, v37
	v_min_i32_e32 v48, v34, v44
	v_max_i32_e32 v129, v130, v131
	v_max_i32_e32 v42, v40, v38
	v_min_i32_e32 v140, v140, v150
	v_max_i32_e32 v34, v34, v44
	v_max_i32_e32 v44, v128, v47
	v_min_i32_e32 v45, v41, v43
	v_min_i32_e32 v161, v155, v138
	v_max_i32_e32 v151, v134, v149
	v_min_i32_e32 v130, v48, v129
	v_max_i32_e32 v131, v155, v138
	v_max_i32_e32 v148, v42, v140
	v_min_i32_e32 v37, v49, v37
	v_min_i32_e32 v46, v44, v45
	v_min_i32_e32 v154, v161, v151
	v_min_i32_e32 v138, v130, v131
	v_min_i32_e32 v49, v148, v37
	v_min_i32_e32 v134, v134, v149
	v_min_i32_e32 v47, v34, v46
	v_min_i32_e32 v42, v42, v140
	v_min_i32_e32 v38, v40, v38
	v_min_i32_e32 v39, v39, v146
	v_max3_i32 v39, v144, v145, v39
	v_max3_i32 v38, v143, v124, v38
	v_max3_i32 v40, v147, v125, v42
; #define LAS __attribute__((address_space(3)))
; #define MFMA32(a, b, c) __builtin_amdgcn_mfma_f32_32x32x16_bf16((a), (b), (c), 0, 0, 0)
; __device__ __forceinline__ void route_task(int task, int tl0, const bf16* QP  , const LAS bf16* KHL, LAS unsigned short* EL, LAS float* GL, int lane) {
;     ...
;         for (int kt = 0; kt < 4; ++kt) {
;             f32x16 X;
; #pragma unroll
;             for (int i = 0; i < 16; ++i) X[i] = 8.f;
;             const LAS bf16* khp = KHL + (half * 128 + 32 * kt + r) * 72 + 8 * hi;
; #pragma unroll
;             for (int ks = 0; ks < 4; ++ks) {
;                 const bf16x8 kh = lds8(khp + 16 * ks);
;                 X = MFMA32(kh, qa[half][ks], X);
;             }
;             int grp[16];
; #pragma unroll
;             for (int i = 0; i < 16; ++i) grp[i] = (int)((__float_as_uint(X[i]) | 127u) - (unsigned)(32 * kt + (i & 3) + 8 * (i >> 2)));
;             sort16_desc(grp);
;             if (kt == 0) {
; #pragma unroll
;                 for (int i = 0; i < 16; ++i) cur[i] = grp[i];
;             } else merge16_desc(cur, grp);
	v_max3_i32 v42, v142, v126, v49
	v_max3_i32 v37, v127, v148, v37
	v_max3_i32 v49, v156, v157, v134
	v_max3_i32 v124, v158, v159, v154
	v_max3_i32 v125, v160, v161, v151
	v_max3_i32 v126, v137, v152, v138
	v_max3_i32 v127, v153, v130, v131
	v_max3_i32 v48, v82, v48, v129
	v_max3_i32 v47, v141, v132, v47
	v_max3_i32 v34, v135, v34, v46
	v_max3_i32 v44, v139, v44, v45
	v_max3_i32 v41, v136, v41, v43
	v_max3_i32 v35, v133, v35, v36
	v_max_i32_e32 v36, v39, v126
	v_min_i32_e32 v39, v39, v126
	v_max_i32_e32 v43, v38, v127
	v_min_i32_e32 v38, v38, v127
	v_max_i32_e32 v45, v40, v48
	v_min_i32_e32 v40, v40, v48
	v_max_i32_e32 v46, v42, v47
	v_min_i32_e32 v42, v42, v47
	v_max_i32_e32 v47, v37, v34
	v_min_i32_e32 v34, v37, v34
	v_max_i32_e32 v37, v49, v44
	v_min_i32_e32 v44, v49, v44
	v_max_i32_e32 v48, v124, v41
	v_min_i32_e32 v41, v124, v41
	v_max_i32_e32 v49, v125, v35
	v_min_i32_e32 v35, v125, v35
	ds_read_b128 v[124:127], v94 offset:27648
	ds_read_b128 v[128:131], v94 offset:27680
	v_max_i32_e32 v82, v36, v47
	v_min_i32_e32 v132, v36, v47
	v_max_i32_e32 v36, v43, v37
	v_min_i32_e32 v133, v43, v37
	v_max_i32_e32 v37, v45, v48
	v_max_i32_e32 v43, v46, v49
	v_min_i32_e32 v134, v45, v48
	v_min_i32_e32 v135, v46, v49
	v_max_i32_e32 v136, v39, v34
	v_min_i32_e32 v137, v39, v34
	v_max_i32_e32 v138, v38, v44
	v_min_i32_e32 v139, v38, v44
	v_max_i32_e32 v140, v40, v41
	v_min_i32_e32 v141, v40, v41
	v_max_i32_e32 v142, v42, v35
	v_min_i32_e32 v143, v42, v35
	v_max_i32_e32 v144, v82, v37
	v_min_i32_e32 v82, v82, v37
	v_max_i32_e32 v145, v36, v43
	v_min_i32_e32 v146, v36, v43
	s_waitcnt lgkmcnt(1)
	v_mfma_f32_32x32x16_bf16 v[34:49], v[124:127], v[62:65], v[18:33]
	ds_read_b128 v[124:127], v94 offset:27712
	v_max_i32_e32 v147, v132, v134
	v_min_i32_e32 v132, v132, v134
	v_max_i32_e32 v134, v133, v135
	v_min_i32_e32 v133, v133, v135
	v_max_i32_e32 v135, v136, v140
	v_min_i32_e32 v136, v136, v140
	s_waitcnt lgkmcnt(1)
	v_mfma_f32_32x32x16_bf16 v[34:49], v[128:131], v[58:61], v[34:49]
	ds_read_b128 v[128:131], v94 offset:27744
	v_max_i32_e32 v140, v138, v142
	v_min_i32_e32 v138, v138, v142
	v_max_i32_e32 v142, v137, v141
	v_min_i32_e32 v137, v137, v141
	v_max_i32_e32 v141, v139, v143
	v_min_i32_e32 v139, v139, v143
	s_waitcnt lgkmcnt(1)
	v_mfma_f32_32x32x16_bf16 v[34:49], v[124:127], v[54:57], v[34:49]
	v_min_i32_e32 v143, v144, v145
	v_min_i32_e32 v124, v82, v146
	v_min_i32_e32 v127, v135, v140
	v_min_i32_e32 v125, v147, v134
	v_min_i32_e32 v126, v132, v133
	v_min_i32_e32 v149, v142, v141
	v_min_i32_e32 v148, v136, v138
	s_waitcnt lgkmcnt(0)
	v_mfma_f32_32x32x16_bf16 v[34:49], v[128:131], v[50:53], v[34:49]
	v_min_i32_e32 v150, v137, v139
	s_nop 10
	v_or_b32_e32 v37, 0x7f, v37
	v_or_b32_e32 v48, 0x7f, v48
	v_or_b32_e32 v38, 0x7f, v38
	v_or_b32_e32 v42, 0x7f, v42
	v_or_b32_e32 v34, 0x7f, v34
	v_or_b32_e32 v47, 0x7f, v47
	v_or_b32_e32 v39, 0x7f, v39
	v_or_b32_e32 v40, 0x7f, v40
	v_or_b32_e32 v43, 0x7f, v43
	v_or_b32_e32 v44, 0x7f, v44
	v_or_b32_e32 v36, 0x7f, v36
	v_or_b32_e32 v49, 0x7f, v49
	v_or_b32_e32 v41, 0x7f, v41
	v_or_b32_e32 v45, 0x7f, v45
	v_or_b32_e32 v35, 0x7f, v35
	v_or_b32_e32 v46, 0x7f, v46
	v_add_u32_e32 v37, 0xffffffbd, v37
	v_add_u32_e32 v48, 0xffffffa6, v48
	v_add_u32_e32 v38, 0xffffffb8, v38
	v_add_u32_e32 v42, 0xffffffb0, v42
	v_subrev_u32_e32 v34, 64, v34
	v_add_u32_e32 v47, 0xffffffa7, v47
	v_add_u32_e32 v39, 0xffffffb7, v39
	v_add_u32_e32 v40, 0xffffffb6, v40
	v_add_u32_e32 v43, 0xffffffaf, v43
	v_add_u32_e32 v44, 0xffffffae, v44
	v_add_u32_e32 v36, 0xffffffbe, v36
	v_add_u32_e32 v49, 0xffffffa5, v49
	v_add_u32_e32 v41, 0xffffffb5, v41
	v_add_u32_e32 v45, 0xffffffad, v45
	v_add_u32_e32 v35, 0xffffffbf, v35
	v_add_u32_e32 v46, 0xffffffa8, v46
	v_max_i32_e32 v128, v37, v48
	v_max_i32_e32 v129, v38, v42
	v_max_i32_e32 v131, v34, v47
	v_max_i32_e32 v151, v39, v40
	v_min_i32_e32 v154, v43, v44
	v_min_i32_e32 v155, v36, v49
	v_min_i32_e32 v157, v41, v45
	v_min_i32_e32 v158, v35, v46
	v_min_i32_e32 v39, v39, v40
	v_min_i32_e32 v34, v34, v47
	v_min_i32_e32 v38, v38, v42
	v_min_i32_e32 v37, v37, v48
	v_max_i32_e32 v35, v35, v46
	v_max_i32_e32 v41, v41, v45
	v_max_i32_e32 v36, v36, v49
	v_max_i32_e32 v43, v43, v44
	v_min_i32_e32 v130, v128, v129
	v_min_i32_e32 v152, v131, v151
	v_max_i32_e32 v156, v154, v155
	v_max_i32_e32 v159, v157, v158
	v_max_i32_e32 v40, v39, v34
	v_max_i32_e32 v42, v38, v37
	v_min_i32_e32 v45, v35, v41
	v_min_i32_e32 v44, v36, v43
	v_min_i32_e32 v157, v157, v158
	v_min_i32_e32 v34, v39, v34
	v_min_i32_e32 v37, v38, v37
	v_min_i32_e32 v38, v154, v155
	v_max_i32_e32 v131, v131, v151
	v_max_i32_e32 v35, v35, v41
	v_max_i32_e32 v36, v36, v43
	v_max_i32_e32 v43, v128, v129
	v_min_i32_e32 v153, v130, v152
	v_min_i32_e32 v160, v156, v159
	v_max_i32_e32 v47, v40, v42
	v_max_i32_e32 v46, v45, v44
	v_min_i32_e32 v40, v40, v42
	v_min_i32_e32 v42, v45, v44
	v_max_i32_e32 v45, v130, v152
	v_max_i32_e32 v130, v156, v159
	v_min_i32_e32 v39, v157, v34
	v_min_i32_e32 v154, v37, v38
	v_max_i32_e32 v34, v157, v34
	v_max_i32_e32 v37, v37, v38
	v_min_i32_e32 v41, v131, v35
	v_min_i32_e32 v128, v36, v43
	v_max_i32_e32 v35, v131, v35
	v_max_i32_e32 v36, v36, v43
	v_min_i32_e32 v48, v47, v46
	v_max_i32_e32 v44, v40, v42
	v_min_i32_e32 v152, v45, v130
	v_min_i32_e32 v40, v40, v42
	v_min_i32_e32 v42, v153, v160
	v_max_i32_e32 v155, v39, v154
	v_min_i32_e32 v38, v34, v37
	v_min_i32_e32 v129, v41, v128
	v_max_i32_e32 v41, v41, v128
	v_min_i32_e32 v43, v35, v36
	v_max_i32_e32 v45, v45, v130
	v_max_i32_e32 v46, v47, v46
	v_max_i32_e32 v161, v153, v160
	v_max_i32_e32 v153, v40, v42
	v_max_i32_e32 v157, v155, v38
	v_max_i32_e32 v34, v34, v37
; #define LAS __attribute__((address_space(3)))
; #define MFMA32(a, b, c) __builtin_amdgcn_mfma_f32_32x32x16_bf16((a), (b), (c), 0, 0, 0)
; __device__ __forceinline__ void route_task(int task, int tl0, const bf16* QP  , const LAS bf16* KHL, LAS unsigned short* EL, LAS float* GL, int lane) {
;     ...
;         for (int kt = 0; kt < 4; ++kt) {
;             f32x16 X;
; #pragma unroll
;             for (int i = 0; i < 16; ++i) X[i] = 8.f;
;             const LAS bf16* khp = KHL + (half * 128 + 32 * kt + r) * 72 + 8 * hi;
; #pragma unroll
;             for (int ks = 0; ks < 4; ++ks) {
;                 const bf16x8 kh = lds8(khp + 16 * ks);
;                 X = MFMA32(kh, qa[half][ks], X);
;             }
;             int grp[16];
; #pragma unroll
;             for (int i = 0; i < 16; ++i) grp[i] = (int)((__float_as_uint(X[i]) | 127u) - (unsigned)(32 * kt + (i & 3) + 8 * (i >> 2)));
;             sort16_desc(grp);
;             if (kt == 0) {
; #pragma unroll
;                 for (int i = 0; i < 16; ++i) cur[i] = grp[i];
;             } else merge16_desc(cur, grp);
	v_min_i32_e32 v128, v41, v43
	v_min_i32_e32 v47, v45, v46
	v_min_i32_e32 v49, v161, v48
	v_min_i32_e32 v156, v44, v152
	v_max_i32_e32 v158, v153, v157
	v_min_i32_e32 v37, v129, v34
	v_max_i32_e32 v34, v129, v34
	v_min_i32_e32 v129, v128, v47
	v_max_i32_e32 v48, v161, v48
	v_max_i32_e32 v44, v44, v152
	v_min_i32_e32 v40, v40, v42
	v_min_i32_e32 v38, v155, v38
	v_max_i32_e32 v159, v49, v156
	v_max_i32_e32 v151, v158, v37
	v_min_i32_e32 v130, v34, v129
	v_min_i32_e32 v131, v48, v44
	v_min_i32_e32 v49, v49, v156
	v_min_i32_e32 v37, v158, v37
	v_max_i32_e32 v34, v34, v129
	v_max_i32_e32 v44, v48, v44
	v_max_i32_e32 v42, v40, v38
	v_min_i32_e32 v153, v153, v157
	v_max_i32_e32 v160, v159, v151
	v_min_i32_e32 v152, v130, v131
	v_max_i32_e32 v156, v49, v37
	v_min_i32_e32 v48, v34, v44
	v_max_i32_e32 v129, v130, v131
	v_max_i32_e32 v155, v42, v153
	v_min_i32_e32 v37, v49, v37
	v_min_i32_e32 v151, v159, v151
	v_min_i32_e32 v130, v48, v129
	v_max_i32_e32 v131, v160, v152
	v_min_i32_e32 v49, v155, v37
	v_max_i32_e32 v41, v41, v43
	v_max_i32_e32 v43, v45, v46
	v_min_i32_e32 v42, v42, v153
	v_min_i32_e32 v38, v40, v38
	v_min_i32_e32 v161, v160, v152
	v_max_i32_e32 v158, v151, v156
	v_min_i32_e32 v151, v151, v156
	v_max_i32_e32 v34, v34, v44
	v_max_i32_e32 v44, v128, v47
	v_min_i32_e32 v45, v41, v43
	v_max_i32_e32 v40, v41, v43
	v_max_i32_e32 v38, v143, v38
	v_max3_i32 v41, v82, v146, v42
	v_max_i32_e32 v42, v124, v49
	v_max3_i32 v124, v127, v130, v131
	v_min_i32_e32 v46, v44, v45
	v_max_i32_e32 v43, v125, v151
	v_max3_i32 v49, v126, v161, v158
	v_max3_i32 v44, v149, v44, v45
	v_max_i32_e32 v45, v38, v124
	v_min_i32_e32 v38, v38, v124
	ds_read_b128 v[124:127], v98
	v_min_i32_e32 v159, v161, v158
	v_min_i32_e32 v152, v130, v131
	v_max_i32_e32 v37, v155, v37
	v_max_i32_e32 v48, v48, v129
	v_min_i32_e32 v47, v34, v46
	v_max_i32_e32 v34, v34, v46
	v_min_i32_e32 v39, v39, v154
	v_max3_i32 v39, v144, v145, v39
	v_max3_i32 v37, v147, v134, v37
	v_max3_i32 v46, v132, v133, v159
	v_max3_i32 v82, v135, v140, v152
	v_max3_i32 v48, v136, v138, v48
	v_max_i32_e32 v47, v148, v47
	v_max3_i32 v34, v142, v141, v34
	v_max3_i32 v40, v137, v139, v40
	v_max3_i32 v35, v150, v35, v36
	v_max_i32_e32 v36, v39, v82
	v_min_i32_e32 v39, v39, v82
	v_max_i32_e32 v82, v41, v48
	v_min_i32_e32 v41, v41, v48
	v_max_i32_e32 v48, v42, v47
	v_min_i32_e32 v42, v42, v47
	v_max_i32_e32 v47, v37, v34
	v_min_i32_e32 v34, v37, v34
	v_max_i32_e32 v37, v43, v44
	v_min_i32_e32 v43, v43, v44
	v_max_i32_e32 v44, v46, v40
	v_min_i32_e32 v40, v46, v40
	v_max_i32_e32 v46, v49, v35
	v_min_i32_e32 v35, v49, v35
	v_max_i32_e32 v49, v36, v47
	v_min_i32_e32 v132, v36, v47
	v_max_i32_e32 v36, v45, v37
	v_min_i32_e32 v133, v45, v37
	v_max_i32_e32 v37, v82, v44
	v_min_i32_e32 v82, v82, v44
	v_max_i32_e32 v44, v48, v46
	ds_read_b128 v[128:131], v98 offset:32
	v_min_i32_e32 v134, v48, v46
	v_max_i32_e32 v135, v39, v34
	v_min_i32_e32 v136, v39, v34
	v_max_i32_e32 v137, v38, v43
	v_min_i32_e32 v138, v38, v43
	v_max_i32_e32 v139, v41, v40
	v_min_i32_e32 v140, v41, v40
	v_max_i32_e32 v141, v42, v35
	v_min_i32_e32 v142, v42, v35
	v_max_i32_e32 v143, v49, v37
	v_min_i32_e32 v144, v49, v37
	v_max_i32_e32 v145, v36, v44
	v_min_i32_e32 v146, v36, v44
	s_waitcnt lgkmcnt(1)
	v_mfma_f32_32x32x16_bf16 v[34:49], v[124:127], v[62:65], v[18:33]
	v_max_i32_e32 v147, v132, v82
	s_nop 5
	ds_read_b128 v[18:21], v98 offset:64
	ds_read_b128 v[22:25], v98 offset:96
	s_waitcnt lgkmcnt(2)
	v_mfma_f32_32x32x16_bf16 v[34:49], v[128:131], v[58:61], v[34:49]
	v_min_i32_e32 v26, v132, v82
	v_max_i32_e32 v27, v133, v134
	v_min_i32_e32 v30, v135, v139
	v_min_i32_e32 v32, v137, v141
	v_max_i32_e32 v33, v136, v140
	v_max_i32_e32 v59, v138, v142
	v_min_i32_e32 v28, v133, v134
	s_waitcnt lgkmcnt(1)
	v_mfma_f32_32x32x16_bf16 v[34:49], v[18:21], v[54:57], v[34:49]
	v_min_i32_e32 v19, v147, v27
	v_min_i32_e32 v54, v30, v32
	v_min_i32_e32 v55, v33, v59
	v_max_i32_e32 v29, v135, v139
	v_max_i32_e32 v31, v137, v141
	v_min_i32_e32 v58, v136, v140
	v_min_i32_e32 v60, v138, v142
	s_waitcnt lgkmcnt(0)
	v_mfma_f32_32x32x16_bf16 v[34:49], v[22:25], v[50:53], v[34:49]
	v_min_i32_e32 v18, v144, v146
	v_min_i32_e32 v61, v143, v145
	v_min_i32_e32 v20, v26, v28
	v_min_i32_e32 v21, v29, v31
	v_min_i32_e32 v56, v58, v60
	s_nop 6
	v_or_b32_e32 v22, 0x7f, v41
	v_or_b32_e32 v23, 0x7f, v45
	v_or_b32_e32 v25, 0x7f, v35
	v_or_b32_e32 v35, 0x7f, v46
	v_or_b32_e32 v39, 0x7f, v39
	v_or_b32_e32 v40, 0x7f, v40
	v_or_b32_e32 v34, 0x7f, v34
	v_or_b32_e32 v47, 0x7f, v47
	v_or_b32_e32 v38, 0x7f, v38
	v_or_b32_e32 v42, 0x7f, v42
	v_or_b32_e32 v37, 0x7f, v37
	v_or_b32_e32 v48, 0x7f, v48
	v_or_b32_e32 v43, 0x7f, v43
	v_or_b32_e32 v44, 0x7f, v44
	v_or_b32_e32 v36, 0x7f, v36
	v_or_b32_e32 v49, 0x7f, v49
	v_add_u32_e32 v22, 0xffffff95, v22
	v_add_u32_e32 v23, 0xffffff8d, v23
	v_add_u32_e32 v25, 0xffffff9f, v25
	v_add_u32_e32 v35, 0xffffff88, v35
	v_add_u32_e32 v39, 0xffffff97, v39
	v_add_u32_e32 v40, 0xffffff96, v40
	v_add_u32_e32 v34, 0xffffffa0, v34
	v_add_u32_e32 v47, 0xffffff87, v47
	v_add_u32_e32 v38, 0xffffff98, v38
	v_add_u32_e32 v42, 0xffffff90, v42
	v_add_u32_e32 v37, 0xffffff9d, v37
	v_add_u32_e32 v48, 0xffffff86, v48
	v_add_u32_e32 v43, 0xffffff8f, v43
	v_add_u32_e32 v44, 0xffffff8e, v44
	v_add_u32_e32 v36, 0xffffff9e, v36
	v_add_u32_e32 v49, 0xffffff85, v49
	v_min_i32_e32 v24, v22, v23
	v_min_i32_e32 v41, v25, v35
	v_min_i32_e32 v46, v39, v40
	v_min_i32_e32 v50, v34, v47
	v_min_i32_e32 v53, v38, v42
	v_min_i32_e32 v57, v37, v48
	v_min_i32_e32 v63, v43, v44
	v_min_i32_e32 v64, v36, v49
	v_max_i32_e32 v34, v34, v47
	v_max_i32_e32 v39, v39, v40
	v_max_i32_e32 v25, v25, v35
; #define CE_(a, b) ce_desc(v[a], v[b])
; __device__ __forceinline__ void sort16_desc(int (&v)[16]) {
;     ...
;     CE_(0,13); CE_(1,12); CE_(2,15); CE_(3,14); CE_(4,8); CE_(5,6); CE_(7,11); CE_(9,10);
;     CE_(0,5); CE_(1,7); CE_(2,9); CE_(3,4); CE_(6,13); CE_(8,14); CE_(10,15); CE_(11,12);
;     CE_(0,1); CE_(2,3); CE_(4,5); CE_(6,8); CE_(7,9); CE_(10,11); CE_(12,13); CE_(14,15);
;     CE_(0,2); CE_(1,3); CE_(4,10); CE_(5,11); CE_(6,7); CE_(8,9); CE_(12,14); CE_(13,15);
;     CE_(1,2); CE_(3,12); CE_(4,6); CE_(5,7); CE_(8,10); CE_(9,11); CE_(13,14);
;     CE_(1,4); CE_(2,6); CE_(5,8); CE_(7,10); CE_(9,13); CE_(11,14);
;     CE_(2,4); CE_(3,6); CE_(9,12); CE_(11,13);
;     CE_(3,5); CE_(6,8); CE_(7,9); CE_(10,12);
;     CE_(3,4); CE_(5,6); CE_(7,8); CE_(9,10); CE_(11,12);
;     CE_(6,7); CE_(8,9);
;     ...
; }
; __device__ __forceinline__ void merge16_desc(int (&a)[16], const int (&b)[16]) {
; #pragma unroll
;     for (int i = 0; i < 16; ++i) a[i] = a[i] > b[15 - i] ? a[i] : b[15 - i];
; #pragma unroll
;     for (int j = 8; j > 0; j >>= 1)
; #pragma unroll
;         for (int i = 0; i < 16; ++i) { const int l = i ^ j; if (l > i) ce_desc(a[i], a[l]); }
; }
; __device__ __forceinline__ void route_task(int task, int tl0, const bf16* QP  , const LAS bf16* KHL, LAS unsigned short* EL, LAS float* GL, int lane) {
;     ...
;         { const unsigned h4 = 4u * (unsigned)hi;
; #pragma unroll
;           for (int i = 0; i < 16; ++i) cur[i] -= (int)h4; }
;         int oth[16];
; #pragma unroll
;         for (int i = 0; i < 16; ++i) oth[i] = __shfl_xor(cur[i], 32);
;         merge16_desc(cur, oth);
	v_max_i32_e32 v22, v22, v23
	v_max_i32_e32 v36, v36, v49
	v_max_i32_e32 v43, v43, v44
	v_max_i32_e32 v37, v37, v48
	v_max_i32_e32 v38, v38, v42
	v_min_i32_e32 v45, v24, v41
	v_min_i32_e32 v51, v46, v50
	v_max_i32_e32 v40, v34, v39
	v_max_i32_e32 v23, v25, v22
	v_max_i32_e32 v44, v36, v43
	v_max_i32_e32 v42, v37, v38
	v_min_i32_e32 v37, v37, v38
	v_min_i32_e32 v34, v34, v39
	v_max_i32_e32 v39, v63, v64
	v_max_i32_e32 v24, v24, v41
	v_max_i32_e32 v46, v46, v50
	v_max_i32_e32 v50, v53, v57
	v_min_i32_e32 v22, v25, v22
	v_min_i32_e32 v25, v36, v43
	v_min_i32_e32 v62, v53, v57
	v_min_i32_e32 v65, v63, v64
	v_min_i32_e32 v35, v40, v23
	v_min_i32_e32 v47, v44, v42
	v_max_i32_e32 v23, v40, v23
	v_max_i32_e32 v40, v44, v42
	v_max_i32_e32 v38, v37, v34
	v_max_i32_e32 v41, v39, v24
	v_max_i32_e32 v53, v46, v50
	v_max_i32_e32 v36, v22, v25
	v_min_i32_e32 v46, v46, v50
	v_min_i32_e32 v22, v22, v25
	v_min_i32_e32 v52, v45, v51
	v_min_i32_e32 v82, v62, v65
	v_min_i32_e32 v48, v35, v47
	v_max_i32_e32 v45, v45, v51
	v_max_i32_e32 v49, v62, v65
	v_max_i32_e32 v35, v35, v47
	v_min_i32_e32 v42, v23, v40
	v_max_i32_e32 v47, v38, v41
	v_max_i32_e32 v43, v53, v36
	v_min_i32_e32 v34, v37, v34
	v_min_i32_e32 v24, v39, v24
	v_max_i32_e32 v25, v46, v22
	v_min_i32_e32 v38, v38, v41
	v_max_i32_e32 v51, v45, v49
	v_min_i32_e32 v44, v35, v42
	v_min_i32_e32 v57, v47, v43
	v_max_i32_e32 v37, v34, v24
	v_min_i32_e32 v36, v53, v36
	v_max_i32_e32 v41, v25, v38
	v_min_i32_e32 v25, v25, v38
	v_min_i32_e32 v22, v46, v22
	v_min_i32_e32 v24, v34, v24
	v_max_i32_e32 v38, v52, v82
	v_min_i32_e32 v45, v45, v49
	v_max_i32_e32 v62, v48, v51
	v_min_i32_e32 v63, v44, v57
	v_max_i32_e32 v39, v37, v36
	v_max_i32_e32 v34, v22, v24
	v_max_i32_e32 v46, v38, v45
	v_max_i32_e32 v64, v62, v63
	v_max_i32_e32 v50, v39, v41
	v_min_i32_e32 v62, v62, v63
	v_min_i32_e32 v39, v39, v41
	v_min_i32_e32 v36, v37, v36
	v_max_i32_e32 v49, v34, v46
	v_min_i32_e32 v48, v48, v51
	v_min_i32_e32 v22, v22, v24
	v_min_i32_e32 v24, v38, v45
	v_min_i32_e32 v53, v64, v50
	v_max_i32_e32 v41, v62, v39
	v_max_i32_e32 v37, v36, v25
	v_max_i32_e32 v51, v49, v48
	v_max_i32_e32 v38, v22, v24
	v_min_i32_e32 v34, v34, v46
	v_min_i32_e32 v25, v36, v25
	v_min_i32_e32 v36, v49, v48
	v_min_i32_e32 v124, v52, v82
	v_max_i32_e32 v52, v37, v51
	v_min_i32_e32 v39, v62, v39
	v_max_i32_e32 v45, v38, v34
	v_min_i32_e32 v46, v25, v36
	v_max_i32_e32 v35, v35, v42
	v_max_i32_e32 v42, v47, v43
	v_min_i32_e32 v34, v38, v34
	v_max_i32_e32 v38, v53, v41
	v_min_i32_e32 v37, v37, v51
	v_max_i32_e32 v25, v25, v36
	v_max_i32_e32 v48, v45, v46
	v_max_i32_e32 v44, v44, v57
	v_min_i32_e32 v43, v35, v42
	v_max3_i32 v30, v30, v32, v38
	v_min_i32_e32 v38, v52, v39
	v_max_i32_e32 v36, v37, v25
	v_min_i32_e32 v25, v37, v25
	v_min_i32_e32 v63, v53, v41
	v_max_i32_e32 v62, v52, v39
	v_max3_i32 v27, v147, v27, v48
	v_max_i32_e32 v48, v64, v50
	v_min_i32_e32 v47, v44, v43
	v_min_i32_e32 v39, v38, v36
	v_max_i32_e32 v19, v19, v25
	v_max3_i32 v25, v55, v44, v43
	v_min_i32_e32 v43, v45, v46
	v_min_i32_e32 v65, v63, v62
	v_max_i32_e32 v49, v48, v47
	v_max3_i32 v26, v26, v28, v39
	v_max_i32_e32 v28, v35, v42
	v_min_i32_e32 v22, v22, v24
	v_max_i32_e32 v18, v18, v43
	v_min_i32_e32 v43, v48, v47
	v_max3_i32 v124, v143, v145, v124
	v_max3_i32 v29, v29, v31, v65
	v_max3_i32 v33, v33, v59, v49
	v_max3_i32 v34, v144, v146, v34
	v_max3_i32 v28, v58, v60, v28
	v_max_i32_e32 v22, v61, v22
	v_max3_i32 v21, v21, v63, v62
	v_max_i32_e32 v43, v54, v43
	v_max3_i32 v20, v20, v38, v36
	v_max3_i32 v23, v56, v23, v40
	v_min_i32_e32 v31, v124, v29
	v_min_i32_e32 v49, v27, v33
	v_min_i32_e32 v32, v34, v30
	v_min_i32_e32 v35, v26, v28
	v_min_i32_e32 v24, v22, v21
	v_min_i32_e32 v37, v19, v25
	v_min_i32_e32 v44, v18, v43
	v_min_i32_e32 v36, v20, v23
	v_max_i32_e32 v29, v124, v29
	v_max_i32_e32 v27, v27, v33
	v_max_i32_e32 v30, v34, v30
	v_max_i32_e32 v26, v26, v28
	v_max_i32_e32 v21, v22, v21
	v_max_i32_e32 v19, v19, v25
	v_max_i32_e32 v18, v18, v43
	v_max_i32_e32 v20, v20, v23
	v_max_i32_e32 v33, v29, v27
	v_max_i32_e32 v28, v30, v26
	v_max_i32_e32 v22, v21, v19
	v_max_i32_e32 v23, v18, v20
	v_max_i32_e32 v34, v33, v28
	v_max_i32_e32 v25, v22, v23
	v_min_i32_e32 v28, v33, v28
	v_min_i32_e32 v22, v22, v23
	v_min_i32_e32 v27, v29, v27
	v_min_i32_e32 v26, v30, v26
	v_min_i32_e32 v19, v21, v19
	v_min_i32_e32 v18, v18, v20
	v_max_i32_e32 v23, v28, v22
	v_min_i32_e32 v22, v28, v22
	v_max_i32_e32 v28, v27, v26
	v_max_i32_e32 v20, v19, v18
	v_min_i32_e32 v26, v27, v26
	v_min_i32_e32 v18, v19, v18
	v_min_i32_e32 v42, v24, v37
	v_max_i32_e32 v19, v26, v18
	v_min_i32_e32 v18, v26, v18
	v_max_i32_e32 v26, v31, v49
	v_max_i32_e32 v27, v32, v35
	v_max_i32_e32 v24, v24, v37
	v_max_i32_e32 v29, v44, v36
	v_min_i32_e32 v50, v31, v49
	v_min_i32_e32 v39, v32, v35
	v_min_i32_e32 v38, v44, v36
	v_max_i32_e32 v21, v28, v20
	v_min_i32_e32 v20, v28, v20
	v_max_i32_e32 v28, v26, v27
	v_max_i32_e32 v30, v24, v29
	v_min_i32_e32 v26, v26, v27
	v_min_i32_e32 v24, v24, v29
	v_min_i32_e32 v41, v50, v39
	v_min_i32_e32 v40, v42, v38
	v_max_i32_e32 v27, v26, v24
	v_min_i32_e32 v24, v26, v24
	v_max_i32_e32 v26, v50, v39
	v_max_i32_e32 v29, v42, v38
	v_min_i32_e32 v45, v41, v40
	v_max_i32_e32 v43, v34, v25
	v_min_i32_e32 v25, v34, v25
	v_max_i32_e32 v31, v28, v30
	v_min_i32_e32 v28, v28, v30
	v_max_i32_e32 v30, v26, v29
	v_min_i32_e32 v26, v26, v29
	v_max_i32_e32 v29, v41, v40
	v_sub_u32_e32 v32, v43, v87
	v_sub_u32_e32 v25, v25, v87
	v_sub_u32_e32 v23, v23, v87
	v_sub_u32_e32 v22, v22, v87
	v_sub_u32_e32 v21, v21, v87
	v_sub_u32_e32 v20, v20, v87
	v_sub_u32_e32 v19, v19, v87
	v_sub_u32_e32 v18, v18, v87
	v_sub_u32_e32 v31, v31, v87
	v_sub_u32_e32 v28, v28, v87
	v_sub_u32_e32 v27, v27, v87
	v_sub_u32_e32 v24, v24, v87
	v_sub_u32_e32 v30, v30, v87
	v_sub_u32_e32 v26, v26, v87
	v_sub_u32_e32 v29, v29, v87
	v_sub_u32_e32 v33, v45, v87
	ds_bpermute_b32 v34, v123, v32
	ds_bpermute_b32 v35, v123, v25
	ds_bpermute_b32 v36, v123, v23
	ds_bpermute_b32 v37, v123, v22
	ds_bpermute_b32 v38, v123, v21
	ds_bpermute_b32 v39, v123, v20
	ds_bpermute_b32 v40, v123, v19
	ds_bpermute_b32 v41, v123, v18
	ds_bpermute_b32 v42, v123, v31
	ds_bpermute_b32 v43, v123, v28
	ds_bpermute_b32 v44, v123, v27
	ds_bpermute_b32 v45, v123, v33
	ds_bpermute_b32 v46, v123, v29
	ds_bpermute_b32 v47, v123, v26
	ds_bpermute_b32 v48, v123, v30
	ds_bpermute_b32 v49, v123, v24
	s_waitcnt lgkmcnt(4)
; __device__ __forceinline__ void route_task(int task, int tl0, const bf16* QP  , const LAS bf16* KHL, LAS unsigned short* EL, LAS float* GL, int lane) {
;     ...
;         merge16_desc(cur, oth);
; #pragma unroll
;         for (int i = 0; i < 16; ++i) top[half][i] = cur[i];
;     }
;     unsigned P1[4], P2[4];
; #pragma unroll
;     for (int q = 0; q < 4; ++q) { P1[q] = 0u; P2[q] = 0u;
; #pragma unroll
;         for (int s = 0; s < 4; ++s) { P1[q] |= (127u - ((unsigned)top[0][4 * q + s] & 127u)) << (8 * s); P2[q] |= (127u - ((unsigned)top[1][4 * q + s] & 127u)) << (8 * s); } }
;     int bk[16];
;     {
;         int hi2 = hi; asm volatile("" : "+v"(hi2));
;         const bool h1 = hi2 != 0;
;         constexpr int A1[16] = {1, 1, 1, 1, 1, 1, 1, 1, 2, 2, 2, 2, 2, 3, 3, 3}, B1[16] = {0, 1, 2, 3, 4, 5, 6, 7, 0, 1, 2, 3, 4, 0, 1, 2};
; #pragma unroll
;         for (int i = 0; i < 16; ++i) { const float ta = __int_as_float(h1 ? top[0][A1[i]] : top[0][0]), tb = __int_as_float(h1 ? top[1][B1[i]] : top[1][i]); const unsigned code = h1 ? (unsigned)(A1[i] * 16 + B1[i]) : (unsigned)i;
;             bk[i] = (int)((__float_as_uint(ta + tb) | 255u) - code); }
	v_max_i32_e32 v32, v32, v45
	s_waitcnt lgkmcnt(3)
	v_max_i32_e32 v25, v25, v46
	s_waitcnt lgkmcnt(2)
	v_max_i32_e32 v23, v23, v47
	s_waitcnt lgkmcnt(1)
	v_max_i32_e32 v22, v22, v48
	s_waitcnt lgkmcnt(0)
	v_max_i32_e32 v21, v21, v49
	v_max_i32_e32 v20, v20, v44
	v_max_i32_e32 v19, v19, v43
	v_max_i32_e32 v18, v18, v42
	v_max_i32_e32 v31, v31, v41
	v_max_i32_e32 v28, v28, v40
	v_max_i32_e32 v27, v27, v39
	v_max_i32_e32 v24, v24, v38
	v_max_i32_e32 v30, v30, v37
	v_max_i32_e32 v26, v26, v36
	v_max_i32_e32 v29, v29, v35
	v_max_i32_e32 v33, v33, v34
	v_max_i32_e32 v34, v32, v31
	v_min_i32_e32 v31, v32, v31
	v_max_i32_e32 v32, v25, v28
	v_min_i32_e32 v25, v25, v28
	v_max_i32_e32 v28, v23, v27
	v_min_i32_e32 v23, v23, v27
	v_max_i32_e32 v27, v22, v24
	v_min_i32_e32 v22, v22, v24
	v_max_i32_e32 v24, v21, v30
	v_min_i32_e32 v21, v21, v30
	v_max_i32_e32 v30, v20, v26
	v_min_i32_e32 v20, v20, v26
	v_max_i32_e32 v26, v19, v29
	v_min_i32_e32 v19, v19, v29
	v_max_i32_e32 v29, v18, v33
	v_min_i32_e32 v18, v18, v33
	v_max_i32_e32 v33, v34, v24
	v_min_i32_e32 v24, v34, v24
	v_max_i32_e32 v34, v32, v30
	v_min_i32_e32 v30, v32, v30
	v_max_i32_e32 v32, v28, v26
	v_min_i32_e32 v26, v28, v26
	v_max_i32_e32 v28, v27, v29
	v_min_i32_e32 v27, v27, v29
	v_max_i32_e32 v29, v31, v21
	v_min_i32_e32 v21, v31, v21
	v_max_i32_e32 v31, v25, v20
	v_min_i32_e32 v20, v25, v20
	v_max_i32_e32 v25, v23, v19
	v_min_i32_e32 v19, v23, v19
	v_max_i32_e32 v23, v22, v18
	v_min_i32_e32 v18, v22, v18
	v_max_i32_e32 v22, v33, v32
	v_min_i32_e32 v32, v33, v32
	v_max_i32_e32 v33, v34, v28
	v_min_i32_e32 v28, v34, v28
	v_max_i32_e32 v34, v24, v26
	v_min_i32_e32 v24, v24, v26
	v_max_i32_e32 v35, v30, v27
	v_min_i32_e32 v27, v30, v27
	v_max_i32_e32 v30, v29, v25
	v_min_i32_e32 v25, v29, v25
	v_max_i32_e32 v29, v31, v23
	v_min_i32_e32 v23, v31, v23
	v_max_i32_e32 v31, v21, v19
	v_min_i32_e32 v19, v21, v19
	v_max_i32_e32 v21, v20, v18
	v_min_i32_e32 v18, v20, v18
	v_max_i32_e32 v26, v22, v33
	v_min_i32_e32 v33, v22, v33
	v_lshlrev_b32_e32 v20, 8, v81
	v_lshlrev_b32_e32 v22, 16, v80
	v_max_i32_e32 v36, v32, v28
	v_max_i32_e32 v40, v19, v18
	v_min_i32_e32 v41, v19, v18
	v_and_b32_e32 v18, 0x7f, v79
	v_and_b32_e32 v20, 0x7f00, v20
	v_and_b32_e32 v22, 0x7f0000, v22
	v_max_i32_e32 v39, v31, v21
	v_min_i32_e32 v31, v31, v21
	v_lshlrev_b32_e32 v21, 8, v33
	v_or3_b32 v18, v20, v18, v22
	v_lshlrev_b32_e32 v20, 16, v36
	v_and_b32_e32 v19, 0x7f, v26
	v_and_b32_e32 v21, 0x7f00, v21
	v_and_b32_e32 v20, 0x7f0000, v20
	v_or3_b32 v20, v21, v19, v20
	v_lshlrev_b32_e32 v19, 24, v78
	v_min_i32_e32 v28, v32, v28
	v_and_b32_e32 v19, 0x7f000000, v19
	v_bitop3_b32 v19, v18, s68, v19 bitop3:0x36
	v_lshlrev_b32_e32 v18, 24, v28
	v_max_i32_e32 v32, v34, v35
	v_min_i32_e32 v34, v34, v35
	v_max_i32_e32 v35, v24, v27
	v_min_i32_e32 v27, v24, v27
	v_and_b32_e32 v18, 0x7f000000, v18
	v_lshlrev_b32_e32 v22, 8, v76
	v_lshlrev_b32_e32 v24, 16, v75
	v_bitop3_b32 v18, v20, s68, v18 bitop3:0x36
	v_and_b32_e32 v20, 0x7f, v77
	v_and_b32_e32 v22, 0x7f00, v22
	v_and_b32_e32 v24, 0x7f0000, v24
	v_max_i32_e32 v37, v30, v29
	v_min_i32_e32 v29, v30, v29
	v_max_i32_e32 v30, v25, v23
	v_min_i32_e32 v38, v25, v23
	v_lshlrev_b32_e32 v23, 8, v34
	v_or3_b32 v20, v22, v20, v24
	v_lshlrev_b32_e32 v22, 16, v35
	v_and_b32_e32 v21, 0x7f, v32
	v_and_b32_e32 v23, 0x7f00, v23
	v_and_b32_e32 v22, 0x7f0000, v22
	v_or3_b32 v22, v23, v21, v22
	v_lshlrev_b32_e32 v21, 24, v73
	v_and_b32_e32 v21, 0x7f000000, v21
	v_bitop3_b32 v21, v20, s68, v21 bitop3:0x36
	v_lshlrev_b32_e32 v20, 24, v27
	v_and_b32_e32 v20, 0x7f000000, v20
	v_lshlrev_b32_e32 v24, 8, v74
	v_lshlrev_b32_e32 v42, 16, v72
	v_bitop3_b32 v20, v22, s68, v20 bitop3:0x36
	v_and_b32_e32 v22, 0x7f, v71
	v_and_b32_e32 v24, 0x7f00, v24
	v_and_b32_e32 v42, 0x7f0000, v42
	v_lshlrev_b32_e32 v25, 8, v29
	v_or3_b32 v22, v24, v22, v42
	v_lshlrev_b32_e32 v24, 16, v30
	v_and_b32_e32 v23, 0x7f, v37
	v_and_b32_e32 v25, 0x7f00, v25
	v_and_b32_e32 v24, 0x7f0000, v24
	v_or3_b32 v24, v25, v23, v24
	v_lshlrev_b32_e32 v23, 24, v70
	v_and_b32_e32 v23, 0x7f000000, v23
	v_bitop3_b32 v23, v22, s68, v23 bitop3:0x36
	v_lshlrev_b32_e32 v22, 24, v38
	v_and_b32_e32 v22, 0x7f000000, v22
	v_lshlrev_b32_e32 v42, 8, v68
	v_lshlrev_b32_e32 v44, 16, v67
	v_bitop3_b32 v22, v24, s68, v22 bitop3:0x36
	v_and_b32_e32 v24, 0x7f, v69
	v_and_b32_e32 v42, 0x7f00, v42
	v_and_b32_e32 v44, 0x7f0000, v44
	v_lshlrev_b32_e32 v43, 8, v31
	v_or3_b32 v24, v42, v24, v44
	v_lshlrev_b32_e32 v42, 16, v40
	v_and_b32_e32 v25, 0x7f, v39
	v_and_b32_e32 v43, 0x7f00, v43
	v_and_b32_e32 v42, 0x7f0000, v42
	v_or3_b32 v42, v43, v25, v42
	v_lshlrev_b32_e32 v25, 24, v66
	v_and_b32_e32 v25, 0x7f000000, v25
	v_bitop3_b32 v25, v24, s68, v25 bitop3:0x36
	v_lshlrev_b32_e32 v24, 24, v41
	v_and_b32_e32 v24, 0x7f000000, v24
	v_bitop3_b32 v24, v42, s68, v24 bitop3:0x36
	v_mov_b32_e32 v42, v86
	v_add_f32_e32 v62, v74, v26
	v_cmp_eq_u32_e32 vcc, 0, v42
	v_add_f32_e32 v63, v72, v26
	v_add_f32_e32 v64, v70, v26
	v_cndmask_b32_e32 v42, v81, v79, vcc
	v_add_f32_e32 v44, v42, v26
	v_cndmask_b32_e64 v43, -16, 0, vcc
	v_or_b32_e32 v44, 0xff, v44
	v_add_f32_e32 v45, v42, v33
	v_add_u32_e32 v43, v44, v43
	v_cndmask_b32_e64 v44, v99, -1, vcc
	v_or_b32_e32 v45, 0xff, v45
	v_add_f32_e32 v46, v42, v36
	v_add_u32_e32 v44, v45, v44
	v_cndmask_b32_e64 v45, v100, -2, vcc
	v_or_b32_e32 v46, 0xff, v46
	v_add_f32_e32 v47, v42, v28
	v_add_u32_e32 v45, v46, v45
	v_cndmask_b32_e64 v46, v101, -3, vcc
	v_or_b32_e32 v47, 0xff, v47
	v_add_f32_e32 v48, v42, v32
	v_add_u32_e32 v46, v47, v46
	v_cndmask_b32_e64 v47, v102, -4, vcc
	v_or_b32_e32 v48, 0xff, v48
	v_add_f32_e32 v34, v42, v34
	v_add_f32_e32 v35, v42, v35
; __device__ __forceinline__ void route_task(int task, int tl0, const bf16* QP  , const LAS bf16* KHL, LAS unsigned short* EL, LAS float* GL, int lane) {
;     ...
; #pragma unroll
;         for (int i = 0; i < 16; ++i) { const float ta = __int_as_float(h1 ? top[0][A1[i]] : top[0][0]), tb = __int_as_float(h1 ? top[1][B1[i]] : top[1][i]); const unsigned code = h1 ? (unsigned)(A1[i] * 16 + B1[i]) : (unsigned)i;
;             bk[i] = (int)((__float_as_uint(ta + tb) | 255u) - code); }
;         sort16_desc(bk);
;         int oth[16];
; #pragma unroll
;         for (int i = 0; i < 16; ++i) oth[i] = __shfl_xor(bk[i], 32);
;         merge16_desc(bk, oth);
	v_add_f32_e32 v27, v42, v27
	v_cndmask_b32_e32 v42, v80, v79, vcc
	v_cndmask_b32_e32 v32, v32, v39, vcc
	v_add_u32_e32 v47, v48, v47
	v_cndmask_b32_e64 v48, v103, -5, vcc
	v_or_b32_e32 v34, 0xff, v34
	v_add_f32_e32 v32, v42, v32
	v_add_u32_e32 v34, v34, v48
	v_cndmask_b32_e64 v48, v104, -6, vcc
	v_or_b32_e32 v35, 0xff, v35
	v_cndmask_b32_e32 v37, v26, v37, vcc
	v_cndmask_b32_e64 v39, v116, -12, vcc
	v_or_b32_e32 v32, 0xff, v32
	v_add_u32_e32 v35, v35, v48
	v_cndmask_b32_e64 v48, v105, -7, vcc
	v_or_b32_e32 v27, 0xff, v27
	v_add_f32_e32 v37, v42, v37
	v_cndmask_b32_e32 v29, v33, v29, vcc
	v_add_u32_e32 v32, v32, v39
	v_cndmask_b32_e32 v39, v78, v79, vcc
	v_cndmask_b32_e32 v31, v26, v31, vcc
	v_add_u32_e32 v27, v27, v48
	v_cndmask_b32_e64 v48, v106, -8, vcc
	v_or_b32_e32 v37, 0xff, v37
	v_add_f32_e32 v29, v42, v29
	v_cndmask_b32_e32 v30, v36, v30, vcc
	v_cndmask_b32_e32 v38, v28, v38, vcc
	v_add_f32_e32 v31, v39, v31
	v_cndmask_b32_e32 v40, v33, v40, vcc
	v_add_u32_e32 v37, v37, v48
	v_cndmask_b32_e64 v48, v107, -9, vcc
	v_or_b32_e32 v29, 0xff, v29
	v_add_f32_e32 v30, v42, v30
	v_add_f32_e32 v38, v42, v38
	v_cndmask_b32_e64 v42, v117, -13, vcc
	v_or_b32_e32 v31, 0xff, v31
	v_add_f32_e32 v40, v39, v40
	v_cndmask_b32_e32 v41, v36, v41, vcc
	v_add_u32_e32 v29, v29, v48
	v_cndmask_b32_e64 v48, v114, -10, vcc
	v_or_b32_e32 v30, 0xff, v30
	v_add_u32_e32 v31, v31, v42
	v_cndmask_b32_e64 v42, v118, -14, vcc
	v_or_b32_e32 v40, 0xff, v40
	v_add_f32_e32 v39, v39, v41
	v_add_u32_e32 v30, v30, v48
	v_cndmask_b32_e64 v48, v115, -11, vcc
	v_or_b32_e32 v38, 0xff, v38
	v_add_u32_e32 v40, v40, v42
	v_cndmask_b32_e64 v42, v119, -15, vcc
	v_or_b32_e32 v39, 0xff, v39
	v_add_u32_e32 v38, v38, v48
	v_add_u32_e32 v39, v39, v42
	v_max_i32_e32 v41, v43, v31
	v_min_i32_e32 v31, v43, v31
	v_max_i32_e32 v42, v44, v32
	v_min_i32_e32 v32, v44, v32
	v_max_i32_e32 v43, v45, v39
	v_min_i32_e32 v39, v45, v39
	v_max_i32_e32 v44, v46, v40
	v_min_i32_e32 v40, v46, v40
	v_max_i32_e32 v45, v47, v37
	v_min_i32_e32 v37, v47, v37
	v_max_i32_e32 v46, v34, v35
	v_min_i32_e32 v34, v34, v35
	v_max_i32_e32 v35, v27, v38
	v_min_i32_e32 v27, v27, v38
	v_max_i32_e32 v38, v29, v30
	v_min_i32_e32 v29, v29, v30
	v_max_i32_e32 v30, v41, v46
	v_min_i32_e32 v41, v41, v46
	v_max_i32_e32 v46, v42, v35
	v_min_i32_e32 v35, v42, v35
	v_max_i32_e32 v42, v43, v38
	v_min_i32_e32 v38, v43, v38
	v_max_i32_e32 v43, v44, v45
	v_min_i32_e32 v44, v44, v45
	v_max_i32_e32 v45, v34, v31
	v_min_i32_e32 v31, v34, v31
	v_max_i32_e32 v34, v37, v40
	v_min_i32_e32 v37, v37, v40
	v_max_i32_e32 v40, v29, v39
	v_min_i32_e32 v29, v29, v39
	v_max_i32_e32 v39, v27, v32
	v_min_i32_e32 v27, v27, v32
	v_max_i32_e32 v32, v30, v46
	v_min_i32_e32 v30, v30, v46
	v_max_i32_e32 v46, v42, v43
	v_min_i32_e32 v42, v42, v43
	v_max_i32_e32 v43, v44, v41
	v_min_i32_e32 v41, v44, v41
	v_max_i32_e32 v44, v45, v34
	v_min_i32_e32 v34, v45, v34
	v_max_i32_e32 v45, v35, v38
	v_min_i32_e32 v35, v35, v38
	v_max_i32_e32 v38, v40, v39
	v_min_i32_e32 v39, v40, v39
	v_max_i32_e32 v40, v27, v31
	v_min_i32_e32 v27, v27, v31
	v_max_i32_e32 v31, v37, v29
	v_min_i32_e32 v29, v37, v29
	v_max_i32_e32 v37, v32, v46
	v_min_i32_e32 v32, v32, v46
	v_max_i32_e32 v46, v30, v42
	v_min_i32_e32 v30, v30, v42
	v_max_i32_e32 v42, v43, v38
	v_min_i32_e32 v38, v43, v38
	v_max_i32_e32 v43, v41, v39
	v_min_i32_e32 v39, v41, v39
	v_max_i32_e32 v41, v44, v45
	v_min_i32_e32 v44, v44, v45
	v_max_i32_e32 v45, v34, v35
	v_min_i32_e32 v34, v34, v35
	v_max_i32_e32 v35, v40, v31
	v_min_i32_e32 v31, v40, v31
	v_max_i32_e32 v40, v27, v29
	v_min_i32_e32 v27, v27, v29
	v_max_i32_e32 v29, v46, v32
	v_min_i32_e32 v32, v46, v32
	v_max_i32_e32 v46, v30, v35
	v_min_i32_e32 v30, v30, v35
	v_max_i32_e32 v35, v42, v41
	v_min_i32_e32 v41, v42, v41
	v_max_i32_e32 v42, v43, v44
	v_min_i32_e32 v43, v43, v44
	v_max_i32_e32 v44, v45, v38
	v_min_i32_e32 v38, v45, v38
	v_max_i32_e32 v45, v34, v39
	v_min_i32_e32 v34, v34, v39
	v_max_i32_e32 v39, v40, v31
	v_min_i32_e32 v31, v40, v31
	v_max_i32_e32 v40, v29, v35
	v_min_i32_e32 v29, v29, v35
	v_max_i32_e32 v35, v32, v41
	v_min_i32_e32 v32, v32, v41
	v_max_i32_e32 v41, v42, v44
	v_min_i32_e32 v42, v42, v44
	v_max_i32_e32 v44, v43, v38
	v_min_i32_e32 v38, v43, v38
	v_max_i32_e32 v43, v45, v39
	v_min_i32_e32 v39, v45, v39
	v_max_i32_e32 v45, v34, v31
	v_min_i32_e32 v31, v34, v31
	v_max_i32_e32 v34, v35, v29
	v_min_i32_e32 v29, v35, v29
	v_max_i32_e32 v35, v46, v32
	v_min_i32_e32 v32, v46, v32
	v_max_i32_e32 v46, v43, v30
	v_min_i32_e32 v30, v43, v30
	v_max_i32_e32 v43, v45, v39
	v_min_i32_e32 v39, v45, v39
	v_max_i32_e32 v45, v35, v41
	v_min_i32_e32 v35, v35, v41
	v_max_i32_e32 v41, v32, v42
	v_min_i32_e32 v32, v32, v42
	v_max_i32_e32 v42, v44, v46
	v_min_i32_e32 v44, v44, v46
	v_max_i32_e32 v46, v38, v30
	v_min_i32_e32 v30, v38, v30
	v_max_i32_e32 v38, v45, v29
	v_min_i32_e32 v29, v45, v29
	v_max_i32_e32 v45, v35, v41
	v_min_i32_e32 v35, v35, v41
	v_max_i32_e32 v41, v42, v32
	v_min_i32_e32 v32, v42, v32
	v_max_i32_e32 v42, v44, v46
	v_min_i32_e32 v44, v44, v46
	v_max_i32_e32 v46, v43, v30
	v_min_i32_e32 v30, v43, v30
	v_max_i32_e32 v43, v35, v41
	v_min_i32_e32 v35, v35, v41
	v_max_i32_e32 v41, v32, v42
	v_min_i32_e32 v32, v32, v42
	ds_bpermute_b32 v54, v123, v41
	ds_bpermute_b32 v55, v123, v32
	ds_bpermute_b32 v56, v123, v44
	ds_bpermute_b32 v57, v123, v27
	ds_bpermute_b32 v58, v123, v31
	ds_bpermute_b32 v59, v123, v39
	ds_bpermute_b32 v60, v123, v30
	ds_bpermute_b32 v61, v123, v46
	ds_bpermute_b32 v42, v123, v37
	ds_bpermute_b32 v47, v123, v40
	ds_bpermute_b32 v48, v123, v34
	ds_bpermute_b32 v49, v123, v38
	ds_bpermute_b32 v50, v123, v29
	ds_bpermute_b32 v51, v123, v45
	ds_bpermute_b32 v52, v123, v43
	ds_bpermute_b32 v53, v123, v35
	s_waitcnt lgkmcnt(12)
; #define CAND(a, b) (int)((__float_as_uint(__int_as_float(top[0][a]) + __int_as_float(top[1][b])) | 255u) - (unsigned)((a) * 16 + (b)))
; __device__ __forceinline__ void route_task(int task, int tl0, const bf16* QP  , const LAS bf16* KHL, LAS unsigned short* EL, LAS float* GL, int lane) {
;     ...
; #pragma unroll
;         for (int i = 0; i < 16; ++i) oth[i] = __shfl_xor(bk[i], 32);
;         merge16_desc(bk, oth);
;     }
;     ...
;     {
;         int gk[16];
;         gk[0] = CAND(3, 3); gk[1] = CAND(4, 0); gk[2] = CAND(4, 1); gk[3] = CAND(4, 2); gk[4] = CAND(5, 0); gk[5] = CAND(5, 1); gk[6] = CAND(6, 0); gk[7] = CAND(6, 1);
;         gk[8] = CAND(7, 0); gk[9] = CAND(7, 1); gk[10] = CAND(8, 0); gk[11] = CAND(9, 0); gk[12] = CAND(10, 0); gk[13] = CAND(11, 0); gk[14] = CAND(12, 0); gk[15] = CAND(13, 0);
;         sort16_desc(gk);
	v_max_i32_e32 v37, v37, v57
	s_waitcnt lgkmcnt(11)
	v_max_i32_e32 v40, v40, v58
	s_waitcnt lgkmcnt(10)
	v_max_i32_e32 v34, v34, v59
	s_waitcnt lgkmcnt(9)
	v_max_i32_e32 v38, v38, v60
	s_waitcnt lgkmcnt(8)
	v_max_i32_e32 v29, v29, v61
	v_max_i32_e32 v45, v45, v56
	v_max_i32_e32 v43, v43, v55
	v_max_i32_e32 v35, v35, v54
	v_add_f32_e32 v28, v78, v28
	v_add_f32_e32 v54, v77, v26
	v_add_f32_e32 v55, v77, v33
	v_add_f32_e32 v36, v77, v36
	v_add_f32_e32 v56, v76, v26
	v_add_f32_e32 v57, v76, v33
	v_add_f32_e32 v58, v75, v26
	v_add_f32_e32 v59, v75, v33
	v_add_f32_e32 v60, v73, v26
	v_add_f32_e32 v33, v73, v33
	v_add_f32_e32 v61, v71, v26
	v_add_f32_e32 v65, v69, v26
	v_add_f32_e32 v68, v68, v26
	v_or_b32_e32 v28, 0xff, v28
	v_or_b32_e32 v54, 0xff, v54
	v_or_b32_e32 v55, 0xff, v55
	v_or_b32_e32 v36, 0xff, v36
	v_or_b32_e32 v56, 0xff, v56
	v_or_b32_e32 v57, 0xff, v57
	v_or_b32_e32 v58, 0xff, v58
	v_or_b32_e32 v59, 0xff, v59
	v_or_b32_e32 v60, 0xff, v60
	v_or_b32_e32 v33, 0xff, v33
	v_or_b32_e32 v61, 0xff, v61
	v_or_b32_e32 v62, 0xff, v62
	v_or_b32_e32 v63, 0xff, v63
	v_or_b32_e32 v64, 0xff, v64
	v_or_b32_e32 v65, 0xff, v65
	v_or_b32_e32 v68, 0xff, v68
	v_subrev_u32_e32 v28, 51, v28
	v_subrev_u32_e32 v54, 64, v54
	v_add_u32_e32 v55, 0xffffffbf, v55
	v_add_u32_e32 v36, 0xffffffbe, v36
	v_add_u32_e32 v56, 0xffffffb0, v56
	v_add_u32_e32 v57, 0xffffffaf, v57
	v_add_u32_e32 v58, 0xffffffa0, v58
	v_add_u32_e32 v59, 0xffffff9f, v59
	v_add_u32_e32 v60, 0xffffff90, v60
	v_add_u32_e32 v33, 0xffffff8f, v33
	v_add_u32_e32 v61, 0xffffff80, v61
	v_add_u32_e32 v62, 0xffffff70, v62
	v_add_u32_e32 v63, 0xffffff60, v63
	v_add_u32_e32 v64, 0xffffff50, v64
	v_add_u32_e32 v65, 0xffffff40, v65
	v_add_u32_e32 v68, 0xffffff30, v68
	v_max_i32_e32 v69, v28, v64
	v_min_i32_e32 v28, v28, v64
	v_max_i32_e32 v64, v54, v63
	v_min_i32_e32 v54, v54, v63
	v_max_i32_e32 v63, v55, v68
	v_min_i32_e32 v55, v55, v68
	v_max_i32_e32 v68, v36, v65
	v_min_i32_e32 v36, v36, v65
	v_max_i32_e32 v65, v56, v60
	v_min_i32_e32 v56, v56, v60
	v_max_i32_e32 v60, v57, v58
	v_min_i32_e32 v57, v57, v58
	v_max_i32_e32 v58, v59, v62
	v_min_i32_e32 v59, v59, v62
	v_max_i32_e32 v62, v33, v61
	v_min_i32_e32 v33, v33, v61
	v_max_i32_e32 v61, v69, v60
	v_min_i32_e32 v60, v69, v60
	v_max_i32_e32 v69, v64, v58
	v_min_i32_e32 v58, v64, v58
	v_max_i32_e32 v64, v63, v62
	v_min_i32_e32 v62, v63, v62
	v_max_i32_e32 v63, v68, v65
	v_min_i32_e32 v65, v68, v65
	v_max_i32_e32 v68, v57, v28
	v_min_i32_e32 v28, v57, v28
	v_max_i32_e32 v57, v56, v36
	v_min_i32_e32 v36, v56, v36
	v_max_i32_e32 v56, v33, v55
	v_min_i32_e32 v33, v33, v55
	v_max_i32_e32 v55, v59, v54
	v_min_i32_e32 v54, v59, v54
	v_max_i32_e32 v59, v61, v69
	v_min_i32_e32 v61, v61, v69
	v_max_i32_e32 v69, v64, v63
	v_min_i32_e32 v63, v64, v63
	v_max_i32_e32 v64, v65, v60
	v_min_i32_e32 v60, v65, v60
	v_max_i32_e32 v65, v68, v57
	v_min_i32_e32 v57, v68, v57
	v_max_i32_e32 v68, v58, v62
	v_min_i32_e32 v58, v58, v62
	v_max_i32_e32 v62, v56, v55
	v_min_i32_e32 v55, v56, v55
	v_max_i32_e32 v56, v54, v28
	v_min_i32_e32 v28, v54, v28
	v_max_i32_e32 v54, v36, v33
	v_min_i32_e32 v33, v36, v33
	v_min_i32_e32 v36, v59, v69
	v_max_i32_e32 v70, v61, v63
	v_min_i32_e32 v61, v61, v63
	v_max_i32_e32 v63, v64, v62
	v_min_i32_e32 v62, v64, v62
	v_max_i32_e32 v64, v60, v55
	v_min_i32_e32 v55, v60, v55
	v_max_i32_e32 v60, v65, v68
	v_min_i32_e32 v65, v65, v68
	v_max_i32_e32 v68, v57, v58
	v_min_i32_e32 v57, v57, v58
	v_max_i32_e32 v58, v56, v54
	v_min_i32_e32 v54, v56, v54
	v_max_i32_e32 v56, v28, v33
	v_min_i32_e32 v28, v28, v33
	v_max_i32_e32 v33, v70, v36
	v_min_i32_e32 v36, v70, v36
	v_max_i32_e32 v70, v61, v58
	v_min_i32_e32 v58, v61, v58
	v_max_i32_e32 v61, v63, v60
	v_min_i32_e32 v60, v63, v60
	v_max_i32_e32 v63, v64, v65
	v_min_i32_e32 v64, v64, v65
	v_max_i32_e32 v65, v68, v62
	v_min_i32_e32 v62, v68, v62
	v_max_i32_e32 v68, v57, v55
	v_min_i32_e32 v55, v57, v55
	v_max_i32_e32 v57, v56, v54
	s_waitcnt lgkmcnt(0)
	v_max_i32_e32 v41, v41, v53
	v_max_i32_e32 v32, v32, v52
	v_max_i32_e32 v44, v44, v51
	v_max_i32_e32 v46, v46, v50
	v_max_i32_e32 v30, v30, v49
	v_max_i32_e32 v39, v39, v48
	v_max_i32_e32 v31, v31, v47
	v_max_i32_e32 v27, v27, v42
	v_min_i32_e32 v54, v56, v54
	v_max_i32_e32 v56, v33, v61
	v_min_i32_e32 v33, v33, v61
	v_max_i32_e32 v61, v36, v60
	v_min_i32_e32 v36, v36, v60
	v_max_i32_e32 v60, v63, v65
	v_min_i32_e32 v63, v63, v65
	v_max_i32_e32 v65, v64, v62
	v_min_i32_e32 v62, v64, v62
	v_max_i32_e32 v64, v68, v57
	v_max_i32_e32 v42, v37, v41
	v_min_i32_e32 v37, v37, v41
	v_max_i32_e32 v41, v40, v32
	v_min_i32_e32 v32, v40, v32
	v_max_i32_e32 v40, v34, v44
	v_min_i32_e32 v34, v34, v44
	v_max_i32_e32 v44, v38, v46
	v_min_i32_e32 v38, v38, v46
	v_max_i32_e32 v46, v29, v30
	v_min_i32_e32 v29, v29, v30
	v_max_i32_e32 v30, v45, v39
	v_min_i32_e32 v39, v45, v39
	v_max_i32_e32 v45, v43, v31
	v_min_i32_e32 v31, v43, v31
	v_max_i32_e32 v43, v35, v27
	v_min_i32_e32 v27, v35, v27
	v_min_i32_e32 v57, v68, v57
	v_max_i32_e32 v68, v55, v54
	v_max_i32_e32 v71, v70, v36
	v_min_i32_e32 v36, v70, v36
	v_max_i32_e32 v70, v64, v58
	v_min_i32_e32 v58, v64, v58
	v_max_i32_e32 v35, v42, v46
	v_min_i32_e32 v42, v42, v46
	v_max_i32_e32 v46, v41, v30
	v_min_i32_e32 v30, v41, v30
	v_max_i32_e32 v41, v40, v45
	v_min_i32_e32 v40, v40, v45
	v_max_i32_e32 v45, v44, v43
	v_min_i32_e32 v43, v44, v43
	v_max_i32_e32 v44, v37, v29
	v_min_i32_e32 v29, v37, v29
	v_max_i32_e32 v37, v32, v39
	v_min_i32_e32 v32, v32, v39
	v_max_i32_e32 v39, v34, v31
	v_min_i32_e32 v31, v34, v31
	v_max_i32_e32 v34, v38, v27
	v_min_i32_e32 v27, v38, v27
	v_min_i32_e32 v54, v55, v54
	v_min_i32_e32 v55, v61, v33
; #define CAND(a, b) (int)((__float_as_uint(__int_as_float(top[0][a]) + __int_as_float(top[1][b])) | 255u) - (unsigned)((a) * 16 + (b)))
; __device__ __forceinline__ void route_task(int task, int tl0, const bf16* QP  , const LAS bf16* KHL, LAS unsigned short* EL, LAS float* GL, int lane) {
;     ...
;         merge16_desc(bk, gk);
;     }
;     {
;         const int c14 = CAND(14, 0), c15 = CAND(15, 0);
;         const int n14 = max(bk[14], c14), n15 = max(min(bk[14], c14), max(bk[15], c15));
;         bk[14] = n14; bk[15] = n15;
;     }
;     ...
;     int my[8];
; #pragma unroll
;     for (int i = 0; i < 8; ++i) { int lo_ = bk[i], hi_ = bk[8 + i]; asm volatile("" : "+v"(lo_), "+v"(hi_)); my[i] = hi ? hi_ : lo_; }
;     int bv[8];
; #pragma unroll
;     for (int i = 0; i < 8; ++i) {
;         const unsigned cd = 255u - ((unsigned)my[i] & 255u), ca = cd >> 4, cb = cd & 15u;
;         const unsigned wa = (ca >> 2) == 0u ? P1[0] : (ca >> 2) == 1u ? P1[1] : (ca >> 2) == 2u ? P1[2] : P1[3];
;         const unsigned wb = (cb >> 2) == 0u ? P2[0] : (cb >> 2) == 1u ? P2[1] : (cb >> 2) == 2u ? P2[2] : P2[3];
;         bv[i] = (int)((((wa >> (8u * (ca & 3u))) & 255u) << 7) | ((wb >> (8u * (cb & 3u))) & 255u));
	v_max_i32_e32 v64, v68, v57
	v_min_i32_e32 v57, v68, v57
	v_max_i32_e32 v68, v71, v60
	v_min_i32_e32 v60, v71, v60
	v_max_i32_e32 v71, v36, v63
	v_min_i32_e32 v36, v36, v63
	v_max_i32_e32 v63, v65, v70
	v_min_i32_e32 v65, v65, v70
	v_max_i32_e32 v70, v62, v58
	v_max_i32_e32 v38, v35, v41
	v_min_i32_e32 v35, v35, v41
	v_max_i32_e32 v41, v46, v45
	v_min_i32_e32 v45, v46, v45
	v_max_i32_e32 v46, v42, v40
	v_min_i32_e32 v40, v42, v40
	v_max_i32_e32 v42, v30, v43
	v_min_i32_e32 v30, v30, v43
	v_max_i32_e32 v43, v44, v39
	v_min_i32_e32 v39, v44, v39
	v_max_i32_e32 v44, v37, v34
	v_min_i32_e32 v34, v37, v34
	v_max_i32_e32 v37, v29, v31
	v_min_i32_e32 v29, v29, v31
	v_max_i32_e32 v31, v32, v27
	v_min_i32_e32 v27, v32, v27
	v_min_i32_e32 v58, v62, v58
	v_max_i32_e32 v62, v68, v55
	v_min_i32_e32 v55, v68, v55
	v_max_i32_e32 v68, v60, v71
	v_min_i32_e32 v60, v60, v71
	v_max_i32_e32 v71, v63, v36
	v_min_i32_e32 v36, v63, v36
	v_max_i32_e32 v63, v65, v70
	v_min_i32_e32 v32, v38, v41
	v_min_i32_e32 v47, v35, v45
	v_min_i32_e32 v48, v46, v42
	v_min_i32_e32 v49, v40, v30
	v_min_i32_e32 v50, v43, v44
	v_min_i32_e32 v51, v39, v34
	v_min_i32_e32 v52, v37, v31
	v_min_i32_e32 v53, v29, v27
	v_min_i32_e32 v65, v65, v70
	v_max_i32_e32 v70, v64, v58
	v_min_i32_e32 v58, v64, v58
	v_min_i32_e32 v64, v60, v71
	v_min_i32_e32 v72, v36, v63
	v_max3_i32 v28, v38, v41, v28
	v_max_i32_e32 v32, v32, v54
	v_max3_i32 v35, v35, v45, v57
	v_max_i32_e32 v38, v47, v58
	v_max3_i32 v41, v46, v42, v70
	v_max_i32_e32 v42, v48, v65
	v_max3_i32 v30, v40, v30, v72
	v_max3_i32 v36, v49, v36, v63
	v_max3_i32 v40, v43, v44, v64
	v_max3_i32 v43, v50, v60, v71
	v_max3_i32 v34, v39, v34, v68
	v_max_i32_e32 v39, v51, v55
	v_max3_i32 v31, v37, v31, v62
	v_max3_i32 v33, v52, v61, v33
	v_max3_i32 v27, v29, v27, v56
	v_max3_i32 v29, v53, v59, v69
	v_max_i32_e32 v37, v28, v40
	v_min_i32_e32 v28, v28, v40
	v_max_i32_e32 v40, v32, v43
	v_min_i32_e32 v32, v32, v43
	v_max_i32_e32 v43, v35, v34
	v_min_i32_e32 v34, v35, v34
	v_max_i32_e32 v35, v38, v39
	v_min_i32_e32 v38, v38, v39
	v_max_i32_e32 v39, v41, v31
	v_min_i32_e32 v31, v41, v31
	v_max_i32_e32 v41, v42, v33
	v_min_i32_e32 v33, v42, v33
	v_max_i32_e32 v42, v30, v27
	v_min_i32_e32 v27, v30, v27
	v_max_i32_e32 v30, v36, v29
	v_min_i32_e32 v29, v36, v29
	v_max_i32_e32 v36, v37, v39
	v_min_i32_e32 v37, v37, v39
	v_max_i32_e32 v39, v40, v41
	v_min_i32_e32 v40, v40, v41
	v_max_i32_e32 v41, v43, v42
	v_min_i32_e32 v42, v43, v42
	v_max_i32_e32 v43, v35, v30
	v_min_i32_e32 v30, v35, v30
	v_max_i32_e32 v35, v28, v31
	v_min_i32_e32 v28, v28, v31
	v_max_i32_e32 v31, v32, v33
	v_min_i32_e32 v32, v32, v33
	v_max_i32_e32 v33, v34, v27
	v_min_i32_e32 v27, v34, v27
	v_max_i32_e32 v34, v38, v29
	v_min_i32_e32 v29, v38, v29
	v_max_i32_e32 v38, v36, v41
	v_min_i32_e32 v36, v36, v41
	v_max_i32_e32 v41, v39, v43
	v_min_i32_e32 v39, v39, v43
	v_max_i32_e32 v43, v37, v42
	v_min_i32_e32 v37, v37, v42
	v_max_i32_e32 v42, v40, v30
	v_min_i32_e32 v30, v40, v30
	v_max_i32_e32 v40, v35, v33
	v_min_i32_e32 v33, v35, v33
	v_max_i32_e32 v35, v31, v34
	v_min_i32_e32 v31, v31, v34
	v_max_i32_e32 v34, v28, v27
	v_min_i32_e32 v27, v28, v27
	v_max_i32_e32 v28, v32, v29
	v_min_i32_e32 v29, v32, v29
	v_max_i32_e32 v32, v38, v41
	v_min_i32_e32 v38, v38, v41
	v_max_i32_e32 v41, v36, v39
	v_min_i32_e32 v36, v36, v39
	v_max_i32_e32 v39, v43, v42
	v_min_i32_e32 v42, v43, v42
	v_max_i32_e32 v43, v37, v30
	v_min_i32_e32 v30, v37, v30
	v_max_i32_e32 v37, v40, v35
	v_min_i32_e32 v35, v40, v35
	v_max_i32_e32 v40, v33, v31
	v_min_i32_e32 v31, v33, v31
	v_max_i32_e32 v33, v34, v28
	v_min_i32_e32 v28, v34, v28
	v_max_i32_e32 v34, v27, v29
	v_min_i32_e32 v27, v27, v29
	v_add_f32_e32 v29, v67, v26
	v_or_b32_e32 v29, 0xff, v29
	v_add_f32_e32 v26, v66, v26
	v_add_u32_e32 v29, 0xffffff20, v29
	v_or_b32_e32 v26, 0xff, v26
	v_add_u32_e32 v26, 0xffffff10, v26
	v_max_i32_e32 v44, v34, v29
	v_min_i32_e32 v29, v34, v29
	v_max3_i32 v26, v29, v27, v26
	v_mov_b32_e32 v27, v32
	s_nop 0
	v_cndmask_b32_e64 v27, v37, v27, s[6:7]
	v_not_b32_e32 v29, v27
	v_bfe_u32 v45, v29, 6, 2
	v_cmp_eq_u32_e32 vcc, 2, v45
	v_cndmask_b32_e64 v30, v26, v30, s[6:7]
	v_bitop3_b32 v26, v27, s3, v27 bitop3:0xc
	v_cndmask_b32_e32 v46, v25, v23, vcc
	v_cmp_eq_u32_e32 vcc, 1, v45
	v_cndmask_b32_e64 v34, v35, v38, s[6:7]
	v_not_b32_e32 v35, v34
	v_cndmask_b32_e32 v45, v46, v21, vcc
	v_cmp_gt_u32_e32 vcc, 64, v26
	v_cndmask_b32_e64 v37, v40, v41, s[6:7]
	v_cndmask_b32_e64 v41, v44, v43, s[6:7]
	v_cndmask_b32_e32 v26, v45, v19, vcc
	v_bfe_u32 v45, v29, 2, 2
	v_cmp_eq_u32_e32 vcc, 2, v45
	v_bitop3_b32 v44, v27, 15, v27 bitop3:0xc
	v_bfe_u32 v47, v35, 6, 2
	v_cndmask_b32_e32 v46, v24, v22, vcc
	v_cmp_eq_u32_e32 vcc, 1, v45
	v_not_b32_e32 v38, v37
	v_bfe_u32 v49, v38, 6, 2
	v_cndmask_b32_e32 v45, v46, v20, vcc
	v_cmp_gt_u32_e32 vcc, 4, v44
	v_bitop3_b32 v46, v34, 15, v34 bitop3:0xc
	v_cndmask_b32_e64 v31, v31, v36, s[6:7]
	v_cndmask_b32_e32 v44, v45, v18, vcc
	v_cmp_eq_u32_e32 vcc, 2, v47
	v_bitop3_b32 v45, v34, s3, v34 bitop3:0xc
	v_not_b32_e32 v36, v31
	v_cndmask_b32_e32 v48, v25, v23, vcc
	v_cmp_eq_u32_e32 vcc, 1, v47
	v_bfe_u32 v51, v36, 6, 2
	v_cndmask_b32_e64 v33, v33, v39, s[6:7]
	v_cndmask_b32_e32 v47, v48, v21, vcc
	v_cmp_gt_u32_e32 vcc, 64, v45
	v_not_b32_e32 v39, v33
	v_bfe_u32 v53, v39, 6, 2
	v_cndmask_b32_e32 v45, v47, v19, vcc
	v_bfe_u32 v47, v35, 2, 2
	v_cmp_eq_u32_e32 vcc, 2, v47
	v_cndmask_b32_e64 v28, v28, v42, s[6:7]
	v_not_b32_e32 v40, v28
	v_cndmask_b32_e32 v48, v24, v22, vcc
	v_cmp_eq_u32_e32 vcc, 1, v47
	v_bfe_u32 v55, v40, 6, 2
	v_not_b32_e32 v42, v41
	v_cndmask_b32_e32 v47, v48, v20, vcc
	v_cmp_gt_u32_e32 vcc, 4, v46
; __device__ __forceinline__ void route_task(int task, int tl0, const bf16* QP  , const LAS bf16* KHL, LAS unsigned short* EL, LAS float* GL, int lane) {
;     ...
;         const unsigned cd = 255u - ((unsigned)my[i] & 255u), ca = cd >> 4, cb = cd & 15u;
;         const unsigned wa = (ca >> 2) == 0u ? P1[0] : (ca >> 2) == 1u ? P1[1] : (ca >> 2) == 2u ? P1[2] : P1[3];
;         const unsigned wb = (cb >> 2) == 0u ? P2[0] : (cb >> 2) == 1u ? P2[1] : (cb >> 2) == 2u ? P2[2] : P2[3];
;         bv[i] = (int)((((wa >> (8u * (ca & 3u))) & 255u) << 7) | ((wb >> (8u * (cb & 3u))) & 255u));
;     }
;     float e[8], se = 0.f;
; #pragma unroll
;     for (int i = 0; i < 8; ++i) { e[i] = __expf(__int_as_float(my[i]) - __int_as_float(bk[0])); se += e[i]; }
;     se += __shfl_xor(se, 32);
	v_bitop3_b32 v48, v37, 15, v37 bitop3:0xc
	v_bfe_u32 v57, v42, 6, 2
	v_cndmask_b32_e32 v46, v47, v18, vcc
	v_cmp_eq_u32_e32 vcc, 2, v49
	v_bitop3_b32 v47, v37, s3, v37 bitop3:0xc
	v_not_b32_e32 v43, v30
	v_cndmask_b32_e32 v50, v25, v23, vcc
	v_cmp_eq_u32_e32 vcc, 1, v49
	v_bfe_u32 v59, v43, 6, 2
	s_nop 0
	v_cndmask_b32_e32 v49, v50, v21, vcc
	v_cmp_gt_u32_e32 vcc, 64, v47
	s_nop 1
	v_cndmask_b32_e32 v47, v49, v19, vcc
	v_bfe_u32 v49, v38, 2, 2
	v_cmp_eq_u32_e32 vcc, 2, v49
	s_nop 1
	v_cndmask_b32_e32 v50, v24, v22, vcc
	v_cmp_eq_u32_e32 vcc, 1, v49
	s_nop 1
	v_cndmask_b32_e32 v49, v50, v20, vcc
	v_cmp_gt_u32_e32 vcc, 4, v48
	v_bitop3_b32 v50, v31, 15, v31 bitop3:0xc
	s_nop 0
	v_cndmask_b32_e32 v48, v49, v18, vcc
	v_cmp_eq_u32_e32 vcc, 2, v51
	v_bitop3_b32 v49, v31, s3, v31 bitop3:0xc
	s_nop 0
	v_cndmask_b32_e32 v52, v25, v23, vcc
	v_cmp_eq_u32_e32 vcc, 1, v51
	s_nop 1
	v_cndmask_b32_e32 v51, v52, v21, vcc
	v_cmp_gt_u32_e32 vcc, 64, v49
	s_nop 1
	v_cndmask_b32_e32 v49, v51, v19, vcc
	v_bfe_u32 v51, v36, 2, 2
	v_cmp_eq_u32_e32 vcc, 2, v51
	s_nop 1
	v_cndmask_b32_e32 v52, v24, v22, vcc
	v_cmp_eq_u32_e32 vcc, 1, v51
	s_nop 1
	v_cndmask_b32_e32 v51, v52, v20, vcc
	v_cmp_gt_u32_e32 vcc, 4, v50
	v_bitop3_b32 v52, v33, 15, v33 bitop3:0xc
	s_nop 0
	v_cndmask_b32_e32 v50, v51, v18, vcc
	v_cmp_eq_u32_e32 vcc, 2, v53
	v_bitop3_b32 v51, v33, s3, v33 bitop3:0xc
	s_nop 0
	v_cndmask_b32_e32 v54, v25, v23, vcc
	v_cmp_eq_u32_e32 vcc, 1, v53
	s_nop 1
	v_cndmask_b32_e32 v53, v54, v21, vcc
	v_cmp_gt_u32_e32 vcc, 64, v51
	s_nop 1
	v_cndmask_b32_e32 v51, v53, v19, vcc
	v_bfe_u32 v53, v39, 2, 2
	v_cmp_eq_u32_e32 vcc, 2, v53
	s_nop 1
	v_cndmask_b32_e32 v54, v24, v22, vcc
	v_cmp_eq_u32_e32 vcc, 1, v53
	s_nop 1
	v_cndmask_b32_e32 v53, v54, v20, vcc
	v_cmp_gt_u32_e32 vcc, 4, v52
	v_bitop3_b32 v54, v28, 15, v28 bitop3:0xc
	s_nop 0
	v_cndmask_b32_e32 v52, v53, v18, vcc
	v_cmp_eq_u32_e32 vcc, 2, v55
	v_bitop3_b32 v53, v28, s3, v28 bitop3:0xc
	s_nop 0
	v_cndmask_b32_e32 v56, v25, v23, vcc
	v_cmp_eq_u32_e32 vcc, 1, v55
	s_nop 1
	v_cndmask_b32_e32 v55, v56, v21, vcc
	v_cmp_gt_u32_e32 vcc, 64, v53
	s_nop 1
	v_cndmask_b32_e32 v53, v55, v19, vcc
	v_bfe_u32 v55, v40, 2, 2
	v_cmp_eq_u32_e32 vcc, 2, v55
	s_nop 1
	v_cndmask_b32_e32 v56, v24, v22, vcc
	v_cmp_eq_u32_e32 vcc, 1, v55
	s_nop 1
	v_cndmask_b32_e32 v55, v56, v20, vcc
	v_cmp_gt_u32_e32 vcc, 4, v54
	v_bitop3_b32 v56, v41, 15, v41 bitop3:0xc
	s_nop 0
	v_cndmask_b32_e32 v54, v55, v18, vcc
	v_cmp_eq_u32_e32 vcc, 2, v57
	v_bitop3_b32 v55, v41, s3, v41 bitop3:0xc
	s_nop 0
	v_cndmask_b32_e32 v58, v25, v23, vcc
	v_cmp_eq_u32_e32 vcc, 1, v57
	s_nop 1
	v_cndmask_b32_e32 v57, v58, v21, vcc
	v_cmp_gt_u32_e32 vcc, 64, v55
	s_nop 1
	v_cndmask_b32_e32 v55, v57, v19, vcc
	v_bfe_u32 v57, v42, 2, 2
	v_cmp_eq_u32_e32 vcc, 2, v57
	s_nop 1
	v_cndmask_b32_e32 v58, v24, v22, vcc
	v_cmp_eq_u32_e32 vcc, 1, v57
	s_nop 1
	v_cndmask_b32_e32 v57, v58, v20, vcc
	v_cmp_gt_u32_e32 vcc, 4, v56
	v_bitop3_b32 v58, v30, 15, v30 bitop3:0xc
	s_nop 0
	v_cndmask_b32_e32 v56, v57, v18, vcc
	v_cmp_eq_u32_e32 vcc, 2, v59
	v_bitop3_b32 v57, v30, s3, v30 bitop3:0xc
	s_nop 0
	v_cndmask_b32_e32 v23, v25, v23, vcc
	v_cmp_eq_u32_e32 vcc, 1, v59
	v_sub_f32_e32 v25, v31, v32
	v_mul_f32_e32 v25, 0x3fb8aa3b, v25
	v_cndmask_b32_e32 v21, v23, v21, vcc
	v_cmp_gt_u32_e32 vcc, 64, v57
	v_lshrrev_b32_e32 v23, 1, v39
	v_and_b32_e32 v23, 24, v23
	v_cndmask_b32_e32 v19, v21, v19, vcc
	v_bfe_u32 v21, v43, 2, 2
	v_cmp_eq_u32_e32 vcc, 2, v21
	v_lshrrev_b32_e32 v23, v23, v51
	v_lshlrev_b32_e32 v23, 7, v23
	v_cndmask_b32_e32 v22, v24, v22, vcc
	v_cmp_eq_u32_e32 vcc, 1, v21
	v_lshrrev_b32_e32 v21, 1, v42
	v_and_b32_e32 v21, 24, v21
	v_cndmask_b32_e32 v20, v22, v20, vcc
	v_cmp_gt_u32_e32 vcc, 4, v58
	v_lshrrev_b32_e32 v21, v21, v55
	v_lshrrev_b32_e32 v22, 1, v40
	v_cndmask_b32_e32 v18, v20, v18, vcc
	v_lshlrev_b32_e32 v20, 3, v42
	v_lshlrev_b32_e32 v21, 7, v21
	v_and_b32_e32 v22, 24, v22
	v_lshrrev_b32_e32 v20, v20, v56
	v_and_b32_e32 v21, 0x7f80, v21
	v_lshrrev_b32_e32 v22, v22, v53
	v_and_or_b32 v21, v20, s3, v21
	v_lshlrev_b32_e32 v20, 3, v40
	v_lshlrev_b32_e32 v22, 7, v22
	v_lshrrev_b32_e32 v20, v20, v54
	v_and_b32_e32 v22, 0x7f80, v22
	v_and_or_b32 v20, v20, s3, v22
	v_lshlrev_b32_e32 v22, 3, v39
	v_lshrrev_b32_e32 v22, v22, v52
	v_and_b32_e32 v23, 0x7f80, v23
	v_and_or_b32 v39, v22, s3, v23
	v_lshrrev_b32_e32 v23, 1, v36
	v_and_b32_e32 v23, 24, v23
	v_lshrrev_b32_e32 v23, v23, v49
	v_lshlrev_b32_e32 v22, 3, v36
	v_lshlrev_b32_e32 v23, 7, v23
	v_lshrrev_b32_e32 v22, v22, v50
	v_and_b32_e32 v23, 0x7f80, v23
	v_and_or_b32 v36, v22, s3, v23
	v_lshrrev_b32_e32 v23, 1, v38
	v_and_b32_e32 v23, 24, v23
	v_lshrrev_b32_e32 v23, v23, v47
	v_lshlrev_b32_e32 v22, 3, v38
	v_lshlrev_b32_e32 v23, 7, v23
	v_lshrrev_b32_e32 v22, v22, v48
	v_and_b32_e32 v23, 0x7f80, v23
	v_and_or_b32 v38, v22, s3, v23
	v_lshrrev_b32_e32 v23, 1, v35
	v_and_b32_e32 v23, 24, v23
	v_lshrrev_b32_e32 v23, v23, v45
	v_lshlrev_b32_e32 v22, 3, v35
	v_lshlrev_b32_e32 v23, 7, v23
	v_lshrrev_b32_e32 v22, v22, v46
	v_and_b32_e32 v23, 0x7f80, v23
	v_and_or_b32 v35, v22, s3, v23
	v_lshrrev_b32_e32 v23, 1, v29
	v_and_b32_e32 v23, 24, v23
	v_lshrrev_b32_e32 v23, v23, v26
	v_lshlrev_b32_e32 v22, 3, v29
	v_lshlrev_b32_e32 v23, 7, v23
	v_lshrrev_b32_e32 v22, v22, v44
	v_and_b32_e32 v23, 0x7f80, v23
	v_and_or_b32 v40, v22, s3, v23
	v_sub_f32_e32 v22, v27, v32
	v_mul_f32_e32 v22, 0x3fb8aa3b, v22
	v_sub_f32_e32 v23, v34, v32
	v_exp_f32_e32 v22, v22
	v_mul_f32_e32 v23, 0x3fb8aa3b, v23
	v_sub_f32_e32 v24, v37, v32
	v_exp_f32_e32 v23, v23
	v_mul_f32_e32 v24, 0x3fb8aa3b, v24
	v_exp_f32_e32 v24, v24
	v_exp_f32_e32 v25, v25
	v_add_f32_e32 v26, 0, v22
	v_add_f32_e32 v26, v23, v26
	v_add_f32_e32 v26, v24, v26
	v_add_f32_e32 v31, v25, v26
	v_sub_f32_e32 v26, v33, v32
	v_mul_f32_e32 v26, 0x3fb8aa3b, v26
	v_sub_f32_e32 v27, v28, v32
	v_exp_f32_e32 v26, v26
	v_mul_f32_e32 v27, 0x3fb8aa3b, v27
	v_sub_f32_e32 v28, v41, v32
	v_exp_f32_e32 v27, v27
	v_mul_f32_e32 v28, 0x3fb8aa3b, v28
	v_sub_f32_e32 v29, v30, v32
	v_exp_f32_e32 v28, v28
	v_mul_f32_e32 v29, 0x3fb8aa3b, v29
	v_exp_f32_e32 v29, v29
	v_add_f32_e32 v30, v26, v31
	v_add_f32_e32 v30, v27, v30
	v_add_f32_e32 v30, v28, v30
	v_add_f32_e32 v30, v29, v30
	ds_bpermute_b32 v31, v123, v30
	v_lshrrev_b32_e32 v42, 1, v43
	v_and_b32_e32 v32, 24, v42
	v_lshrrev_b32_e32 v19, v32, v19
	v_lshlrev_b32_e32 v19, 7, v19
	s_waitcnt lgkmcnt(0)
; #define LAS __attribute__((address_space(3)))
; __device__ __forceinline__ void peer_u_item(int p, int j, const LAS unsigned short* EL  , const unsigned char* __restrict__ XQ, const unsigned char* __restrict__ U8, LAS int* ACC  , int lane, int wave) {
;     ...
;     const int gidx = lane >> 3; const unsigned coff = (unsigned)(p * 128 + (lane & 7) * 16), toff = (unsigned)(p * (16384 * 128) + (lane & 7) * 16);
; #pragma unroll 1
;     for (int it = 0; it < 8; ++it) {
;         const int t = j * 64 + it * 8 + wave;
;         unsigned E[8];
;         { const LAS v4u* ep = (const LAS v4u*)(EL + (it * 8 + wave) * 128 + 16 * gidx); const v4u e0 = ep[0], e1 = ep[1];
;           E[0] = e0.x; E[1] = e0.y; E[2] = e0.z; E[3] = e0.w; E[4] = e1.x; E[5] = e1.y; E[6] = e1.z; E[7] = e1.w; }
;         uint4 uu[16];
; #pragma unroll
;         for (int i = 0; i < 16; ++i) uu[i] = *(const uint4*)(U8 + (size_t)(PE_ID(E, i) * 128u + toff));
;         const uint4 xh = *(const uint4*)(XQ + (size_t)t * 512 + coff), xl = *(const uint4*)(XQ + 8 * MiB + (size_t)t * 512 + coff);
; __device__ __forceinline__ void route_task(int task, int tl0, const bf16* QP  , const LAS bf16* KHL, LAS unsigned short* EL, LAS float* GL, int lane) {
;     ...
;     const float inv = 1.f / se;
;     {
;         int l2 = lane; asm volatile("" : "+v"(l2));
;         const int o2 = (tl0 + ((l2 & 31) >> 3)) * 128 + (l2 & 7) * 16 + 8 * (l2 >> 5);
;         LAS v4u* ip = (LAS v4u*)(EL + o2); typedef float f4v __attribute__((ext_vector_type(4))); LAS f4v* gp = (LAS f4v*)(GL + o2);
;         ip[0] = (v4u){(unsigned)bv[0] | ((unsigned)bv[1] << 16), (unsigned)bv[2] | ((unsigned)bv[3] << 16), (unsigned)bv[4] | ((unsigned)bv[5] << 16), (unsigned)bv[6] | ((unsigned)bv[7] << 16)};
;         gp[0] = (f4v){e[0] * inv, e[1] * inv, e[2] * inv, e[3] * inv}; gp[1] = (f4v){e[4] * inv, e[5] * inv, e[6] * inv, e[7] * inv};
;     }
	v_add_f32_e32 v30, v30, v31
	v_div_scale_f32 v31, s[12:13], v30, v30, 1.0
	v_rcp_f32_e32 v32, v31
	v_lshlrev_b32_e32 v33, 3, v43
	v_and_b32_e32 v19, 0x7f80, v19
	v_lshrrev_b32_e32 v18, v33, v18
	v_and_or_b32 v33, v18, s3, v19
	v_fma_f32 v18, -v31, v32, 1.0
	v_fmac_f32_e32 v32, v18, v32
	v_div_scale_f32 v18, vcc, 1.0, v30, 1.0
	v_mul_f32_e32 v19, v18, v32
	v_fma_f32 v34, -v31, v19, v18
	v_fmac_f32_e32 v19, v34, v32
	v_fma_f32 v18, -v31, v19, v18
	v_div_fmas_f32 v18, v18, v32, v19
	v_div_fixup_f32 v30, v18, v30, 1.0
	v_mov_b32_e32 v18, v1
	v_lshl_or_b32 v20, v20, 16, v39
	v_lshrrev_b32_e32 v19, 3, v18
	v_and_or_b32 v19, v19, 3, s57
	v_lshlrev_b32_e32 v31, 4, v18
	v_ashrrev_i32_e32 v18, 2, v18
	v_lshlrev_b32_e32 v19, 7, v19
	v_and_b32_e32 v31, 0x70, v31
	v_and_b32_e32 v18, -8, v18
	v_add3_u32 v18, v18, v31, v19
	v_lshl_add_u32 v31, v18, 1, s11
	v_lshl_add_u32 v32, v18, 2, s69
	v_lshl_or_b32 v18, v35, 16, v40
	v_lshl_or_b32 v19, v36, 16, v38
	v_lshl_or_b32 v21, v33, 16, v21
	ds_write_b128 v31, v[18:21]
	v_pk_mul_f32 v[20:21], v[24:25], v[30:31] op_sel_hi:[1,0]
	v_pk_mul_f32 v[18:19], v[22:23], v[30:31] op_sel_hi:[1,0]
	ds_write_b128 v32, v[18:21]
	v_pk_mul_f32 v[20:21], v[28:29], v[30:31] op_sel_hi:[1,0]
	v_pk_mul_f32 v[18:19], v[26:27], v[30:31] op_sel_hi:[1,0]
	ds_write_b128 v32, v[18:21] offset:16
	v_xor_b32_e32 v18, 4, v112
	v_cmp_lt_i32_e32 vcc, v18, v122
	s_waitcnt lgkmcnt(0)
	s_barrier
	v_cndmask_b32_e32 v18, v112, v18, vcc
	v_lshlrev_b32_e32 v30, 2, v18
	v_xor_b32_e32 v18, 2, v112
	v_cmp_lt_i32_e32 vcc, v18, v122
	s_nop 1
	v_cndmask_b32_e32 v18, v112, v18, vcc
	v_lshlrev_b32_e32 v31, 2, v18
	v_xor_b32_e32 v18, 1, v112
	v_cmp_lt_i32_e32 vcc, v18, v122
	s_nop 1
	v_cndmask_b32_e32 v18, v112, v18, vcc
	v_lshlrev_b32_e32 v32, 2, v18
	v_lshlrev_b32_e32 v56, 4, v1
	v_and_b32_e32 v56, 0x70, v56
	v_lshrrev_b32_e32 v59, 3, v1
	v_lshlrev_b32_e32 v59, 5, v59
	v_add_u32_e32 v59, s66, v59
	v_add_u32_e32 v59, -16, v59
	v_lshl_add_u32 v60, v1, 3, s64
	v_and_b32_e32 v38, 4, v1
	v_cmp_ne_u32_e64 s[10:11], 0, v38
	v_and_b32_e32 v38, 2, v1
	v_cmp_ne_u32_e64 s[12:13], 0, v38
	v_and_b32_e32 v38, 1, v1
	v_cmp_ne_u32_e64 s[14:15], 0, v38
	s_movk_i32 s94, 0x80
	s_mov_b32 s42, 0
	s_mov_b32 s43, 0
	s_mov_b32 s44, 1
	s_mov_b32 s45, 0
	s_lshl_b32 s32, s42, 11
	v_add_u32_e32 v39, s32, v59
	ds_read_b128 v[202:205], v39
	ds_read_b128 v[206:209], v39 offset:16
	s_lshl_b32 s46, s42, 3
	s_add_i32 s46, s46, s40
	s_lshl_b32 s46, s46, 9
	s_lshl_b32 s32, s43, 7
	s_add_i32 s46, s46, s32
	v_add_u32_e32 v57, s46, v56
	global_load_dwordx4 v[186:189], v57, s[34:35]
	global_load_dwordx4 v[190:193], v57, s[36:37]
	v_mov_b32_e32 v58, v56
	s_waitcnt lgkmcnt(0)
	v_and_b32_e32 v38, 0xffff, v202
	v_lshl_add_u32 v38, v38, 7, v58
	global_load_dwordx4 v[122:125], v38, s[96:97]
	v_lshrrev_b32_e32 v38, 16, v202
	v_lshl_add_u32 v38, v38, 7, v58
	global_load_dwordx4 v[126:129], v38, s[96:97]
	v_and_b32_e32 v38, 0xffff, v203
	v_lshl_add_u32 v38, v38, 7, v58
	global_load_dwordx4 v[130:133], v38, s[96:97]
	v_lshrrev_b32_e32 v38, 16, v203
	v_lshl_add_u32 v38, v38, 7, v58
	global_load_dwordx4 v[134:137], v38, s[96:97]
	v_and_b32_e32 v38, 0xffff, v204
	v_lshl_add_u32 v38, v38, 7, v58
	global_load_dwordx4 v[138:141], v38, s[96:97]
	v_lshrrev_b32_e32 v38, 16, v204
	v_lshl_add_u32 v38, v38, 7, v58
	global_load_dwordx4 v[142:145], v38, s[96:97]
	v_and_b32_e32 v38, 0xffff, v205
	v_lshl_add_u32 v38, v38, 7, v58
	global_load_dwordx4 v[146:149], v38, s[96:97]
	v_lshrrev_b32_e32 v38, 16, v205
	v_lshl_add_u32 v38, v38, 7, v58
	global_load_dwordx4 v[150:153], v38, s[96:97]
	v_and_b32_e32 v38, 0xffff, v206
	v_lshl_add_u32 v38, v38, 7, v58
	global_load_dwordx4 v[154:157], v38, s[96:97]
	v_lshrrev_b32_e32 v38, 16, v206
	v_lshl_add_u32 v38, v38, 7, v58
	global_load_dwordx4 v[158:161], v38, s[96:97]
	v_and_b32_e32 v38, 0xffff, v207
	v_lshl_add_u32 v38, v38, 7, v58
	global_load_dwordx4 v[162:165], v38, s[96:97]
	v_lshrrev_b32_e32 v38, 16, v207
	v_lshl_add_u32 v38, v38, 7, v58
	global_load_dwordx4 v[166:169], v38, s[96:97]
	v_and_b32_e32 v38, 0xffff, v208
	v_lshl_add_u32 v38, v38, 7, v58
	global_load_dwordx4 v[170:173], v38, s[96:97]
	v_lshrrev_b32_e32 v38, 16, v208
	v_lshl_add_u32 v38, v38, 7, v58
	global_load_dwordx4 v[174:177], v38, s[96:97]
	v_and_b32_e32 v38, 0xffff, v209
	v_lshl_add_u32 v38, v38, 7, v58
	global_load_dwordx4 v[178:181], v38, s[96:97]
	v_lshrrev_b32_e32 v38, 16, v209
	v_lshl_add_u32 v38, v38, 7, v58
	global_load_dwordx4 v[182:185], v38, s[96:97]
	s_mov_b32 s47, 16
